# row passes (P0, P3, P8, P10, P13): first four levels of every wave_sum butterfly as DPP moves instead of ds_bpermute (strategy: DPP for intra-wave movement)
# baseline (speedup 1.0000x reference)
; #define LAS __attribute__((address_space(3)))
; __device__ __forceinline__ unsigned cvt_pk_nv(float lo, float hi) { unsigned r; asm("v_cvt_pk_bf16_f32 %0, %1, %2" : "=v"(r) : "v"(lo), "v"(hi)); return r; }
; __device__ __forceinline__ void p0_block_item(const float* W, const float* gk, int K, int N, bf16* WT, int mode, int item, LAS float* tile, int tid) {
;     ...
;     __syncthreads();
; #pragma unroll
;     for (int i = 0; i < 8; ++i) { LAS float* p = tile + (lr + 8 * i) * 257 + lc; p[0] = v[i].x; p[1] = v[i].y; p[2] = v[i].z; p[3] = v[i].w; }
;     __syncthreads();
;     const int c = tid & 7;
; #pragma unroll
;     for (int j = 0; j < 4; ++j) {
;         const int n = (tid >> 3) + 64 * j, ng = n0 + n;
;         const int drow = (mode == 0) ? ng : (256 * (ng >> 7) + (ng & 127) + (mode == 2 ? 128 : 0));
;         const LAS float* sp = tile + (8 * c) * 257 + n;
;         v4u o; o.x = cvt_pk_nv(sp[0 * 257], sp[1 * 257]); o.y = cvt_pk_nv(sp[2 * 257], sp[3 * 257]); o.z = cvt_pk_nv(sp[4 * 257], sp[5 * 257]); o.w = cvt_pk_nv(sp[6 * 257], sp[7 * 257]);
;         *(v4u*)(WT + (size_t)drow * K + k0 + 8 * c) = o;
;     }
.LBB0_17:
	s_load_dwordx2 s[20:21], s[20:21], 0x110
	s_ashr_i32 s19, s18, 31
	s_lshl_b64 s[18:19], s[18:19], 1
	v_mov_b32_e32 v35, v33
	s_mulk_i32 s50, 0xea00
	s_waitcnt lgkmcnt(0)
	s_add_u32 s18, s20, s18
	s_addc_u32 s19, s21, s19
	s_barrier
	s_waitcnt vmcnt(7)
	ds_write2_b32 v39, v4, v5 offset1:1
	ds_write2_b32 v39, v6, v7 offset0:2 offset1:3
	s_waitcnt vmcnt(6)
	ds_write2_b32 v52, v0, v1 offset1:1
	ds_write2_b32 v53, v2, v3 offset1:1
	s_waitcnt vmcnt(5)
	ds_write2_b32 v54, v12, v13 offset1:1
	ds_write2_b32 v55, v14, v15 offset1:1
	s_waitcnt vmcnt(4)
	ds_write2_b32 v56, v8, v9 offset1:1
	ds_write2_b32 v57, v10, v11 offset1:1
	s_waitcnt vmcnt(3)
	ds_write2_b32 v58, v20, v21 offset1:1
	ds_write2_b32 v59, v22, v23 offset1:1
	s_waitcnt vmcnt(2)
	ds_write2_b32 v60, v16, v17 offset1:1
	ds_write2_b32 v61, v18, v19 offset1:1
	s_waitcnt vmcnt(1)
	ds_write2_b32 v62, v28, v29 offset1:1
	ds_write2_b32 v63, v30, v31 offset1:1
	s_waitcnt vmcnt(0)
	ds_write2_b32 v64, v24, v25 offset1:1
	ds_write2_b32 v65, v26, v27 offset1:1
	v_lshl_add_u64 v[0:1], s[18:19], 0, v[34:35]
	v_add_u32_e32 v35, s50, v51
	v_and_or_b32 v6, v35, s48, v45
	s_waitcnt lgkmcnt(0)
	s_barrier
	ds_read2st64_b32 v[8:9], v41 offset1:1
	ds_read2st64_b32 v[10:11], v66 offset0:4 offset1:5
	ds_read2st64_b32 v[12:13], v67 offset0:8 offset1:9
	ds_read2st64_b32 v[14:15], v68 offset0:12 offset1:13
	ds_read2st64_b32 v[16:17], v41 offset0:2 offset1:3
	ds_read2st64_b32 v[18:19], v66 offset0:6 offset1:7
	ds_read2st64_b32 v[20:21], v67 offset0:10 offset1:11
	ds_read2st64_b32 v[22:23], v68 offset0:14 offset1:15
	ds_read2st64_b32 v[24:25], v69 offset0:16 offset1:17
	ds_read2st64_b32 v[26:27], v70 offset0:20 offset1:21
	ds_read2st64_b32 v[28:29], v71 offset0:24 offset1:25
	ds_read2st64_b32 v[30:31], v72 offset0:28 offset1:29
	ds_read2st64_b32 v[36:37], v69 offset0:18 offset1:19
	ds_read2st64_b32 v[74:75], v70 offset0:22 offset1:23
	v_ashrrev_i32_e32 v7, 31, v6
	v_lshl_add_u64 v[4:5], v[0:1], 0, s[16:17]
	v_lshlrev_b64 v[6:7], 11, v[6:7]
	s_waitcnt lgkmcnt(0)
	v_cvt_pk_bf16_f32 v0, v8, v10
	v_lshl_add_u64 v[6:7], v[4:5], 0, v[6:7]
	s_waitcnt lgkmcnt(0)
	v_cvt_pk_bf16_f32 v1, v12, v14
	s_waitcnt lgkmcnt(0)
	v_cvt_pk_bf16_f32 v2, v24, v26
	ds_read2st64_b32 v[76:77], v71 offset0:26 offset1:27
	ds_read2st64_b32 v[78:79], v72 offset0:30 offset1:31
	s_waitcnt lgkmcnt(0)
	v_cvt_pk_bf16_f32 v3, v28, v30
	global_store_dwordx4 v[6:7], v[0:3], off
	s_nop 1
	v_add_u32_e32 v0, 0x80, v35
	v_and_or_b32 v6, v0, s48, v46
	v_ashrrev_i32_e32 v7, 31, v6
	v_lshlrev_b64 v[6:7], 11, v[6:7]
	v_cvt_pk_bf16_f32 v0, v9, v11
	v_lshl_add_u64 v[6:7], v[4:5], 0, v[6:7]
	v_cvt_pk_bf16_f32 v1, v13, v15
	v_cvt_pk_bf16_f32 v2, v25, v27
	v_cvt_pk_bf16_f32 v3, v29, v31
	global_store_dwordx4 v[6:7], v[0:3], off
	s_nop 1
	v_add_u32_e32 v0, 0x100, v35
	v_and_or_b32 v6, v0, s48, v45
	v_ashrrev_i32_e32 v7, 31, v6
	v_lshlrev_b64 v[6:7], 11, v[6:7]
	v_cvt_pk_bf16_f32 v0, v16, v18
	v_lshl_add_u64 v[6:7], v[4:5], 0, v[6:7]
	v_cvt_pk_bf16_f32 v1, v20, v22
	s_waitcnt lgkmcnt(0)
	v_cvt_pk_bf16_f32 v2, v36, v74
	s_waitcnt lgkmcnt(0)
	v_cvt_pk_bf16_f32 v3, v76, v78
	global_store_dwordx4 v[6:7], v[0:3], off
	s_nop 1
	v_add_u32_e32 v0, 0x180, v35
	v_and_or_b32 v6, v0, s48, v47
	v_ashrrev_i32_e32 v7, 31, v6
	v_lshlrev_b64 v[6:7], 11, v[6:7]
	v_lshl_add_u64 v[4:5], v[4:5], 0, v[6:7]
	v_cvt_pk_bf16_f32 v0, v17, v19
	v_cvt_pk_bf16_f32 v1, v21, v23
	v_cvt_pk_bf16_f32 v2, v37, v75
	v_cvt_pk_bf16_f32 v3, v77, v79
	global_store_dwordx4 v[4:5], v[0:3], off

; __device__ __forceinline__ void p0_block_item(const float* W, const float* gk, int K, int N, bf16* WT, int mode, int item, LAS float* tile, int tid) {
;     ...
; #pragma unroll
;     for (int i = 0; i < 8; ++i) v[i] = __builtin_nontemporal_load((const v4f*)(W + (size_t)(k0 + lr + 8 * i) * N + n0 + lc));
;     if (gk) {
; #pragma unroll
;         for (int i = 0; i < 8; ++i) v[i] = v[i] * gk[k0 + lr + 8 * i];
;     }
;     __syncthreads();
; #pragma unroll
;     for (int i = 0; i < 8; ++i) { LAS float* p = tile + (lr + 8 * i) * 257 + lc; p[0] = v[i].x; p[1] = v[i].y; p[2] = v[i].z; p[3] = v[i].w; }
;     __syncthreads();
;     const int c = tid & 7;
; #pragma unroll
;     for (int j = 0; j < 4; ++j) {
;         const int n = (tid >> 3) + 64 * j, ng = n0 + n;
;         const int drow = (mode == 0) ? ng : (256 * (ng >> 7) + (ng & 127) + (mode == 2 ? 128 : 0));
;         const LAS float* sp = tile + (8 * c) * 257 + n;
;         v4u o; o.x = cvt_pk_nv(sp[0 * 257], sp[1 * 257]); o.y = cvt_pk_nv(sp[2 * 257], sp[3 * 257]); o.z = cvt_pk_nv(sp[4 * 257], sp[5 * 257]); o.w = cvt_pk_nv(sp[6 * 257], sp[7 * 257]);
;         *(v4u*)(WT + (size_t)drow * K + k0 + 8 * c) = o;
; __device__ __forceinline__ void p0_prologue(const Ctx& C, LAS unsigned char* lds, int wave, int lane, int tid) {
;     ...
;     for (int it = blockIdx.x; it < NITEMS; it += gridDim.x) {
;         int r = it;
;         if (r < I_GU) { p0_block_item(C.in(5), C.in(4), DM, DFF, C.Wgu1(), 1, r, tile, tid); continue; } r -= I_GU;
;         if (r < I_GU) { p0_block_item(C.in(6), C.in(4), DM, DFF, C.Wgu1(), 2, r, tile, tid); continue; } r -= I_GU;
;         if (r < I_GU) { p0_block_item(C.in(29), C.in(28), DM, DFF, C.Wgu2(), 1, r, tile, tid); continue; } r -= I_GU;
;         if (r < I_GU) { p0_block_item(C.in(30), C.in(28), DM, DFF, C.Wgu2(), 2, r, tile, tid); continue; } r -= I_GU;
;         if (r < I_D) { p0_block_item(C.in(7), nullptr, DFF, DM, C.Wd1(), 0, r, tile, tid); continue; } r -= I_D;
;         if (r < I_D) { p0_block_item(C.in(31), nullptr, DFF, DM, C.Wd2(), 0, r, tile, tid); continue; } r -= I_D;
;         if (r < I_IN) { p0_block_item(C.in(10), C.in(9), DM, DIN, C.Win(), 0, r, tile, tid); continue; } r -= I_IN;
;         if (r < I_GLU) { p0_block_item(C.in(22), nullptr, BWD, BWD, C.Wglu(), 0, r, tile, tid); continue; } r -= I_GLU;
;         p0_block_item(C.in(26), nullptr, DM, DM, C.Wout(), 0, r, tile, tid);
.LBB0_19:
	s_cmpk_gt_i32 s49, 0xaf
	s_mov_b64 s[18:19], -1
	s_cbranch_scc0 .LBB0_57
	s_cmpk_gt_u32 s49, 0x15f
	s_cbranch_scc0 .LBB0_52
	s_cmpk_gt_u32 s49, 0x20f
	s_cbranch_scc0 .LBB0_47
	s_cmpk_gt_u32 s49, 0x2bf
	s_cbranch_scc0 .LBB0_42
	s_cmpk_gt_u32 s49, 0x36f
	s_cbranch_scc0 .LBB0_39
	s_cmpk_gt_u32 s49, 0x41f
	s_cbranch_scc0 .LBB0_36
	s_cmpk_gt_u32 s49, 0x47f
	s_cbranch_scc0 .LBB0_31
	s_cmpk_gt_u32 s49, 0x48f
	s_cbranch_scc0 .LBB0_28
	s_mov_b64 s[18:19], s[80:81]
	s_load_dwordx2 s[20:21], s[18:19], 0xd0
	s_and_b32 s18, s25, 0x300
	s_and_b32 s1, s27, 0xfc0
	s_lshl_b32 s2, s18, 2
	v_add_u32_e32 v0, s1, v38
	s_waitcnt lgkmcnt(0)
	s_add_u32 s20, s20, s2
	s_addc_u32 s21, s21, 0
	v_ashrrev_i32_e32 v1, 31, v0
	v_lshl_add_u64 v[2:3], s[20:21], 0, v[32:33]
	v_lshlrev_b64 v[0:1], 12, v[0:1]
	v_lshl_add_u64 v[28:29], v[2:3], 0, v[0:1]
	v_add_co_u32_e32 v4, vcc, s31, v28
	s_mov_b64 s[22:23], s[80:81]
	s_nop 0
	v_addc_co_u32_e32 v5, vcc, 0, v29, vcc
	v_add_co_u32_e32 v8, vcc, s0, v28
	global_load_dwordx4 v[0:3], v[28:29], off nt
	s_nop 0
	global_load_dwordx4 v[4:7], v[4:5], off nt
	v_addc_co_u32_e32 v9, vcc, 0, v29, vcc
	v_add_co_u32_e32 v12, vcc, s34, v28
	s_lshl_b32 s1, s1, 1
	s_nop 0
	v_addc_co_u32_e32 v13, vcc, 0, v29, vcc
	v_add_co_u32_e32 v16, vcc, s35, v28
	global_load_dwordx4 v[8:11], v[8:9], off nt
	s_nop 0
	global_load_dwordx4 v[12:15], v[12:13], off nt
	v_addc_co_u32_e32 v17, vcc, 0, v29, vcc
	v_add_co_u32_e32 v20, vcc, s36, v28
	v_mov_b32_e32 v35, v33
	s_nop 0
	v_addc_co_u32_e32 v21, vcc, 0, v29, vcc
	global_load_dwordx4 v[16:19], v[16:17], off nt
	s_nop 0
	global_load_dwordx4 v[20:23], v[20:21], off nt
	v_add_co_u32_e32 v24, vcc, s37, v28
	s_load_dwordx2 s[20:21], s[22:23], 0x110
	s_nop 0
	v_addc_co_u32_e32 v25, vcc, 0, v29, vcc
	global_load_dwordx4 v[24:27], v[24:25], off nt
	v_add_co_u32_e32 v28, vcc, s38, v28
	s_waitcnt lgkmcnt(0)
	s_add_u32 s20, s20, s1
	v_addc_co_u32_e32 v29, vcc, 0, v29, vcc
	global_load_dwordx4 v[28:31], v[28:29], off nt
	v_add_u32_e32 v36, s18, v40
	s_addc_u32 s21, s21, 0
	s_barrier
	v_lshl_add_u64 v[74:75], s[20:21], 0, v[34:35]
	v_ashrrev_i32_e32 v37, 31, v36
	v_lshl_add_u64 v[74:75], v[74:75], 0, s[4:5]
	v_lshlrev_b64 v[36:37], 11, v[36:37]
	v_lshl_add_u64 v[36:37], v[74:75], 0, v[36:37]
	s_waitcnt vmcnt(7)
	ds_write2_b32 v39, v0, v1 offset1:1
	ds_write2_b32 v39, v2, v3 offset0:2 offset1:3
	s_waitcnt vmcnt(6)
	ds_write2_b32 v52, v4, v5 offset1:1
	ds_write2_b32 v53, v6, v7 offset1:1
	s_waitcnt vmcnt(5)
	ds_write2_b32 v54, v8, v9 offset1:1
	ds_write2_b32 v55, v10, v11 offset1:1
	s_waitcnt vmcnt(4)
	ds_write2_b32 v56, v12, v13 offset1:1
	ds_write2_b32 v57, v14, v15 offset1:1
	s_waitcnt vmcnt(3)
	ds_write2_b32 v58, v16, v17 offset1:1
	ds_write2_b32 v59, v18, v19 offset1:1
	s_waitcnt vmcnt(2)
	ds_write2_b32 v60, v20, v21 offset1:1
	ds_write2_b32 v61, v22, v23 offset1:1
	s_waitcnt vmcnt(1)
	ds_write2_b32 v62, v24, v25 offset1:1
	ds_write2_b32 v63, v26, v27 offset1:1
	s_waitcnt vmcnt(0)
	ds_write2_b32 v64, v28, v29 offset1:1
	ds_write2_b32 v65, v30, v31 offset1:1
	s_waitcnt lgkmcnt(0)
	s_barrier
	ds_read2st64_b32 v[4:5], v70 offset0:20 offset1:21
	ds_read2st64_b32 v[6:7], v71 offset0:24 offset1:25
	ds_read2st64_b32 v[8:9], v72 offset0:28 offset1:29
	ds_read2st64_b32 v[10:11], v41 offset1:1
	ds_read2st64_b32 v[12:13], v41 offset0:2 offset1:3
	ds_read2st64_b32 v[14:15], v66 offset0:4 offset1:5
	ds_read2st64_b32 v[16:17], v66 offset0:6 offset1:7
	ds_read2st64_b32 v[18:19], v67 offset0:8 offset1:9
	ds_read2st64_b32 v[20:21], v67 offset0:10 offset1:11
	ds_read2st64_b32 v[22:23], v68 offset0:12 offset1:13
	ds_read2st64_b32 v[24:25], v68 offset0:14 offset1:15
	ds_read2st64_b32 v[26:27], v69 offset0:16 offset1:17
	ds_read2st64_b32 v[28:29], v69 offset0:18 offset1:19
	ds_read2st64_b32 v[30:31], v70 offset0:22 offset1:23
	s_waitcnt lgkmcnt(0)
	v_cvt_pk_bf16_f32 v2, v26, v4
	v_add_u32_e32 v4, s18, v42
	v_cvt_pk_bf16_f32 v0, v10, v14
	v_cvt_pk_bf16_f32 v1, v18, v22
	ds_read2st64_b32 v[76:77], v71 offset0:26 offset1:27
	ds_read2st64_b32 v[78:79], v72 offset0:30 offset1:31
	v_cvt_pk_bf16_f32 v3, v6, v8
	global_store_dwordx4 v[36:37], v[0:3], off
	s_nop 1
	v_cvt_pk_bf16_f32 v2, v27, v5
	v_ashrrev_i32_e32 v5, 31, v4
	v_lshlrev_b64 v[4:5], 11, v[4:5]
	v_lshl_add_u64 v[4:5], v[74:75], 0, v[4:5]
	v_cvt_pk_bf16_f32 v0, v11, v15
	v_cvt_pk_bf16_f32 v1, v19, v23
	v_cvt_pk_bf16_f32 v3, v7, v9
	global_store_dwordx4 v[4:5], v[0:3], off
	v_add_u32_e32 v4, s18, v43
	v_ashrrev_i32_e32 v5, 31, v4
	v_lshlrev_b64 v[4:5], 11, v[4:5]
	v_lshl_add_u64 v[4:5], v[74:75], 0, v[4:5]
	v_cvt_pk_bf16_f32 v0, v12, v16
	v_cvt_pk_bf16_f32 v1, v20, v24
	s_waitcnt lgkmcnt(0)
	v_cvt_pk_bf16_f32 v2, v28, v30
	s_waitcnt lgkmcnt(0)
	v_cvt_pk_bf16_f32 v3, v76, v78
	global_store_dwordx4 v[4:5], v[0:3], off
	v_add_u32_e32 v4, s18, v44
	v_ashrrev_i32_e32 v5, 31, v4
	v_lshlrev_b64 v[4:5], 11, v[4:5]
	v_lshl_add_u64 v[4:5], v[74:75], 0, v[4:5]
	v_cvt_pk_bf16_f32 v0, v13, v17
	v_cvt_pk_bf16_f32 v1, v21, v25
	v_cvt_pk_bf16_f32 v2, v29, v31
	v_cvt_pk_bf16_f32 v3, v77, v79
	global_store_dwordx4 v[4:5], v[0:3], off
	s_mov_b64 s[18:19], 0
; #define LAS __attribute__((address_space(3)))
; __device__ __forceinline__ unsigned cvt_pk_nv(float lo, float hi) { unsigned r; asm("v_cvt_pk_bf16_f32 %0, %1, %2" : "=v"(r) : "v"(lo), "v"(hi)); return r; }
; __device__ __forceinline__ void p0_block_item(const float* W, const float* gk, int K, int N, bf16* WT, int mode, int item, LAS float* tile, int tid) {
;     ...
; #pragma unroll
;     for (int i = 0; i < 8; ++i) v[i] = __builtin_nontemporal_load((const v4f*)(W + (size_t)(k0 + lr + 8 * i) * N + n0 + lc));
;     if (gk) {
; #pragma unroll
;         for (int i = 0; i < 8; ++i) v[i] = v[i] * gk[k0 + lr + 8 * i];
;     }
;     __syncthreads();
; #pragma unroll
;     for (int i = 0; i < 8; ++i) { LAS float* p = tile + (lr + 8 * i) * 257 + lc; p[0] = v[i].x; p[1] = v[i].y; p[2] = v[i].z; p[3] = v[i].w; }
;     __syncthreads();
;     const int c = tid & 7;
; #pragma unroll
;     for (int j = 0; j < 4; ++j) {
;         const int n = (tid >> 3) + 64 * j, ng = n0 + n;
;         const int drow = (mode == 0) ? ng : (256 * (ng >> 7) + (ng & 127) + (mode == 2 ? 128 : 0));
;         const LAS float* sp = tile + (8 * c) * 257 + n;
;         v4u o; o.x = cvt_pk_nv(sp[0 * 257], sp[1 * 257]); o.y = cvt_pk_nv(sp[2 * 257], sp[3 * 257]); o.z = cvt_pk_nv(sp[4 * 257], sp[5 * 257]); o.w = cvt_pk_nv(sp[6 * 257], sp[7 * 257]);
;         *(v4u*)(WT + (size_t)drow * K + k0 + 8 * c) = o;
;     }
.LBB0_28:
	s_andn2_b64 vcc, exec, s[18:19]
	s_cbranch_vccnz .LBB0_30
	s_mov_b64 s[18:19], s[80:81]
	s_load_dwordx2 s[20:21], s[18:19], 0xb0
	s_and_b32 s1, s29, 0x1fc0
	s_and_b32 s18, s25, 0x100
	s_xor_b32 s1, s1, 0x1000
	s_lshl_b32 s2, s18, 2
	v_add_u32_e32 v0, s1, v38
	s_waitcnt lgkmcnt(0)
	s_add_u32 s20, s20, s2
	s_addc_u32 s21, s21, 0
	v_ashrrev_i32_e32 v1, 31, v0
	v_lshl_add_u64 v[2:3], s[20:21], 0, v[32:33]
	v_lshlrev_b64 v[0:1], 11, v[0:1]
	v_lshl_add_u64 v[28:29], v[2:3], 0, v[0:1]
	v_add_co_u32_e32 v4, vcc, s39, v28
	s_mov_b64 s[22:23], s[80:81]
	s_nop 0
	v_addc_co_u32_e32 v5, vcc, 0, v29, vcc
	v_add_co_u32_e32 v8, vcc, s31, v28
	global_load_dwordx4 v[0:3], v[28:29], off nt
	s_nop 0
	global_load_dwordx4 v[4:7], v[4:5], off nt
	v_addc_co_u32_e32 v9, vcc, 0, v29, vcc
	v_add_co_u32_e32 v12, vcc, s40, v28
	s_lshl_b32 s1, s1, 1
	s_nop 0
	v_addc_co_u32_e32 v13, vcc, 0, v29, vcc
	v_add_co_u32_e32 v16, vcc, s0, v28
	global_load_dwordx4 v[8:11], v[8:9], off nt
	s_nop 0
	global_load_dwordx4 v[12:15], v[12:13], off nt
	v_addc_co_u32_e32 v17, vcc, 0, v29, vcc
	v_add_co_u32_e32 v20, vcc, s41, v28
	v_mov_b32_e32 v35, v33
	s_nop 0
	v_addc_co_u32_e32 v21, vcc, 0, v29, vcc
	global_load_dwordx4 v[16:19], v[16:17], off nt
	s_nop 0
	global_load_dwordx4 v[20:23], v[20:21], off nt
	v_add_co_u32_e32 v24, vcc, s34, v28
	s_load_dwordx2 s[20:21], s[22:23], 0x110
	s_nop 0
	v_addc_co_u32_e32 v25, vcc, 0, v29, vcc
	global_load_dwordx4 v[24:27], v[24:25], off nt
	v_add_co_u32_e32 v28, vcc, s42, v28
	s_waitcnt lgkmcnt(0)
	s_add_u32 s20, s20, s1
	v_addc_co_u32_e32 v29, vcc, 0, v29, vcc
	global_load_dwordx4 v[28:31], v[28:29], off nt
	v_add_u32_e32 v36, s18, v40
	s_addc_u32 s21, s21, 0
	s_barrier
	v_lshl_add_u64 v[74:75], s[20:21], 0, v[34:35]
	v_ashrrev_i32_e32 v37, 31, v36
	v_lshl_add_u64 v[74:75], v[74:75], 0, s[6:7]
	v_lshlrev_b64 v[36:37], 10, v[36:37]
	v_lshl_add_u64 v[36:37], v[74:75], 0, v[36:37]
	s_waitcnt vmcnt(7)
	ds_write2_b32 v39, v0, v1 offset1:1
	ds_write2_b32 v39, v2, v3 offset0:2 offset1:3
	s_waitcnt vmcnt(6)
	ds_write2_b32 v52, v4, v5 offset1:1
	ds_write2_b32 v53, v6, v7 offset1:1
	s_waitcnt vmcnt(5)
	ds_write2_b32 v54, v8, v9 offset1:1
	ds_write2_b32 v55, v10, v11 offset1:1
	s_waitcnt vmcnt(4)
	ds_write2_b32 v56, v12, v13 offset1:1
	ds_write2_b32 v57, v14, v15 offset1:1
	s_waitcnt vmcnt(3)
	ds_write2_b32 v58, v16, v17 offset1:1
	ds_write2_b32 v59, v18, v19 offset1:1
	s_waitcnt vmcnt(2)
	ds_write2_b32 v60, v20, v21 offset1:1
	ds_write2_b32 v61, v22, v23 offset1:1
	s_waitcnt vmcnt(1)
	ds_write2_b32 v62, v24, v25 offset1:1
	ds_write2_b32 v63, v26, v27 offset1:1
	s_waitcnt vmcnt(0)
	ds_write2_b32 v64, v28, v29 offset1:1
	ds_write2_b32 v65, v30, v31 offset1:1
	s_waitcnt lgkmcnt(0)
	s_barrier
	ds_read2st64_b32 v[4:5], v70 offset0:20 offset1:21
	ds_read2st64_b32 v[6:7], v71 offset0:24 offset1:25
	ds_read2st64_b32 v[8:9], v72 offset0:28 offset1:29
	ds_read2st64_b32 v[10:11], v41 offset1:1
	ds_read2st64_b32 v[12:13], v41 offset0:2 offset1:3
	ds_read2st64_b32 v[14:15], v66 offset0:4 offset1:5
	ds_read2st64_b32 v[16:17], v66 offset0:6 offset1:7
	ds_read2st64_b32 v[18:19], v67 offset0:8 offset1:9
	ds_read2st64_b32 v[20:21], v67 offset0:10 offset1:11
	ds_read2st64_b32 v[22:23], v68 offset0:12 offset1:13
	ds_read2st64_b32 v[24:25], v68 offset0:14 offset1:15
	ds_read2st64_b32 v[26:27], v69 offset0:16 offset1:17
	ds_read2st64_b32 v[28:29], v69 offset0:18 offset1:19
	ds_read2st64_b32 v[30:31], v70 offset0:22 offset1:23
	s_waitcnt lgkmcnt(0)
	v_cvt_pk_bf16_f32 v2, v26, v4
	v_add_u32_e32 v4, s18, v42
	v_cvt_pk_bf16_f32 v0, v10, v14
	v_cvt_pk_bf16_f32 v1, v18, v22
	ds_read2st64_b32 v[76:77], v71 offset0:26 offset1:27
	ds_read2st64_b32 v[78:79], v72 offset0:30 offset1:31
	v_cvt_pk_bf16_f32 v3, v6, v8
	global_store_dwordx4 v[36:37], v[0:3], off
	s_nop 1
	v_cvt_pk_bf16_f32 v2, v27, v5
	v_ashrrev_i32_e32 v5, 31, v4
	v_lshlrev_b64 v[4:5], 10, v[4:5]
	v_lshl_add_u64 v[4:5], v[74:75], 0, v[4:5]
	v_cvt_pk_bf16_f32 v0, v11, v15
	v_cvt_pk_bf16_f32 v1, v19, v23
	v_cvt_pk_bf16_f32 v3, v7, v9
	global_store_dwordx4 v[4:5], v[0:3], off
	v_add_u32_e32 v4, s18, v43
	v_ashrrev_i32_e32 v5, 31, v4
	v_lshlrev_b64 v[4:5], 10, v[4:5]
	v_lshl_add_u64 v[4:5], v[74:75], 0, v[4:5]
	v_cvt_pk_bf16_f32 v0, v12, v16
	v_cvt_pk_bf16_f32 v1, v20, v24
	s_waitcnt lgkmcnt(0)
	v_cvt_pk_bf16_f32 v2, v28, v30
	s_waitcnt lgkmcnt(0)
	v_cvt_pk_bf16_f32 v3, v76, v78
	global_store_dwordx4 v[4:5], v[0:3], off
	v_add_u32_e32 v4, s18, v44
	v_ashrrev_i32_e32 v5, 31, v4
	v_lshlrev_b64 v[4:5], 10, v[4:5]
	v_lshl_add_u64 v[4:5], v[74:75], 0, v[4:5]
	v_cvt_pk_bf16_f32 v0, v13, v17
	v_cvt_pk_bf16_f32 v1, v21, v25
	v_cvt_pk_bf16_f32 v2, v29, v31
	v_cvt_pk_bf16_f32 v3, v77, v79
	global_store_dwordx4 v[4:5], v[0:3], off

; #define LAS __attribute__((address_space(3)))
; __device__ __forceinline__ unsigned cvt_pk_nv(float lo, float hi) { unsigned r; asm("v_cvt_pk_bf16_f32 %0, %1, %2" : "=v"(r) : "v"(lo), "v"(hi)); return r; }
; __device__ __forceinline__ void p0_block_item(const float* W, const float* gk, int K, int N, bf16* WT, int mode, int item, LAS float* tile, int tid) {
;     ...
;     __syncthreads();
; #pragma unroll
;     for (int i = 0; i < 8; ++i) { LAS float* p = tile + (lr + 8 * i) * 257 + lc; p[0] = v[i].x; p[1] = v[i].y; p[2] = v[i].z; p[3] = v[i].w; }
;     __syncthreads();
;     const int c = tid & 7;
; #pragma unroll
;     for (int j = 0; j < 4; ++j) {
;         const int n = (tid >> 3) + 64 * j, ng = n0 + n;
;         const int drow = (mode == 0) ? ng : (256 * (ng >> 7) + (ng & 127) + (mode == 2 ? 128 : 0));
;         const LAS float* sp = tile + (8 * c) * 257 + n;
;         v4u o; o.x = cvt_pk_nv(sp[0 * 257], sp[1 * 257]); o.y = cvt_pk_nv(sp[2 * 257], sp[3 * 257]); o.z = cvt_pk_nv(sp[4 * 257], sp[5 * 257]); o.w = cvt_pk_nv(sp[6 * 257], sp[7 * 257]);
;         *(v4u*)(WT + (size_t)drow * K + k0 + 8 * c) = o;
;     }
.LBB0_34:
	s_load_dwordx2 s[18:19], s[18:19], 0x110
	s_lshl_b32 s1, s23, 8
	s_lshl_b32 s2, s22, 1
	s_waitcnt lgkmcnt(0)
	s_barrier
	s_add_u32 s18, s18, s2
	s_waitcnt vmcnt(7)
	ds_write2_b32 v39, v4, v5 offset1:1
	ds_write2_b32 v39, v6, v7 offset0:2 offset1:3
	s_waitcnt vmcnt(6)
	ds_write2_b32 v52, v0, v1 offset1:1
	ds_write2_b32 v53, v2, v3 offset1:1
	s_waitcnt vmcnt(5)
	ds_write2_b32 v54, v12, v13 offset1:1
	ds_write2_b32 v55, v14, v15 offset1:1
	s_waitcnt vmcnt(4)
	ds_write2_b32 v56, v8, v9 offset1:1
	ds_write2_b32 v57, v10, v11 offset1:1
	s_waitcnt vmcnt(3)
	ds_write2_b32 v58, v20, v21 offset1:1
	ds_write2_b32 v59, v22, v23 offset1:1
	s_waitcnt vmcnt(2)
	ds_write2_b32 v60, v16, v17 offset1:1
	ds_write2_b32 v61, v18, v19 offset1:1
	s_waitcnt vmcnt(1)
	ds_write2_b32 v62, v28, v29 offset1:1
	ds_write2_b32 v63, v30, v31 offset1:1
	s_waitcnt vmcnt(0)
	ds_write2_b32 v64, v24, v25 offset1:1
	ds_write2_b32 v65, v26, v27 offset1:1
	s_addc_u32 s19, s19, 0
	v_mov_b32_e32 v35, v33
	v_add_u32_e32 v6, s1, v40
	s_waitcnt lgkmcnt(0)
	s_barrier
	v_lshl_add_u64 v[0:1], s[18:19], 0, v[34:35]
	ds_read2st64_b32 v[8:9], v41 offset1:1
	ds_read2st64_b32 v[10:11], v66 offset0:4 offset1:5
	ds_read2st64_b32 v[12:13], v67 offset0:8 offset1:9
	ds_read2st64_b32 v[14:15], v68 offset0:12 offset1:13
	ds_read2st64_b32 v[16:17], v41 offset0:2 offset1:3
	ds_read2st64_b32 v[18:19], v66 offset0:6 offset1:7
	ds_read2st64_b32 v[20:21], v67 offset0:10 offset1:11
	ds_read2st64_b32 v[22:23], v68 offset0:14 offset1:15
	ds_read2st64_b32 v[24:25], v69 offset0:16 offset1:17
	ds_read2st64_b32 v[26:27], v70 offset0:20 offset1:21
	ds_read2st64_b32 v[28:29], v71 offset0:24 offset1:25
	ds_read2st64_b32 v[30:31], v72 offset0:28 offset1:29
	ds_read2st64_b32 v[36:37], v69 offset0:18 offset1:19
	ds_read2st64_b32 v[74:75], v70 offset0:22 offset1:23
	v_ashrrev_i32_e32 v7, 31, v6
	v_lshl_add_u64 v[4:5], v[0:1], 0, s[8:9]
	v_lshlrev_b64 v[6:7], 11, v[6:7]
	v_lshl_add_u64 v[6:7], v[4:5], 0, v[6:7]
	s_waitcnt lgkmcnt(0)
	v_cvt_pk_bf16_f32 v0, v8, v10
	s_waitcnt lgkmcnt(0)
	v_cvt_pk_bf16_f32 v1, v12, v14
	s_waitcnt lgkmcnt(0)
	v_cvt_pk_bf16_f32 v2, v24, v26
	ds_read2st64_b32 v[76:77], v71 offset0:26 offset1:27
	ds_read2st64_b32 v[78:79], v72 offset0:30 offset1:31
	s_waitcnt lgkmcnt(0)
	v_cvt_pk_bf16_f32 v3, v28, v30
	global_store_dwordx4 v[6:7], v[0:3], off
	v_add_u32_e32 v6, s1, v42
	v_ashrrev_i32_e32 v7, 31, v6
	v_lshlrev_b64 v[6:7], 11, v[6:7]
	v_lshl_add_u64 v[6:7], v[4:5], 0, v[6:7]
	v_cvt_pk_bf16_f32 v0, v9, v11
	v_cvt_pk_bf16_f32 v1, v13, v15
	v_cvt_pk_bf16_f32 v2, v25, v27
	v_cvt_pk_bf16_f32 v3, v29, v31
	global_store_dwordx4 v[6:7], v[0:3], off
	v_add_u32_e32 v6, s1, v43
	v_ashrrev_i32_e32 v7, 31, v6
	v_lshlrev_b64 v[6:7], 11, v[6:7]
	v_lshl_add_u64 v[6:7], v[4:5], 0, v[6:7]
	v_cvt_pk_bf16_f32 v0, v16, v18
	v_cvt_pk_bf16_f32 v1, v20, v22
	s_waitcnt lgkmcnt(0)
	v_cvt_pk_bf16_f32 v2, v36, v74
	s_waitcnt lgkmcnt(0)
	v_cvt_pk_bf16_f32 v3, v76, v78
	global_store_dwordx4 v[6:7], v[0:3], off
	v_add_u32_e32 v6, s1, v44
	v_ashrrev_i32_e32 v7, 31, v6
	v_lshlrev_b64 v[6:7], 11, v[6:7]
	v_lshl_add_u64 v[4:5], v[4:5], 0, v[6:7]
	v_cvt_pk_bf16_f32 v0, v17, v19
	v_cvt_pk_bf16_f32 v1, v21, v23
	v_cvt_pk_bf16_f32 v2, v37, v75
	v_cvt_pk_bf16_f32 v3, v77, v79
	global_store_dwordx4 v[4:5], v[0:3], off

; #define LAS __attribute__((address_space(3)))
; __device__ __forceinline__ unsigned cvt_pk_nv(float lo, float hi) { unsigned r; asm("v_cvt_pk_bf16_f32 %0, %1, %2" : "=v"(r) : "v"(lo), "v"(hi)); return r; }
; __device__ __forceinline__ void p0_block_item(const float* W, const float* gk, int K, int N, bf16* WT, int mode, int item, LAS float* tile, int tid) {
;     ...
; #pragma unroll
;     for (int i = 0; i < 8; ++i) v[i] = __builtin_nontemporal_load((const v4f*)(W + (size_t)(k0 + lr + 8 * i) * N + n0 + lc));
;     if (gk) {
; #pragma unroll
;         for (int i = 0; i < 8; ++i) v[i] = v[i] * gk[k0 + lr + 8 * i];
;     }
;     __syncthreads();
; #pragma unroll
;     for (int i = 0; i < 8; ++i) { LAS float* p = tile + (lr + 8 * i) * 257 + lc; p[0] = v[i].x; p[1] = v[i].y; p[2] = v[i].z; p[3] = v[i].w; }
;     __syncthreads();
;     const int c = tid & 7;
; #pragma unroll
;     for (int j = 0; j < 4; ++j) {
;         const int n = (tid >> 3) + 64 * j, ng = n0 + n;
;         const int drow = (mode == 0) ? ng : (256 * (ng >> 7) + (ng & 127) + (mode == 2 ? 128 : 0));
;         const LAS float* sp = tile + (8 * c) * 257 + n;
;         v4u o; o.x = cvt_pk_nv(sp[0 * 257], sp[1 * 257]); o.y = cvt_pk_nv(sp[2 * 257], sp[3 * 257]); o.z = cvt_pk_nv(sp[4 * 257], sp[5 * 257]); o.w = cvt_pk_nv(sp[6 * 257], sp[7 * 257]);
;         *(v4u*)(WT + (size_t)drow * K + k0 + 8 * c) = o;
;     }
.LBB0_36:
	s_andn2_b64 vcc, exec, s[18:19]
	s_cbranch_vccnz .LBB0_38
	s_mov_b64 s[18:19], s[80:81]
	s_load_dwordx2 s[20:21], s[18:19], 0xf8
	s_add_i32 s1, s27, 0x200
	s_and_b32 s18, s25, 0x300
	s_and_b32 s1, s1, 0xfc0
	s_lshl_b32 s2, s18, 2
	v_add_u32_e32 v0, s1, v38
	s_waitcnt lgkmcnt(0)
	s_add_u32 s20, s20, s2
	s_addc_u32 s21, s21, 0
	v_ashrrev_i32_e32 v1, 31, v0
	v_lshl_add_u64 v[2:3], s[20:21], 0, v[32:33]
	v_lshlrev_b64 v[0:1], 12, v[0:1]
	v_lshl_add_u64 v[28:29], v[2:3], 0, v[0:1]
	v_add_co_u32_e32 v4, vcc, s31, v28
	s_mov_b64 s[22:23], s[80:81]
	s_nop 0
	v_addc_co_u32_e32 v5, vcc, 0, v29, vcc
	v_add_co_u32_e32 v8, vcc, s0, v28
	global_load_dwordx4 v[0:3], v[28:29], off nt
	s_nop 0
	global_load_dwordx4 v[4:7], v[4:5], off nt
	v_addc_co_u32_e32 v9, vcc, 0, v29, vcc
	v_add_co_u32_e32 v12, vcc, s34, v28
	s_lshl_b32 s1, s1, 1
	s_nop 0
	v_addc_co_u32_e32 v13, vcc, 0, v29, vcc
	v_add_co_u32_e32 v16, vcc, s35, v28
	global_load_dwordx4 v[8:11], v[8:9], off nt
	s_nop 0
	global_load_dwordx4 v[12:15], v[12:13], off nt
	v_addc_co_u32_e32 v17, vcc, 0, v29, vcc
	v_add_co_u32_e32 v20, vcc, s36, v28
	v_mov_b32_e32 v35, v33
	s_nop 0
	v_addc_co_u32_e32 v21, vcc, 0, v29, vcc
	global_load_dwordx4 v[16:19], v[16:17], off nt
	s_nop 0
	global_load_dwordx4 v[20:23], v[20:21], off nt
	v_add_co_u32_e32 v24, vcc, s37, v28
	s_load_dwordx2 s[20:21], s[22:23], 0x110
	s_nop 0
	v_addc_co_u32_e32 v25, vcc, 0, v29, vcc
	global_load_dwordx4 v[24:27], v[24:25], off nt
	v_add_co_u32_e32 v28, vcc, s38, v28
	s_waitcnt lgkmcnt(0)
	s_add_u32 s20, s20, s1
	v_addc_co_u32_e32 v29, vcc, 0, v29, vcc
	global_load_dwordx4 v[28:31], v[28:29], off nt
	s_addc_u32 s21, s21, 0
	s_barrier
	v_lshl_add_u64 v[36:37], s[20:21], 0, v[34:35]
	v_add_u32_e32 v73, s18, v40
	v_lshl_add_u64 v[36:37], v[36:37], 0, s[10:11]
	v_mad_i64_i32 v[78:79], s[20:21], v73, s46, v[36:37]
	s_waitcnt vmcnt(7)
	ds_write2_b32 v39, v0, v1 offset1:1
	ds_write2_b32 v39, v2, v3 offset0:2 offset1:3
	s_waitcnt vmcnt(6)
	ds_write2_b32 v52, v4, v5 offset1:1
	ds_write2_b32 v53, v6, v7 offset1:1
	s_waitcnt vmcnt(5)
	ds_write2_b32 v54, v8, v9 offset1:1
	ds_write2_b32 v55, v10, v11 offset1:1
	s_waitcnt vmcnt(4)
	ds_write2_b32 v56, v12, v13 offset1:1
	ds_write2_b32 v57, v14, v15 offset1:1
	s_waitcnt vmcnt(3)
	ds_write2_b32 v58, v16, v17 offset1:1
	ds_write2_b32 v59, v18, v19 offset1:1
	s_waitcnt vmcnt(2)
	ds_write2_b32 v60, v20, v21 offset1:1
	ds_write2_b32 v61, v22, v23 offset1:1
	s_waitcnt vmcnt(1)
	ds_write2_b32 v62, v24, v25 offset1:1
	ds_write2_b32 v63, v26, v27 offset1:1
	s_waitcnt vmcnt(0)
	ds_write2_b32 v64, v28, v29 offset1:1
	ds_write2_b32 v65, v30, v31 offset1:1
	s_waitcnt lgkmcnt(0)
	s_barrier
	ds_read2st64_b32 v[4:5], v70 offset0:20 offset1:21
	ds_read2st64_b32 v[6:7], v71 offset0:24 offset1:25
	ds_read2st64_b32 v[8:9], v72 offset0:28 offset1:29
	ds_read2st64_b32 v[10:11], v41 offset1:1
	ds_read2st64_b32 v[12:13], v41 offset0:2 offset1:3
	ds_read2st64_b32 v[14:15], v66 offset0:4 offset1:5
	ds_read2st64_b32 v[16:17], v66 offset0:6 offset1:7
	ds_read2st64_b32 v[18:19], v67 offset0:8 offset1:9
	ds_read2st64_b32 v[20:21], v67 offset0:10 offset1:11
	ds_read2st64_b32 v[22:23], v68 offset0:12 offset1:13
	ds_read2st64_b32 v[24:25], v68 offset0:14 offset1:15
	ds_read2st64_b32 v[26:27], v69 offset0:16 offset1:17
	ds_read2st64_b32 v[28:29], v69 offset0:18 offset1:19
	ds_read2st64_b32 v[30:31], v70 offset0:22 offset1:23
	ds_read2st64_b32 v[74:75], v71 offset0:26 offset1:27
	ds_read2st64_b32 v[76:77], v72 offset0:30 offset1:31
	s_waitcnt lgkmcnt(0)
	v_cvt_pk_bf16_f32 v2, v26, v4
	v_add_u32_e32 v4, s18, v42
	v_cvt_pk_bf16_f32 v0, v10, v14
	v_cvt_pk_bf16_f32 v1, v18, v22
	v_cvt_pk_bf16_f32 v3, v6, v8
	global_store_dwordx4 v[78:79], v[0:3], off
	s_nop 1
	v_cvt_pk_bf16_f32 v2, v27, v5
	v_mad_i64_i32 v[4:5], s[20:21], v4, s46, v[36:37]
	v_cvt_pk_bf16_f32 v0, v11, v15
	v_cvt_pk_bf16_f32 v1, v19, v23
	v_cvt_pk_bf16_f32 v3, v7, v9
	global_store_dwordx4 v[4:5], v[0:3], off
	v_add_u32_e32 v4, s18, v43
	v_mad_i64_i32 v[4:5], s[20:21], v4, s46, v[36:37]
	v_cvt_pk_bf16_f32 v0, v12, v16
	v_cvt_pk_bf16_f32 v1, v20, v24
	s_waitcnt lgkmcnt(0)
	v_cvt_pk_bf16_f32 v2, v28, v30
	s_waitcnt lgkmcnt(0)
	v_cvt_pk_bf16_f32 v3, v74, v76
	global_store_dwordx4 v[4:5], v[0:3], off
	v_add_u32_e32 v4, s18, v44
	v_mad_i64_i32 v[4:5], s[18:19], v4, s46, v[36:37]
	v_cvt_pk_bf16_f32 v0, v13, v17
	v_cvt_pk_bf16_f32 v1, v21, v25
	v_cvt_pk_bf16_f32 v2, v29, v31
	v_cvt_pk_bf16_f32 v3, v75, v77
	global_store_dwordx4 v[4:5], v[0:3], off

; #define LAS __attribute__((address_space(3)))
; __device__ __forceinline__ unsigned cvt_pk_nv(float lo, float hi) { unsigned r; asm("v_cvt_pk_bf16_f32 %0, %1, %2" : "=v"(r) : "v"(lo), "v"(hi)); return r; }
; __device__ __forceinline__ void p0_block_item(const float* W, const float* gk, int K, int N, bf16* WT, int mode, int item, LAS float* tile, int tid) {
;     ...
; #pragma unroll
;     for (int i = 0; i < 8; ++i) v[i] = __builtin_nontemporal_load((const v4f*)(W + (size_t)(k0 + lr + 8 * i) * N + n0 + lc));
;     if (gk) {
; #pragma unroll
;         for (int i = 0; i < 8; ++i) v[i] = v[i] * gk[k0 + lr + 8 * i];
;     }
;     __syncthreads();
; #pragma unroll
;     for (int i = 0; i < 8; ++i) { LAS float* p = tile + (lr + 8 * i) * 257 + lc; p[0] = v[i].x; p[1] = v[i].y; p[2] = v[i].z; p[3] = v[i].w; }
;     __syncthreads();
;     const int c = tid & 7;
; #pragma unroll
;     for (int j = 0; j < 4; ++j) {
;         const int n = (tid >> 3) + 64 * j, ng = n0 + n;
;         const int drow = (mode == 0) ? ng : (256 * (ng >> 7) + (ng & 127) + (mode == 2 ? 128 : 0));
;         const LAS float* sp = tile + (8 * c) * 257 + n;
;         v4u o; o.x = cvt_pk_nv(sp[0 * 257], sp[1 * 257]); o.y = cvt_pk_nv(sp[2 * 257], sp[3 * 257]); o.z = cvt_pk_nv(sp[4 * 257], sp[5 * 257]); o.w = cvt_pk_nv(sp[6 * 257], sp[7 * 257]);
;         *(v4u*)(WT + (size_t)drow * K + k0 + 8 * c) = o;
;     }
.LBB0_39:
	s_andn2_b64 vcc, exec, s[18:19]
	s_cbranch_vccnz .LBB0_41
	s_mov_b64 s[18:19], s[80:81]
	s_load_dwordx2 s[20:21], s[18:19], 0x38
	s_add_i32 s1, s27, 0xfffffd00
	s_and_b32 s18, s25, 0x300
	s_and_b32 s1, s1, 0xfc0
	s_lshl_b32 s2, s18, 2
	v_add_u32_e32 v0, s1, v38
	s_waitcnt lgkmcnt(0)
	s_add_u32 s20, s20, s2
	s_addc_u32 s21, s21, 0
	v_ashrrev_i32_e32 v1, 31, v0
	v_lshl_add_u64 v[2:3], s[20:21], 0, v[32:33]
	v_lshlrev_b64 v[0:1], 12, v[0:1]
	v_lshl_add_u64 v[28:29], v[2:3], 0, v[0:1]
	v_add_co_u32_e32 v4, vcc, s31, v28
	s_mov_b64 s[22:23], s[80:81]
	s_nop 0
	v_addc_co_u32_e32 v5, vcc, 0, v29, vcc
	v_add_co_u32_e32 v8, vcc, s0, v28
	global_load_dwordx4 v[0:3], v[28:29], off nt
	s_nop 0
	global_load_dwordx4 v[4:7], v[4:5], off nt
	v_addc_co_u32_e32 v9, vcc, 0, v29, vcc
	v_add_co_u32_e32 v12, vcc, s34, v28
	s_lshl_b32 s1, s1, 1
	s_nop 0
	v_addc_co_u32_e32 v13, vcc, 0, v29, vcc
	v_add_co_u32_e32 v16, vcc, s35, v28
	global_load_dwordx4 v[8:11], v[8:9], off nt
	s_nop 0
	global_load_dwordx4 v[12:15], v[12:13], off nt
	v_addc_co_u32_e32 v17, vcc, 0, v29, vcc
	v_add_co_u32_e32 v20, vcc, s36, v28
	v_mov_b32_e32 v35, v33
	s_nop 0
	v_addc_co_u32_e32 v21, vcc, 0, v29, vcc
	global_load_dwordx4 v[16:19], v[16:17], off nt
	s_nop 0
	global_load_dwordx4 v[20:23], v[20:21], off nt
	v_add_co_u32_e32 v24, vcc, s37, v28
	s_load_dwordx2 s[20:21], s[22:23], 0x110
	s_nop 0
	v_addc_co_u32_e32 v25, vcc, 0, v29, vcc
	global_load_dwordx4 v[24:27], v[24:25], off nt
	v_add_co_u32_e32 v28, vcc, s38, v28
	s_waitcnt lgkmcnt(0)
	s_add_u32 s20, s20, s1
	v_addc_co_u32_e32 v29, vcc, 0, v29, vcc
	global_load_dwordx4 v[28:31], v[28:29], off nt
	s_addc_u32 s21, s21, 0
	s_barrier
	v_lshl_add_u64 v[36:37], s[20:21], 0, v[34:35]
	v_add_u32_e32 v73, s18, v40
	v_lshl_add_u64 v[36:37], v[36:37], 0, s[12:13]
	v_mad_i64_i32 v[78:79], s[20:21], v73, s46, v[36:37]
	s_waitcnt vmcnt(7)
	ds_write2_b32 v39, v0, v1 offset1:1
	ds_write2_b32 v39, v2, v3 offset0:2 offset1:3
	s_waitcnt vmcnt(6)
	ds_write2_b32 v52, v4, v5 offset1:1
	ds_write2_b32 v53, v6, v7 offset1:1
	s_waitcnt vmcnt(5)
	ds_write2_b32 v54, v8, v9 offset1:1
	ds_write2_b32 v55, v10, v11 offset1:1
	s_waitcnt vmcnt(4)
	ds_write2_b32 v56, v12, v13 offset1:1
	ds_write2_b32 v57, v14, v15 offset1:1
	s_waitcnt vmcnt(3)
	ds_write2_b32 v58, v16, v17 offset1:1
	ds_write2_b32 v59, v18, v19 offset1:1
	s_waitcnt vmcnt(2)
	ds_write2_b32 v60, v20, v21 offset1:1
	ds_write2_b32 v61, v22, v23 offset1:1
	s_waitcnt vmcnt(1)
	ds_write2_b32 v62, v24, v25 offset1:1
	ds_write2_b32 v63, v26, v27 offset1:1
	s_waitcnt vmcnt(0)
	ds_write2_b32 v64, v28, v29 offset1:1
	ds_write2_b32 v65, v30, v31 offset1:1
	s_waitcnt lgkmcnt(0)
	s_barrier
	ds_read2st64_b32 v[4:5], v70 offset0:20 offset1:21
	ds_read2st64_b32 v[6:7], v71 offset0:24 offset1:25
	ds_read2st64_b32 v[8:9], v72 offset0:28 offset1:29
	ds_read2st64_b32 v[10:11], v41 offset1:1
	ds_read2st64_b32 v[12:13], v41 offset0:2 offset1:3
	ds_read2st64_b32 v[14:15], v66 offset0:4 offset1:5
	ds_read2st64_b32 v[16:17], v66 offset0:6 offset1:7
	ds_read2st64_b32 v[18:19], v67 offset0:8 offset1:9
	ds_read2st64_b32 v[20:21], v67 offset0:10 offset1:11
	ds_read2st64_b32 v[22:23], v68 offset0:12 offset1:13
	ds_read2st64_b32 v[24:25], v68 offset0:14 offset1:15
	ds_read2st64_b32 v[26:27], v69 offset0:16 offset1:17
	ds_read2st64_b32 v[28:29], v69 offset0:18 offset1:19
	ds_read2st64_b32 v[30:31], v70 offset0:22 offset1:23
	ds_read2st64_b32 v[74:75], v71 offset0:26 offset1:27
	ds_read2st64_b32 v[76:77], v72 offset0:30 offset1:31
	s_waitcnt lgkmcnt(0)
	v_cvt_pk_bf16_f32 v2, v26, v4
	v_add_u32_e32 v4, s18, v42
	v_cvt_pk_bf16_f32 v0, v10, v14
	v_cvt_pk_bf16_f32 v1, v18, v22
	v_cvt_pk_bf16_f32 v3, v6, v8
	global_store_dwordx4 v[78:79], v[0:3], off
	s_nop 1
	v_cvt_pk_bf16_f32 v2, v27, v5
	v_mad_i64_i32 v[4:5], s[20:21], v4, s46, v[36:37]
	v_cvt_pk_bf16_f32 v0, v11, v15
	v_cvt_pk_bf16_f32 v1, v19, v23
	v_cvt_pk_bf16_f32 v3, v7, v9
	global_store_dwordx4 v[4:5], v[0:3], off
	v_add_u32_e32 v4, s18, v43
	v_mad_i64_i32 v[4:5], s[20:21], v4, s46, v[36:37]
	v_cvt_pk_bf16_f32 v0, v12, v16
	v_cvt_pk_bf16_f32 v1, v20, v24
	s_waitcnt lgkmcnt(0)
	v_cvt_pk_bf16_f32 v2, v28, v30
	s_waitcnt lgkmcnt(0)
	v_cvt_pk_bf16_f32 v3, v74, v76
	global_store_dwordx4 v[4:5], v[0:3], off
	v_add_u32_e32 v4, s18, v44
	v_mad_i64_i32 v[4:5], s[18:19], v4, s46, v[36:37]
	v_cvt_pk_bf16_f32 v0, v13, v17
	v_cvt_pk_bf16_f32 v1, v21, v25
	v_cvt_pk_bf16_f32 v2, v29, v31
	v_cvt_pk_bf16_f32 v3, v75, v77
	global_store_dwordx4 v[4:5], v[0:3], off

; #define LAS __attribute__((address_space(3)))
; __device__ __forceinline__ unsigned cvt_pk_nv(float lo, float hi) { unsigned r; asm("v_cvt_pk_bf16_f32 %0, %1, %2" : "=v"(r) : "v"(lo), "v"(hi)); return r; }
; __device__ __forceinline__ void p0_block_item(const float* W, const float* gk, int K, int N, bf16* WT, int mode, int item, LAS float* tile, int tid) {
;     ...
;     __syncthreads();
; #pragma unroll
;     for (int i = 0; i < 8; ++i) { LAS float* p = tile + (lr + 8 * i) * 257 + lc; p[0] = v[i].x; p[1] = v[i].y; p[2] = v[i].z; p[3] = v[i].w; }
;     __syncthreads();
;     const int c = tid & 7;
; #pragma unroll
;     for (int j = 0; j < 4; ++j) {
;         const int n = (tid >> 3) + 64 * j, ng = n0 + n;
;         const int drow = (mode == 0) ? ng : (256 * (ng >> 7) + (ng & 127) + (mode == 2 ? 128 : 0));
;         const LAS float* sp = tile + (8 * c) * 257 + n;
;         v4u o; o.x = cvt_pk_nv(sp[0 * 257], sp[1 * 257]); o.y = cvt_pk_nv(sp[2 * 257], sp[3 * 257]); o.z = cvt_pk_nv(sp[4 * 257], sp[5 * 257]); o.w = cvt_pk_nv(sp[6 * 257], sp[7 * 257]);
;         *(v4u*)(WT + (size_t)drow * K + k0 + 8 * c) = o;
;     }
.LBB0_45:
	s_load_dwordx2 s[18:19], s[18:19], 0x110
	s_lshl_b32 s1, s23, 8
	s_lshl_b32 s2, s22, 1
	v_mov_b32_e32 v35, v33
	s_waitcnt lgkmcnt(0)
	s_add_u32 s18, s18, s2
	s_addc_u32 s19, s19, 0
	s_barrier
	s_waitcnt vmcnt(7)
	ds_write2_b32 v39, v4, v5 offset1:1
	ds_write2_b32 v39, v6, v7 offset0:2 offset1:3
	s_waitcnt vmcnt(6)
	ds_write2_b32 v52, v0, v1 offset1:1
	ds_write2_b32 v53, v2, v3 offset1:1
	s_waitcnt vmcnt(5)
	ds_write2_b32 v54, v12, v13 offset1:1
	ds_write2_b32 v55, v14, v15 offset1:1
	s_waitcnt vmcnt(4)
	ds_write2_b32 v56, v8, v9 offset1:1
	ds_write2_b32 v57, v10, v11 offset1:1
	s_waitcnt vmcnt(3)
	ds_write2_b32 v58, v20, v21 offset1:1
	ds_write2_b32 v59, v22, v23 offset1:1
	s_waitcnt vmcnt(2)
	ds_write2_b32 v60, v16, v17 offset1:1
	ds_write2_b32 v61, v18, v19 offset1:1
	s_waitcnt vmcnt(1)
	ds_write2_b32 v62, v28, v29 offset1:1
	ds_write2_b32 v63, v30, v31 offset1:1
	s_waitcnt vmcnt(0)
	ds_write2_b32 v64, v24, v25 offset1:1
	ds_write2_b32 v65, v26, v27 offset1:1
	v_lshl_add_u64 v[0:1], s[18:19], 0, v[34:35]
	v_lshl_add_u64 v[4:5], v[0:1], 0, s[14:15]
	v_add_lshl_u32 v0, s1, v40, 1
	v_and_or_b32 v6, v0, s48, v48
	s_waitcnt lgkmcnt(0)
	s_barrier
	ds_read2st64_b32 v[8:9], v41 offset1:1
	ds_read2st64_b32 v[10:11], v66 offset0:4 offset1:5
	ds_read2st64_b32 v[12:13], v67 offset0:8 offset1:9
	ds_read2st64_b32 v[14:15], v68 offset0:12 offset1:13
	ds_read2st64_b32 v[16:17], v41 offset0:2 offset1:3
	ds_read2st64_b32 v[18:19], v66 offset0:6 offset1:7
	ds_read2st64_b32 v[20:21], v67 offset0:10 offset1:11
	ds_read2st64_b32 v[22:23], v68 offset0:14 offset1:15
	ds_read2st64_b32 v[24:25], v69 offset0:16 offset1:17
	ds_read2st64_b32 v[26:27], v70 offset0:20 offset1:21
	ds_read2st64_b32 v[28:29], v71 offset0:24 offset1:25
	ds_read2st64_b32 v[30:31], v72 offset0:28 offset1:29
	ds_read2st64_b32 v[36:37], v69 offset0:18 offset1:19
	ds_read2st64_b32 v[74:75], v70 offset0:22 offset1:23
	v_ashrrev_i32_e32 v7, 31, v6
	v_lshlrev_b64 v[6:7], 11, v[6:7]
	s_waitcnt lgkmcnt(0)
	v_cvt_pk_bf16_f32 v0, v8, v10
	v_lshl_add_u64 v[6:7], v[4:5], 0, v[6:7]
	s_waitcnt lgkmcnt(0)
	v_cvt_pk_bf16_f32 v1, v12, v14
	s_waitcnt lgkmcnt(0)
	v_cvt_pk_bf16_f32 v2, v24, v26
	ds_read2st64_b32 v[76:77], v71 offset0:26 offset1:27
	ds_read2st64_b32 v[78:79], v72 offset0:30 offset1:31
	s_waitcnt lgkmcnt(0)
	v_cvt_pk_bf16_f32 v3, v28, v30
	global_store_dwordx4 v[6:7], v[0:3], off
	s_nop 1
	v_add_lshl_u32 v0, s1, v42, 1
	v_and_or_b32 v6, v0, s48, v49
	v_ashrrev_i32_e32 v7, 31, v6
	v_lshlrev_b64 v[6:7], 11, v[6:7]
	v_cvt_pk_bf16_f32 v0, v9, v11
	v_lshl_add_u64 v[6:7], v[4:5], 0, v[6:7]
	v_cvt_pk_bf16_f32 v1, v13, v15
	v_cvt_pk_bf16_f32 v2, v25, v27
	v_cvt_pk_bf16_f32 v3, v29, v31
	global_store_dwordx4 v[6:7], v[0:3], off
	s_nop 1
	v_add_lshl_u32 v0, s1, v43, 1
	v_and_or_b32 v6, v0, s48, v48
	v_ashrrev_i32_e32 v7, 31, v6
	v_lshlrev_b64 v[6:7], 11, v[6:7]
	v_cvt_pk_bf16_f32 v0, v16, v18
	v_lshl_add_u64 v[6:7], v[4:5], 0, v[6:7]
	v_cvt_pk_bf16_f32 v1, v20, v22
	s_waitcnt lgkmcnt(0)
	v_cvt_pk_bf16_f32 v2, v36, v74
	s_waitcnt lgkmcnt(0)
	v_cvt_pk_bf16_f32 v3, v76, v78
	global_store_dwordx4 v[6:7], v[0:3], off
	s_nop 1
	v_add_lshl_u32 v0, s1, v44, 1
	v_and_or_b32 v6, v0, s48, v50
	v_ashrrev_i32_e32 v7, 31, v6
	v_lshlrev_b64 v[6:7], 11, v[6:7]
	v_lshl_add_u64 v[4:5], v[4:5], 0, v[6:7]
	v_cvt_pk_bf16_f32 v0, v17, v19
	v_cvt_pk_bf16_f32 v1, v21, v23
	v_cvt_pk_bf16_f32 v2, v37, v75
	v_cvt_pk_bf16_f32 v3, v77, v79
	global_store_dwordx4 v[4:5], v[0:3], off

; #define LAS __attribute__((address_space(3)))
; __device__ __forceinline__ unsigned cvt_pk_nv(float lo, float hi) { unsigned r; asm("v_cvt_pk_bf16_f32 %0, %1, %2" : "=v"(r) : "v"(lo), "v"(hi)); return r; }
; __device__ __forceinline__ void p0_block_item(const float* W, const float* gk, int K, int N, bf16* WT, int mode, int item, LAS float* tile, int tid) {
;     ...
;     __syncthreads();
; #pragma unroll
;     for (int i = 0; i < 8; ++i) { LAS float* p = tile + (lr + 8 * i) * 257 + lc; p[0] = v[i].x; p[1] = v[i].y; p[2] = v[i].z; p[3] = v[i].w; }
;     __syncthreads();
;     const int c = tid & 7;
; #pragma unroll
;     for (int j = 0; j < 4; ++j) {
;         const int n = (tid >> 3) + 64 * j, ng = n0 + n;
;         const int drow = (mode == 0) ? ng : (256 * (ng >> 7) + (ng & 127) + (mode == 2 ? 128 : 0));
;         const LAS float* sp = tile + (8 * c) * 257 + n;
;         v4u o; o.x = cvt_pk_nv(sp[0 * 257], sp[1 * 257]); o.y = cvt_pk_nv(sp[2 * 257], sp[3 * 257]); o.z = cvt_pk_nv(sp[4 * 257], sp[5 * 257]); o.w = cvt_pk_nv(sp[6 * 257], sp[7 * 257]);
;         *(v4u*)(WT + (size_t)drow * K + k0 + 8 * c) = o;
;     }
.LBB0_50:
	s_load_dwordx2 s[18:19], s[18:19], 0x110
	s_lshl_b32 s1, s23, 8
	s_lshl_b32 s2, s22, 1
	v_mov_b32_e32 v35, v33
	s_waitcnt lgkmcnt(0)
	s_add_u32 s18, s18, s2
	s_addc_u32 s19, s19, 0
	s_barrier
	s_waitcnt vmcnt(7)
	ds_write2_b32 v39, v4, v5 offset1:1
	ds_write2_b32 v39, v6, v7 offset0:2 offset1:3
	s_waitcnt vmcnt(6)
	ds_write2_b32 v52, v0, v1 offset1:1
	ds_write2_b32 v53, v2, v3 offset1:1
	s_waitcnt vmcnt(5)
	ds_write2_b32 v54, v12, v13 offset1:1
	ds_write2_b32 v55, v14, v15 offset1:1
	s_waitcnt vmcnt(4)
	ds_write2_b32 v56, v8, v9 offset1:1
	ds_write2_b32 v57, v10, v11 offset1:1
	s_waitcnt vmcnt(3)
	ds_write2_b32 v58, v20, v21 offset1:1
	ds_write2_b32 v59, v22, v23 offset1:1
	s_waitcnt vmcnt(2)
	ds_write2_b32 v60, v16, v17 offset1:1
	ds_write2_b32 v61, v18, v19 offset1:1
	s_waitcnt vmcnt(1)
	ds_write2_b32 v62, v28, v29 offset1:1
	ds_write2_b32 v63, v30, v31 offset1:1
	s_waitcnt vmcnt(0)
	ds_write2_b32 v64, v24, v25 offset1:1
	ds_write2_b32 v65, v26, v27 offset1:1
	v_lshl_add_u64 v[0:1], s[18:19], 0, v[34:35]
	v_lshl_add_u64 v[4:5], v[0:1], 0, s[14:15]
	v_add_lshl_u32 v0, s1, v40, 1
	v_and_or_b32 v6, v0, s48, v45
	s_waitcnt lgkmcnt(0)
	s_barrier
	ds_read2st64_b32 v[8:9], v41 offset1:1
	ds_read2st64_b32 v[10:11], v66 offset0:4 offset1:5
	ds_read2st64_b32 v[12:13], v67 offset0:8 offset1:9
	ds_read2st64_b32 v[14:15], v68 offset0:12 offset1:13
	ds_read2st64_b32 v[16:17], v41 offset0:2 offset1:3
	ds_read2st64_b32 v[18:19], v66 offset0:6 offset1:7
	ds_read2st64_b32 v[20:21], v67 offset0:10 offset1:11
	ds_read2st64_b32 v[22:23], v68 offset0:14 offset1:15
	ds_read2st64_b32 v[24:25], v69 offset0:16 offset1:17
	ds_read2st64_b32 v[26:27], v70 offset0:20 offset1:21
	ds_read2st64_b32 v[28:29], v71 offset0:24 offset1:25
	ds_read2st64_b32 v[30:31], v72 offset0:28 offset1:29
	ds_read2st64_b32 v[36:37], v69 offset0:18 offset1:19
	ds_read2st64_b32 v[74:75], v70 offset0:22 offset1:23
	v_ashrrev_i32_e32 v7, 31, v6
	v_lshlrev_b64 v[6:7], 11, v[6:7]
	s_waitcnt lgkmcnt(0)
	v_cvt_pk_bf16_f32 v0, v8, v10
	v_lshl_add_u64 v[6:7], v[4:5], 0, v[6:7]
	s_waitcnt lgkmcnt(0)
	v_cvt_pk_bf16_f32 v1, v12, v14
	s_waitcnt lgkmcnt(0)
	v_cvt_pk_bf16_f32 v2, v24, v26
	ds_read2st64_b32 v[76:77], v71 offset0:26 offset1:27
	ds_read2st64_b32 v[78:79], v72 offset0:30 offset1:31
	s_waitcnt lgkmcnt(0)
	v_cvt_pk_bf16_f32 v3, v28, v30
	global_store_dwordx4 v[6:7], v[0:3], off
	s_nop 1
	v_add_lshl_u32 v0, s1, v42, 1
	v_and_or_b32 v6, v0, s48, v46
	v_ashrrev_i32_e32 v7, 31, v6
	v_lshlrev_b64 v[6:7], 11, v[6:7]
	v_cvt_pk_bf16_f32 v0, v9, v11
	v_lshl_add_u64 v[6:7], v[4:5], 0, v[6:7]
	v_cvt_pk_bf16_f32 v1, v13, v15
	v_cvt_pk_bf16_f32 v2, v25, v27
	v_cvt_pk_bf16_f32 v3, v29, v31
	global_store_dwordx4 v[6:7], v[0:3], off
	s_nop 1
	v_add_lshl_u32 v0, s1, v43, 1
	v_and_or_b32 v6, v0, s48, v45
	v_ashrrev_i32_e32 v7, 31, v6
	v_lshlrev_b64 v[6:7], 11, v[6:7]
	v_cvt_pk_bf16_f32 v0, v16, v18
	v_lshl_add_u64 v[6:7], v[4:5], 0, v[6:7]
	v_cvt_pk_bf16_f32 v1, v20, v22
	s_waitcnt lgkmcnt(0)
	v_cvt_pk_bf16_f32 v2, v36, v74
	s_waitcnt lgkmcnt(0)
	v_cvt_pk_bf16_f32 v3, v76, v78
	global_store_dwordx4 v[6:7], v[0:3], off
	s_nop 1
	v_add_lshl_u32 v0, s1, v44, 1
	v_and_or_b32 v6, v0, s48, v47
	v_ashrrev_i32_e32 v7, 31, v6
	v_lshlrev_b64 v[6:7], 11, v[6:7]
	v_lshl_add_u64 v[4:5], v[4:5], 0, v[6:7]
	v_cvt_pk_bf16_f32 v0, v17, v19
	v_cvt_pk_bf16_f32 v1, v21, v23
	v_cvt_pk_bf16_f32 v2, v37, v75
	v_cvt_pk_bf16_f32 v3, v77, v79
	global_store_dwordx4 v[4:5], v[0:3], off

; #define LAS __attribute__((address_space(3)))
; __device__ __forceinline__ unsigned cvt_pk_nv(float lo, float hi) { unsigned r; asm("v_cvt_pk_bf16_f32 %0, %1, %2" : "=v"(r) : "v"(lo), "v"(hi)); return r; }
; __device__ __forceinline__ void p0_block_item(const float* W, const float* gk, int K, int N, bf16* WT, int mode, int item, LAS float* tile, int tid) {
;     ...
;     __syncthreads();
; #pragma unroll
;     for (int i = 0; i < 8; ++i) { LAS float* p = tile + (lr + 8 * i) * 257 + lc; p[0] = v[i].x; p[1] = v[i].y; p[2] = v[i].z; p[3] = v[i].w; }
;     __syncthreads();
;     const int c = tid & 7;
; #pragma unroll
;     for (int j = 0; j < 4; ++j) {
;         const int n = (tid >> 3) + 64 * j, ng = n0 + n;
;         const int drow = (mode == 0) ? ng : (256 * (ng >> 7) + (ng & 127) + (mode == 2 ? 128 : 0));
;         const LAS float* sp = tile + (8 * c) * 257 + n;
;         v4u o; o.x = cvt_pk_nv(sp[0 * 257], sp[1 * 257]); o.y = cvt_pk_nv(sp[2 * 257], sp[3 * 257]); o.z = cvt_pk_nv(sp[4 * 257], sp[5 * 257]); o.w = cvt_pk_nv(sp[6 * 257], sp[7 * 257]);
;         *(v4u*)(WT + (size_t)drow * K + k0 + 8 * c) = o;
;     }
.LBB0_55:
	s_load_dwordx2 s[18:19], s[18:19], 0x110
	s_lshl_b32 s1, s23, 8
	s_lshl_b32 s2, s22, 1
	v_mov_b32_e32 v35, v33
	s_waitcnt lgkmcnt(0)
	s_add_u32 s18, s18, s2
	s_addc_u32 s19, s19, 0
	s_barrier
	s_waitcnt vmcnt(7)
	ds_write2_b32 v39, v4, v5 offset1:1
	ds_write2_b32 v39, v6, v7 offset0:2 offset1:3
	s_waitcnt vmcnt(6)
	ds_write2_b32 v52, v0, v1 offset1:1
	ds_write2_b32 v53, v2, v3 offset1:1
	s_waitcnt vmcnt(5)
	ds_write2_b32 v54, v12, v13 offset1:1
	ds_write2_b32 v55, v14, v15 offset1:1
	s_waitcnt vmcnt(4)
	ds_write2_b32 v56, v8, v9 offset1:1
	ds_write2_b32 v57, v10, v11 offset1:1
	s_waitcnt vmcnt(3)
	ds_write2_b32 v58, v20, v21 offset1:1
	ds_write2_b32 v59, v22, v23 offset1:1
	s_waitcnt vmcnt(2)
	ds_write2_b32 v60, v16, v17 offset1:1
	ds_write2_b32 v61, v18, v19 offset1:1
	s_waitcnt vmcnt(1)
	ds_write2_b32 v62, v28, v29 offset1:1
	ds_write2_b32 v63, v30, v31 offset1:1
	s_waitcnt vmcnt(0)
	ds_write2_b32 v64, v24, v25 offset1:1
	ds_write2_b32 v65, v26, v27 offset1:1
	v_lshl_add_u64 v[0:1], s[18:19], 0, v[34:35]
	v_lshl_add_u64 v[4:5], v[0:1], 0, s[16:17]
	v_add_lshl_u32 v0, s1, v40, 1
	v_and_or_b32 v6, v0, s48, v48
	s_waitcnt lgkmcnt(0)
	s_barrier
	ds_read2st64_b32 v[8:9], v41 offset1:1
	ds_read2st64_b32 v[10:11], v66 offset0:4 offset1:5
	ds_read2st64_b32 v[12:13], v67 offset0:8 offset1:9
	ds_read2st64_b32 v[14:15], v68 offset0:12 offset1:13
	ds_read2st64_b32 v[16:17], v41 offset0:2 offset1:3
	ds_read2st64_b32 v[18:19], v66 offset0:6 offset1:7
	ds_read2st64_b32 v[20:21], v67 offset0:10 offset1:11
	ds_read2st64_b32 v[22:23], v68 offset0:14 offset1:15
	ds_read2st64_b32 v[24:25], v69 offset0:16 offset1:17
	ds_read2st64_b32 v[26:27], v70 offset0:20 offset1:21
	ds_read2st64_b32 v[28:29], v71 offset0:24 offset1:25
	ds_read2st64_b32 v[30:31], v72 offset0:28 offset1:29
	ds_read2st64_b32 v[36:37], v69 offset0:18 offset1:19
	ds_read2st64_b32 v[74:75], v70 offset0:22 offset1:23
	v_ashrrev_i32_e32 v7, 31, v6
	v_lshlrev_b64 v[6:7], 11, v[6:7]
	s_waitcnt lgkmcnt(0)
	v_cvt_pk_bf16_f32 v0, v8, v10
	v_lshl_add_u64 v[6:7], v[4:5], 0, v[6:7]
	s_waitcnt lgkmcnt(0)
	v_cvt_pk_bf16_f32 v1, v12, v14
	s_waitcnt lgkmcnt(0)
	v_cvt_pk_bf16_f32 v2, v24, v26
	ds_read2st64_b32 v[76:77], v71 offset0:26 offset1:27
	ds_read2st64_b32 v[78:79], v72 offset0:30 offset1:31
	s_waitcnt lgkmcnt(0)
	v_cvt_pk_bf16_f32 v3, v28, v30
	global_store_dwordx4 v[6:7], v[0:3], off
	s_nop 1
	v_add_lshl_u32 v0, s1, v42, 1
	v_and_or_b32 v6, v0, s48, v49
	v_ashrrev_i32_e32 v7, 31, v6
	v_lshlrev_b64 v[6:7], 11, v[6:7]
	v_cvt_pk_bf16_f32 v0, v9, v11
	v_lshl_add_u64 v[6:7], v[4:5], 0, v[6:7]
	v_cvt_pk_bf16_f32 v1, v13, v15
	v_cvt_pk_bf16_f32 v2, v25, v27
	v_cvt_pk_bf16_f32 v3, v29, v31
	global_store_dwordx4 v[6:7], v[0:3], off
	s_nop 1
	v_add_lshl_u32 v0, s1, v43, 1
	v_and_or_b32 v6, v0, s48, v48
	v_ashrrev_i32_e32 v7, 31, v6
	v_lshlrev_b64 v[6:7], 11, v[6:7]
	v_cvt_pk_bf16_f32 v0, v16, v18
	v_lshl_add_u64 v[6:7], v[4:5], 0, v[6:7]
	v_cvt_pk_bf16_f32 v1, v20, v22
	s_waitcnt lgkmcnt(0)
	v_cvt_pk_bf16_f32 v2, v36, v74
	s_waitcnt lgkmcnt(0)
	v_cvt_pk_bf16_f32 v3, v76, v78
	global_store_dwordx4 v[6:7], v[0:3], off
	s_nop 1
	v_add_lshl_u32 v0, s1, v44, 1
	v_and_or_b32 v6, v0, s48, v50
	v_ashrrev_i32_e32 v7, 31, v6
	v_lshlrev_b64 v[6:7], 11, v[6:7]
	v_lshl_add_u64 v[4:5], v[4:5], 0, v[6:7]
	v_cvt_pk_bf16_f32 v0, v17, v19
	v_cvt_pk_bf16_f32 v1, v21, v23
	v_cvt_pk_bf16_f32 v2, v37, v75
	v_cvt_pk_bf16_f32 v3, v77, v79
	global_store_dwordx4 v[4:5], v[0:3], off

; __device__ __forceinline__ const float* xrow_ptr(const Ctx& C, int row) { return row < MPROMPT ? C.in(0) + (size_t)row * DM : C.in(1) + (size_t)(row - MPROMPT) * DM; }
; __device__ __forceinline__ float ssq4(v4f v) { return (v.x * v.x + v.y * v.y) + (v.z * v.z + v.w * v.w); }
; template <int R>
; __device__ __forceinline__ void rows_x0(const Ctx& C, int m0, int stride, int mx, int lane) {
;     v4f v[R][4]; float ss[R]; int mr[R]; bool ok[R];
; #pragma unroll
;     for (int r = 0; r < R; ++r) { mr[r] = (r == 4) ? mx : m0 + r * stride; ok[r] = (r == 4) ? (mx < M) : (mr[r] < MPROMPT); const float* x = xrow_ptr(C, ok[r] ? mr[r] : 0);
; #pragma unroll
;         for (int j = 0; j < 4; ++j) v[r][j] = __builtin_nontemporal_load((const v4f*)(x + 4 * lane + 256 * j)); }
;     bf16* XN = C.XN();
; #pragma unroll
;     for (int r = 0; r < R; ++r) { float s = 0.f;
; #pragma unroll
;         for (int j = 0; j < 4; ++j) s += ssq4(v[r][j]);
;         ss[r] = s; }
.LBB0_63:
	s_mov_b64 s[6:7], s[80:81]
	s_cmpk_gt_i32 s12, 0x7fff
	s_cselect_b64 s[34:35], -1, 0
	s_load_dwordx2 s[6:7], s[6:7], 0x0
	s_and_b64 vcc, s[34:35], exec
	s_cselect_b32 s10, 0, s12
	s_ashr_i32 s11, s10, 31
	s_lshl_b64 s[10:11], s[10:11], 12
	s_waitcnt lgkmcnt(0)
	s_add_u32 s6, s6, s10
	s_addc_u32 s7, s7, s11
	s_add_i32 s24, s46, s12
	global_load_dwordx4 v[60:63], v85, s[6:7] nt
	global_load_dwordx4 v[56:59], v85, s[6:7] offset:1024 nt
	global_load_dwordx4 v[52:55], v85, s[6:7] offset:2048 nt
	global_load_dwordx4 v[48:51], v85, s[6:7] offset:3072 nt
	s_mov_b64 s[6:7], s[80:81]
	s_cmp_lt_i32 s24, 0x8000
	s_cselect_b64 s[30:31], -1, 0
	s_cmpk_gt_i32 s24, 0x7fff
	s_load_dwordx2 s[6:7], s[6:7], 0x0
	s_cselect_b64 s[28:29], -1, 0
	s_and_b64 s[10:11], s[28:29], exec
	s_cselect_b32 s10, 0, s24
	s_ashr_i32 s11, s10, 31
	s_lshl_b64 s[10:11], s[10:11], 12
	s_waitcnt lgkmcnt(0)
	s_add_u32 s6, s6, s10
	s_addc_u32 s7, s7, s11
	global_load_dwordx4 v[44:47], v85, s[6:7] nt
	global_load_dwordx4 v[40:43], v85, s[6:7] offset:1024 nt
	s_add_i32 s18, s2, s12
	s_cmp_lt_i32 s18, 0x8000
	s_mov_b64 s[10:11], s[80:81]
	s_cselect_b64 s[26:27], -1, 0
	s_cmpk_gt_i32 s18, 0x7fff
	global_load_dwordx4 v[36:39], v85, s[6:7] offset:2048 nt
	global_load_dwordx4 v[32:35], v85, s[6:7] offset:3072 nt
	s_load_dwordx2 s[6:7], s[10:11], 0x0
	s_cselect_b64 s[22:23], -1, 0
	s_and_b64 s[10:11], s[22:23], exec
	s_cselect_b32 s10, 0, s18
	s_ashr_i32 s11, s10, 31
	s_lshl_b64 s[10:11], s[10:11], 12
	s_waitcnt lgkmcnt(0)
	s_add_u32 s6, s6, s10
	s_addc_u32 s7, s7, s11
	global_load_dwordx4 v[28:31], v85, s[6:7] nt
	global_load_dwordx4 v[24:27], v85, s[6:7] offset:1024 nt
	s_add_i32 s14, s1, s12
	s_cmp_lt_i32 s14, 0x8000
	s_mov_b64 s[10:11], s[80:81]
	s_cselect_b64 s[20:21], -1, 0
	s_cmpk_gt_i32 s14, 0x7fff
	global_load_dwordx4 v[20:23], v85, s[6:7] offset:2048 nt
	global_load_dwordx4 v[16:19], v85, s[6:7] offset:3072 nt
	s_load_dwordx2 s[6:7], s[10:11], 0x0
	s_cselect_b64 s[16:17], -1, 0
	s_and_b64 s[10:11], s[16:17], exec
	s_cselect_b32 s10, 0, s14
	s_ashr_i32 s11, s10, 31
	s_lshl_b64 s[10:11], s[10:11], 12
	s_waitcnt lgkmcnt(0)
	s_add_u32 s6, s6, s10
	s_addc_u32 s7, s7, s11
	global_load_dwordx4 v[12:15], v85, s[6:7] nt
	global_load_dwordx4 v[8:11], v85, s[6:7] offset:1024 nt
	global_load_dwordx4 v[4:7], v85, s[6:7] offset:2048 nt
	global_load_dwordx4 v[0:3], v85, s[6:7] offset:3072 nt
	v_cmp_lt_i32_e64 s[6:7], v68, v67
	s_mov_b64 s[10:11], s[80:81]
	s_load_dwordx2 s[36:37], s[10:11], 0x110
	s_waitcnt vmcnt(15)
	v_mul_f32_e32 v64, v61, v61
	v_mul_f32_e32 v65, v63, v63
	s_waitcnt vmcnt(14)
	v_mul_f32_e32 v76, v57, v57
	v_mul_f32_e32 v77, v59, v59
	s_waitcnt vmcnt(13)
	v_mul_f32_e32 v78, v53, v53
	v_mul_f32_e32 v79, v55, v55
	v_fmac_f32_e32 v64, v60, v60
	v_fmac_f32_e32 v65, v62, v62
	v_fmac_f32_e32 v76, v56, v56
	v_fmac_f32_e32 v77, v58, v58
	v_fmac_f32_e32 v78, v52, v52
	v_fmac_f32_e32 v79, v54, v54
	v_add_f32_e32 v64, v64, v65
	v_add_f32_e32 v65, v76, v77
	s_waitcnt vmcnt(12)
	v_mul_f32_e32 v83, v49, v49
	v_mul_f32_e32 v87, v51, v51
	v_add_f32_e32 v76, v78, v79
	v_add_f32_e32 v64, v64, v65
	v_fmac_f32_e32 v83, v48, v48
	v_fmac_f32_e32 v87, v50, v50
	v_add_f32_e32 v64, v64, v76
	s_waitcnt vmcnt(11)
	v_mul_f32_e32 v65, v45, v45
	v_mul_f32_e32 v76, v47, v47
	v_add_f32_e32 v77, v83, v87
	v_fmac_f32_e32 v65, v44, v44
	v_fmac_f32_e32 v76, v46, v46
	v_add_f32_e32 v64, v64, v77
	s_waitcnt vmcnt(10)
	v_mul_f32_e32 v77, v41, v41
	v_add_f32_e32 v65, v65, v76
	v_mul_f32_e32 v76, v43, v43
	v_fmac_f32_e32 v77, v40, v40
	v_fmac_f32_e32 v76, v42, v42
	v_add_f32_e32 v76, v77, v76
	v_add_f32_e32 v65, v65, v76
	s_waitcnt vmcnt(9)
	v_mul_f32_e32 v76, v37, v37
	v_mul_f32_e32 v77, v39, v39
	v_fmac_f32_e32 v76, v36, v36
	v_fmac_f32_e32 v77, v38, v38
	v_add_f32_e32 v76, v76, v77
	v_add_f32_e32 v65, v65, v76
	s_waitcnt vmcnt(8)
	v_mul_f32_e32 v76, v33, v33
	v_mul_f32_e32 v77, v35, v35
	v_fmac_f32_e32 v76, v32, v32
	v_fmac_f32_e32 v77, v34, v34
	v_add_f32_e32 v76, v76, v77
	v_add_f32_e32 v65, v65, v76
	s_waitcnt vmcnt(7)
	v_mul_f32_e32 v76, v29, v29
	v_mul_f32_e32 v77, v31, v31
	v_fmac_f32_e32 v76, v28, v28
	v_fmac_f32_e32 v77, v30, v30
	v_add_f32_e32 v76, v76, v77
	s_waitcnt vmcnt(6)
	v_mul_f32_e32 v77, v25, v25
	v_mul_f32_e32 v78, v27, v27
	v_fmac_f32_e32 v77, v24, v24
	v_fmac_f32_e32 v78, v26, v26
	v_add_f32_e32 v77, v77, v78
	v_add_f32_e32 v76, v76, v77
	s_waitcnt vmcnt(5)
	v_mul_f32_e32 v77, v21, v21
	v_mul_f32_e32 v78, v23, v23
	v_fmac_f32_e32 v77, v20, v20
	v_fmac_f32_e32 v78, v22, v22
	v_add_f32_e32 v77, v77, v78
	v_add_f32_e32 v76, v76, v77
	s_waitcnt vmcnt(4)
	v_mul_f32_e32 v77, v17, v17
	v_mul_f32_e32 v78, v19, v19
	v_fmac_f32_e32 v77, v16, v16
	v_fmac_f32_e32 v78, v18, v18
	v_add_f32_e32 v77, v77, v78
	v_add_f32_e32 v76, v76, v77
	s_waitcnt vmcnt(3)
; __device__ __forceinline__ void st4_bf16(bf16* p, v4f o) { v2u w; w.x = cvt_pk_nv(o.x, o.y); w.y = cvt_pk_nv(o.z, o.w); *(v2u*)p = w; }
; __device__ __forceinline__ float ssq4(v4f v) { return (v.x * v.x + v.y * v.y) + (v.z * v.z + v.w * v.w); }
; template <int R>
; __device__ __forceinline__ void rows_x0(const Ctx& C, int m0, int stride, int mx, int lane) {
;     ...
;     for (int r = 0; r < R; ++r) { float s = 0.f;
; #pragma unroll
;         for (int j = 0; j < 4; ++j) s += ssq4(v[r][j]);
;         ss[r] = s; }
;     float* rs = C.RS();
; #pragma unroll
;     for (int r = 0; r < R; ++r) ss[r] = wave_sum(ss[r]) * (1.f / DM) + EPS;
; #pragma unroll
;     for (int r = 0; r < R; ++r) { const float rstd = rsqrtf(ss[r]);
; #pragma unroll
;         for (int j = 0; j < 4; ++j) if (ok[r]) st4_bf16(XN + (size_t)mr[r] * DM + 4 * lane + 256 * j, v[r][j] * rstd);
	v_mul_f32_e32 v77, v13, v13
	v_mul_f32_e32 v78, v15, v15
	v_fmac_f32_e32 v77, v12, v12
	v_fmac_f32_e32 v78, v14, v14
	v_add_f32_e32 v77, v77, v78
	s_waitcnt vmcnt(2)
	v_mul_f32_e32 v78, v9, v9
	v_mul_f32_e32 v79, v11, v11
	v_fmac_f32_e32 v78, v8, v8
	v_fmac_f32_e32 v79, v10, v10
	v_add_f32_e32 v78, v78, v79
	v_add_f32_e32 v77, v77, v78
	s_waitcnt vmcnt(1)
	v_mul_f32_e32 v78, v5, v5
	v_mul_f32_e32 v79, v7, v7
	v_fmac_f32_e32 v78, v4, v4
	v_fmac_f32_e32 v79, v6, v6
	v_add_f32_e32 v78, v78, v79
	v_cndmask_b32_e64 v79, v66, v68, s[6:7]
	v_lshlrev_b32_e32 v79, 2, v79
	ds_bpermute_b32 v83, v79, v64
	v_cmp_lt_i32_e64 s[6:7], v69, v67
	v_add_f32_e32 v77, v77, v78
	s_waitcnt vmcnt(0)
	v_mul_f32_e32 v78, v1, v1
	v_cndmask_b32_e64 v87, v66, v69, s[6:7]
	v_lshlrev_b32_e32 v87, 2, v87
	s_waitcnt lgkmcnt(0)
	v_add_f32_e32 v64, v64, v83
	ds_bpermute_b32 v83, v87, v64
	v_cmp_lt_i32_e64 s[6:7], v70, v67
	v_mul_f32_e32 v88, v3, v3
	v_fmac_f32_e32 v78, v0, v0
	v_cndmask_b32_e64 v89, v66, v70, s[6:7]
	v_lshlrev_b32_e32 v89, 2, v89
	s_waitcnt lgkmcnt(0)
	v_add_f32_e32 v64, v64, v83
	ds_bpermute_b32 v83, v89, v64
	v_cmp_lt_i32_e64 s[6:7], v71, v67
	v_fmac_f32_e32 v88, v2, v2
	v_add_f32_e32 v78, v78, v88
	v_cndmask_b32_e64 v90, v66, v71, s[6:7]
	v_lshlrev_b32_e32 v90, 2, v90
	s_waitcnt lgkmcnt(0)
	v_add_f32_e32 v64, v64, v83
	ds_bpermute_b32 v83, v90, v64
	v_cmp_lt_i32_e64 s[6:7], v72, v67
	v_add_f32_e32 v77, v77, v78
	ds_bpermute_b32 v92, v79, v65
	v_cndmask_b32_e64 v88, v66, v72, s[6:7]
	v_lshlrev_b32_e32 v88, 2, v88
	s_waitcnt lgkmcnt(0)
	v_add_f32_e32 v64, v64, v83
	ds_bpermute_b32 v83, v88, v64
	v_cmp_lt_i32_e64 s[6:7], v73, v67
	s_waitcnt lgkmcnt(0)
	v_add_f32_e32 v65, v65, v92
	s_waitcnt lgkmcnt(0)
	v_add_f32_e32 v64, v64, v83
	v_cndmask_b32_e64 v78, v66, v73, s[6:7]
	v_lshlrev_b32_e32 v91, 2, v78
	ds_bpermute_b32 v78, v91, v64
	s_mov_b64 s[6:7], s[80:81]
	s_load_dwordx2 s[6:7], s[6:7], 0x110
	s_waitcnt lgkmcnt(0)
	v_add_f32_e32 v64, v64, v78
	ds_bpermute_b32 v78, v79, v76
	v_fmamk_f32 v83, v64, 0x3a800000, v74
	ds_bpermute_b32 v64, v79, v77
	ds_bpermute_b32 v79, v87, v65
	s_waitcnt lgkmcnt(0)
	v_add_f32_e32 v76, v76, v78
	ds_bpermute_b32 v78, v87, v76
	s_waitcnt lgkmcnt(0)
	v_add_f32_e32 v64, v77, v64
	ds_bpermute_b32 v77, v87, v64
	s_waitcnt lgkmcnt(0)
	v_add_f32_e32 v65, v65, v79
	ds_bpermute_b32 v79, v89, v65
	s_waitcnt lgkmcnt(0)
	v_add_f32_e32 v76, v76, v78
	ds_bpermute_b32 v78, v89, v76
	s_waitcnt lgkmcnt(0)
	v_add_f32_e32 v64, v64, v77
	ds_bpermute_b32 v77, v89, v64
	s_waitcnt lgkmcnt(0)
	v_add_f32_e32 v65, v65, v79
	ds_bpermute_b32 v79, v90, v65
	s_waitcnt lgkmcnt(0)
	v_add_f32_e32 v76, v76, v78
	ds_bpermute_b32 v78, v90, v76
	s_waitcnt lgkmcnt(0)
	v_add_f32_e32 v64, v64, v77
	ds_bpermute_b32 v77, v90, v64
	s_waitcnt lgkmcnt(0)
	v_add_f32_e32 v65, v65, v79
	ds_bpermute_b32 v79, v88, v65
	s_waitcnt lgkmcnt(0)
	v_add_f32_e32 v76, v76, v78
	ds_bpermute_b32 v78, v88, v76
	s_waitcnt lgkmcnt(0)
	v_add_f32_e32 v64, v64, v77
	ds_bpermute_b32 v77, v88, v64
	s_waitcnt lgkmcnt(0)
	v_add_f32_e32 v87, v65, v79
	ds_bpermute_b32 v88, v91, v87
	s_waitcnt lgkmcnt(0)
	v_add_f32_e32 v78, v76, v78
	ds_bpermute_b32 v79, v91, v78
	s_waitcnt lgkmcnt(0)
	v_add_f32_e32 v76, v64, v77
	ds_bpermute_b32 v77, v91, v76
	v_lshl_add_u64 v[64:65], s[36:37], 0, v[80:81]
	v_lshl_add_u64 v[64:65], v[64:65], 0, s[8:9]
	s_cbranch_vccnz .LBB0_65
	v_mul_f32_e32 v89, 0x4b800000, v83
	v_cmp_gt_f32_e32 vcc, s38, v83
	s_ashr_i32 s13, s12, 31
	s_lshl_b64 s[10:11], s[12:13], 11
	v_cndmask_b32_e32 v89, v83, v89, vcc
	v_rsq_f32_e32 v89, v89
	v_lshl_add_u64 v[92:93], v[64:65], 0, s[10:11]
	v_mul_f32_e32 v90, 0x45800000, v89
	v_cndmask_b32_e32 v90, v89, v90, vcc
	v_pk_mul_f32 v[60:61], v[60:61], v[90:91] op_sel_hi:[1,0]
	v_pk_mul_f32 v[56:57], v[56:57], v[90:91] op_sel_hi:[1,0]
	v_pk_mul_f32 v[52:53], v[52:53], v[90:91] op_sel_hi:[1,0]
	v_pk_mul_f32 v[48:49], v[48:49], v[90:91] op_sel_hi:[1,0]
	v_pk_mul_f32 v[62:63], v[62:63], v[90:91] op_sel_hi:[1,0]
	v_cvt_pk_bf16_f32 v60, v60, v61
	v_pk_mul_f32 v[58:59], v[58:59], v[90:91] op_sel_hi:[1,0]
	v_cvt_pk_bf16_f32 v61, v62, v63
	global_store_dwordx2 v[92:93], v[60:61], off
	v_cvt_pk_bf16_f32 v56, v56, v57
	v_cvt_pk_bf16_f32 v57, v58, v59
	global_store_dwordx2 v[92:93], v[56:57], off offset:512
	v_pk_mul_f32 v[54:55], v[54:55], v[90:91] op_sel_hi:[1,0]
	v_cvt_pk_bf16_f32 v52, v52, v53
	v_pk_mul_f32 v[50:51], v[50:51], v[90:91] op_sel_hi:[1,0]
	v_cvt_pk_bf16_f32 v53, v54, v55
	global_store_dwordx2 v[92:93], v[52:53], off offset:1024
	v_cvt_pk_bf16_f32 v48, v48, v49
	v_cvt_pk_bf16_f32 v49, v50, v51
	global_store_dwordx2 v[92:93], v[48:49], off offset:1536

; __device__ __forceinline__ void st4_bf16(bf16* p, v4f o) { v2u w; w.x = cvt_pk_nv(o.x, o.y); w.y = cvt_pk_nv(o.z, o.w); *(v2u*)p = w; }
; template <int R>
; __device__ __forceinline__ void rows_x0(const Ctx& C, int m0, int stride, int mx, int lane) {
;     ...
;     for (int r = 0; r < R; ++r) ss[r] = wave_sum(ss[r]) * (1.f / DM) + EPS;
; #pragma unroll
;     for (int r = 0; r < R; ++r) { const float rstd = rsqrtf(ss[r]);
; #pragma unroll
;         for (int j = 0; j < 4; ++j) if (ok[r]) st4_bf16(XN + (size_t)mr[r] * DM + 4 * lane + 256 * j, v[r][j] * rstd);
;         if (lane == 0 && ok[r]) rs[mr[r]] = sqrtf(ss[r]); }
.LBB0_67:
	s_or_b64 exec, exec, s[34:35]
	s_waitcnt lgkmcnt(0)
	v_add_f32_e32 v48, v87, v88
	s_andn2_b64 vcc, exec, s[30:31]
	v_fmamk_f32 v48, v48, 0x3a800000, v74
	s_cbranch_vccnz .LBB0_69
	v_mul_f32_e32 v49, 0x4b800000, v48
	v_cmp_gt_f32_e32 vcc, s38, v48
	s_ashr_i32 s25, s24, 31
	s_lshl_b64 s[6:7], s[24:25], 11
	v_cndmask_b32_e32 v49, v48, v49, vcc
	v_rsq_f32_e32 v49, v49
	v_lshl_add_u64 v[52:53], v[64:65], 0, s[6:7]
	v_mul_f32_e32 v50, 0x45800000, v49
	v_cndmask_b32_e32 v50, v49, v50, vcc
	v_pk_mul_f32 v[44:45], v[44:45], v[50:51] op_sel_hi:[1,0]
	v_pk_mul_f32 v[40:41], v[40:41], v[50:51] op_sel_hi:[1,0]
	v_pk_mul_f32 v[36:37], v[36:37], v[50:51] op_sel_hi:[1,0]
	v_pk_mul_f32 v[32:33], v[32:33], v[50:51] op_sel_hi:[1,0]
	v_pk_mul_f32 v[46:47], v[46:47], v[50:51] op_sel_hi:[1,0]
	v_cvt_pk_bf16_f32 v44, v44, v45
	v_pk_mul_f32 v[42:43], v[42:43], v[50:51] op_sel_hi:[1,0]
	v_cvt_pk_bf16_f32 v45, v46, v47
	global_store_dwordx2 v[52:53], v[44:45], off
	v_cvt_pk_bf16_f32 v40, v40, v41
	v_cvt_pk_bf16_f32 v41, v42, v43
	global_store_dwordx2 v[52:53], v[40:41], off offset:512
	v_pk_mul_f32 v[38:39], v[38:39], v[50:51] op_sel_hi:[1,0]
	v_cvt_pk_bf16_f32 v36, v36, v37
	v_pk_mul_f32 v[34:35], v[34:35], v[50:51] op_sel_hi:[1,0]
	v_cvt_pk_bf16_f32 v37, v38, v39
	global_store_dwordx2 v[52:53], v[36:37], off offset:1024
	v_cvt_pk_bf16_f32 v32, v32, v33
	v_cvt_pk_bf16_f32 v33, v34, v35
	global_store_dwordx2 v[52:53], v[32:33], off offset:1536

; __device__ __forceinline__ void st4_bf16(bf16* p, v4f o) { v2u w; w.x = cvt_pk_nv(o.x, o.y); w.y = cvt_pk_nv(o.z, o.w); *(v2u*)p = w; }
; template <int R>
; __device__ __forceinline__ void rows_x0(const Ctx& C, int m0, int stride, int mx, int lane) {
;     ...
;     for (int r = 0; r < R; ++r) ss[r] = wave_sum(ss[r]) * (1.f / DM) + EPS;
; #pragma unroll
;     for (int r = 0; r < R; ++r) { const float rstd = rsqrtf(ss[r]);
; #pragma unroll
;         for (int j = 0; j < 4; ++j) if (ok[r]) st4_bf16(XN + (size_t)mr[r] * DM + 4 * lane + 256 * j, v[r][j] * rstd);
;         if (lane == 0 && ok[r]) rs[mr[r]] = sqrtf(ss[r]); }
.LBB0_71:
	s_or_b64 exec, exec, s[28:29]
	s_waitcnt lgkmcnt(0)
	v_add_f32_e32 v32, v78, v79
	s_andn2_b64 vcc, exec, s[26:27]
	v_fmamk_f32 v32, v32, 0x3a800000, v74
	s_cbranch_vccnz .LBB0_73
	v_mul_f32_e32 v33, 0x4b800000, v32
	v_cmp_gt_f32_e32 vcc, s38, v32
	s_ashr_i32 s19, s18, 31
	s_lshl_b64 s[6:7], s[18:19], 11
	v_cndmask_b32_e32 v33, v32, v33, vcc
	v_rsq_f32_e32 v33, v33
	v_lshl_add_u64 v[36:37], v[64:65], 0, s[6:7]
	v_mul_f32_e32 v34, 0x45800000, v33
	v_cndmask_b32_e32 v34, v33, v34, vcc
	v_pk_mul_f32 v[28:29], v[28:29], v[34:35] op_sel_hi:[1,0]
	v_pk_mul_f32 v[24:25], v[24:25], v[34:35] op_sel_hi:[1,0]
	v_pk_mul_f32 v[20:21], v[20:21], v[34:35] op_sel_hi:[1,0]
	v_pk_mul_f32 v[16:17], v[16:17], v[34:35] op_sel_hi:[1,0]
	v_pk_mul_f32 v[30:31], v[30:31], v[34:35] op_sel_hi:[1,0]
	v_cvt_pk_bf16_f32 v28, v28, v29
	v_pk_mul_f32 v[26:27], v[26:27], v[34:35] op_sel_hi:[1,0]
	v_cvt_pk_bf16_f32 v29, v30, v31
	global_store_dwordx2 v[36:37], v[28:29], off
	v_cvt_pk_bf16_f32 v24, v24, v25
	v_cvt_pk_bf16_f32 v25, v26, v27
	global_store_dwordx2 v[36:37], v[24:25], off offset:512
	v_pk_mul_f32 v[22:23], v[22:23], v[34:35] op_sel_hi:[1,0]
	v_cvt_pk_bf16_f32 v20, v20, v21
	v_pk_mul_f32 v[18:19], v[18:19], v[34:35] op_sel_hi:[1,0]
	v_cvt_pk_bf16_f32 v21, v22, v23
	global_store_dwordx2 v[36:37], v[20:21], off offset:1024
	v_cvt_pk_bf16_f32 v16, v16, v17
	v_cvt_pk_bf16_f32 v17, v18, v19
	global_store_dwordx2 v[36:37], v[16:17], off offset:1536

; __device__ __forceinline__ const float* xrow_ptr(const Ctx& C, int row) { return row < MPROMPT ? C.in(0) + (size_t)row * DM : C.in(1) + (size_t)(row - MPROMPT) * DM; }
; __device__ __forceinline__ float ssq4(v4f v) { return (v.x * v.x + v.y * v.y) + (v.z * v.z + v.w * v.w); }
; __device__ __forceinline__ float wave_sum(float v) {
; #pragma unroll
;     for (int o = 1; o < 64; o <<= 1) v += __shfl_xor(v, o);
;     return v;
; }
; template <int R>
; __device__ __forceinline__ void rows_x0(const Ctx& C, int m0, int stride, int mx, int lane) {
;     ...
;     for (int r = 0; r < R; ++r) { mr[r] = (r == 4) ? mx : m0 + r * stride; ok[r] = (r == 4) ? (mx < M) : (mr[r] < MPROMPT); const float* x = xrow_ptr(C, ok[r] ? mr[r] : 0);
; #pragma unroll
;         for (int j = 0; j < 4; ++j) v[r][j] = __builtin_nontemporal_load((const v4f*)(x + 4 * lane + 256 * j)); }
;     bf16* XN = C.XN();
; #pragma unroll
;     for (int r = 0; r < R; ++r) { float s = 0.f;
; #pragma unroll
;         for (int j = 0; j < 4; ++j) s += ssq4(v[r][j]);
;         ss[r] = s; }
;     float* rs = C.RS();
; #pragma unroll
;     for (int r = 0; r < R; ++r) ss[r] = wave_sum(ss[r]) * (1.f / DM) + EPS;
.LBB0_83:
	s_load_dwordx2 s[6:7], s[40:41], 0x0
	s_lshl_b64 s[10:11], s[42:43], 12
	s_waitcnt vmcnt(15)
	v_mul_f32_e32 v81, v77, v77
	v_mul_f32_e32 v83, v79, v79
	v_fmac_f32_e32 v81, v76, v76
	s_waitcnt lgkmcnt(0)
	s_add_u32 s6, s6, s10
	s_addc_u32 s7, s7, s11
	global_load_dwordx4 v[12:15], v85, s[6:7] nt
	global_load_dwordx4 v[8:11], v85, s[6:7] offset:1024 nt
	global_load_dwordx4 v[4:7], v85, s[6:7] offset:2048 nt
	global_load_dwordx4 v[0:3], v85, s[6:7] offset:3072 nt
	v_fmac_f32_e32 v83, v78, v78
	v_add_f32_e32 v81, v81, v83
	s_waitcnt vmcnt(18)
	v_mul_f32_e32 v83, v73, v73
	v_mul_f32_e32 v87, v75, v75
	v_fmac_f32_e32 v83, v72, v72
	v_fmac_f32_e32 v87, v74, v74
	v_add_f32_e32 v83, v83, v87
	v_add_f32_e32 v81, v81, v83
	s_waitcnt vmcnt(17)
	v_mul_f32_e32 v83, v69, v69
	v_mul_f32_e32 v87, v71, v71
	v_fmac_f32_e32 v83, v68, v68
	v_fmac_f32_e32 v87, v70, v70
	v_add_f32_e32 v83, v83, v87
	v_add_f32_e32 v81, v81, v83
	s_waitcnt vmcnt(16)
	v_mul_f32_e32 v83, v65, v65
	v_mul_f32_e32 v87, v67, v67
	v_fmac_f32_e32 v83, v64, v64
	v_fmac_f32_e32 v87, v66, v66
	v_add_f32_e32 v83, v83, v87
	v_add_f32_e32 v81, v81, v83
	s_waitcnt vmcnt(15)
	v_mul_f32_e32 v83, v61, v61
	v_mul_f32_e32 v87, v63, v63
	v_fmac_f32_e32 v83, v60, v60
	v_fmac_f32_e32 v87, v62, v62
	v_add_f32_e32 v83, v83, v87
	s_waitcnt vmcnt(14)
	v_mul_f32_e32 v87, v57, v57
	v_mul_f32_e32 v88, v59, v59
	v_fmac_f32_e32 v87, v56, v56
	v_fmac_f32_e32 v88, v58, v58
	v_add_f32_e32 v87, v87, v88
	v_add_f32_e32 v83, v83, v87
	s_waitcnt vmcnt(13)
	v_mul_f32_e32 v87, v53, v53
	v_mul_f32_e32 v88, v55, v55
	v_fmac_f32_e32 v87, v52, v52
	v_fmac_f32_e32 v88, v54, v54
	v_add_f32_e32 v87, v87, v88
	v_add_f32_e32 v83, v83, v87
	s_waitcnt vmcnt(12)
	v_mul_f32_e32 v87, v49, v49
	v_mul_f32_e32 v88, v51, v51
	v_fmac_f32_e32 v87, v48, v48
	v_fmac_f32_e32 v88, v50, v50
	v_add_f32_e32 v87, v87, v88
	v_add_f32_e32 v83, v83, v87
	s_waitcnt vmcnt(11)
	v_mul_f32_e32 v87, v45, v45
	v_mul_f32_e32 v88, v47, v47
	v_fmac_f32_e32 v87, v44, v44
	v_fmac_f32_e32 v88, v46, v46
	v_add_f32_e32 v87, v87, v88
	s_waitcnt vmcnt(10)
	v_mul_f32_e32 v88, v41, v41
	v_mul_f32_e32 v89, v43, v43
	v_fmac_f32_e32 v88, v40, v40
	v_fmac_f32_e32 v89, v42, v42
	v_add_f32_e32 v88, v88, v89
	v_add_f32_e32 v87, v87, v88
	s_waitcnt vmcnt(9)
	v_mul_f32_e32 v88, v37, v37
	v_mul_f32_e32 v89, v39, v39
	v_fmac_f32_e32 v88, v36, v36
	v_fmac_f32_e32 v89, v38, v38
	v_add_f32_e32 v88, v88, v89
	v_add_f32_e32 v87, v87, v88
	s_waitcnt vmcnt(8)
	v_mul_f32_e32 v88, v33, v33
	v_mul_f32_e32 v89, v35, v35
	v_fmac_f32_e32 v88, v32, v32
	v_fmac_f32_e32 v89, v34, v34
	v_add_f32_e32 v88, v88, v89
	v_add_f32_e32 v87, v87, v88
	s_waitcnt vmcnt(7)
	v_mul_f32_e32 v88, v29, v29
	v_mul_f32_e32 v89, v31, v31
	v_fmac_f32_e32 v88, v28, v28
	v_fmac_f32_e32 v89, v30, v30
	v_add_f32_e32 v88, v88, v89
	s_waitcnt vmcnt(6)
	v_mul_f32_e32 v89, v25, v25
	v_mul_f32_e32 v90, v27, v27
	v_fmac_f32_e32 v89, v24, v24
	v_fmac_f32_e32 v90, v26, v26
	v_add_f32_e32 v89, v89, v90
	v_add_f32_e32 v88, v88, v89
	s_waitcnt vmcnt(5)
	v_mul_f32_e32 v89, v21, v21
	v_mul_f32_e32 v90, v23, v23
	v_fmac_f32_e32 v89, v20, v20
	v_fmac_f32_e32 v90, v22, v22
	v_add_f32_e32 v89, v89, v90
	v_add_f32_e32 v88, v88, v89
	s_waitcnt vmcnt(4)
	v_mul_f32_e32 v89, v17, v17
	v_mul_f32_e32 v90, v19, v19
	v_fmac_f32_e32 v89, v16, v16
	v_fmac_f32_e32 v90, v18, v18
	v_add_f32_e32 v89, v89, v90
	v_add_f32_e32 v88, v88, v89
	s_waitcnt vmcnt(3)
	v_mul_f32_e32 v89, v13, v13
	v_mul_f32_e32 v90, v15, v15
	v_fmac_f32_e32 v89, v12, v12
	v_fmac_f32_e32 v90, v14, v14
	v_add_f32_e32 v89, v89, v90
	s_waitcnt vmcnt(2)
	v_mul_f32_e32 v90, v9, v9
	v_mul_f32_e32 v91, v11, v11
	v_fmac_f32_e32 v90, v8, v8
	v_fmac_f32_e32 v91, v10, v10
	v_add_f32_e32 v90, v90, v91
	v_add_f32_e32 v89, v89, v90
	s_waitcnt vmcnt(1)
	v_mul_f32_e32 v90, v5, v5
	v_mul_f32_e32 v91, v7, v7
	v_fmac_f32_e32 v90, v4, v4
	v_fmac_f32_e32 v91, v6, v6
	v_mbcnt_hi_u32_b32 v82, -1, v82
	v_add_f32_e32 v90, v90, v91
	v_and_b32_e32 v91, 64, v82
	v_add_u32_e32 v91, 64, v91
	v_xor_b32_e32 v92, 1, v82
	v_cmp_lt_i32_e32 vcc, v92, v91
	v_xor_b32_e32 v94, 2, v82
	v_xor_b32_e32 v95, 16, v82
	v_cndmask_b32_e32 v92, v82, v92, vcc
	v_lshlrev_b32_e32 v183, 2, v92
	s_nop 1
	v_mov_b32_dpp v92, v81 quad_perm:[1,0,3,2] row_mask:0xf bank_mask:0xf
	v_cmp_lt_i32_e32 vcc, v94, v91
	v_xor_b32_e32 v96, 32, v82
	v_add_f32_e32 v89, v89, v90
	v_cndmask_b32_e32 v94, v82, v94, vcc
	s_waitcnt lgkmcnt(0)
	v_add_f32_e32 v81, v81, v92
	v_lshlrev_b32_e32 v184, 2, v94
	s_nop 1
	v_mov_b32_dpp v92, v81 quad_perm:[2,3,0,1] row_mask:0xf bank_mask:0xf
	v_xor_b32_e32 v94, 4, v82
	v_cmp_lt_i32_e32 vcc, v94, v91
	s_waitcnt vmcnt(0)
	v_mul_f32_e32 v90, v1, v1
	v_mul_f32_e32 v93, v3, v3
	v_cndmask_b32_e32 v94, v82, v94, vcc
	s_waitcnt lgkmcnt(0)
; __device__ __forceinline__ void st4_bf16(bf16* p, v4f o) { v2u w; w.x = cvt_pk_nv(o.x, o.y); w.y = cvt_pk_nv(o.z, o.w); *(v2u*)p = w; }
; __device__ __forceinline__ float wave_sum(float v) {
; #pragma unroll
;     for (int o = 1; o < 64; o <<= 1) v += __shfl_xor(v, o);
;     return v;
; }
; template <int R>
; __device__ __forceinline__ void rows_x0(const Ctx& C, int m0, int stride, int mx, int lane) {
;     ...
;     for (int r = 0; r < R; ++r) ss[r] = wave_sum(ss[r]) * (1.f / DM) + EPS;
; #pragma unroll
;     for (int r = 0; r < R; ++r) { const float rstd = rsqrtf(ss[r]);
; #pragma unroll
;         for (int j = 0; j < 4; ++j) if (ok[r]) st4_bf16(XN + (size_t)mr[r] * DM + 4 * lane + 256 * j, v[r][j] * rstd);
;         if (lane == 0 && ok[r]) rs[mr[r]] = sqrtf(ss[r]); }
	v_add_f32_e32 v81, v81, v92
	v_lshlrev_b32_e32 v185, 2, v94
	s_nop 1
	v_mov_b32_dpp v92, v81 row_half_mirror row_mask:0xf bank_mask:0xf
	v_xor_b32_e32 v94, 8, v82
	v_cmp_lt_i32_e32 vcc, v94, v91
	v_fmac_f32_e32 v90, v0, v0
	v_fmac_f32_e32 v93, v2, v2
	v_cndmask_b32_e32 v94, v82, v94, vcc
	s_waitcnt lgkmcnt(0)
	v_add_f32_e32 v81, v81, v92
	v_lshlrev_b32_e32 v186, 2, v94
	s_nop 1
	v_mov_b32_dpp v92, v81 row_mirror row_mask:0xf bank_mask:0xf
	s_nop 1
	v_mov_b32_dpp v94, v83 quad_perm:[1,0,3,2] row_mask:0xf bank_mask:0xf
	v_cmp_lt_i32_e32 vcc, v95, v91
	v_add_f32_e32 v90, v90, v93
	v_add_f32_e32 v89, v89, v90
	v_cndmask_b32_e32 v95, v82, v95, vcc
	s_waitcnt lgkmcnt(0)
	v_add_f32_e32 v81, v81, v92
	v_lshlrev_b32_e32 v187, 2, v95
	s_waitcnt lgkmcnt(0)
	v_add_f32_e32 v83, v83, v94
	ds_bpermute_b32 v94, v187, v81
	v_cmp_lt_i32_e32 vcc, v96, v91
	s_nop 1
	v_mov_b32_dpp v92, v83 quad_perm:[2,3,0,1] row_mask:0xf bank_mask:0xf
	s_nop 1
	v_mov_b32_dpp v90, v88 quad_perm:[1,0,3,2] row_mask:0xf bank_mask:0xf
	v_cndmask_b32_e32 v82, v82, v96, vcc
	s_waitcnt lgkmcnt(0)
	v_add_f32_e32 v81, v81, v94
	v_lshlrev_b32_e32 v188, 2, v82
	ds_bpermute_b32 v82, v188, v81
	s_waitcnt lgkmcnt(0)
	v_add_f32_e32 v83, v83, v92
	s_nop 1
	v_mov_b32_dpp v92, v89 quad_perm:[1,0,3,2] row_mask:0xf bank_mask:0xf
	s_waitcnt lgkmcnt(0)
	v_add_f32_e32 v88, v88, v90
	s_nop 1
	v_mov_b32_dpp v90, v88 quad_perm:[2,3,0,1] row_mask:0xf bank_mask:0xf
	s_waitcnt lgkmcnt(0)
	v_add_f32_e32 v81, v81, v82
	s_nop 1
	v_mov_b32_dpp v82, v87 quad_perm:[1,0,3,2] row_mask:0xf bank_mask:0xf
	s_waitcnt lgkmcnt(0)
	v_add_f32_e32 v89, v89, v92
	s_nop 1
	v_mov_b32_dpp v92, v89 quad_perm:[2,3,0,1] row_mask:0xf bank_mask:0xf
	s_waitcnt lgkmcnt(0)
	v_add_f32_e32 v88, v88, v90
	s_nop 1
	v_mov_b32_dpp v91, v83 row_half_mirror row_mask:0xf bank_mask:0xf
	s_waitcnt lgkmcnt(0)
	v_add_f32_e32 v82, v87, v82
	s_nop 1
	v_mov_b32_dpp v87, v82 quad_perm:[2,3,0,1] row_mask:0xf bank_mask:0xf
	s_waitcnt lgkmcnt(0)
	v_add_f32_e32 v89, v89, v92
	s_nop 1
	v_mov_b32_dpp v90, v88 row_half_mirror row_mask:0xf bank_mask:0xf
	s_nop 1
	v_mov_b32_dpp v92, v89 row_half_mirror row_mask:0xf bank_mask:0xf
	s_waitcnt lgkmcnt(0)
	v_add_f32_e32 v83, v83, v91
	s_waitcnt lgkmcnt(0)
	v_add_f32_e32 v82, v82, v87
	s_nop 1
	v_mov_b32_dpp v87, v82 row_half_mirror row_mask:0xf bank_mask:0xf
	s_waitcnt lgkmcnt(0)
	v_add_f32_e32 v88, v88, v90
	s_waitcnt lgkmcnt(0)
	v_add_f32_e32 v89, v89, v92
	s_nop 1
	v_mov_b32_dpp v91, v83 row_mirror row_mask:0xf bank_mask:0xf
	s_nop 1
	v_mov_b32_dpp v90, v88 row_mirror row_mask:0xf bank_mask:0xf
	s_waitcnt lgkmcnt(0)
	v_add_f32_e32 v82, v82, v87
	s_nop 1
	v_mov_b32_dpp v87, v82 row_mirror row_mask:0xf bank_mask:0xf
	s_nop 1
	v_mov_b32_dpp v92, v89 row_mirror row_mask:0xf bank_mask:0xf
	s_waitcnt lgkmcnt(0)
	v_add_f32_e32 v83, v83, v91
	s_waitcnt lgkmcnt(0)
	v_add_f32_e32 v88, v88, v90
	ds_bpermute_b32 v91, v187, v83
	s_waitcnt lgkmcnt(0)
	v_add_f32_e32 v82, v82, v87
	s_waitcnt lgkmcnt(0)
	v_add_f32_e32 v92, v89, v92
	ds_bpermute_b32 v87, v187, v82
	ds_bpermute_b32 v90, v187, v88
	ds_bpermute_b32 v95, v187, v92
	s_mov_b64 s[6:7], s[80:81]
	s_load_dwordx2 s[10:11], s[6:7], 0x110
	s_mov_b64 s[6:7], s[80:81]
	s_waitcnt lgkmcnt(0)
	v_add_f32_e32 v94, v83, v91
	v_add_f32_e32 v91, v82, v87
	v_add_f32_e32 v89, v88, v90
	v_add_f32_e32 v87, v92, v95
	s_load_dwordx2 s[6:7], s[6:7], 0x110
	ds_bpermute_b32 v95, v188, v94
	ds_bpermute_b32 v92, v188, v91
	ds_bpermute_b32 v90, v188, v89
	ds_bpermute_b32 v88, v188, v87
	v_mov_b32_e32 v93, 0x358637bd
	v_fmac_f32_e32 v93, 0x3a800000, v81
	v_mov_b32_e32 v81, 0
	s_mov_b64 s[40:41], 0x3000000
	v_lshl_add_u64 v[82:83], s[10:11], 0, v[80:81]
	s_andn2_b64 vcc, exec, s[4:5]
	v_lshl_add_u64 v[82:83], v[82:83], 0, s[40:41]
	s_cbranch_vccnz .LBB0_85
	s_mov_b32 s0, 0x800000
	v_mul_f32_e32 v81, 0x4b800000, v93
	v_cmp_gt_f32_e32 vcc, s0, v93
	s_ashr_i32 s37, s36, 31
	s_lshl_b64 s[4:5], s[36:37], 11
	v_cndmask_b32_e32 v81, v93, v81, vcc
	v_rsq_f32_e32 v81, v81
	v_lshl_add_u64 v[98:99], v[82:83], 0, s[4:5]
	v_mul_f32_e32 v96, 0x45800000, v81
	v_cndmask_b32_e32 v96, v81, v96, vcc
	v_pk_mul_f32 v[76:77], v[76:77], v[96:97] op_sel_hi:[1,0]
	v_pk_mul_f32 v[72:73], v[72:73], v[96:97] op_sel_hi:[1,0]
	v_pk_mul_f32 v[68:69], v[68:69], v[96:97] op_sel_hi:[1,0]
	v_pk_mul_f32 v[64:65], v[64:65], v[96:97] op_sel_hi:[1,0]
	v_pk_mul_f32 v[78:79], v[78:79], v[96:97] op_sel_hi:[1,0]
	v_cvt_pk_bf16_f32 v76, v76, v77
	v_pk_mul_f32 v[74:75], v[74:75], v[96:97] op_sel_hi:[1,0]
	v_cvt_pk_bf16_f32 v77, v78, v79
	global_store_dwordx2 v[98:99], v[76:77], off
	v_cvt_pk_bf16_f32 v72, v72, v73
	v_cvt_pk_bf16_f32 v73, v74, v75
	global_store_dwordx2 v[98:99], v[72:73], off offset:512
	v_pk_mul_f32 v[70:71], v[70:71], v[96:97] op_sel_hi:[1,0]
	v_cvt_pk_bf16_f32 v68, v68, v69
	v_pk_mul_f32 v[66:67], v[66:67], v[96:97] op_sel_hi:[1,0]
	v_cvt_pk_bf16_f32 v69, v70, v71
	global_store_dwordx2 v[98:99], v[68:69], off offset:1024
	v_cvt_pk_bf16_f32 v64, v64, v65
	v_cvt_pk_bf16_f32 v65, v66, v67
	global_store_dwordx2 v[98:99], v[64:65], off offset:1536

; __device__ __forceinline__ float ssq4(v4f v) { return (v.x * v.x + v.y * v.y) + (v.z * v.z + v.w * v.w); }
; __device__ __forceinline__ float wave_sum(float v) {
; #pragma unroll
;     for (int o = 1; o < 64; o <<= 1) v += __shfl_xor(v, o);
;     return v;
; }
; template <int R>
; __device__ __forceinline__ void rows_x0(const Ctx& C, int m0, int stride, int mx, int lane) {
;     ...
;         for (int j = 0; j < 4; ++j) v[r][j] = __builtin_nontemporal_load((const v4f*)(x + 4 * lane + 256 * j)); }
;     bf16* XN = C.XN();
; #pragma unroll
;     for (int r = 0; r < R; ++r) { float s = 0.f;
; #pragma unroll
;         for (int j = 0; j < 4; ++j) s += ssq4(v[r][j]);
;         ss[r] = s; }
;     float* rs = C.RS();
; #pragma unroll
;     for (int r = 0; r < R; ++r) ss[r] = wave_sum(ss[r]) * (1.f / DM) + EPS;
.LBB0_110:
	s_load_dwordx2 s[6:7], s[6:7], 0x0
	s_lshl_b64 s[42:43], s[42:43], 12
	s_waitcnt vmcnt(11)
	v_mul_f32_e32 v66, v61, v61
	v_mul_f32_e32 v67, v63, v63
	s_waitcnt vmcnt(10)
	v_mul_f32_e32 v70, v57, v57
	s_waitcnt lgkmcnt(0)
	s_add_u32 s42, s6, s42
	s_addc_u32 s43, s7, s43
	global_load_dwordx4 v[4:7], v85, s[42:43] nt
	global_load_dwordx4 v[0:3], v85, s[42:43] offset:1024 nt
	global_load_dwordx4 v[12:15], v85, s[42:43] offset:2048 nt
	global_load_dwordx4 v[20:23], v85, s[42:43] offset:3072 nt
	v_mul_f32_e32 v71, v59, v59
	s_waitcnt vmcnt(13)
	v_mul_f32_e32 v72, v53, v53
	v_mul_f32_e32 v73, v55, v55
	v_fmac_f32_e32 v66, v60, v60
	v_fmac_f32_e32 v67, v62, v62
	v_fmac_f32_e32 v70, v56, v56
	v_fmac_f32_e32 v71, v58, v58
	s_waitcnt vmcnt(12)
	v_mul_f32_e32 v74, v49, v49
	v_mul_f32_e32 v75, v51, v51
	v_fmac_f32_e32 v72, v52, v52
	v_fmac_f32_e32 v73, v54, v54
	v_add_f32_e32 v66, v66, v67
	v_add_f32_e32 v67, v70, v71
	v_fmac_f32_e32 v74, v48, v48
	v_fmac_f32_e32 v75, v50, v50
	v_add_f32_e32 v70, v72, v73
	v_add_f32_e32 v66, v66, v67
	v_add_f32_e32 v71, v74, v75
	v_add_f32_e32 v66, v66, v70
	v_add_f32_e32 v66, v66, v71
	s_nop 1
	v_mov_b32_dpp v71, v66 quad_perm:[1,0,3,2] row_mask:0xf bank_mask:0xf
	s_waitcnt vmcnt(11)
	v_mul_f32_e32 v76, v45, v45
	v_mul_f32_e32 v77, v47, v47
	s_waitcnt vmcnt(10)
	v_mul_f32_e32 v78, v41, v41
	v_mul_f32_e32 v79, v43, v43
	s_waitcnt lgkmcnt(0)
	v_add_f32_e32 v66, v66, v71
	s_nop 1
	v_mov_b32_dpp v71, v66 quad_perm:[2,3,0,1] row_mask:0xf bank_mask:0xf
	s_waitcnt vmcnt(7)
	v_mul_f32_e32 v88, v29, v29
	v_mul_f32_e32 v89, v31, v31
	s_waitcnt vmcnt(6)
	v_mul_f32_e32 v90, v25, v25
	v_mul_f32_e32 v91, v27, v27
	s_waitcnt lgkmcnt(0)
	v_add_f32_e32 v66, v66, v71
	s_nop 1
	v_mov_b32_dpp v71, v66 row_half_mirror row_mask:0xf bank_mask:0xf
	s_waitcnt vmcnt(5)
	v_mul_f32_e32 v92, v17, v17
	v_mul_f32_e32 v93, v19, v19
	v_fmac_f32_e32 v76, v44, v44
	v_fmac_f32_e32 v77, v46, v46
	s_waitcnt lgkmcnt(0)
	v_add_f32_e32 v66, v66, v71
	s_nop 1
	v_mov_b32_dpp v71, v66 row_mirror row_mask:0xf bank_mask:0xf
	v_fmac_f32_e32 v78, v40, v40
	v_fmac_f32_e32 v79, v42, v42
	v_fmac_f32_e32 v88, v28, v28
	v_fmac_f32_e32 v89, v30, v30
	v_fmac_f32_e32 v90, v24, v24
	v_fmac_f32_e32 v91, v26, v26
	v_fmac_f32_e32 v92, v16, v16
	v_fmac_f32_e32 v93, v18, v18
	v_add_f32_e32 v72, v76, v77
	v_add_f32_e32 v73, v78, v79
	v_add_f32_e32 v76, v88, v89
	v_add_f32_e32 v77, v90, v91
	v_mul_f32_e32 v82, v37, v37
	v_mul_f32_e32 v83, v39, v39
	v_add_f32_e32 v78, v92, v93
	v_add_f32_e32 v67, v72, v73
	v_add_f32_e32 v72, v76, v77
	s_waitcnt lgkmcnt(0)
	v_add_f32_e32 v66, v66, v71
	v_fmac_f32_e32 v82, v36, v36
	v_fmac_f32_e32 v83, v38, v38
	v_add_f32_e32 v70, v72, v78
	ds_bpermute_b32 v71, v187, v66
	v_add_f32_e32 v74, v82, v83
	v_add_f32_e32 v67, v67, v74
	v_mul_f32_e32 v86, v33, v33
	v_mul_f32_e32 v87, v35, v35
	s_waitcnt lgkmcnt(0)
	v_add_f32_e32 v66, v66, v71
	ds_bpermute_b32 v71, v188, v66
	s_waitcnt vmcnt(4)
	v_mul_f32_e32 v94, v9, v9
	v_mul_f32_e32 v95, v11, v11
	v_fmac_f32_e32 v86, v32, v32
	v_fmac_f32_e32 v87, v34, v34
	v_fmac_f32_e32 v94, v8, v8
	v_fmac_f32_e32 v95, v10, v10
	v_add_f32_e32 v75, v86, v87
	v_add_f32_e32 v79, v94, v95
	v_add_f32_e32 v67, v67, v75
	s_waitcnt vmcnt(3)
	v_mul_f32_e32 v72, v5, v5
	v_mul_f32_e32 v73, v7, v7
	v_fmac_f32_e32 v72, v4, v4
	v_fmac_f32_e32 v73, v6, v6
	s_waitcnt vmcnt(2)
	v_mul_f32_e32 v74, v1, v1
	v_add_f32_e32 v72, v72, v73
	v_mul_f32_e32 v73, v3, v3
	v_fmac_f32_e32 v74, v0, v0
	v_fmac_f32_e32 v73, v2, v2
	v_add_f32_e32 v73, v74, v73
	v_add_f32_e32 v72, v72, v73
	s_waitcnt vmcnt(1)
	v_mul_f32_e32 v73, v13, v13
	v_mul_f32_e32 v74, v15, v15
	v_fmac_f32_e32 v73, v12, v12
	v_fmac_f32_e32 v74, v14, v14
	v_add_f32_e32 v73, v73, v74
	v_add_f32_e32 v72, v72, v73
	s_waitcnt vmcnt(0)
	v_mul_f32_e32 v73, v21, v21
	v_mul_f32_e32 v74, v23, v23
	v_fmac_f32_e32 v73, v20, v20
	v_fmac_f32_e32 v74, v22, v22
	v_add_f32_e32 v73, v73, v74
	v_add_f32_e32 v70, v70, v79
	v_add_f32_e32 v72, v72, v73
	s_waitcnt lgkmcnt(0)
	v_add_f32_e32 v66, v66, v71
	s_nop 1
	v_mov_b32_dpp v73, v67 quad_perm:[1,0,3,2] row_mask:0xf bank_mask:0xf
	s_nop 1
	v_mov_b32_dpp v71, v70 quad_perm:[1,0,3,2] row_mask:0xf bank_mask:0xf
	v_fmamk_f32 v74, v66, 0x3a800000, v68
	s_nop 1
	v_mov_b32_dpp v66, v72 quad_perm:[1,0,3,2] row_mask:0xf bank_mask:0xf
	s_mov_b64 s[6:7], s[80:81]
	s_waitcnt lgkmcnt(0)
	v_add_f32_e32 v67, v67, v73
	s_waitcnt lgkmcnt(0)
	v_add_f32_e32 v70, v70, v71
	s_nop 1
	v_mov_b32_dpp v73, v67 quad_perm:[2,3,0,1] row_mask:0xf bank_mask:0xf
	s_waitcnt lgkmcnt(0)
	v_add_f32_e32 v66, v72, v66
	s_nop 1
	v_mov_b32_dpp v71, v70 quad_perm:[2,3,0,1] row_mask:0xf bank_mask:0xf
	s_nop 1
	v_mov_b32_dpp v72, v66 quad_perm:[2,3,0,1] row_mask:0xf bank_mask:0xf
	s_waitcnt lgkmcnt(0)
	v_add_f32_e32 v67, v67, v73
	s_nop 1
	v_mov_b32_dpp v73, v67 row_half_mirror row_mask:0xf bank_mask:0xf
	s_waitcnt lgkmcnt(0)
	v_add_f32_e32 v70, v70, v71
	s_waitcnt lgkmcnt(0)
	v_add_f32_e32 v66, v66, v72
	s_nop 1
	v_mov_b32_dpp v71, v70 row_half_mirror row_mask:0xf bank_mask:0xf
	s_nop 1
	v_mov_b32_dpp v72, v66 row_half_mirror row_mask:0xf bank_mask:0xf
	s_waitcnt lgkmcnt(0)
	v_add_f32_e32 v67, v67, v73
	s_nop 1
	v_mov_b32_dpp v73, v67 row_mirror row_mask:0xf bank_mask:0xf
	s_load_dwordx2 s[60:61], s[6:7], 0x110
	s_waitcnt lgkmcnt(0)
	v_add_f32_e32 v70, v70, v71
	v_add_f32_e32 v66, v66, v72
	s_nop 1
	v_mov_b32_dpp v71, v70 row_mirror row_mask:0xf bank_mask:0xf
	s_nop 1
	v_mov_b32_dpp v72, v66 row_mirror row_mask:0xf bank_mask:0xf
	v_add_f32_e32 v67, v67, v73
	ds_bpermute_b32 v73, v187, v67
	s_mov_b64 s[6:7], s[80:81]
	s_waitcnt lgkmcnt(0)
	v_add_f32_e32 v70, v70, v71
	s_waitcnt lgkmcnt(0)
	v_add_f32_e32 v66, v66, v72
	ds_bpermute_b32 v71, v187, v70
	ds_bpermute_b32 v77, v187, v66
	s_waitcnt lgkmcnt(0)
	v_add_f32_e32 v75, v67, v73
	s_load_dwordx2 s[58:59], s[6:7], 0x110
	s_waitcnt lgkmcnt(0)
	v_add_f32_e32 v72, v70, v71
	v_add_f32_e32 v70, v66, v77
	ds_bpermute_b32 v76, v188, v75
	ds_bpermute_b32 v73, v188, v72
	ds_bpermute_b32 v71, v188, v70
	v_lshl_add_u64 v[66:67], s[60:61], 0, v[80:81]
	s_andn2_b64 vcc, exec, s[14:15]
	v_lshl_add_u64 v[66:67], v[66:67], 0, s[50:51]
	s_cbranch_vccnz .LBB0_112
; __device__ __forceinline__ void st4_bf16(bf16* p, v4f o) { v2u w; w.x = cvt_pk_nv(o.x, o.y); w.y = cvt_pk_nv(o.z, o.w); *(v2u*)p = w; }
; template <int R>
; __device__ __forceinline__ void rows_x0(const Ctx& C, int m0, int stride, int mx, int lane) {
;     ...
;     for (int r = 0; r < R; ++r) { const float rstd = rsqrtf(ss[r]);
; #pragma unroll
;         for (int j = 0; j < 4; ++j) if (ok[r]) st4_bf16(XN + (size_t)mr[r] * DM + 4 * lane + 256 * j, v[r][j] * rstd);
;         if (lane == 0 && ok[r]) rs[mr[r]] = sqrtf(ss[r]); }
	v_mul_f32_e32 v77, 0x4b800000, v74
	v_cmp_gt_f32_e32 vcc, s64, v74
	v_lshl_add_u64 v[78:79], v[66:67], 0, s[26:27]
	s_nop 0
	v_cndmask_b32_e32 v77, v74, v77, vcc
	v_rsq_f32_e32 v77, v77
	s_nop 0
	v_mul_f32_e32 v82, 0x45800000, v77
	v_cndmask_b32_e32 v82, v77, v82, vcc
	v_pk_mul_f32 v[60:61], v[60:61], v[82:83] op_sel_hi:[1,0]
	v_pk_mul_f32 v[56:57], v[56:57], v[82:83] op_sel_hi:[1,0]
	v_pk_mul_f32 v[52:53], v[52:53], v[82:83] op_sel_hi:[1,0]
	v_pk_mul_f32 v[48:49], v[48:49], v[82:83] op_sel_hi:[1,0]
	v_pk_mul_f32 v[62:63], v[62:63], v[82:83] op_sel_hi:[1,0]
	v_cvt_pk_bf16_f32 v60, v60, v61
	v_pk_mul_f32 v[58:59], v[58:59], v[82:83] op_sel_hi:[1,0]
	v_cvt_pk_bf16_f32 v61, v62, v63
	global_store_dwordx2 v[78:79], v[60:61], off
	v_cvt_pk_bf16_f32 v56, v56, v57
	v_cvt_pk_bf16_f32 v57, v58, v59
	global_store_dwordx2 v[78:79], v[56:57], off offset:512
	v_pk_mul_f32 v[54:55], v[54:55], v[82:83] op_sel_hi:[1,0]
	v_cvt_pk_bf16_f32 v52, v52, v53
	v_pk_mul_f32 v[50:51], v[50:51], v[82:83] op_sel_hi:[1,0]
	v_cvt_pk_bf16_f32 v53, v54, v55
	global_store_dwordx2 v[78:79], v[52:53], off offset:1024
	v_cvt_pk_bf16_f32 v48, v48, v49
	v_cvt_pk_bf16_f32 v49, v50, v51
	global_store_dwordx2 v[78:79], v[48:49], off offset:1536

; __device__ __forceinline__ void st4_bf16(bf16* p, v4f o) { v2u w; w.x = cvt_pk_nv(o.x, o.y); w.y = cvt_pk_nv(o.z, o.w); *(v2u*)p = w; }
; template <int R>
; __device__ __forceinline__ void rows_x0(const Ctx& C, int m0, int stride, int mx, int lane) {
;     ...
;     for (int r = 0; r < R; ++r) ss[r] = wave_sum(ss[r]) * (1.f / DM) + EPS;
; #pragma unroll
;     for (int r = 0; r < R; ++r) { const float rstd = rsqrtf(ss[r]);
; #pragma unroll
;         for (int j = 0; j < 4; ++j) if (ok[r]) st4_bf16(XN + (size_t)mr[r] * DM + 4 * lane + 256 * j, v[r][j] * rstd);
;         if (lane == 0 && ok[r]) rs[mr[r]] = sqrtf(ss[r]); }
.LBB0_114:
	s_or_b64 exec, exec, s[42:43]
	s_waitcnt lgkmcnt(0)
	v_add_f32_e32 v48, v75, v76
	s_andn2_b64 vcc, exec, s[18:19]
	v_fmamk_f32 v48, v48, 0x3a800000, v68
	s_cbranch_vccnz .LBB0_116
	v_mul_f32_e32 v49, 0x4b800000, v48
	v_cmp_gt_f32_e32 vcc, s64, v48
	v_lshl_add_u64 v[50:51], v[66:67], 0, s[30:31]
	s_nop 0
	v_cndmask_b32_e32 v49, v48, v49, vcc
	v_rsq_f32_e32 v49, v49
	s_nop 0
	v_mul_f32_e32 v52, 0x45800000, v49
	v_cndmask_b32_e32 v52, v49, v52, vcc
	v_pk_mul_f32 v[44:45], v[44:45], v[52:53] op_sel_hi:[1,0]
	v_pk_mul_f32 v[40:41], v[40:41], v[52:53] op_sel_hi:[1,0]
	v_pk_mul_f32 v[36:37], v[36:37], v[52:53] op_sel_hi:[1,0]
	v_pk_mul_f32 v[32:33], v[32:33], v[52:53] op_sel_hi:[1,0]
	v_pk_mul_f32 v[46:47], v[46:47], v[52:53] op_sel_hi:[1,0]
	v_cvt_pk_bf16_f32 v44, v44, v45
	v_pk_mul_f32 v[42:43], v[42:43], v[52:53] op_sel_hi:[1,0]
	v_cvt_pk_bf16_f32 v45, v46, v47
	global_store_dwordx2 v[50:51], v[44:45], off
	v_cvt_pk_bf16_f32 v40, v40, v41
	v_cvt_pk_bf16_f32 v41, v42, v43
	global_store_dwordx2 v[50:51], v[40:41], off offset:512
	v_pk_mul_f32 v[38:39], v[38:39], v[52:53] op_sel_hi:[1,0]
	v_cvt_pk_bf16_f32 v36, v36, v37
	v_pk_mul_f32 v[34:35], v[34:35], v[52:53] op_sel_hi:[1,0]
	v_cvt_pk_bf16_f32 v37, v38, v39
	global_store_dwordx2 v[50:51], v[36:37], off offset:1024
	v_cvt_pk_bf16_f32 v32, v32, v33
	v_cvt_pk_bf16_f32 v33, v34, v35
	global_store_dwordx2 v[50:51], v[32:33], off offset:1536

; __device__ __forceinline__ void st4_bf16(bf16* p, v4f o) { v2u w; w.x = cvt_pk_nv(o.x, o.y); w.y = cvt_pk_nv(o.z, o.w); *(v2u*)p = w; }
; template <int R>
; __device__ __forceinline__ void rows_x0(const Ctx& C, int m0, int stride, int mx, int lane) {
;     ...
;     for (int r = 0; r < R; ++r) ss[r] = wave_sum(ss[r]) * (1.f / DM) + EPS;
; #pragma unroll
;     for (int r = 0; r < R; ++r) { const float rstd = rsqrtf(ss[r]);
; #pragma unroll
;         for (int j = 0; j < 4; ++j) if (ok[r]) st4_bf16(XN + (size_t)mr[r] * DM + 4 * lane + 256 * j, v[r][j] * rstd);
;         if (lane == 0 && ok[r]) rs[mr[r]] = sqrtf(ss[r]); }
.LBB0_118:
	s_or_b64 exec, exec, s[42:43]
	s_waitcnt lgkmcnt(0)
	v_add_f32_e32 v32, v72, v73
	s_andn2_b64 vcc, exec, s[22:23]
	v_fmamk_f32 v32, v32, 0x3a800000, v68
	s_cbranch_vccnz .LBB0_120
	v_mul_f32_e32 v33, 0x4b800000, v32
	v_cmp_gt_f32_e32 vcc, s64, v32
	v_lshl_add_u64 v[34:35], v[66:67], 0, s[36:37]
	s_nop 0
	v_cndmask_b32_e32 v33, v32, v33, vcc
	v_rsq_f32_e32 v33, v33
	s_nop 0
	v_mul_f32_e32 v36, 0x45800000, v33
	v_cndmask_b32_e32 v36, v33, v36, vcc
	v_pk_mul_f32 v[28:29], v[28:29], v[36:37] op_sel_hi:[1,0]
	v_pk_mul_f32 v[24:25], v[24:25], v[36:37] op_sel_hi:[1,0]
	v_pk_mul_f32 v[16:17], v[16:17], v[36:37] op_sel_hi:[1,0]
	v_pk_mul_f32 v[8:9], v[8:9], v[36:37] op_sel_hi:[1,0]
	v_pk_mul_f32 v[30:31], v[30:31], v[36:37] op_sel_hi:[1,0]
	v_cvt_pk_bf16_f32 v28, v28, v29
	v_pk_mul_f32 v[26:27], v[26:27], v[36:37] op_sel_hi:[1,0]
	v_cvt_pk_bf16_f32 v29, v30, v31
	global_store_dwordx2 v[34:35], v[28:29], off
	v_cvt_pk_bf16_f32 v24, v24, v25
	v_cvt_pk_bf16_f32 v25, v26, v27
	global_store_dwordx2 v[34:35], v[24:25], off offset:512
	v_pk_mul_f32 v[18:19], v[18:19], v[36:37] op_sel_hi:[1,0]
	v_cvt_pk_bf16_f32 v16, v16, v17
	v_pk_mul_f32 v[10:11], v[10:11], v[36:37] op_sel_hi:[1,0]
	v_cvt_pk_bf16_f32 v17, v18, v19
	global_store_dwordx2 v[34:35], v[16:17], off offset:1024
	v_cvt_pk_bf16_f32 v8, v8, v9
	v_cvt_pk_bf16_f32 v9, v10, v11
	global_store_dwordx2 v[34:35], v[8:9], off offset:1536

; __device__ __forceinline__ unsigned xb_add(unsigned* p, unsigned v) { return __hip_atomic_fetch_add(p, v, __ATOMIC_RELAXED, __HIP_MEMORY_SCOPE_AGENT); }
; __device__ __forceinline__ void xcd_barrier(const XcdBarrier& b) {
;     asm volatile("s_waitcnt vmcnt(0)" ::: "memory");
;     __syncthreads();
;     if (threadIdx.x == 0) {
;         unsigned* bar = b.bar;
;         __builtin_amdgcn_s_waitcnt(0);
;         unsigned nloc = b.st[0], nx = b.st[1];
;         if (nloc == 0u) { xcd_barrier_complete(bar, b.x, nloc, nx); b.st[0] = nloc; b.st[1] = nx; }
;         const unsigned old = xb_add(&bar[XB_XSUB(b.x)], 1u);
.LBB0_144:
	s_or_b64 exec, exec, s[4:5]
	s_mov_b64 s[6:7], s[80:81]
	s_getreg_b32 s8, hwreg(HW_REG_XCC_ID, 0, 4)
	s_waitcnt vmcnt(0)
	s_waitcnt lgkmcnt(0)
	s_barrier
	s_and_saveexec_b64 s[4:5], s[96:97]
	v_readlane_b32 s45, v232, 8
	v_readlane_b32 s70, v232, 7
	s_cbranch_execz .LBB0_196
	s_add_i32 s0, 0, 0x23fc0
	v_mov_b32_e32 v0, s0
	s_load_dwordx2 s[6:7], s[6:7], 0x110
	s_waitcnt vmcnt(0) expcnt(0) lgkmcnt(0)
	ds_read_b32 v2, v0
	s_add_i32 s0, 0, 0x23fc4
	v_mov_b32_e32 v0, s0
	ds_read_b32 v0, v0
	s_and_b32 s10, s8, 15
	s_waitcnt lgkmcnt(0)
	v_cmp_ne_u32_e32 vcc, 0, v2
	s_cbranch_vccnz .LBB0_160
	s_add_u32 s8, s6, 0x1000
	s_addc_u32 s9, s7, 0
	s_add_u32 s12, s6, 0x1100
	s_addc_u32 s13, s7, 0
	s_add_u32 s14, s6, 0x1200
	s_addc_u32 s15, s7, 0
	s_mul_i32 s11, s95, s93
	s_add_u32 s16, s6, 0x1300
	s_mul_i32 s11, s11, s94
	s_addc_u32 s17, s7, 0
	s_mov_b32 s24, 1
	v_mov_b32_e32 v16, 0
	s_branch .LBB0_148

; __device__ __forceinline__ const float* xrow_ptr(const Ctx& C, int row) { return row < MPROMPT ? C.in(0) + (size_t)row * DM : C.in(1) + (size_t)(row - MPROMPT) * DM; }
; __device__ __forceinline__ v4f ld4_bf16(const bf16* p) { const v2u w = *(const v2u*)p; return (v4f){bf_lo(w.x), bf_hi(w.x), bf_lo(w.y), bf_hi(w.y)}; }
; template <int R, bool BASE_F32, bool OUT_F32>
; __device__ __forceinline__ void rows_res(const Ctx& C, int m0, int stride, int mx, const float* gpost, float scale, int lane) {
;     ...
;     for (int r = 0; r < R; ++r) { mr[r] = (r == 4) ? mx : m0 + r * stride; ok[r] = (r == 4) ? (mx < M) : (mr[r] < MPROMPT); const int mm = ok[r] ? mr[r] : 0;
; #pragma unroll
;         for (int j = 0; j < 4; ++j) d[r][j] = ld4_bf16(D + (size_t)mm * DM + 4 * lane + 256 * j);
;         if (BASE_F32) { const float* x = xrow_ptr(C, mm);
; #pragma unroll
;             for (int j = 0; j < 4; ++j) b[r][j] = ld4_f32(x + 4 * lane + 256 * j);
;         } else { const float inv = C.RS()[mm];
; #pragma unroll
;             for (int j = 0; j < 4; ++j) b[r][j] = ld4_bf16(XN + (size_t)mm * DM + 4 * lane + 256 * j) * inv;
;         } }
.LBB0_369:
	s_mov_b64 s[0:1], s[80:81]
	s_load_dwordx2 s[0:1], s[0:1], 0x110
	s_cmpk_gt_i32 s20, 0x7fff
	s_cselect_b64 s[40:41], -1, 0
	s_mov_b64 s[10:11], s[80:81]
	s_waitcnt lgkmcnt(0)
	v_lshl_add_u64 v[8:9], s[0:1], 0, v[0:1]
	s_and_b64 s[0:1], s[40:41], exec
	s_cselect_b32 s0, 0, s20
	s_ashr_i32 s1, s0, 31
	v_lshl_add_u64 v[14:15], v[8:9], 0, s[12:13]
	s_lshl_b64 s[22:23], s[0:1], 11
	v_lshl_add_u64 v[8:9], v[14:15], 0, s[22:23]
	s_mov_b64 s[24:25], s[80:81]
	s_load_dwordx2 s[10:11], s[10:11], 0x110
	global_load_dwordx2 v[100:101], v[8:9], off
	global_load_dwordx2 v[92:93], v[8:9], off offset:512
	global_load_dwordx2 v[98:99], v[8:9], off offset:1024
	global_load_dwordx2 v[20:21], v[8:9], off offset:1536
	s_load_dwordx2 s[24:25], s[24:25], 0x110
	s_lshl_b64 s[0:1], s[0:1], 2
	s_waitcnt lgkmcnt(0)
	v_lshl_add_u64 v[8:9], s[10:11], 0, v[0:1]
	v_lshl_add_u64 v[8:9], v[8:9], 0, s[16:17]
	v_lshl_add_u64 v[12:13], v[8:9], 0, s[22:23]
	s_add_u32 s0, s24, s0
	s_addc_u32 s1, s25, s1
	s_add_i32 s34, s46, s20
	s_cmp_lt_i32 s34, 0x8000
	s_cselect_b64 s[52:53], -1, 0
	s_cmpk_gt_i32 s34, 0x7fff
	s_cselect_b64 s[36:37], -1, 0
	global_load_dword v10, v3, s[0:1]
	s_and_b64 s[0:1], s[36:37], exec
	s_cselect_b32 s0, 0, s34
	s_ashr_i32 s1, s0, 31
	s_lshl_b64 s[10:11], s[0:1], 11
	global_load_dwordx2 v[22:23], v[12:13], off
	global_load_dwordx2 v[24:25], v[12:13], off offset:512
	global_load_dwordx2 v[26:27], v[12:13], off offset:1024
	global_load_dwordx2 v[28:29], v[12:13], off offset:1536
	v_lshl_add_u64 v[12:13], v[14:15], 0, s[10:11]
	s_mov_b64 s[22:23], s[80:81]
	global_load_dwordx2 v[108:109], v[12:13], off
	global_load_dwordx2 v[104:105], v[12:13], off offset:512
	global_load_dwordx2 v[106:107], v[12:13], off offset:1024
	global_load_dwordx2 v[30:31], v[12:13], off offset:1536
	s_load_dwordx2 s[22:23], s[22:23], 0x110
	s_lshl_b64 s[0:1], s[0:1], 2
	v_lshl_add_u64 v[16:17], v[8:9], 0, s[10:11]
	s_waitcnt lgkmcnt(0)
	s_add_u32 s0, s22, s0
	s_addc_u32 s1, s23, s1
	s_add_i32 s26, s70, s20
	s_cmp_lt_i32 s26, 0x8000
	s_cselect_b64 s[38:39], -1, 0
	s_cmpk_gt_i32 s26, 0x7fff
	s_cselect_b64 s[28:29], -1, 0
	global_load_dword v12, v3, s[0:1]
	s_and_b64 s[0:1], s[28:29], exec
	s_cselect_b32 s0, 0, s26
	s_ashr_i32 s1, s0, 31
	s_lshl_b64 s[10:11], s[0:1], 11
	global_load_dwordx2 v[32:33], v[16:17], off
	global_load_dwordx2 v[34:35], v[16:17], off offset:512
	global_load_dwordx2 v[38:39], v[16:17], off offset:1024
	global_load_dwordx2 v[42:43], v[16:17], off offset:1536
	v_lshl_add_u64 v[16:17], v[14:15], 0, s[10:11]
	s_mov_b64 s[22:23], s[80:81]
	global_load_dwordx2 v[120:121], v[16:17], off
	global_load_dwordx2 v[116:117], v[16:17], off offset:512
	global_load_dwordx2 v[118:119], v[16:17], off offset:1024
	global_load_dwordx2 v[44:45], v[16:17], off offset:1536
	s_load_dwordx2 s[22:23], s[22:23], 0x110
	s_lshl_b64 s[0:1], s[0:1], 2
	v_lshl_add_u64 v[16:17], v[8:9], 0, s[10:11]
	global_load_dwordx2 v[48:49], v[16:17], off
	global_load_dwordx2 v[50:51], v[16:17], off offset:512
	global_load_dwordx2 v[66:67], v[16:17], off offset:1024
	global_load_dwordx2 v[74:75], v[16:17], off offset:1536
	s_waitcnt lgkmcnt(0)
	s_add_u32 s0, s22, s0
	s_addc_u32 s1, s23, s1
	s_add_i32 s22, s45, s20
	s_cmp_lt_i32 s22, 0x8000
	s_cselect_b64 s[30:31], -1, 0
	s_cmpk_gt_i32 s22, 0x7fff
	s_cselect_b64 s[24:25], -1, 0
	s_and_b64 s[10:11], s[24:25], exec
	s_cselect_b32 s10, 0, s22
	s_ashr_i32 s11, s10, 31
	s_lshl_b64 s[56:57], s[10:11], 11
	v_lshl_add_u64 v[14:15], v[14:15], 0, s[56:57]
	global_load_dwordx2 v[78:79], v[14:15], off offset:1536
	global_load_dwordx2 v[138:139], v[14:15], off
	global_load_dwordx2 v[134:135], v[14:15], off offset:512
	global_load_dwordx2 v[136:137], v[14:15], off offset:1024
	s_nop 0
	global_load_dword v14, v3, s[0:1]
	s_mov_b64 s[0:1], s[80:81]
	v_lshl_add_u64 v[80:81], v[8:9], 0, s[56:57]
	global_load_dwordx2 v[82:83], v[80:81], off
	global_load_dwordx2 v[102:103], v[80:81], off offset:512
	global_load_dwordx2 v[110:111], v[80:81], off offset:1024
	s_load_dwordx2 s[0:1], s[0:1], 0x110
	s_lshl_b64 s[10:11], s[10:11], 2
	s_waitcnt lgkmcnt(0)
	s_add_u32 s0, s0, s10
	s_addc_u32 s1, s1, s11
	global_load_dword v36, v3, s[0:1]
	global_load_dwordx2 v[132:133], v[80:81], off offset:1536
	s_mov_b64 s[0:1], s[80:81]
	s_waitcnt vmcnt(35)
	v_and_b32_e32 v115, 0xffff0000, v101
	v_and_b32_e32 v113, 0xffff0000, v100
	v_lshlrev_b32_e32 v114, 16, v101
	s_waitcnt vmcnt(32)
	v_and_b32_e32 v17, 0xffff0000, v20
	v_mul_f32_e32 v16, v115, v115
	v_lshlrev_b32_e32 v112, 16, v100
	v_lshlrev_b32_e32 v19, 16, v20
	v_lshlrev_b32_e32 v101, 16, v93
	v_lshlrev_b32_e32 v100, 16, v92
	v_mov_b32_e32 v127, v19
	v_lshlrev_b32_e32 v20, 16, v21
	v_and_b32_e32 v21, 0xffff0000, v21
	s_waitcnt vmcnt(30)
	v_lshlrev_b32_e32 v88, 16, v22
	s_waitcnt vmcnt(29)
	v_lshlrev_b32_e32 v58, 16, v25
	v_and_b32_e32 v59, 0xffff0000, v25
	s_waitcnt vmcnt(28)
	v_lshlrev_b32_e32 v52, 16, v26
	v_and_b32_e32 v53, 0xffff0000, v26
	v_lshlrev_b32_e32 v54, 16, v27
	v_and_b32_e32 v55, 0xffff0000, v27
	s_waitcnt vmcnt(23)
	v_lshlrev_b32_e32 v25, 16, v30
	v_and_b32_e32 v11, 0xffff0000, v30
	v_lshlrev_b32_e32 v26, 16, v31
	v_and_b32_e32 v27, 0xffff0000, v31
	v_lshlrev_b32_e32 v56, 16, v24
	v_and_b32_e32 v57, 0xffff0000, v24
	v_mul_f32_e32 v24, v17, v17
	v_mov_b32_e32 v141, v25
	v_and_b32_e32 v89, 0xffff0000, v22
	v_lshlrev_b32_e32 v90, 16, v23
	v_and_b32_e32 v91, 0xffff0000, v23
	v_lshlrev_b32_e32 v22, 16, v28
	v_and_b32_e32 v23, 0xffff0000, v28
	v_lshlrev_b32_e32 v28, 16, v29
	v_and_b32_e32 v29, 0xffff0000, v29
	s_waitcnt vmcnt(21)
	v_lshlrev_b32_e32 v40, 16, v32
	s_waitcnt vmcnt(20)
; __device__ __forceinline__ float ssq4(v4f v) { return (v.x * v.x + v.y * v.y) + (v.z * v.z + v.w * v.w); }
; __device__ __forceinline__ float wave_sum(float v) {
; #pragma unroll
;     for (int o = 1; o < 64; o <<= 1) v += __shfl_xor(v, o);
;     return v;
; }
; template <int R, bool BASE_F32, bool OUT_F32>
; __device__ __forceinline__ void rows_res(const Ctx& C, int m0, int stride, int mx, const float* gpost, float scale, int lane) {
;     ...
; #pragma unroll
;     for (int r = 0; r < R; ++r) { float s = 0.f;
; #pragma unroll
;         for (int j = 0; j < 4; ++j) s += ssq4(d[r][j]);
;         r1[r] = s; }
; #pragma unroll
;     for (int r = 0; r < R; ++r) r1[r] = rsqrtf(wave_sum(r1[r]) * (1.f / DM) + EPS) * scale;
	v_lshlrev_b32_e32 v68, 16, v34
	v_and_b32_e32 v69, 0xffff0000, v34
	v_lshlrev_b32_e32 v70, 16, v35
	v_and_b32_e32 v71, 0xffff0000, v35
	s_waitcnt vmcnt(19)
	v_lshlrev_b32_e32 v60, 16, v38
	v_and_b32_e32 v61, 0xffff0000, v38
	v_lshlrev_b32_e32 v62, 16, v39
	v_and_b32_e32 v63, 0xffff0000, v39
	s_waitcnt vmcnt(18)
	v_lshlrev_b32_e32 v30, 16, v42
	v_and_b32_e32 v31, 0xffff0000, v42
	v_lshlrev_b32_e32 v38, 16, v43
	v_and_b32_e32 v39, 0xffff0000, v43
	s_waitcnt vmcnt(14)
	v_lshlrev_b32_e32 v34, 16, v45
	v_and_b32_e32 v35, 0xffff0000, v45
	s_waitcnt vmcnt(13)
	v_lshlrev_b32_e32 v84, 16, v48
	v_and_b32_e32 v85, 0xffff0000, v48
	v_lshlrev_b32_e32 v86, 16, v49
	v_and_b32_e32 v87, 0xffff0000, v49
	s_waitcnt vmcnt(12)
	v_lshlrev_b32_e32 v72, 16, v50
	v_and_b32_e32 v73, 0xffff0000, v50
	v_lshlrev_b32_e32 v76, 16, v51
	v_and_b32_e32 v77, 0xffff0000, v51
	s_waitcnt vmcnt(10)
	v_lshlrev_b32_e32 v42, 16, v74
	v_and_b32_e32 v43, 0xffff0000, v74
	v_lshlrev_b32_e32 v50, 16, v75
	v_and_b32_e32 v51, 0xffff0000, v75
	s_waitcnt vmcnt(9)
	v_lshlrev_b32_e32 v45, 16, v78
	v_and_b32_e32 v15, 0xffff0000, v78
	v_lshlrev_b32_e32 v48, 16, v79
	v_and_b32_e32 v49, 0xffff0000, v79
	s_waitcnt vmcnt(4)
	v_lshlrev_b32_e32 v94, 16, v82
	v_and_b32_e32 v95, 0xffff0000, v82
	v_lshlrev_b32_e32 v96, 16, v83
	v_and_b32_e32 v97, 0xffff0000, v83
	s_waitcnt vmcnt(3)
	v_lshlrev_b32_e32 v80, 16, v102
	v_and_b32_e32 v81, 0xffff0000, v102
	v_lshlrev_b32_e32 v82, 16, v103
	v_and_b32_e32 v83, 0xffff0000, v103
	s_waitcnt vmcnt(2)
	v_lshlrev_b32_e32 v74, 16, v110
	v_and_b32_e32 v75, 0xffff0000, v110
	v_lshlrev_b32_e32 v78, 16, v111
	v_and_b32_e32 v79, 0xffff0000, v111
	v_pk_fma_f32 v[110:111], v[114:115], v[114:115], v[16:17] op_sel_hi:[1,1,0]
	v_and_b32_e32 v103, 0xffff0000, v93
	v_and_b32_e32 v102, 0xffff0000, v92
	v_mul_f32_e32 v16, v113, v113
	v_pk_mul_f32 v[92:93], v[102:103], v[102:103]
	v_pk_fma_f32 v[124:125], v[112:113], v[112:113], v[16:17] op_sel_hi:[1,1,0]
	v_pk_fma_f32 v[122:123], v[100:101], v[100:101], v[92:93]
	v_mov_b32_e32 v18, v124
	v_mov_b32_e32 v126, v110
	v_and_b32_e32 v93, 0xffff0000, v98
	v_pk_add_f32 v[110:111], v[124:125], v[110:111]
	v_pk_mul_f32 v[124:125], v[18:19], v[126:127]
	v_pk_add_f32 v[122:123], v[122:123], v[122:123] op_sel:[0,1] op_sel_hi:[1,0]
	v_lshlrev_b32_e32 v92, 16, v98
	v_lshlrev_b32_e32 v98, 16, v99
	v_and_b32_e32 v99, 0xffff0000, v99
	v_mov_b32_e32 v111, v125
	v_mov_b32_e32 v123, v24
	v_mul_f32_e32 v16, v93, v93
	v_pk_add_f32 v[110:111], v[110:111], v[122:123]
	v_pk_fma_f32 v[122:123], v[92:93], v[92:93], v[16:17] op_sel_hi:[1,1,0]
	v_mul_f32_e32 v16, v99, v99
	v_and_b32_e32 v41, 0xffff0000, v32
	v_lshlrev_b32_e32 v46, 16, v33
	v_and_b32_e32 v47, 0xffff0000, v33
	v_lshlrev_b32_e32 v33, 16, v44
	v_and_b32_e32 v13, 0xffff0000, v44
	v_mul_f32_e32 v32, v20, v20
	v_mul_f32_e32 v44, v21, v21
	v_pk_fma_f32 v[124:125], v[98:99], v[98:99], v[16:17] op_sel_hi:[1,1,0]
	v_mov_b32_e32 v123, v32
	v_mov_b32_e32 v125, v44
	v_and_b32_e32 v127, 0xffff0000, v109
	v_pk_add_f32 v[122:123], v[122:123], v[124:125]
	v_and_b32_e32 v125, 0xffff0000, v108
	v_lshlrev_b32_e32 v126, 16, v109
	v_mul_f32_e32 v16, v127, v127
	v_pk_add_f32 v[146:147], v[110:111], v[122:123]
	v_lshlrev_b32_e32 v124, 16, v108
	v_pk_fma_f32 v[122:123], v[126:127], v[126:127], v[16:17] op_sel_hi:[1,1,0]
	v_and_b32_e32 v111, 0xffff0000, v105
	v_and_b32_e32 v110, 0xffff0000, v104
	v_mul_f32_e32 v16, v125, v125
	v_lshlrev_b32_e32 v109, 16, v105
	v_lshlrev_b32_e32 v108, 16, v104
	v_pk_mul_f32 v[104:105], v[110:111], v[110:111]
	v_pk_fma_f32 v[130:131], v[124:125], v[124:125], v[16:17] op_sel_hi:[1,1,0]
	v_pk_fma_f32 v[128:129], v[108:109], v[108:109], v[104:105]
	v_mov_b32_e32 v24, v130
	v_mov_b32_e32 v140, v122
	v_and_b32_e32 v105, 0xffff0000, v106
	v_mul_f32_e32 v18, v11, v11
	v_pk_add_f32 v[122:123], v[130:131], v[122:123]
	v_pk_mul_f32 v[130:131], v[24:25], v[140:141]
	v_pk_add_f32 v[128:129], v[128:129], v[128:129] op_sel:[0,1] op_sel_hi:[1,0]
	v_lshlrev_b32_e32 v104, 16, v106
	v_lshlrev_b32_e32 v106, 16, v107
	v_and_b32_e32 v107, 0xffff0000, v107
	v_mov_b32_e32 v123, v131
	v_mov_b32_e32 v129, v18
	v_mul_f32_e32 v16, v105, v105
	v_pk_add_f32 v[122:123], v[122:123], v[128:129]
	v_pk_fma_f32 v[128:129], v[104:105], v[104:105], v[16:17] op_sel_hi:[1,1,0]
	v_mul_f32_e32 v16, v107, v107
	v_mul_f32_e32 v32, v26, v26
	v_mul_f32_e32 v44, v27, v27
	v_pk_fma_f32 v[130:131], v[106:107], v[106:107], v[16:17] op_sel_hi:[1,1,0]
	v_mov_b32_e32 v129, v32
	v_mov_b32_e32 v131, v44
	v_pk_add_f32 v[128:129], v[128:129], v[130:131]
	v_and_b32_e32 v131, 0xffff0000, v121
	v_pk_add_f32 v[150:151], v[122:123], v[128:129]
	v_and_b32_e32 v129, 0xffff0000, v120
	v_lshlrev_b32_e32 v130, 16, v121
	v_mul_f32_e32 v16, v131, v131
	v_lshlrev_b32_e32 v128, 16, v120
	v_pk_fma_f32 v[140:141], v[130:131], v[130:131], v[16:17] op_sel_hi:[1,1,0]
	v_and_b32_e32 v123, 0xffff0000, v117
	v_and_b32_e32 v122, 0xffff0000, v116
	v_mul_f32_e32 v16, v129, v129
	v_lshlrev_b32_e32 v121, 16, v117
	v_lshlrev_b32_e32 v120, 16, v116
	v_pk_mul_f32 v[116:117], v[122:123], v[122:123]
	v_pk_fma_f32 v[144:145], v[128:129], v[128:129], v[16:17] op_sel_hi:[1,1,0]
	v_pk_fma_f32 v[142:143], v[120:121], v[120:121], v[116:117]
	v_mov_b32_e32 v32, v144
	v_mov_b32_e32 v152, v140
	v_mov_b32_e32 v153, v33
	v_mov_b32_e32 v160, v150
	v_mov_b32_e32 v161, v146
	v_mov_b32_e32 v146, v151
	v_and_b32_e32 v117, 0xffff0000, v118
	v_mul_f32_e32 v18, v13, v13
	v_pk_add_f32 v[140:141], v[144:145], v[140:141]
	v_pk_mul_f32 v[144:145], v[32:33], v[152:153]
	v_pk_add_f32 v[142:143], v[142:143], v[142:143] op_sel:[0,1] op_sel_hi:[1,0]
	v_pk_add_f32 v[146:147], v[160:161], v[146:147]
	v_lshlrev_b32_e32 v116, 16, v118
	v_lshlrev_b32_e32 v118, 16, v119
	v_and_b32_e32 v119, 0xffff0000, v119
	v_mov_b32_e32 v141, v145
	v_mov_b32_e32 v143, v18
	v_mul_f32_e32 v16, v117, v117
	s_nop 1
	v_mov_b32_dpp v151, v147 quad_perm:[1,0,3,2] row_mask:0xf bank_mask:0xf
	s_nop 1
	v_mov_b32_dpp v150, v146 quad_perm:[1,0,3,2] row_mask:0xf bank_mask:0xf
	v_pk_add_f32 v[140:141], v[140:141], v[142:143]
	v_pk_fma_f32 v[142:143], v[116:117], v[116:117], v[16:17] op_sel_hi:[1,1,0]
	v_mul_f32_e32 v16, v119, v119
	v_mul_f32_e32 v24, v34, v34
	v_mul_f32_e32 v44, v35, v35
	v_pk_fma_f32 v[144:145], v[118:119], v[118:119], v[16:17] op_sel_hi:[1,1,0]
	v_mov_b32_e32 v143, v24
	v_mov_b32_e32 v145, v44
	v_pk_add_f32 v[142:143], v[142:143], v[144:145]
	v_and_b32_e32 v145, 0xffff0000, v139
	v_pk_add_f32 v[154:155], v[140:141], v[142:143]
	v_and_b32_e32 v143, 0xffff0000, v138
	v_lshlrev_b32_e32 v144, 16, v139
	v_mul_f32_e32 v16, v145, v145
	s_waitcnt lgkmcnt(0)
; __device__ __forceinline__ float wave_sum(float v) {
; #pragma unroll
;     for (int o = 1; o < 64; o <<= 1) v += __shfl_xor(v, o);
;     return v;
; }
; template <int R, bool BASE_F32, bool OUT_F32>
; __device__ __forceinline__ void rows_res(const Ctx& C, int m0, int stride, int mx, const float* gpost, float scale, int lane) {
;     ...
;     for (int r = 0; r < R; ++r) r1[r] = rsqrtf(wave_sum(r1[r]) * (1.f / DM) + EPS) * scale;
; #pragma unroll
;     for (int j = 0; j < 4; ++j) { const v4f gp = ld4_f32(gpost + 4 * lane + 256 * j);
	v_pk_add_f32 v[146:147], v[146:147], v[150:151]
	v_lshlrev_b32_e32 v142, 16, v138
	v_pk_fma_f32 v[152:153], v[144:145], v[144:145], v[16:17] op_sel_hi:[1,1,0]
	v_and_b32_e32 v141, 0xffff0000, v135
	v_and_b32_e32 v140, 0xffff0000, v134
	v_mul_f32_e32 v16, v143, v143
	s_nop 1
	v_mov_b32_dpp v151, v147 quad_perm:[2,3,0,1] row_mask:0xf bank_mask:0xf
	s_nop 1
	v_mov_b32_dpp v150, v146 quad_perm:[2,3,0,1] row_mask:0xf bank_mask:0xf
	v_lshlrev_b32_e32 v139, 16, v135
	v_lshlrev_b32_e32 v138, 16, v134
	v_pk_mul_f32 v[134:135], v[140:141], v[140:141]
	v_pk_fma_f32 v[158:159], v[142:143], v[142:143], v[16:17] op_sel_hi:[1,1,0]
	v_pk_fma_f32 v[156:157], v[138:139], v[138:139], v[134:135]
	v_mov_b32_e32 v44, v158
	v_mov_b32_e32 v160, v152
	v_mov_b32_e32 v161, v45
	v_mul_f32_e32 v18, v15, v15
	v_pk_add_f32 v[152:153], v[158:159], v[152:153]
	v_pk_mul_f32 v[158:159], v[44:45], v[160:161]
	v_pk_add_f32 v[156:157], v[156:157], v[156:157] op_sel:[0,1] op_sel_hi:[1,0]
	v_mov_b32_e32 v153, v159
	v_mov_b32_e32 v157, v18
	v_pk_add_f32 v[156:157], v[152:153], v[156:157]
	s_waitcnt lgkmcnt(0)
	v_pk_add_f32 v[146:147], v[146:147], v[150:151]
	global_load_dwordx4 v[150:153], v[4:5], off
	s_nop 1
	v_mov_b32_dpp v159, v147 row_half_mirror row_mask:0xf bank_mask:0xf
	s_nop 1
	v_mov_b32_dpp v158, v146 row_half_mirror row_mask:0xf bank_mask:0xf
	v_and_b32_e32 v135, 0xffff0000, v136
	v_lshlrev_b32_e32 v134, 16, v136
	v_lshlrev_b32_e32 v136, 16, v137
	v_and_b32_e32 v137, 0xffff0000, v137
	v_mul_f32_e32 v16, v135, v135
	s_waitcnt lgkmcnt(0)
	v_pk_add_f32 v[146:147], v[146:147], v[158:159]
	v_pk_fma_f32 v[160:161], v[134:135], v[134:135], v[16:17] op_sel_hi:[1,1,0]
	v_mul_f32_e32 v16, v137, v137
	s_nop 1
	v_mov_b32_dpp v159, v147 row_mirror row_mask:0xf bank_mask:0xf
	s_nop 1
	v_mov_b32_dpp v158, v146 row_mirror row_mask:0xf bank_mask:0xf
	v_mul_f32_e32 v24, v48, v48
	v_mul_f32_e32 v32, v49, v49
	v_pk_fma_f32 v[162:163], v[136:137], v[136:137], v[16:17] op_sel_hi:[1,1,0]
	v_mov_b32_e32 v161, v24
	v_mov_b32_e32 v163, v32
	v_pk_add_f32 v[160:161], v[160:161], v[162:163]
	s_waitcnt lgkmcnt(0)
	v_pk_add_f32 v[158:159], v[146:147], v[158:159]
	v_pk_add_f32 v[156:157], v[156:157], v[160:161]
	v_mov_b32_e32 v147, v154
	v_mov_b32_e32 v146, v156
	v_mov_b32_e32 v154, v157
	v_pk_add_f32 v[154:155], v[146:147], v[154:155]
	ds_bpermute_b32 v161, v187, v159
	ds_bpermute_b32 v160, v187, v158
	s_nop 1
	v_mov_b32_dpp v157, v155 quad_perm:[1,0,3,2] row_mask:0xf bank_mask:0xf
	s_nop 1
	v_mov_b32_dpp v156, v154 quad_perm:[1,0,3,2] row_mask:0xf bank_mask:0xf
	v_lshlrev_b32_e32 v64, 16, v66
	v_and_b32_e32 v65, 0xffff0000, v66
	s_waitcnt lgkmcnt(0)
	v_pk_add_f32 v[158:159], v[158:159], v[160:161]
	ds_bpermute_b32 v161, v188, v159
	s_waitcnt lgkmcnt(0)
	v_pk_add_f32 v[162:163], v[154:155], v[156:157]
	ds_bpermute_b32 v160, v188, v158
	s_nop 1
	v_mov_b32_dpp v165, v163 quad_perm:[2,3,0,1] row_mask:0xf bank_mask:0xf
	s_nop 1
	v_mov_b32_dpp v164, v162 quad_perm:[2,3,0,1] row_mask:0xf bank_mask:0xf
	global_load_dwordx4 v[154:157], v[4:5], off offset:1024
	v_lshlrev_b32_e32 v66, 16, v67
	s_waitcnt lgkmcnt(0)
	v_pk_add_f32 v[158:159], v[158:159], v[160:161]
	v_and_b32_e32 v67, 0xffff0000, v67
	s_waitcnt lgkmcnt(0)
	v_pk_add_f32 v[160:161], v[162:163], v[164:165]
	s_nop 1
	v_mov_b32_dpp v163, v161 row_half_mirror row_mask:0xf bank_mask:0xf
	s_nop 1
	v_mov_b32_dpp v162, v160 row_half_mirror row_mask:0xf bank_mask:0xf
	v_pk_fma_f32 v[158:159], v[158:159], s[18:19], v[6:7] op_sel_hi:[1,0,0]
	s_waitcnt vmcnt(2)
	v_lshlrev_b32_e32 v146, 16, v132
	v_mul_f32_e32 v16, 0x4b800000, v159
	v_cmp_gt_f32_e32 vcc, s19, v159
	s_waitcnt lgkmcnt(0)
	v_pk_add_f32 v[160:161], v[160:161], v[162:163]
	s_nop 1
	v_mov_b32_dpp v163, v161 row_mirror row_mask:0xf bank_mask:0xf
	s_nop 1
	v_mov_b32_dpp v162, v160 row_mirror row_mask:0xf bank_mask:0xf
	v_cndmask_b32_e32 v16, v159, v16, vcc
	v_rsq_f32_e32 v16, v16
	v_and_b32_e32 v147, 0xffff0000, v132
	v_lshlrev_b32_e32 v132, 16, v133
	s_waitcnt lgkmcnt(0)
	v_pk_add_f32 v[160:161], v[160:161], v[162:163]
	ds_bpermute_b32 v163, v187, v161
	ds_bpermute_b32 v162, v187, v160
	v_mul_f32_e32 v18, 0x45800000, v16
	v_cndmask_b32_e32 v16, v16, v18, vcc
	v_mul_f32_e32 v18, 0.5, v16
	v_mul_f32_e32 v16, 0x4b800000, v158
	v_cmp_gt_f32_e32 vcc, s19, v158
	s_waitcnt lgkmcnt(0)
	v_pk_add_f32 v[162:163], v[160:161], v[162:163]
	ds_bpermute_b32 v165, v188, v163
	v_cndmask_b32_e32 v16, v158, v16, vcc
	ds_bpermute_b32 v164, v188, v162
	v_rsq_f32_e32 v16, v16
	global_load_dwordx4 v[158:161], v[4:5], off offset:2048
	v_pk_mul_f32 v[114:115], v[18:19], v[114:115] op_sel_hi:[0,1]
	v_pk_mul_f32 v[112:113], v[18:19], v[112:113] op_sel_hi:[0,1]
	v_mul_f32_e32 v24, 0x45800000, v16
	s_waitcnt lgkmcnt(0)
	v_pk_add_f32 v[162:163], v[162:163], v[164:165]
	v_cndmask_b32_e32 v16, v16, v24, vcc
	v_pk_fma_f32 v[162:163], v[162:163], s[18:19], v[6:7] op_sel_hi:[1,0,0]
	v_mul_f32_e32 v24, 0.5, v16
	v_mul_f32_e32 v16, 0x4b800000, v163
	v_cmp_gt_f32_e32 vcc, s19, v163
	v_mul_f32_e32 v32, 0x4b800000, v162
	v_cmp_gt_f32_e64 s[10:11], s19, v162
	v_cndmask_b32_e32 v16, v163, v16, vcc
	v_rsq_f32_e32 v16, v16
	v_cndmask_b32_e64 v32, v162, v32, s[10:11]
	s_waitcnt vmcnt(2)
; template <int R, bool BASE_F32, bool OUT_F32>
; __device__ __forceinline__ void rows_res(const Ctx& C, int m0, int stride, int mx, const float* gpost, float scale, int lane) {
;     ...
;     for (int j = 0; j < 4; ++j) { const v4f gp = ld4_f32(gpost + 4 * lane + 256 * j);
; #pragma unroll
;         for (int r = 0; r < R; ++r) d[r][j] = b[r][j] + d[r][j] * r1[r] * gp; }
	v_pk_mul_f32 v[162:163], v[112:113], v[150:151]
	v_pk_mul_f32 v[112:113], v[114:115], v[152:153]
	v_pk_fma_f32 v[114:115], v[10:11], v[88:89], v[162:163] op_sel_hi:[0,1,1]
	v_pk_fma_f32 v[112:113], v[10:11], v[90:91], v[112:113] op_sel_hi:[0,1,1]
	v_pk_mul_f32 v[88:89], v[24:25], v[126:127] op_sel_hi:[0,1]
	v_pk_mul_f32 v[90:91], v[24:25], v[124:125] op_sel_hi:[0,1]
	global_load_dwordx4 v[124:127], v[4:5], off offset:3072
	v_rsq_f32_e32 v44, v32
	v_mul_f32_e32 v32, 0x45800000, v16
	v_cndmask_b32_e32 v16, v16, v32, vcc
	v_mul_f32_e32 v32, 0.5, v16
	v_mul_f32_e32 v16, 0x45800000, v44
	v_pk_mul_f32 v[88:89], v[152:153], v[88:89]
	v_cndmask_b32_e64 v16, v44, v16, s[10:11]
	v_pk_mul_f32 v[90:91], v[150:151], v[90:91]
	v_pk_fma_f32 v[88:89], v[12:13], v[46:47], v[88:89] op_sel_hi:[0,1,1]
	v_pk_mul_f32 v[46:47], v[32:33], v[128:129] op_sel_hi:[0,1]
	v_mul_f32_e32 v44, 0.5, v16
	v_pk_fma_f32 v[90:91], v[12:13], v[40:41], v[90:91] op_sel_hi:[0,1,1]
	v_pk_mul_f32 v[40:41], v[32:33], v[130:131] op_sel_hi:[0,1]
	v_pk_mul_f32 v[46:47], v[150:151], v[46:47]
	v_pk_mul_f32 v[40:41], v[152:153], v[40:41]
	v_pk_fma_f32 v[84:85], v[14:15], v[84:85], v[46:47] op_sel_hi:[0,1,1]
	v_pk_mul_f32 v[46:47], v[44:45], v[142:143] op_sel_hi:[0,1]
	v_pk_fma_f32 v[86:87], v[14:15], v[86:87], v[40:41] op_sel_hi:[0,1,1]
	v_pk_mul_f32 v[40:41], v[44:45], v[144:145] op_sel_hi:[0,1]
	v_pk_mul_f32 v[46:47], v[150:151], v[46:47]
	v_pk_mul_f32 v[40:41], v[152:153], v[40:41]
	v_pk_fma_f32 v[46:47], v[36:37], v[94:95], v[46:47] op_sel_hi:[0,1,1]
	v_mov_b32_e32 v94, v101
	v_mov_b32_e32 v101, v102
	v_pk_fma_f32 v[40:41], v[36:37], v[96:97], v[40:41] op_sel_hi:[0,1,1]
	v_pk_mul_f32 v[96:97], v[18:19], v[100:101] op_sel_hi:[0,1]
	v_mov_b32_e32 v95, v103
	s_waitcnt vmcnt(2)
	v_pk_mul_f32 v[96:97], v[96:97], v[154:155]
	v_pk_mul_f32 v[94:95], v[18:19], v[94:95] op_sel_hi:[0,1]
	v_pk_fma_f32 v[102:103], v[10:11], v[56:57], v[96:97] op_sel_hi:[0,1,1]
	v_mov_b32_e32 v56, v109
	v_mov_b32_e32 v57, v111
	v_pk_mul_f32 v[56:57], v[24:25], v[56:57] op_sel_hi:[0,1]
	v_pk_mul_f32 v[94:95], v[94:95], v[156:157]
	v_mov_b32_e32 v109, v110
	v_pk_mul_f32 v[56:57], v[56:57], v[156:157]
	v_pk_fma_f32 v[100:101], v[10:11], v[58:59], v[94:95] op_sel_hi:[0,1,1]
	v_pk_mul_f32 v[58:59], v[24:25], v[108:109] op_sel_hi:[0,1]
	v_pk_fma_f32 v[94:95], v[12:13], v[70:71], v[56:57] op_sel_hi:[0,1,1]
	v_mov_b32_e32 v56, v121
	v_mov_b32_e32 v57, v123
	v_pk_mul_f32 v[58:59], v[58:59], v[154:155]
	v_pk_mul_f32 v[56:57], v[32:33], v[56:57] op_sel_hi:[0,1]
	v_mov_b32_e32 v121, v122
	v_pk_fma_f32 v[96:97], v[12:13], v[68:69], v[58:59] op_sel_hi:[0,1,1]
	v_pk_mul_f32 v[58:59], v[32:33], v[120:121] op_sel_hi:[0,1]
	v_pk_mul_f32 v[56:57], v[156:157], v[56:57]
	v_pk_mul_f32 v[58:59], v[154:155], v[58:59]
	v_pk_fma_f32 v[68:69], v[14:15], v[76:77], v[56:57] op_sel_hi:[0,1,1]
	v_mov_b32_e32 v56, v139
	v_mov_b32_e32 v139, v140
	v_pk_fma_f32 v[70:71], v[14:15], v[72:73], v[58:59] op_sel_hi:[0,1,1]
	v_pk_mul_f32 v[58:59], v[44:45], v[138:139] op_sel_hi:[0,1]
	v_pk_mul_f32 v[72:73], v[18:19], v[98:99] op_sel_hi:[0,1]
	v_mov_b32_e32 v57, v141
	v_pk_mul_f32 v[58:59], v[154:155], v[58:59]
	v_pk_mul_f32 v[56:57], v[44:45], v[56:57] op_sel_hi:[0,1]
	v_pk_fma_f32 v[58:59], v[36:37], v[80:81], v[58:59] op_sel_hi:[0,1,1]
	s_waitcnt vmcnt(1)
	v_pk_mul_f32 v[72:73], v[72:73], v[160:161]
	v_pk_mul_f32 v[76:77], v[18:19], v[92:93] op_sel_hi:[0,1]
	v_pk_fma_f32 v[80:81], v[10:11], v[54:55], v[72:73] op_sel_hi:[0,1,1]
	v_pk_mul_f32 v[54:55], v[24:25], v[104:105] op_sel_hi:[0,1]
	v_pk_mul_f32 v[56:57], v[156:157], v[56:57]
	v_pk_mul_f32 v[76:77], v[76:77], v[158:159]
	v_pk_mul_f32 v[54:55], v[54:55], v[158:159]
	v_mov_b32_e32 v16, v19
	v_pk_fma_f32 v[56:57], v[36:37], v[82:83], v[56:57] op_sel_hi:[0,1,1]
	v_pk_fma_f32 v[82:83], v[10:11], v[52:53], v[76:77] op_sel_hi:[0,1,1]
	v_pk_mul_f32 v[52:53], v[24:25], v[106:107] op_sel_hi:[0,1]
	v_pk_fma_f32 v[76:77], v[12:13], v[60:61], v[54:55] op_sel_hi:[0,1,1]
	v_pk_mul_f32 v[54:55], v[32:33], v[116:117] op_sel_hi:[0,1]
	v_pk_mul_f32 v[20:21], v[18:19], v[20:21] op_sel_hi:[0,1]
	v_pk_mul_f32 v[16:17], v[18:19], v[16:17] op_sel_hi:[0,1]
	v_pk_mul_f32 v[52:53], v[52:53], v[160:161]
	v_pk_mul_f32 v[54:55], v[158:159], v[54:55]
	v_pk_fma_f32 v[72:73], v[12:13], v[62:63], v[52:53] op_sel_hi:[0,1,1]
	v_pk_fma_f32 v[62:63], v[14:15], v[64:65], v[54:55] op_sel_hi:[0,1,1]
	v_pk_mul_f32 v[52:53], v[32:33], v[118:119] op_sel_hi:[0,1]
	v_pk_mul_f32 v[52:53], v[160:161], v[52:53]
	s_waitcnt vmcnt(0)
; __device__ __forceinline__ float ssq4(v4f v) { return (v.x * v.x + v.y * v.y) + (v.z * v.z + v.w * v.w); }
; __device__ __forceinline__ float wave_sum(float v) {
; #pragma unroll
;     for (int o = 1; o < 64; o <<= 1) v += __shfl_xor(v, o);
;     return v;
; }
; template <int R, bool BASE_F32, bool OUT_F32>
; __device__ __forceinline__ void rows_res(const Ctx& C, int m0, int stride, int mx, const float* gpost, float scale, int lane) {
;     ...
;     } else { float* rs = C.RS(); float t[R];
; #pragma unroll
;         for (int r = 0; r < R; ++r) { float s = 0.f;
; #pragma unroll
;             for (int j = 0; j < 4; ++j) s += ssq4(d[r][j]);
;             t[r] = s; }
; #pragma unroll
;         for (int r = 0; r < R; ++r) t[r] = wave_sum(t[r]) * (1.f / DM) + EPS;
	v_pk_mul_f32 v[16:17], v[16:17], v[124:125]
	v_pk_mul_f32 v[18:19], v[20:21], v[126:127]
	v_pk_fma_f32 v[64:65], v[10:11], v[22:23], v[16:17] op_sel_hi:[0,1,1]
	v_pk_fma_f32 v[28:29], v[10:11], v[28:29], v[18:19] op_sel_hi:[0,1,1]
	v_mov_b32_e32 v10, v25
	v_pk_mul_f32 v[16:17], v[24:25], v[26:27] op_sel_hi:[0,1]
	v_pk_mul_f32 v[10:11], v[24:25], v[10:11] op_sel_hi:[0,1]
	v_pk_mul_f32 v[10:11], v[10:11], v[124:125]
	v_pk_mul_f32 v[16:17], v[16:17], v[126:127]
	v_pk_fma_f32 v[22:23], v[12:13], v[30:31], v[10:11] op_sel_hi:[0,1,1]
	v_pk_fma_f32 v[20:21], v[12:13], v[38:39], v[16:17] op_sel_hi:[0,1,1]
	v_mov_b32_e32 v12, v33
	v_pk_mul_f32 v[10:11], v[32:33], v[34:35] op_sel_hi:[0,1]
	v_pk_mul_f32 v[12:13], v[32:33], v[12:13] op_sel_hi:[0,1]
	v_pk_mul_f32 v[12:13], v[124:125], v[12:13]
	v_pk_mul_f32 v[10:11], v[126:127], v[10:11]
	v_pk_fma_f32 v[60:61], v[14:15], v[66:67], v[52:53] op_sel_hi:[0,1,1]
	v_pk_fma_f32 v[16:17], v[14:15], v[50:51], v[10:11] op_sel_hi:[0,1,1]
	v_pk_fma_f32 v[18:19], v[14:15], v[42:43], v[12:13] op_sel_hi:[0,1,1]
	v_mov_b32_e32 v14, v45
	v_pk_mul_f32 v[12:13], v[44:45], v[14:15] op_sel_hi:[0,1]
	v_mul_f32_e32 v14, v115, v115
	v_mul_f32_e32 v15, v113, v113
	v_fmac_f32_e32 v14, v114, v114
	v_fmac_f32_e32 v15, v112, v112
	v_add_f32_e32 v14, v14, v15
	v_mul_f32_e32 v15, v103, v103
	v_mul_f32_e32 v24, v101, v101
	v_fmac_f32_e32 v15, v102, v102
	v_fmac_f32_e32 v24, v100, v100
	v_add_f32_e32 v15, v15, v24
	v_add_f32_e32 v14, v14, v15
	v_mul_f32_e32 v15, v83, v83
	v_mul_f32_e32 v24, v81, v81
	v_fmac_f32_e32 v15, v82, v82
	v_fmac_f32_e32 v24, v80, v80
	v_add_f32_e32 v15, v15, v24
	v_add_f32_e32 v14, v14, v15
	v_mul_f32_e32 v15, v65, v65
	v_mul_f32_e32 v24, v29, v29
	v_fmac_f32_e32 v15, v64, v64
	v_fmac_f32_e32 v24, v28, v28
	v_add_f32_e32 v15, v15, v24
	v_add_f32_e32 v14, v14, v15
	v_mul_f32_e32 v15, v91, v91
	v_mul_f32_e32 v24, v89, v89
	v_fmac_f32_e32 v15, v90, v90
	v_fmac_f32_e32 v24, v88, v88
	v_add_f32_e32 v15, v15, v24
	v_mul_f32_e32 v24, v97, v97
	v_mul_f32_e32 v25, v95, v95
	v_fmac_f32_e32 v24, v96, v96
	v_fmac_f32_e32 v25, v94, v94
	v_add_f32_e32 v24, v24, v25
	v_add_f32_e32 v15, v15, v24
	v_mul_f32_e32 v24, v77, v77
	v_mul_f32_e32 v25, v73, v73
	v_fmac_f32_e32 v24, v76, v76
	v_fmac_f32_e32 v25, v72, v72
	v_add_f32_e32 v24, v24, v25
	v_add_f32_e32 v15, v15, v24
	v_mul_f32_e32 v24, v23, v23
	v_mul_f32_e32 v25, v21, v21
	v_fmac_f32_e32 v24, v22, v22
	v_fmac_f32_e32 v25, v20, v20
	v_add_f32_e32 v24, v24, v25
	v_add_f32_e32 v15, v15, v24
	v_mul_f32_e32 v24, v85, v85
	v_mul_f32_e32 v25, v87, v87
	v_fmac_f32_e32 v24, v84, v84
	v_fmac_f32_e32 v25, v86, v86
	v_add_f32_e32 v24, v24, v25
	v_mul_f32_e32 v25, v71, v71
	v_mul_f32_e32 v26, v69, v69
	v_fmac_f32_e32 v25, v70, v70
	v_fmac_f32_e32 v26, v68, v68
	v_add_f32_e32 v25, v25, v26
	v_add_f32_e32 v24, v24, v25
	v_mul_f32_e32 v25, v63, v63
	v_mul_f32_e32 v26, v61, v61
	v_fmac_f32_e32 v25, v62, v62
	v_fmac_f32_e32 v26, v60, v60
	v_add_f32_e32 v25, v25, v26
	v_add_f32_e32 v24, v25, v24
	v_mul_f32_e32 v25, v19, v19
	v_mul_f32_e32 v26, v17, v17
	v_fmac_f32_e32 v25, v18, v18
	v_fmac_f32_e32 v26, v16, v16
	v_add_f32_e32 v25, v25, v26
	s_nop 1
	v_mov_b32_dpp v26, v14 quad_perm:[1,0,3,2] row_mask:0xf bank_mask:0xf
	v_add_f32_e32 v24, v25, v24
	v_mul_f32_e32 v25, v47, v47
	v_mul_f32_e32 v27, v41, v41
	v_fmac_f32_e32 v25, v46, v46
	s_waitcnt lgkmcnt(0)
	v_add_f32_e32 v14, v14, v26
	s_nop 1
	v_mov_b32_dpp v26, v14 quad_perm:[2,3,0,1] row_mask:0xf bank_mask:0xf
	v_fmac_f32_e32 v27, v40, v40
	v_pk_mul_f32 v[52:53], v[44:45], v[136:137] op_sel_hi:[0,1]
	v_pk_mul_f32 v[54:55], v[44:45], v[134:135] op_sel_hi:[0,1]
	v_add_f32_e32 v25, v25, v27
	s_waitcnt lgkmcnt(0)
	v_add_f32_e32 v14, v14, v26
	s_nop 1
	v_mov_b32_dpp v26, v14 row_half_mirror row_mask:0xf bank_mask:0xf
	v_mul_f32_e32 v27, v59, v59
	v_mul_f32_e32 v30, v57, v57
	v_pk_mul_f32 v[54:55], v[158:159], v[54:55]
	v_pk_mul_f32 v[52:53], v[160:161], v[52:53]
	s_waitcnt lgkmcnt(0)
	v_add_f32_e32 v14, v14, v26
	s_nop 1
	v_mov_b32_dpp v26, v14 row_mirror row_mask:0xf bank_mask:0xf
	v_fmac_f32_e32 v27, v58, v58
	v_fmac_f32_e32 v30, v56, v56
	v_pk_fma_f32 v[52:53], v[36:37], v[78:79], v[52:53] op_sel_hi:[0,1,1]
	v_pk_fma_f32 v[54:55], v[36:37], v[74:75], v[54:55] op_sel_hi:[0,1,1]
	s_waitcnt lgkmcnt(0)
; __device__ __forceinline__ void st4_bf16(bf16* p, v4f o) { v2u w; w.x = cvt_pk_nv(o.x, o.y); w.y = cvt_pk_nv(o.z, o.w); *(v2u*)p = w; }
; template <int R, bool BASE_F32, bool OUT_F32>
; __device__ __forceinline__ void rows_res(const Ctx& C, int m0, int stride, int mx, const float* gpost, float scale, int lane) {
;     ...
;         for (int r = 0; r < R; ++r) t[r] = wave_sum(t[r]) * (1.f / DM) + EPS;
; #pragma unroll
;         for (int r = 0; r < R; ++r) { const float rstd = rsqrtf(t[r]);
; #pragma unroll
;             for (int j = 0; j < 4; ++j) if (ok[r]) st4_bf16(XN + (size_t)mr[r] * DM + 4 * lane + 256 * j, d[r][j] * rstd);
;             if (lane == 0 && ok[r]) rs[mr[r]] = sqrtf(t[r]); }
	v_add_f32_e32 v14, v14, v26
	ds_bpermute_b32 v26, v187, v14
	v_add_f32_e32 v27, v27, v30
	v_pk_mul_f32 v[10:11], v[44:45], v[48:49] op_sel_hi:[0,1]
	v_add_f32_e32 v25, v25, v27
	v_mul_f32_e32 v27, v55, v55
	v_mul_f32_e32 v30, v53, v53
	v_and_b32_e32 v133, 0xffff0000, v133
	v_pk_mul_f32 v[12:13], v[124:125], v[12:13]
	v_pk_mul_f32 v[10:11], v[126:127], v[10:11]
	v_fmac_f32_e32 v27, v54, v54
	v_fmac_f32_e32 v30, v52, v52
	s_waitcnt lgkmcnt(0)
	v_add_f32_e32 v14, v14, v26
	v_pk_fma_f32 v[10:11], v[36:37], v[132:133], v[10:11] op_sel_hi:[0,1,1]
	v_pk_fma_f32 v[12:13], v[36:37], v[146:147], v[12:13] op_sel_hi:[0,1,1]
	v_add_f32_e32 v27, v27, v30
	ds_bpermute_b32 v26, v188, v14
	v_add_f32_e32 v25, v27, v25
	v_mul_f32_e32 v27, v13, v13
	v_mul_f32_e32 v30, v11, v11
	v_fmac_f32_e32 v27, v12, v12
	v_fmac_f32_e32 v30, v10, v10
	v_add_f32_e32 v27, v27, v30
	v_add_f32_e32 v25, v27, v25
	s_nop 1
	v_mov_b32_dpp v30, v15 quad_perm:[1,0,3,2] row_mask:0xf bank_mask:0xf
	s_nop 1
	v_mov_b32_dpp v27, v24 quad_perm:[1,0,3,2] row_mask:0xf bank_mask:0xf
	s_waitcnt lgkmcnt(0)
	v_add_f32_e32 v31, v14, v26
	s_nop 1
	v_mov_b32_dpp v14, v25 quad_perm:[1,0,3,2] row_mask:0xf bank_mask:0xf
	s_waitcnt lgkmcnt(0)
	v_add_f32_e32 v15, v15, v30
	s_waitcnt lgkmcnt(0)
	v_add_f32_e32 v24, v24, v27
	s_nop 1
	v_mov_b32_dpp v26, v15 quad_perm:[2,3,0,1] row_mask:0xf bank_mask:0xf
	s_waitcnt lgkmcnt(0)
	v_add_f32_e32 v14, v25, v14
	s_nop 1
	v_mov_b32_dpp v27, v24 quad_perm:[2,3,0,1] row_mask:0xf bank_mask:0xf
	s_nop 1
	v_mov_b32_dpp v25, v14 quad_perm:[2,3,0,1] row_mask:0xf bank_mask:0xf
	s_load_dwordx2 s[10:11], s[0:1], 0x110
	s_waitcnt lgkmcnt(0)
	v_add_f32_e32 v15, v15, v26
	s_nop 1
	v_mov_b32_dpp v26, v15 row_half_mirror row_mask:0xf bank_mask:0xf
	v_add_f32_e32 v24, v24, v27
	v_add_f32_e32 v14, v14, v25
	s_nop 1
	v_mov_b32_dpp v27, v24 row_half_mirror row_mask:0xf bank_mask:0xf
	s_nop 1
	v_mov_b32_dpp v25, v14 row_half_mirror row_mask:0xf bank_mask:0xf
	s_waitcnt lgkmcnt(0)
	v_add_f32_e32 v15, v15, v26
	s_nop 1
	v_mov_b32_dpp v26, v15 row_mirror row_mask:0xf bank_mask:0xf
	s_and_b64 vcc, s[40:41], exec
	s_waitcnt lgkmcnt(0)
	v_add_f32_e32 v24, v24, v27
	s_waitcnt lgkmcnt(0)
	v_add_f32_e32 v14, v14, v25
	s_nop 1
	v_mov_b32_dpp v27, v24 row_mirror row_mask:0xf bank_mask:0xf
	s_nop 1
	v_mov_b32_dpp v25, v14 row_mirror row_mask:0xf bank_mask:0xf
	s_waitcnt lgkmcnt(0)
	v_add_f32_e32 v15, v15, v26
	ds_bpermute_b32 v26, v187, v15
	s_waitcnt lgkmcnt(0)
	v_add_f32_e32 v24, v24, v27
	s_waitcnt lgkmcnt(0)
	v_add_f32_e32 v14, v14, v25
	ds_bpermute_b32 v30, v187, v24
	ds_bpermute_b32 v32, v187, v14
	s_waitcnt lgkmcnt(0)
	v_add_f32_e32 v26, v15, v26
	ds_bpermute_b32 v27, v188, v26
	s_waitcnt lgkmcnt(0)
	v_add_f32_e32 v24, v24, v30
	s_waitcnt lgkmcnt(0)
	v_add_f32_e32 v14, v14, v32
	ds_bpermute_b32 v25, v188, v24
	ds_bpermute_b32 v15, v188, v14
	v_fmamk_f32 v30, v31, 0x3a800000, v37
	s_cbranch_vccnz .LBB0_371
	v_mul_f32_e32 v31, 0x4b800000, v30
	v_cmp_gt_f32_e32 vcc, s19, v30
	s_ashr_i32 s21, s20, 31
	s_lshl_b64 s[0:1], s[20:21], 11
	v_cndmask_b32_e32 v31, v30, v31, vcc
	v_rsq_f32_e32 v31, v31
	v_lshl_add_u64 v[34:35], v[8:9], 0, s[0:1]
	v_mul_f32_e32 v32, 0x45800000, v31
	v_cndmask_b32_e32 v32, v31, v32, vcc
	v_pk_mul_f32 v[42:43], v[114:115], v[32:33] op_sel_hi:[1,0]
	v_pk_mul_f32 v[38:39], v[112:113], v[32:33] op_sel_hi:[1,0]
	v_cvt_pk_bf16_f32 v42, v42, v43
	v_pk_mul_f32 v[28:29], v[28:29], v[32:33] op_sel_hi:[1,0]
	v_cvt_pk_bf16_f32 v43, v38, v39
	global_store_dwordx2 v[34:35], v[42:43], off
	v_pk_mul_f32 v[42:43], v[102:103], v[32:33] op_sel_hi:[1,0]
	v_pk_mul_f32 v[38:39], v[100:101], v[32:33] op_sel_hi:[1,0]
	v_cvt_pk_bf16_f32 v42, v42, v43
	s_nop 0
	v_cvt_pk_bf16_f32 v43, v38, v39
	global_store_dwordx2 v[34:35], v[42:43], off offset:512
	v_pk_mul_f32 v[38:39], v[80:81], v[32:33] op_sel_hi:[1,0]
	v_pk_mul_f32 v[42:43], v[82:83], v[32:33] op_sel_hi:[1,0]
	v_pk_mul_f32 v[32:33], v[64:65], v[32:33] op_sel_hi:[1,0]
	v_cvt_pk_bf16_f32 v42, v42, v43
	v_cvt_pk_bf16_f32 v43, v38, v39
	global_store_dwordx2 v[34:35], v[42:43], off offset:1024
	v_cvt_pk_bf16_f32 v32, v32, v33
	v_cvt_pk_bf16_f32 v33, v28, v29
	global_store_dwordx2 v[34:35], v[32:33], off offset:1536

; __device__ __forceinline__ void st4_bf16(bf16* p, v4f o) { v2u w; w.x = cvt_pk_nv(o.x, o.y); w.y = cvt_pk_nv(o.z, o.w); *(v2u*)p = w; }
; template <int R, bool BASE_F32, bool OUT_F32>
; __device__ __forceinline__ void rows_res(const Ctx& C, int m0, int stride, int mx, const float* gpost, float scale, int lane) {
;     ...
;         for (int r = 0; r < R; ++r) t[r] = wave_sum(t[r]) * (1.f / DM) + EPS;
; #pragma unroll
;         for (int r = 0; r < R; ++r) { const float rstd = rsqrtf(t[r]);
; #pragma unroll
;             for (int j = 0; j < 4; ++j) if (ok[r]) st4_bf16(XN + (size_t)mr[r] * DM + 4 * lane + 256 * j, d[r][j] * rstd);
.LBB0_373:
	s_or_b64 exec, exec, s[40:41]
	s_waitcnt lgkmcnt(0)
	v_add_f32_e32 v26, v26, v27
	s_andn2_b64 vcc, exec, s[52:53]
	v_fmamk_f32 v26, v26, 0x3a800000, v37
	s_cbranch_vccnz .LBB0_375
	v_mul_f32_e32 v27, 0x4b800000, v26
	v_cmp_gt_f32_e32 vcc, s19, v26
	s_ashr_i32 s35, s34, 31
	s_lshl_b64 s[0:1], s[34:35], 11
	v_cndmask_b32_e32 v27, v26, v27, vcc
	v_rsq_f32_e32 v27, v27
	v_lshl_add_u64 v[30:31], v[8:9], 0, s[0:1]
	v_mul_f32_e32 v28, 0x45800000, v27
	v_cndmask_b32_e32 v28, v27, v28, vcc
	v_pk_mul_f32 v[34:35], v[90:91], v[28:29] op_sel_hi:[1,0]
	v_pk_mul_f32 v[32:33], v[88:89], v[28:29] op_sel_hi:[1,0]
	v_cvt_pk_bf16_f32 v34, v34, v35
	v_pk_mul_f32 v[22:23], v[22:23], v[28:29] op_sel_hi:[1,0]
	v_cvt_pk_bf16_f32 v35, v32, v33
	global_store_dwordx2 v[30:31], v[34:35], off
	v_pk_mul_f32 v[34:35], v[96:97], v[28:29] op_sel_hi:[1,0]
	v_pk_mul_f32 v[32:33], v[94:95], v[28:29] op_sel_hi:[1,0]
	v_cvt_pk_bf16_f32 v34, v34, v35
	v_pk_mul_f32 v[20:21], v[20:21], v[28:29] op_sel_hi:[1,0]
	v_cvt_pk_bf16_f32 v35, v32, v33
	global_store_dwordx2 v[30:31], v[34:35], off offset:512
	v_pk_mul_f32 v[34:35], v[76:77], v[28:29] op_sel_hi:[1,0]
	v_pk_mul_f32 v[32:33], v[72:73], v[28:29] op_sel_hi:[1,0]
	v_cvt_pk_bf16_f32 v34, v34, v35
	v_cvt_pk_bf16_f32 v22, v22, v23
	v_cvt_pk_bf16_f32 v23, v20, v21
	global_store_dwordx2 v[30:31], v[22:23], off offset:1536
	v_cvt_pk_bf16_f32 v35, v32, v33
	global_store_dwordx2 v[30:31], v[34:35], off offset:1024

; __device__ __forceinline__ void st4_bf16(bf16* p, v4f o) { v2u w; w.x = cvt_pk_nv(o.x, o.y); w.y = cvt_pk_nv(o.z, o.w); *(v2u*)p = w; }
; template <int R, bool BASE_F32, bool OUT_F32>
; __device__ __forceinline__ void rows_res(const Ctx& C, int m0, int stride, int mx, const float* gpost, float scale, int lane) {
;     ...
;         for (int r = 0; r < R; ++r) t[r] = wave_sum(t[r]) * (1.f / DM) + EPS;
; #pragma unroll
;         for (int r = 0; r < R; ++r) { const float rstd = rsqrtf(t[r]);
; #pragma unroll
;             for (int j = 0; j < 4; ++j) if (ok[r]) st4_bf16(XN + (size_t)mr[r] * DM + 4 * lane + 256 * j, d[r][j] * rstd);
.LBB0_377:
	s_or_b64 exec, exec, s[36:37]
	s_waitcnt lgkmcnt(0)
	v_add_f32_e32 v20, v24, v25
	s_andn2_b64 vcc, exec, s[38:39]
	v_fmamk_f32 v20, v20, 0x3a800000, v37
	s_cbranch_vccnz .LBB0_379
	v_mul_f32_e32 v21, 0x4b800000, v20
	v_cmp_gt_f32_e32 vcc, s19, v20
	s_ashr_i32 s27, s26, 31
	s_lshl_b64 s[0:1], s[26:27], 11
	v_cndmask_b32_e32 v21, v20, v21, vcc
	v_rsq_f32_e32 v21, v21
	v_lshl_add_u64 v[24:25], v[8:9], 0, s[0:1]
	v_mul_f32_e32 v22, 0x45800000, v21
	v_cndmask_b32_e32 v22, v21, v22, vcc
	v_pk_mul_f32 v[28:29], v[84:85], v[22:23] op_sel_hi:[1,0]
	v_pk_mul_f32 v[26:27], v[86:87], v[22:23] op_sel_hi:[1,0]
	v_cvt_pk_bf16_f32 v28, v28, v29
	v_pk_mul_f32 v[18:19], v[18:19], v[22:23] op_sel_hi:[1,0]
	v_cvt_pk_bf16_f32 v29, v26, v27
	global_store_dwordx2 v[24:25], v[28:29], off
	v_pk_mul_f32 v[28:29], v[70:71], v[22:23] op_sel_hi:[1,0]
	v_pk_mul_f32 v[26:27], v[68:69], v[22:23] op_sel_hi:[1,0]
	v_cvt_pk_bf16_f32 v28, v28, v29
	v_pk_mul_f32 v[16:17], v[16:17], v[22:23] op_sel_hi:[1,0]
	v_cvt_pk_bf16_f32 v29, v26, v27
	global_store_dwordx2 v[24:25], v[28:29], off offset:512
	v_pk_mul_f32 v[28:29], v[62:63], v[22:23] op_sel_hi:[1,0]
	v_pk_mul_f32 v[26:27], v[60:61], v[22:23] op_sel_hi:[1,0]
	v_cvt_pk_bf16_f32 v28, v28, v29
	v_cvt_pk_bf16_f32 v18, v18, v19
	v_cvt_pk_bf16_f32 v19, v16, v17
	global_store_dwordx2 v[24:25], v[18:19], off offset:1536
	v_cvt_pk_bf16_f32 v29, v26, v27
	global_store_dwordx2 v[24:25], v[28:29], off offset:1024

; __device__ __forceinline__ const float* xrow_ptr(const Ctx& C, int row) { return row < MPROMPT ? C.in(0) + (size_t)row * DM : C.in(1) + (size_t)(row - MPROMPT) * DM; }
; __device__ __forceinline__ v4f ld4_bf16(const bf16* p) { const v2u w = *(const v2u*)p; return (v4f){bf_lo(w.x), bf_hi(w.x), bf_lo(w.y), bf_hi(w.y)}; }
; template <int R, bool BASE_F32, bool OUT_F32>
; __device__ __forceinline__ void rows_res(const Ctx& C, int m0, int stride, int mx, const float* gpost, float scale, int lane) {
;     ...
;     for (int r = 0; r < R; ++r) { mr[r] = (r == 4) ? mx : m0 + r * stride; ok[r] = (r == 4) ? (mx < M) : (mr[r] < MPROMPT); const int mm = ok[r] ? mr[r] : 0;
; #pragma unroll
;         for (int j = 0; j < 4; ++j) d[r][j] = ld4_bf16(D + (size_t)mm * DM + 4 * lane + 256 * j);
;         if (BASE_F32) { const float* x = xrow_ptr(C, mm);
; #pragma unroll
;             for (int j = 0; j < 4; ++j) b[r][j] = ld4_f32(x + 4 * lane + 256 * j);
;         } else { const float inv = C.RS()[mm];
; #pragma unroll
;             for (int j = 0; j < 4; ++j) b[r][j] = ld4_bf16(XN + (size_t)mm * DM + 4 * lane + 256 * j) * inv;
;         } }
.LBB0_385:
	v_readlane_b32 s0, v232, 5
	s_mul_i32 s0, s0, s46
	s_lshl_b32 s86, s0, 2
	s_mov_b64 s[0:1], s[80:81]
	s_load_dwordx2 s[0:1], s[0:1], 0x110
	s_mov_b64 s[8:9], s[80:81]
	s_add_i32 s12, s42, s86
	s_add_i32 s16, s42, 0x8000
	s_load_dwordx2 s[8:9], s[8:9], 0x110
	s_cmpk_lt_i32 s42, 0x80
	s_cselect_b64 s[18:19], -1, 0
	s_cmpk_gt_i32 s12, 0x7fff
	s_waitcnt lgkmcnt(0)
	v_lshl_add_u64 v[4:5], s[0:1], 0, v[0:1]
	s_mov_b64 s[0:1], 0x7100000
	s_cselect_b64 s[52:53], -1, 0
	s_ashr_i32 s13, s12, 31
	v_lshl_add_u64 v[18:19], v[4:5], 0, s[0:1]
	s_and_b64 s[0:1], s[52:53], exec
	s_cselect_b32 s1, 0, s13
	s_cselect_b32 s0, 0, s12
	v_lshl_add_u64 v[4:5], s[8:9], 0, v[0:1]
	s_lshl_b64 s[8:9], s[0:1], 11
	v_lshl_add_u64 v[6:7], v[18:19], 0, s[8:9]
	s_mov_b64 s[10:11], s[80:81]
	global_load_dwordx2 v[116:117], v[6:7], off
	global_load_dwordx2 v[106:107], v[6:7], off offset:512
	global_load_dwordx2 v[108:109], v[6:7], off offset:1024
	global_load_dwordx2 v[16:17], v[6:7], off offset:1536
	s_load_dwordx2 s[10:11], s[10:11], 0x110
	s_lshl_b64 s[0:1], s[0:1], 2
	v_mov_b32_e32 v3, 0x2a80000
	s_mov_b64 s[20:21], 0x3000000
	v_lshl_add_u64 v[4:5], v[4:5], 0, s[20:21]
	s_waitcnt lgkmcnt(0)
	s_add_u32 s0, s10, s0
	s_addc_u32 s1, s11, s1
	s_add_i32 s34, s12, s46
	s_cmpk_gt_i32 s34, 0x7fff
	s_cselect_b64 s[38:39], -1, 0
	s_cmp_lt_i32 s34, 0x8000
	s_cselect_b64 s[40:41], -1, 0
	s_ashr_i32 s35, s34, 31
	global_load_dword v6, v3, s[0:1]
	s_and_b64 s[0:1], s[38:39], exec
	s_cselect_b32 s1, 0, s35
	s_cselect_b32 s0, 0, s34
	v_lshl_add_u64 v[8:9], v[4:5], 0, s[8:9]
	s_lshl_b64 s[8:9], s[0:1], 11
	global_load_dwordx2 v[22:23], v[8:9], off
	global_load_dwordx2 v[24:25], v[8:9], off offset:512
	global_load_dwordx2 v[26:27], v[8:9], off offset:1024
	global_load_dwordx2 v[28:29], v[8:9], off offset:1536
	v_lshl_add_u64 v[8:9], v[18:19], 0, s[8:9]
	s_mov_b64 s[10:11], s[80:81]
	global_load_dwordx2 v[130:131], v[8:9], off
	global_load_dwordx2 v[124:125], v[8:9], off offset:512
	global_load_dwordx2 v[126:127], v[8:9], off offset:1024
	global_load_dwordx2 v[30:31], v[8:9], off offset:1536
	s_load_dwordx2 s[10:11], s[10:11], 0x110
	s_lshl_b64 s[0:1], s[0:1], 2
	v_lshl_add_u64 v[10:11], v[4:5], 0, s[8:9]
	s_waitcnt lgkmcnt(0)
	s_add_u32 s0, s10, s0
	s_addc_u32 s1, s11, s1
	s_add_i32 s26, s34, s46
	s_cmpk_gt_i32 s26, 0x7fff
	s_cselect_b64 s[30:31], -1, 0
	s_cmp_lt_i32 s26, 0x8000
	s_cselect_b64 s[36:37], -1, 0
	s_ashr_i32 s27, s26, 31
	global_load_dword v8, v3, s[0:1]
	s_and_b64 s[0:1], s[30:31], exec
	s_cselect_b32 s1, 0, s27
	s_cselect_b32 s0, 0, s26
	s_lshl_b64 s[8:9], s[0:1], 11
	global_load_dwordx2 v[34:35], v[10:11], off
	global_load_dwordx2 v[36:37], v[10:11], off offset:512
	global_load_dwordx2 v[38:39], v[10:11], off offset:1024
	global_load_dwordx2 v[40:41], v[10:11], off offset:1536
	v_lshl_add_u64 v[10:11], v[18:19], 0, s[8:9]
	s_mov_b64 s[10:11], s[80:81]
	global_load_dwordx2 v[142:143], v[10:11], off
	global_load_dwordx2 v[134:135], v[10:11], off offset:512
	global_load_dwordx2 v[138:139], v[10:11], off offset:1024
	global_load_dwordx2 v[42:43], v[10:11], off offset:1536
	s_load_dwordx2 s[10:11], s[10:11], 0x110
	s_lshl_b64 s[0:1], s[0:1], 2
	v_lshl_add_u64 v[12:13], v[4:5], 0, s[8:9]
	s_waitcnt lgkmcnt(0)
	s_add_u32 s0, s10, s0
	s_addc_u32 s1, s11, s1
	s_add_i32 s22, s26, s46
	s_cmpk_gt_i32 s22, 0x7fff
	s_cselect_b64 s[24:25], -1, 0
	s_cmp_lt_i32 s22, 0x8000
	s_cselect_b64 s[28:29], -1, 0
	s_ashr_i32 s23, s22, 31
	global_load_dword v10, v3, s[0:1]
	s_and_b64 s[0:1], s[24:25], exec
	s_cselect_b32 s1, 0, s23
	s_cselect_b32 s0, 0, s22
	s_lshl_b64 s[8:9], s[0:1], 11
	global_load_dwordx2 v[44:45], v[12:13], off
	global_load_dwordx2 v[46:47], v[12:13], off offset:512
	global_load_dwordx2 v[50:51], v[12:13], off offset:1024
	global_load_dwordx2 v[52:53], v[12:13], off offset:1536
	v_lshl_add_u64 v[12:13], v[18:19], 0, s[8:9]
	s_mov_b64 s[10:11], s[80:81]
	global_load_dwordx2 v[154:155], v[12:13], off
	global_load_dwordx2 v[146:147], v[12:13], off offset:512
	global_load_dwordx2 v[150:151], v[12:13], off offset:1024
	global_load_dwordx2 v[54:55], v[12:13], off offset:1536
	s_load_dwordx2 s[10:11], s[10:11], 0x110
	s_lshl_b64 s[0:1], s[0:1], 2
	v_lshl_add_u64 v[32:33], v[4:5], 0, s[8:9]
	global_load_dwordx2 v[56:57], v[32:33], off
	global_load_dwordx2 v[60:61], v[32:33], off offset:512
	s_waitcnt lgkmcnt(0)
	s_add_u32 s10, s10, s0
	s_addc_u32 s11, s11, s1
	s_ashr_i32 s17, s16, 31
	s_cmpk_gt_i32 s42, 0x7f
	s_cselect_b64 s[20:21], -1, 0
	s_and_b64 s[0:1], s[20:21], exec
	s_cselect_b32 s9, 0, s17
	s_cselect_b32 s8, 0, s16
	s_lshl_b64 s[0:1], s[8:9], 11
	v_lshl_add_u64 v[18:19], v[18:19], 0, s[0:1]
	global_load_dwordx2 v[62:63], v[32:33], off offset:1024
	global_load_dwordx2 v[66:67], v[32:33], off offset:1536
	global_load_dwordx2 v[166:167], v[18:19], off
	global_load_dwordx2 v[158:159], v[18:19], off offset:512
	global_load_dwordx2 v[162:163], v[18:19], off offset:1024
	global_load_dwordx2 v[68:69], v[18:19], off offset:1536
	v_lshl_add_u64 v[70:71], v[4:5], 0, s[0:1]
	global_load_dword v18, v3, s[10:11]
	s_mov_b64 s[10:11], s[80:81]
	global_load_dwordx2 v[92:93], v[70:71], off
	global_load_dwordx2 v[96:97], v[70:71], off offset:512
	global_load_dwordx2 v[118:119], v[70:71], off offset:1024
	global_load_dwordx2 v[132:133], v[70:71], off offset:1536
	s_load_dwordx2 s[0:1], s[10:11], 0x110
	s_waitcnt vmcnt(43)
	v_and_b32_e32 v141, 0xffff0000, v117
	s_waitcnt vmcnt(40)
	v_and_b32_e32 v13, 0xffff0000, v16
	v_and_b32_e32 v137, 0xffff0000, v116
	v_lshlrev_b32_e32 v140, 16, v117
	v_mul_f32_e32 v12, v141, v141
	s_lshl_b64 s[8:9], s[8:9], 2
	v_lshlrev_b32_e32 v136, 16, v116
	v_lshlrev_b32_e32 v15, 16, v16
	s_waitcnt lgkmcnt(0)
; __device__ __forceinline__ const float* xrow_ptr(const Ctx& C, int row) { return row < MPROMPT ? C.in(0) + (size_t)row * DM : C.in(1) + (size_t)(row - MPROMPT) * DM; }
; __device__ __forceinline__ v4f ld4_bf16(const bf16* p) { const v2u w = *(const v2u*)p; return (v4f){bf_lo(w.x), bf_hi(w.x), bf_lo(w.y), bf_hi(w.y)}; }
; __device__ __forceinline__ float ssq4(v4f v) { return (v.x * v.x + v.y * v.y) + (v.z * v.z + v.w * v.w); }
; template <int R, bool BASE_F32, bool OUT_F32>
; __device__ __forceinline__ void rows_res(const Ctx& C, int m0, int stride, int mx, const float* gpost, float scale, int lane) {
;     ...
;     for (int r = 0; r < R; ++r) { mr[r] = (r == 4) ? mx : m0 + r * stride; ok[r] = (r == 4) ? (mx < M) : (mr[r] < MPROMPT); const int mm = ok[r] ? mr[r] : 0;
; #pragma unroll
;         for (int j = 0; j < 4; ++j) d[r][j] = ld4_bf16(D + (size_t)mm * DM + 4 * lane + 256 * j);
;         if (BASE_F32) { const float* x = xrow_ptr(C, mm);
; #pragma unroll
;             for (int j = 0; j < 4; ++j) b[r][j] = ld4_f32(x + 4 * lane + 256 * j);
;         } else { const float inv = C.RS()[mm];
; #pragma unroll
;             for (int j = 0; j < 4; ++j) b[r][j] = ld4_bf16(XN + (size_t)mm * DM + 4 * lane + 256 * j) * inv;
;         } }
; #pragma unroll
;     for (int r = 0; r < R; ++r) { float s = 0.f;
; #pragma unroll
;         for (int j = 0; j < 4; ++j) s += ssq4(d[r][j]);
;         r1[r] = s; }
	s_add_u32 s0, s0, s8
	v_lshlrev_b32_e32 v117, 16, v107
	v_lshlrev_b32_e32 v116, 16, v106
	s_addc_u32 s1, s1, s9
	v_mov_b32_e32 v153, v15
	v_lshlrev_b32_e32 v16, 16, v17
	v_and_b32_e32 v17, 0xffff0000, v17
	s_waitcnt vmcnt(37)
	v_lshlrev_b32_e32 v48, 16, v24
	v_and_b32_e32 v49, 0xffff0000, v24
	v_lshlrev_b32_e32 v58, 16, v25
	v_and_b32_e32 v59, 0xffff0000, v25
	s_waitcnt vmcnt(35)
	v_lshlrev_b32_e32 v24, 16, v28
	v_and_b32_e32 v25, 0xffff0000, v28
	v_mul_f32_e32 v28, v16, v16
	v_lshlrev_b32_e32 v32, 16, v26
	v_and_b32_e32 v33, 0xffff0000, v26
	s_waitcnt vmcnt(28)
	v_lshlrev_b32_e32 v86, 16, v36
	v_and_b32_e32 v87, 0xffff0000, v36
	v_mul_f32_e32 v36, v17, v17
	v_lshlrev_b32_e32 v64, 16, v27
	v_and_b32_e32 v65, 0xffff0000, v27
	v_lshlrev_b32_e32 v26, 16, v29
	v_and_b32_e32 v27, 0xffff0000, v29
	v_lshlrev_b32_e32 v29, 16, v30
	v_and_b32_e32 v7, 0xffff0000, v30
	v_mov_b32_e32 v165, v29
	v_lshlrev_b32_e32 v30, 16, v31
	v_and_b32_e32 v31, 0xffff0000, v31
	v_lshlrev_b32_e32 v88, 16, v37
	v_and_b32_e32 v89, 0xffff0000, v37
	s_waitcnt vmcnt(22)
	v_lshlrev_b32_e32 v37, 16, v42
	v_and_b32_e32 v9, 0xffff0000, v42
	v_mov_b32_e32 v175, v37
	v_lshlrev_b32_e32 v70, 16, v38
	v_and_b32_e32 v71, 0xffff0000, v38
	v_lshlrev_b32_e32 v74, 16, v39
	v_and_b32_e32 v75, 0xffff0000, v39
	v_lshlrev_b32_e32 v38, 16, v43
	s_waitcnt vmcnt(20)
	v_lshlrev_b32_e32 v112, 16, v45
	v_and_b32_e32 v113, 0xffff0000, v45
	s_waitcnt vmcnt(19)
	v_lshlrev_b32_e32 v90, 16, v46
	v_and_b32_e32 v91, 0xffff0000, v46
	v_lshlrev_b32_e32 v94, 16, v47
	v_and_b32_e32 v95, 0xffff0000, v47
	s_waitcnt vmcnt(13)
	v_lshlrev_b32_e32 v45, 16, v54
	v_and_b32_e32 v11, 0xffff0000, v54
	v_lshlrev_b32_e32 v46, 16, v55
	v_and_b32_e32 v47, 0xffff0000, v55
	v_lshlrev_b32_e32 v78, 16, v50
	s_waitcnt vmcnt(12)
	v_lshlrev_b32_e32 v122, 16, v57
	v_and_b32_e32 v123, 0xffff0000, v57
	s_waitcnt vmcnt(11)
	v_lshlrev_b32_e32 v98, 16, v60
	v_and_b32_e32 v99, 0xffff0000, v60
	v_lshlrev_b32_e32 v100, 16, v61
	v_and_b32_e32 v101, 0xffff0000, v61
	v_and_b32_e32 v79, 0xffff0000, v50
	global_load_dword v50, v3, s[0:1]
	v_mul_f32_e32 v3, v13, v13
	v_lshlrev_b32_e32 v114, 16, v44
	v_and_b32_e32 v115, 0xffff0000, v44
	s_waitcnt vmcnt(11)
	v_lshlrev_b32_e32 v82, 16, v62
	v_and_b32_e32 v83, 0xffff0000, v62
	v_lshlrev_b32_e32 v84, 16, v63
	v_and_b32_e32 v85, 0xffff0000, v63
	s_waitcnt vmcnt(10)
	v_lshlrev_b32_e32 v54, 16, v66
	v_and_b32_e32 v55, 0xffff0000, v66
	v_lshlrev_b32_e32 v62, 16, v67
	v_and_b32_e32 v63, 0xffff0000, v67
	s_waitcnt vmcnt(6)
	v_lshlrev_b32_e32 v57, 16, v68
	v_and_b32_e32 v19, 0xffff0000, v68
	v_lshlrev_b32_e32 v60, 16, v69
	v_and_b32_e32 v61, 0xffff0000, v69
	s_waitcnt vmcnt(4)
	v_lshlrev_b32_e32 v110, 16, v92
	v_and_b32_e32 v111, 0xffff0000, v92
	v_lshlrev_b32_e32 v128, 16, v93
	v_and_b32_e32 v129, 0xffff0000, v93
	s_waitcnt vmcnt(3)
	v_lshlrev_b32_e32 v102, 16, v96
	v_and_b32_e32 v103, 0xffff0000, v96
	v_lshlrev_b32_e32 v104, 16, v97
	v_and_b32_e32 v105, 0xffff0000, v97
	s_waitcnt vmcnt(2)
	v_lshlrev_b32_e32 v92, 16, v118
	v_and_b32_e32 v93, 0xffff0000, v118
	v_lshlrev_b32_e32 v96, 16, v119
	v_and_b32_e32 v97, 0xffff0000, v119
	s_waitcnt vmcnt(1)
	v_lshlrev_b32_e32 v66, 16, v132
	v_and_b32_e32 v67, 0xffff0000, v132
	v_lshlrev_b32_e32 v68, 16, v133
	v_and_b32_e32 v69, 0xffff0000, v133
	v_pk_fma_f32 v[132:133], v[140:141], v[140:141], v[12:13] op_sel_hi:[1,1,0]
	v_and_b32_e32 v119, 0xffff0000, v107
	v_and_b32_e32 v118, 0xffff0000, v106
	v_mul_f32_e32 v12, v137, v137
	v_pk_mul_f32 v[106:107], v[118:119], v[118:119]
	v_pk_fma_f32 v[148:149], v[136:137], v[136:137], v[12:13] op_sel_hi:[1,1,0]
	v_pk_fma_f32 v[144:145], v[116:117], v[116:117], v[106:107]
	v_mov_b32_e32 v14, v148
	v_mov_b32_e32 v152, v132
	v_and_b32_e32 v107, 0xffff0000, v108
	v_pk_add_f32 v[132:133], v[148:149], v[132:133]
	v_pk_mul_f32 v[148:149], v[14:15], v[152:153]
	v_pk_add_f32 v[144:145], v[144:145], v[144:145] op_sel:[0,1] op_sel_hi:[1,0]
	v_lshlrev_b32_e32 v106, 16, v108
	v_lshlrev_b32_e32 v108, 16, v109
	v_and_b32_e32 v109, 0xffff0000, v109
	v_mov_b32_e32 v133, v149
	v_mov_b32_e32 v145, v3
	v_mul_f32_e32 v12, v107, v107
	v_pk_add_f32 v[132:133], v[132:133], v[144:145]
	v_pk_fma_f32 v[144:145], v[106:107], v[106:107], v[12:13] op_sel_hi:[1,1,0]
	v_mul_f32_e32 v12, v109, v109
	v_pk_fma_f32 v[148:149], v[108:109], v[108:109], v[12:13] op_sel_hi:[1,1,0]
	v_mov_b32_e32 v145, v28
	v_mov_b32_e32 v149, v36
	v_pk_add_f32 v[144:145], v[144:145], v[148:149]
	v_and_b32_e32 v153, 0xffff0000, v131
	v_pk_add_f32 v[132:133], v[132:133], v[144:145]
	v_and_b32_e32 v149, 0xffff0000, v130
	v_lshlrev_b32_e32 v152, 16, v131
	v_mul_f32_e32 v12, v153, v153
	v_add_f32_e32 v3, v132, v133
	v_lshlrev_b32_e32 v148, 16, v130
	v_pk_fma_f32 v[144:145], v[152:153], v[152:153], v[12:13] op_sel_hi:[1,1,0]
	v_and_b32_e32 v133, 0xffff0000, v125
	v_and_b32_e32 v132, 0xffff0000, v124
	v_mul_f32_e32 v12, v149, v149
	v_lshlrev_b32_e32 v131, 16, v125
	v_lshlrev_b32_e32 v130, 16, v124
	v_pk_mul_f32 v[124:125], v[132:133], v[132:133]
	v_pk_fma_f32 v[160:161], v[148:149], v[148:149], v[12:13] op_sel_hi:[1,1,0]
	v_pk_fma_f32 v[156:157], v[130:131], v[130:131], v[124:125]
	v_mov_b32_e32 v28, v160
	v_mov_b32_e32 v164, v144
	v_and_b32_e32 v125, 0xffff0000, v126
	v_mul_f32_e32 v14, v7, v7
	v_pk_add_f32 v[144:145], v[160:161], v[144:145]
	v_pk_mul_f32 v[160:161], v[28:29], v[164:165]
	v_pk_add_f32 v[156:157], v[156:157], v[156:157] op_sel:[0,1] op_sel_hi:[1,0]
	v_lshlrev_b32_e32 v124, 16, v126
	v_lshlrev_b32_e32 v126, 16, v127
	v_and_b32_e32 v127, 0xffff0000, v127
	v_mov_b32_e32 v145, v161
	v_mov_b32_e32 v157, v14
	v_mul_f32_e32 v12, v125, v125
	v_pk_add_f32 v[144:145], v[144:145], v[156:157]
; __device__ __forceinline__ float ssq4(v4f v) { return (v.x * v.x + v.y * v.y) + (v.z * v.z + v.w * v.w); }
; __device__ __forceinline__ float wave_sum(float v) {
; #pragma unroll
;     for (int o = 1; o < 64; o <<= 1) v += __shfl_xor(v, o);
;     return v;
; }
; template <int R, bool BASE_F32, bool OUT_F32>
; __device__ __forceinline__ void rows_res(const Ctx& C, int m0, int stride, int mx, const float* gpost, float scale, int lane) {
;     ...
;     for (int r = 0; r < R; ++r) { float s = 0.f;
; #pragma unroll
;         for (int j = 0; j < 4; ++j) s += ssq4(d[r][j]);
;         r1[r] = s; }
; #pragma unroll
;     for (int r = 0; r < R; ++r) r1[r] = rsqrtf(wave_sum(r1[r]) * (1.f / DM) + EPS) * scale;
	v_pk_fma_f32 v[156:157], v[124:125], v[124:125], v[12:13] op_sel_hi:[1,1,0]
	v_mul_f32_e32 v12, v127, v127
	v_mul_f32_e32 v36, v30, v30
	v_mul_f32_e32 v44, v31, v31
	v_pk_fma_f32 v[160:161], v[126:127], v[126:127], v[12:13] op_sel_hi:[1,1,0]
	v_mov_b32_e32 v157, v36
	v_mov_b32_e32 v161, v44
	v_and_b32_e32 v165, 0xffff0000, v143
	v_pk_add_f32 v[156:157], v[156:157], v[160:161]
	v_and_b32_e32 v161, 0xffff0000, v142
	v_lshlrev_b32_e32 v164, 16, v143
	v_mul_f32_e32 v12, v165, v165
	v_pk_add_f32 v[170:171], v[144:145], v[156:157]
	v_lshlrev_b32_e32 v160, 16, v142
	v_pk_fma_f32 v[156:157], v[164:165], v[164:165], v[12:13] op_sel_hi:[1,1,0]
	v_and_b32_e32 v145, 0xffff0000, v135
	v_and_b32_e32 v144, 0xffff0000, v134
	v_mul_f32_e32 v12, v161, v161
	v_lshlrev_b32_e32 v143, 16, v135
	v_lshlrev_b32_e32 v142, 16, v134
	v_pk_mul_f32 v[134:135], v[144:145], v[144:145]
	v_pk_fma_f32 v[172:173], v[160:161], v[160:161], v[12:13] op_sel_hi:[1,1,0]
	v_pk_fma_f32 v[168:169], v[142:143], v[142:143], v[134:135]
	v_mov_b32_e32 v36, v172
	v_mov_b32_e32 v174, v156
	v_and_b32_e32 v135, 0xffff0000, v138
	v_mul_f32_e32 v14, v9, v9
	v_pk_add_f32 v[156:157], v[172:173], v[156:157]
	v_pk_mul_f32 v[172:173], v[36:37], v[174:175]
	v_pk_add_f32 v[168:169], v[168:169], v[168:169] op_sel:[0,1] op_sel_hi:[1,0]
	v_lshlrev_b32_e32 v134, 16, v138
	v_lshlrev_b32_e32 v138, 16, v139
	v_and_b32_e32 v139, 0xffff0000, v139
	v_mov_b32_e32 v157, v173
	v_mov_b32_e32 v169, v14
	v_mul_f32_e32 v12, v135, v135
	v_and_b32_e32 v39, 0xffff0000, v43
	v_pk_add_f32 v[156:157], v[156:157], v[168:169]
	v_pk_fma_f32 v[168:169], v[134:135], v[134:135], v[12:13] op_sel_hi:[1,1,0]
	v_mul_f32_e32 v12, v139, v139
	v_mul_f32_e32 v28, v38, v38
	v_mul_f32_e32 v44, v39, v39
	v_pk_fma_f32 v[172:173], v[138:139], v[138:139], v[12:13] op_sel_hi:[1,1,0]
	v_mov_b32_e32 v169, v28
	v_mov_b32_e32 v173, v44
	v_and_b32_e32 v177, 0xffff0000, v155
	v_pk_add_f32 v[168:169], v[168:169], v[172:173]
	v_and_b32_e32 v175, 0xffff0000, v154
	v_lshlrev_b32_e32 v176, 16, v155
	v_mul_f32_e32 v12, v177, v177
	v_pk_add_f32 v[172:173], v[156:157], v[168:169]
	v_lshlrev_b32_e32 v174, 16, v154
	v_pk_fma_f32 v[168:169], v[176:177], v[176:177], v[12:13] op_sel_hi:[1,1,0]
	v_and_b32_e32 v157, 0xffff0000, v147
	v_and_b32_e32 v156, 0xffff0000, v146
	v_mul_f32_e32 v12, v175, v175
	v_lshlrev_b32_e32 v155, 16, v147
	v_lshlrev_b32_e32 v154, 16, v146
	v_pk_mul_f32 v[146:147], v[156:157], v[156:157]
	v_pk_fma_f32 v[180:181], v[174:175], v[174:175], v[12:13] op_sel_hi:[1,1,0]
	v_pk_fma_f32 v[178:179], v[154:155], v[154:155], v[146:147]
	v_mov_b32_e32 v44, v180
	v_mov_b32_e32 v190, v168
	v_mov_b32_e32 v191, v45
	v_and_b32_e32 v147, 0xffff0000, v150
	v_mul_f32_e32 v14, v11, v11
	v_pk_add_f32 v[168:169], v[180:181], v[168:169]
	v_pk_mul_f32 v[180:181], v[44:45], v[190:191]
	v_pk_add_f32 v[178:179], v[178:179], v[178:179] op_sel:[0,1] op_sel_hi:[1,0]
	v_lshlrev_b32_e32 v146, 16, v150
	v_mov_b32_e32 v169, v181
	v_mov_b32_e32 v179, v14
	v_mul_f32_e32 v12, v147, v147
	v_lshlrev_b32_e32 v150, 16, v151
	v_and_b32_e32 v151, 0xffff0000, v151
	v_mul_f32_e32 v28, v46, v46
	v_pk_add_f32 v[168:169], v[168:169], v[178:179]
	v_pk_fma_f32 v[178:179], v[146:147], v[146:147], v[12:13] op_sel_hi:[1,1,0]
	v_mul_f32_e32 v12, v151, v151
	v_mov_b32_e32 v179, v28
	s_nop 1
	v_mov_b32_dpp v28, v3 quad_perm:[1,0,3,2] row_mask:0xf bank_mask:0xf
	v_mul_f32_e32 v36, v47, v47
	v_pk_fma_f32 v[180:181], v[150:151], v[150:151], v[12:13] op_sel_hi:[1,1,0]
	v_lshlrev_b32_e32 v120, 16, v56
	v_mov_b32_e32 v181, v36
	v_pk_add_f32 v[178:179], v[178:179], v[180:181]
	v_and_b32_e32 v181, 0xffff0000, v167
	v_pk_add_f32 v[194:195], v[168:169], v[178:179]
	v_and_b32_e32 v179, 0xffff0000, v166
	v_lshlrev_b32_e32 v180, 16, v167
	v_mul_f32_e32 v12, v181, v181
	v_lshlrev_b32_e32 v178, 16, v166
	v_pk_fma_f32 v[190:191], v[180:181], v[180:181], v[12:13] op_sel_hi:[1,1,0]
	v_mul_f32_e32 v12, v179, v179
	s_waitcnt lgkmcnt(0)
	v_add_f32_e32 v3, v3, v28
	v_pk_fma_f32 v[196:197], v[178:179], v[178:179], v[12:13] op_sel_hi:[1,1,0]
	s_nop 1
	v_mov_b32_dpp v12, v3 quad_perm:[2,3,0,1] row_mask:0xf bank_mask:0xf
	v_and_b32_e32 v169, 0xffff0000, v159
	v_and_b32_e32 v168, 0xffff0000, v158
	v_lshlrev_b32_e32 v167, 16, v159
	v_lshlrev_b32_e32 v166, 16, v158
	s_waitcnt lgkmcnt(0)
	v_add_f32_e32 v3, v3, v12
	s_nop 1
	v_mov_b32_dpp v12, v3 row_half_mirror row_mask:0xf bank_mask:0xf
	v_pk_mul_f32 v[158:159], v[168:169], v[168:169]
	v_and_b32_e32 v121, 0xffff0000, v56
	v_pk_fma_f32 v[192:193], v[166:167], v[166:167], v[158:159]
	v_mov_b32_e32 v56, v196
	v_mov_b32_e32 v198, v190
	v_mov_b32_e32 v199, v57
	v_and_b32_e32 v159, 0xffff0000, v162
	v_mul_f32_e32 v14, v19, v19
	v_pk_add_f32 v[190:191], v[196:197], v[190:191]
	v_pk_mul_f32 v[196:197], v[56:57], v[198:199]
	v_pk_add_f32 v[192:193], v[192:193], v[192:193] op_sel:[0,1] op_sel_hi:[1,0]
	v_lshlrev_b32_e32 v158, 16, v162
	v_lshlrev_b32_e32 v162, 16, v163
	v_and_b32_e32 v163, 0xffff0000, v163
	v_mov_b32_e32 v191, v197
	v_mov_b32_e32 v193, v14
	s_waitcnt lgkmcnt(0)
	v_add_f32_e32 v3, v3, v12
	v_mul_f32_e32 v12, v159, v159
	v_pk_add_f32 v[190:191], v[190:191], v[192:193]
	v_pk_fma_f32 v[192:193], v[158:159], v[158:159], v[12:13] op_sel_hi:[1,1,0]
	v_mov_b32_e32 v196, v172
	v_mov_b32_e32 v197, v170
	v_mov_b32_e32 v170, v173
	v_mul_f32_e32 v12, v163, v163
	v_mul_f32_e32 v36, v60, v60
	v_mul_f32_e32 v44, v61, v61
	v_pk_add_f32 v[170:171], v[196:197], v[170:171]
	v_pk_fma_f32 v[196:197], v[162:163], v[162:163], v[12:13] op_sel_hi:[1,1,0]
	v_mov_b32_e32 v193, v36
	v_mov_b32_e32 v197, v44
	v_pk_add_f32 v[192:193], v[192:193], v[196:197]
	s_nop 1
	v_mov_b32_dpp v173, v171 quad_perm:[1,0,3,2] row_mask:0xf bank_mask:0xf
	v_pk_add_f32 v[196:197], v[190:191], v[192:193]
	global_load_dwordx4 v[190:193], v2, s[14:15]
	s_nop 1
	v_mov_b32_dpp v172, v170 quad_perm:[1,0,3,2] row_mask:0xf bank_mask:0xf
	v_mov_b32_e32 v198, v196
	v_mov_b32_e32 v199, v194
	v_mov_b32_e32 v194, v197
	v_pk_add_f32 v[194:195], v[198:199], v[194:195]
	s_waitcnt lgkmcnt(0)
; __device__ __forceinline__ float wave_sum(float v) {
; #pragma unroll
;     for (int o = 1; o < 64; o <<= 1) v += __shfl_xor(v, o);
;     return v;
; }
; template <int R, bool BASE_F32, bool OUT_F32>
; __device__ __forceinline__ void rows_res(const Ctx& C, int m0, int stride, int mx, const float* gpost, float scale, int lane) {
;     ...
;     for (int r = 0; r < R; ++r) r1[r] = rsqrtf(wave_sum(r1[r]) * (1.f / DM) + EPS) * scale;
; #pragma unroll
;     for (int j = 0; j < 4; ++j) { const v4f gp = ld4_f32(gpost + 4 * lane + 256 * j);
; #pragma unroll
;         for (int r = 0; r < R; ++r) d[r][j] = b[r][j] + d[r][j] * r1[r] * gp; }
	v_pk_add_f32 v[170:171], v[170:171], v[172:173]
	s_nop 1
	v_mov_b32_dpp v173, v171 quad_perm:[2,3,0,1] row_mask:0xf bank_mask:0xf
	s_nop 1
	v_mov_b32_dpp v172, v170 quad_perm:[2,3,0,1] row_mask:0xf bank_mask:0xf
	s_nop 1
	v_mov_b32_dpp v197, v195 quad_perm:[1,0,3,2] row_mask:0xf bank_mask:0xf
	s_nop 1
	v_mov_b32_dpp v196, v194 quad_perm:[1,0,3,2] row_mask:0xf bank_mask:0xf
	s_nop 1
	v_mov_b32_dpp v14, v3 row_mirror row_mask:0xf bank_mask:0xf
	s_mov_b32 s11, 0x800000
	s_waitcnt lgkmcnt(0)
	v_pk_add_f32 v[170:171], v[170:171], v[172:173]
	s_nop 1
	v_mov_b32_dpp v173, v171 row_half_mirror row_mask:0xf bank_mask:0xf
	s_nop 1
	v_mov_b32_dpp v172, v170 row_half_mirror row_mask:0xf bank_mask:0xf
	s_waitcnt lgkmcnt(0)
	v_pk_add_f32 v[194:195], v[194:195], v[196:197]
	s_nop 1
	v_mov_b32_dpp v197, v195 quad_perm:[2,3,0,1] row_mask:0xf bank_mask:0xf
	s_nop 1
	v_mov_b32_dpp v196, v194 quad_perm:[2,3,0,1] row_mask:0xf bank_mask:0xf
	s_waitcnt lgkmcnt(0)
	v_add_f32_e32 v3, v3, v14
	s_waitcnt lgkmcnt(0)
	v_pk_add_f32 v[170:171], v[170:171], v[172:173]
	ds_bpermute_b32 v14, v187, v3
	s_nop 1
	v_mov_b32_dpp v173, v171 row_mirror row_mask:0xf bank_mask:0xf
	s_nop 1
	v_mov_b32_dpp v172, v170 row_mirror row_mask:0xf bank_mask:0xf
	s_waitcnt lgkmcnt(0)
	v_pk_add_f32 v[198:199], v[194:195], v[196:197]
	s_nop 1
	v_mov_b32_dpp v201, v199 row_half_mirror row_mask:0xf bank_mask:0xf
	s_nop 1
	v_mov_b32_dpp v200, v198 row_half_mirror row_mask:0xf bank_mask:0xf
	s_waitcnt lgkmcnt(0)
	v_add_f32_e32 v3, v3, v14
	s_waitcnt lgkmcnt(0)
	v_pk_add_f32 v[170:171], v[170:171], v[172:173]
	ds_bpermute_b32 v12, v188, v3
	ds_bpermute_b32 v173, v187, v171
	ds_bpermute_b32 v172, v187, v170
	s_waitcnt lgkmcnt(0)
	v_pk_add_f32 v[198:199], v[198:199], v[200:201]
	s_nop 1
	v_mov_b32_dpp v201, v199 row_mirror row_mask:0xf bank_mask:0xf
	s_nop 1
	v_mov_b32_dpp v200, v198 row_mirror row_mask:0xf bank_mask:0xf
	s_waitcnt lgkmcnt(0)
	v_add_f32_e32 v12, v3, v12
	v_mov_b32_e32 v3, 0x358637bd
	s_waitcnt lgkmcnt(0)
	v_pk_add_f32 v[170:171], v[170:171], v[172:173]
	v_fmamk_f32 v12, v12, 0x3a800000, v3
	ds_bpermute_b32 v173, v188, v171
	ds_bpermute_b32 v172, v188, v170
	v_mul_f32_e32 v14, 0x4b800000, v12
	v_cmp_gt_f32_e32 vcc, s11, v12
	s_waitcnt lgkmcnt(0)
	v_pk_add_f32 v[198:199], v[198:199], v[200:201]
	s_mov_b32 s0, 0x358637bd
	v_cndmask_b32_e32 v12, v12, v14, vcc
	v_rsq_f32_e32 v12, v12
	ds_bpermute_b32 v201, v187, v199
	ds_bpermute_b32 v200, v187, v198
	s_mov_b32 s10, 0x3a800000
	s_waitcnt lgkmcnt(0)
	v_pk_add_f32 v[170:171], v[170:171], v[172:173]
	v_mov_b64_e32 v[172:173], s[0:1]
	v_pk_fma_f32 v[170:171], v[170:171], s[10:11], v[172:173] op_sel_hi:[1,0,0]
	v_mul_f32_e32 v14, 0x45800000, v12
	v_mul_f32_e32 v28, 0x4b800000, v171
	v_cmp_gt_f32_e64 s[8:9], s11, v171
	global_load_dwordx4 v[194:197], v2, s[14:15] offset:1024
	v_cndmask_b32_e32 v12, v12, v14, vcc
	v_cndmask_b32_e64 v28, v171, v28, s[8:9]
	v_mul_f32_e32 v14, 0x4b800000, v170
	v_cmp_gt_f32_e32 vcc, s11, v170
	v_rsq_f32_e32 v28, v28
	v_mul_f32_e32 v44, 0.5, v12
	v_cndmask_b32_e32 v14, v170, v14, vcc
	s_waitcnt lgkmcnt(0)
	v_pk_add_f32 v[170:171], v[198:199], v[200:201]
	ds_bpermute_b32 v199, v188, v171
	ds_bpermute_b32 v198, v188, v170
	v_rsq_f32_e32 v14, v14
	v_mul_f32_e32 v12, 0x45800000, v28
	v_cndmask_b32_e64 v12, v28, v12, s[8:9]
	v_mul_f32_e32 v36, 0.5, v12
	v_mul_f32_e32 v12, 0x45800000, v14
	s_waitcnt lgkmcnt(0)
	v_pk_add_f32 v[170:171], v[170:171], v[198:199]
	v_cndmask_b32_e32 v12, v14, v12, vcc
	v_pk_fma_f32 v[170:171], v[170:171], s[10:11], v[172:173] op_sel_hi:[1,0,0]
	v_mul_f32_e32 v14, 0.5, v12
	v_mul_f32_e32 v12, 0x4b800000, v171
	v_cmp_gt_f32_e32 vcc, s11, v171
	global_load_dwordx4 v[198:201], v2, s[14:15] offset:2048
	v_pk_mul_f32 v[140:141], v[44:45], v[140:141] op_sel_hi:[0,1]
	v_cndmask_b32_e32 v12, v171, v12, vcc
	v_rsq_f32_e32 v12, v12
	v_pk_mul_f32 v[136:137], v[44:45], v[136:137] op_sel_hi:[0,1]
	v_lshlrev_b32_e32 v20, 16, v22
	v_and_b32_e32 v21, 0xffff0000, v22
	v_lshlrev_b32_e32 v22, 16, v23
	v_and_b32_e32 v23, 0xffff0000, v23
	v_mul_f32_e32 v28, 0x4b800000, v170
	v_cmp_gt_f32_e64 s[8:9], s11, v170
	s_waitcnt vmcnt(2)
	v_pk_mul_f32 v[136:137], v[136:137], v[190:191]
	v_pk_mul_f32 v[140:141], v[140:141], v[192:193]
	v_cndmask_b32_e64 v28, v170, v28, s[8:9]
	v_pk_fma_f32 v[170:171], v[6:7], v[22:23], v[140:141] op_sel_hi:[0,1,1]
	v_pk_fma_f32 v[172:173], v[6:7], v[20:21], v[136:137] op_sel_hi:[0,1,1]
	v_pk_mul_f32 v[20:21], v[36:37], v[152:153] op_sel_hi:[0,1]
	v_pk_mul_f32 v[22:23], v[36:37], v[148:149] op_sel_hi:[0,1]
	v_lshlrev_b32_e32 v72, 16, v34
	v_and_b32_e32 v73, 0xffff0000, v34
	v_lshlrev_b32_e32 v76, 16, v35
	v_and_b32_e32 v77, 0xffff0000, v35
	v_lshlrev_b32_e32 v80, 16, v51
	v_and_b32_e32 v81, 0xffff0000, v51
	v_rsq_f32_e32 v51, v28
	v_mul_f32_e32 v28, 0x45800000, v12
	v_pk_mul_f32 v[22:23], v[22:23], v[190:191]
	v_pk_mul_f32 v[20:21], v[20:21], v[192:193]
	v_cndmask_b32_e32 v12, v12, v28, vcc
	v_pk_fma_f32 v[136:137], v[8:9], v[76:77], v[20:21] op_sel_hi:[0,1,1]
	v_pk_fma_f32 v[140:141], v[8:9], v[72:73], v[22:23] op_sel_hi:[0,1,1]
	v_pk_mul_f32 v[20:21], v[14:15], v[164:165] op_sel_hi:[0,1]
	v_pk_mul_f32 v[22:23], v[14:15], v[160:161] op_sel_hi:[0,1]
	v_mul_f32_e32 v28, 0.5, v12
	v_pk_mul_f32 v[22:23], v[190:191], v[22:23]
	v_pk_mul_f32 v[20:21], v[192:193], v[20:21]
	v_pk_fma_f32 v[114:115], v[10:11], v[114:115], v[22:23] op_sel_hi:[0,1,1]
	v_pk_fma_f32 v[112:113], v[10:11], v[112:113], v[20:21] op_sel_hi:[0,1,1]
	v_pk_mul_f32 v[20:21], v[28:29], v[176:177] op_sel_hi:[0,1]
	v_pk_mul_f32 v[22:23], v[28:29], v[174:175] op_sel_hi:[0,1]
	global_load_dwordx4 v[174:177], v2, s[14:15] offset:3072
	v_mul_f32_e32 v12, 0x45800000, v51
	v_cndmask_b32_e64 v12, v51, v12, s[8:9]
	v_mul_f32_e32 v56, 0.5, v12
	v_pk_mul_f32 v[22:23], v[190:191], v[22:23]
	v_mov_b32_e32 v12, v15
	v_pk_fma_f32 v[76:77], v[18:19], v[120:121], v[22:23] op_sel_hi:[0,1,1]
	v_pk_mul_f32 v[22:23], v[56:57], v[178:179] op_sel_hi:[0,1]
	v_pk_mul_f32 v[22:23], v[190:191], v[22:23]
	v_pk_mul_f32 v[16:17], v[44:45], v[16:17] op_sel_hi:[0,1]
	v_pk_fma_f32 v[22:23], v[50:51], v[110:111], v[22:23] op_sel_hi:[0,1,1]
	v_mov_b32_e32 v110, v117
	v_mov_b32_e32 v117, v118
	v_pk_mul_f32 v[116:117], v[44:45], v[116:117] op_sel_hi:[0,1]
	v_mov_b32_e32 v111, v119
	v_pk_mul_f32 v[110:111], v[44:45], v[110:111] op_sel_hi:[0,1]
	v_pk_mul_f32 v[12:13], v[44:45], v[12:13] op_sel_hi:[0,1]
	v_lshlrev_b32_e32 v34, 16, v40
	s_waitcnt vmcnt(2)
;     __device__ __forceinline__ float* out() const { return (float*)karg_in(33); }
; __device__ __forceinline__ float ssq4(v4f v) { return (v.x * v.x + v.y * v.y) + (v.z * v.z + v.w * v.w); }
; template <int R, bool BASE_F32, bool OUT_F32>
; __device__ __forceinline__ void rows_res(const Ctx& C, int m0, int stride, int mx, const float* gpost, float scale, int lane) {
;     ...
;     for (int j = 0; j < 4; ++j) { const v4f gp = ld4_f32(gpost + 4 * lane + 256 * j);
; #pragma unroll
;         for (int r = 0; r < R; ++r) d[r][j] = b[r][j] + d[r][j] * r1[r] * gp; }
;     if (OUT_F32) { float* Y = C.out();
; #pragma unroll
;         for (int r = 0; r < R; ++r)
; #pragma unroll
;             for (int j = 0; j < 4; ++j) if (ok[r]) *(v4f*)(Y + (size_t)mr[r] * DM + 4 * lane + 256 * j) = d[r][j];
;     } else { float* rs = C.RS(); float t[R];
; #pragma unroll
;         for (int r = 0; r < R; ++r) { float s = 0.f;
; #pragma unroll
;             for (int j = 0; j < 4; ++j) s += ssq4(d[r][j]);
;             t[r] = s; }
	v_pk_mul_f32 v[116:117], v[116:117], v[194:195]
	v_pk_mul_f32 v[110:111], v[110:111], v[196:197]
	v_pk_fma_f32 v[120:121], v[6:7], v[48:49], v[116:117] op_sel_hi:[0,1,1]
	v_mov_b32_e32 v48, v131
	v_mov_b32_e32 v49, v133
	v_pk_mul_f32 v[48:49], v[36:37], v[48:49] op_sel_hi:[0,1]
	v_pk_mul_f32 v[48:49], v[48:49], v[196:197]
	v_pk_fma_f32 v[118:119], v[6:7], v[58:59], v[110:111] op_sel_hi:[0,1,1]
	v_mov_b32_e32 v131, v132
	v_pk_fma_f32 v[110:111], v[8:9], v[88:89], v[48:49] op_sel_hi:[0,1,1]
	v_mov_b32_e32 v48, v143
	v_mov_b32_e32 v49, v145
	v_pk_mul_f32 v[58:59], v[36:37], v[130:131] op_sel_hi:[0,1]
	v_pk_mul_f32 v[48:49], v[14:15], v[48:49] op_sel_hi:[0,1]
	v_pk_mul_f32 v[58:59], v[58:59], v[194:195]
	v_mov_b32_e32 v143, v144
	v_pk_mul_f32 v[48:49], v[48:49], v[196:197]
	v_pk_fma_f32 v[116:117], v[8:9], v[86:87], v[58:59] op_sel_hi:[0,1,1]
	v_pk_mul_f32 v[58:59], v[14:15], v[142:143] op_sel_hi:[0,1]
	v_pk_fma_f32 v[94:95], v[10:11], v[94:95], v[48:49] op_sel_hi:[0,1,1]
	v_mov_b32_e32 v48, v155
	v_mov_b32_e32 v49, v157
	v_pk_mul_f32 v[58:59], v[58:59], v[194:195]
	v_pk_mul_f32 v[48:49], v[28:29], v[48:49] op_sel_hi:[0,1]
	v_mov_b32_e32 v155, v156
	v_pk_fma_f32 v[90:91], v[10:11], v[90:91], v[58:59] op_sel_hi:[0,1,1]
	v_pk_mul_f32 v[58:59], v[28:29], v[154:155] op_sel_hi:[0,1]
	v_pk_mul_f32 v[48:49], v[196:197], v[48:49]
	v_pk_mul_f32 v[58:59], v[194:195], v[58:59]
	v_pk_fma_f32 v[86:87], v[18:19], v[100:101], v[48:49] op_sel_hi:[0,1,1]
	v_mov_b32_e32 v48, v167
	v_mov_b32_e32 v49, v169
	v_mov_b32_e32 v167, v168
	v_pk_fma_f32 v[88:89], v[18:19], v[98:99], v[58:59] op_sel_hi:[0,1,1]
	v_pk_mul_f32 v[48:49], v[56:57], v[48:49] op_sel_hi:[0,1]
	v_pk_mul_f32 v[58:59], v[56:57], v[166:167] op_sel_hi:[0,1]
	v_pk_mul_f32 v[98:99], v[44:45], v[108:109] op_sel_hi:[0,1]
	v_pk_mul_f32 v[100:101], v[44:45], v[106:107] op_sel_hi:[0,1]
	v_pk_mul_f32 v[58:59], v[194:195], v[58:59]
	v_pk_mul_f32 v[48:49], v[196:197], v[48:49]
	s_waitcnt vmcnt(1)
	v_pk_mul_f32 v[100:101], v[100:101], v[198:199]
	v_pk_mul_f32 v[98:99], v[98:99], v[200:201]
	v_pk_fma_f32 v[48:49], v[50:51], v[104:105], v[48:49] op_sel_hi:[0,1,1]
	v_pk_fma_f32 v[58:59], v[50:51], v[102:103], v[58:59] op_sel_hi:[0,1,1]
	v_pk_fma_f32 v[102:103], v[6:7], v[64:65], v[98:99] op_sel_hi:[0,1,1]
	v_pk_fma_f32 v[104:105], v[6:7], v[32:33], v[100:101] op_sel_hi:[0,1,1]
	v_pk_mul_f32 v[32:33], v[36:37], v[126:127] op_sel_hi:[0,1]
	v_pk_mul_f32 v[64:65], v[36:37], v[124:125] op_sel_hi:[0,1]
	v_pk_mul_f32 v[64:65], v[64:65], v[198:199]
	v_pk_mul_f32 v[32:33], v[32:33], v[200:201]
	v_pk_fma_f32 v[100:101], v[8:9], v[70:71], v[64:65] op_sel_hi:[0,1,1]
	v_pk_fma_f32 v[98:99], v[8:9], v[74:75], v[32:33] op_sel_hi:[0,1,1]
	v_pk_mul_f32 v[32:33], v[14:15], v[138:139] op_sel_hi:[0,1]
	v_pk_mul_f32 v[64:65], v[14:15], v[134:135] op_sel_hi:[0,1]
	v_pk_mul_f32 v[64:65], v[64:65], v[198:199]
	v_pk_mul_f32 v[32:33], v[32:33], v[200:201]
	v_pk_fma_f32 v[78:79], v[10:11], v[78:79], v[64:65] op_sel_hi:[0,1,1]
	v_pk_fma_f32 v[80:81], v[10:11], v[80:81], v[32:33] op_sel_hi:[0,1,1]
	v_pk_mul_f32 v[32:33], v[28:29], v[150:151] op_sel_hi:[0,1]
	v_pk_mul_f32 v[64:65], v[28:29], v[146:147] op_sel_hi:[0,1]
	v_pk_mul_f32 v[64:65], v[198:199], v[64:65]
	v_pk_mul_f32 v[32:33], v[200:201], v[32:33]
	s_waitcnt vmcnt(0)
	v_pk_mul_f32 v[12:13], v[12:13], v[174:175]
	v_pk_mul_f32 v[16:17], v[16:17], v[176:177]
	v_pk_fma_f32 v[70:71], v[18:19], v[84:85], v[32:33] op_sel_hi:[0,1,1]
	v_pk_fma_f32 v[74:75], v[18:19], v[82:83], v[64:65] op_sel_hi:[0,1,1]
	v_pk_fma_f32 v[82:83], v[6:7], v[26:27], v[16:17] op_sel_hi:[0,1,1]
	v_pk_fma_f32 v[84:85], v[6:7], v[24:25], v[12:13] op_sel_hi:[0,1,1]
	v_mov_b32_e32 v6, v29
	v_pk_mul_f32 v[12:13], v[36:37], v[30:31] op_sel_hi:[0,1]
	v_pk_mul_f32 v[6:7], v[36:37], v[6:7] op_sel_hi:[0,1]
	v_and_b32_e32 v35, 0xffff0000, v40
	v_lshlrev_b32_e32 v40, 16, v41
	v_and_b32_e32 v41, 0xffff0000, v41
	v_pk_mul_f32 v[6:7], v[6:7], v[174:175]
	v_pk_mul_f32 v[12:13], v[12:13], v[176:177]
	v_pk_fma_f32 v[26:27], v[8:9], v[34:35], v[6:7] op_sel_hi:[0,1,1]
	v_pk_fma_f32 v[24:25], v[8:9], v[40:41], v[12:13] op_sel_hi:[0,1,1]
	v_mov_b32_e32 v8, v37
	v_pk_mul_f32 v[6:7], v[14:15], v[38:39] op_sel_hi:[0,1]
	v_pk_mul_f32 v[8:9], v[14:15], v[8:9] op_sel_hi:[0,1]
	v_lshlrev_b32_e32 v42, 16, v52
	v_and_b32_e32 v43, 0xffff0000, v52
	v_lshlrev_b32_e32 v52, 16, v53
	v_and_b32_e32 v53, 0xffff0000, v53
	v_pk_mul_f32 v[8:9], v[8:9], v[174:175]
	v_pk_mul_f32 v[6:7], v[6:7], v[176:177]
	v_pk_fma_f32 v[16:17], v[10:11], v[42:43], v[8:9] op_sel_hi:[0,1,1]
	v_pk_fma_f32 v[14:15], v[10:11], v[52:53], v[6:7] op_sel_hi:[0,1,1]
	v_mov_b32_e32 v10, v45
	v_pk_mul_f32 v[6:7], v[28:29], v[46:47] op_sel_hi:[0,1]
	v_pk_mul_f32 v[8:9], v[28:29], v[10:11] op_sel_hi:[0,1]
	v_pk_mul_f32 v[20:21], v[192:193], v[20:21]
	v_pk_mul_f32 v[8:9], v[174:175], v[8:9]
	v_pk_mul_f32 v[6:7], v[176:177], v[6:7]
	v_pk_fma_f32 v[72:73], v[18:19], v[122:123], v[20:21] op_sel_hi:[0,1,1]
	v_pk_fma_f32 v[10:11], v[18:19], v[62:63], v[6:7] op_sel_hi:[0,1,1]
	v_pk_fma_f32 v[12:13], v[18:19], v[54:55], v[8:9] op_sel_hi:[0,1,1]
	v_mov_b32_e32 v18, v57
	v_pk_mul_f32 v[8:9], v[56:57], v[18:19] op_sel_hi:[0,1]
	v_mul_f32_e32 v18, v173, v173
	v_mul_f32_e32 v19, v171, v171
	v_fmac_f32_e32 v18, v172, v172
	v_fmac_f32_e32 v19, v170, v170
	v_add_f32_e32 v18, v18, v19
	v_mul_f32_e32 v19, v121, v121
	v_mul_f32_e32 v28, v119, v119
	v_fmac_f32_e32 v19, v120, v120
	v_fmac_f32_e32 v28, v118, v118
	v_add_f32_e32 v19, v19, v28
	v_add_f32_e32 v18, v18, v19
	v_mul_f32_e32 v19, v105, v105
	v_mul_f32_e32 v28, v103, v103
	v_fmac_f32_e32 v19, v104, v104
	v_fmac_f32_e32 v28, v102, v102
; __device__ __forceinline__ float ssq4(v4f v) { return (v.x * v.x + v.y * v.y) + (v.z * v.z + v.w * v.w); }
; __device__ __forceinline__ float wave_sum(float v) {
; #pragma unroll
;     for (int o = 1; o < 64; o <<= 1) v += __shfl_xor(v, o);
;     return v;
; }
; template <int R, bool BASE_F32, bool OUT_F32>
; __device__ __forceinline__ void rows_res(const Ctx& C, int m0, int stride, int mx, const float* gpost, float scale, int lane) {
;     ...
;     } else { float* rs = C.RS(); float t[R];
; #pragma unroll
;         for (int r = 0; r < R; ++r) { float s = 0.f;
; #pragma unroll
;             for (int j = 0; j < 4; ++j) s += ssq4(d[r][j]);
;             t[r] = s; }
; #pragma unroll
;         for (int r = 0; r < R; ++r) t[r] = wave_sum(t[r]) * (1.f / DM) + EPS;
	v_add_f32_e32 v19, v19, v28
	v_add_f32_e32 v18, v18, v19
	v_mul_f32_e32 v19, v85, v85
	v_mul_f32_e32 v28, v83, v83
	v_fmac_f32_e32 v19, v84, v84
	v_fmac_f32_e32 v28, v82, v82
	v_add_f32_e32 v19, v19, v28
	v_add_f32_e32 v18, v18, v19
	v_mul_f32_e32 v19, v141, v141
	v_mul_f32_e32 v28, v137, v137
	v_fmac_f32_e32 v19, v140, v140
	v_fmac_f32_e32 v28, v136, v136
	v_add_f32_e32 v19, v19, v28
	v_mul_f32_e32 v28, v117, v117
	v_mul_f32_e32 v29, v111, v111
	v_fmac_f32_e32 v28, v116, v116
	v_fmac_f32_e32 v29, v110, v110
	v_add_f32_e32 v28, v28, v29
	v_add_f32_e32 v19, v19, v28
	v_mul_f32_e32 v28, v101, v101
	v_mul_f32_e32 v29, v99, v99
	v_fmac_f32_e32 v28, v100, v100
	v_fmac_f32_e32 v29, v98, v98
	v_add_f32_e32 v28, v28, v29
	v_add_f32_e32 v19, v19, v28
	v_mul_f32_e32 v28, v27, v27
	v_mul_f32_e32 v29, v25, v25
	v_fmac_f32_e32 v28, v26, v26
	v_fmac_f32_e32 v29, v24, v24
	v_add_f32_e32 v28, v28, v29
	v_add_f32_e32 v19, v19, v28
	v_mul_f32_e32 v28, v115, v115
	v_mul_f32_e32 v29, v113, v113
	v_fmac_f32_e32 v28, v114, v114
	v_fmac_f32_e32 v29, v112, v112
	v_add_f32_e32 v28, v28, v29
	v_mul_f32_e32 v29, v91, v91
	v_mul_f32_e32 v30, v95, v95
	v_fmac_f32_e32 v29, v90, v90
	v_fmac_f32_e32 v30, v94, v94
	v_add_f32_e32 v29, v29, v30
	v_add_f32_e32 v28, v28, v29
	v_mul_f32_e32 v29, v79, v79
	v_mul_f32_e32 v30, v81, v81
	v_fmac_f32_e32 v29, v78, v78
	v_fmac_f32_e32 v30, v80, v80
	v_add_f32_e32 v29, v29, v30
	v_add_f32_e32 v28, v28, v29
	v_mul_f32_e32 v29, v17, v17
	v_mul_f32_e32 v30, v15, v15
	v_fmac_f32_e32 v29, v16, v16
	v_fmac_f32_e32 v30, v14, v14
	v_add_f32_e32 v29, v29, v30
	v_add_f32_e32 v28, v28, v29
	v_mul_f32_e32 v29, v77, v77
	v_mul_f32_e32 v30, v73, v73
	v_fmac_f32_e32 v29, v76, v76
	v_fmac_f32_e32 v30, v72, v72
	v_add_f32_e32 v29, v29, v30
	v_mul_f32_e32 v30, v89, v89
	v_mul_f32_e32 v31, v87, v87
	v_fmac_f32_e32 v30, v88, v88
	v_fmac_f32_e32 v31, v86, v86
	v_add_f32_e32 v30, v30, v31
	v_add_f32_e32 v29, v29, v30
	v_mul_f32_e32 v30, v75, v75
	v_mul_f32_e32 v31, v71, v71
	v_fmac_f32_e32 v30, v74, v74
	v_fmac_f32_e32 v31, v70, v70
	v_add_f32_e32 v30, v30, v31
	v_pk_mul_f32 v[20:21], v[56:57], v[180:181] op_sel_hi:[0,1]
	v_add_f32_e32 v29, v30, v29
	v_mul_f32_e32 v30, v13, v13
	v_mul_f32_e32 v31, v11, v11
	v_pk_mul_f32 v[20:21], v[192:193], v[20:21]
	v_fmac_f32_e32 v30, v12, v12
	v_fmac_f32_e32 v31, v10, v10
	s_nop 1
	v_mov_b32_dpp v35, v18 quad_perm:[1,0,3,2] row_mask:0xf bank_mask:0xf
	v_pk_fma_f32 v[20:21], v[50:51], v[128:129], v[20:21] op_sel_hi:[0,1,1]
	v_add_f32_e32 v30, v30, v31
	v_add_f32_e32 v29, v30, v29
	v_mul_f32_e32 v30, v23, v23
	v_mul_f32_e32 v31, v21, v21
	v_fmac_f32_e32 v30, v22, v22
	v_fmac_f32_e32 v31, v20, v20
	v_add_f32_e32 v30, v30, v31
	v_mul_f32_e32 v31, v59, v59
	v_mul_f32_e32 v34, v49, v49
	v_fmac_f32_e32 v31, v58, v58
	v_fmac_f32_e32 v34, v48, v48
	s_waitcnt lgkmcnt(0)
	v_add_f32_e32 v18, v18, v35
	v_add_f32_e32 v31, v31, v34
	s_nop 1
	v_mov_b32_dpp v34, v18 quad_perm:[2,3,0,1] row_mask:0xf bank_mask:0xf
	s_nop 1
	v_mov_b32_dpp v35, v19 quad_perm:[1,0,3,2] row_mask:0xf bank_mask:0xf
	v_pk_mul_f32 v[32:33], v[56:57], v[162:163] op_sel_hi:[0,1]
	v_pk_mul_f32 v[64:65], v[56:57], v[158:159] op_sel_hi:[0,1]
	v_pk_mul_f32 v[64:65], v[198:199], v[64:65]
	s_waitcnt lgkmcnt(0)
	v_add_f32_e32 v18, v18, v34
	s_waitcnt lgkmcnt(0)
	v_add_f32_e32 v19, v19, v35
	s_nop 1
	v_mov_b32_dpp v34, v18 row_half_mirror row_mask:0xf bank_mask:0xf
	s_nop 1
	v_mov_b32_dpp v35, v19 quad_perm:[2,3,0,1] row_mask:0xf bank_mask:0xf
	v_pk_mul_f32 v[32:33], v[200:201], v[32:33]
	v_pk_fma_f32 v[64:65], v[50:51], v[92:93], v[64:65] op_sel_hi:[0,1,1]
	v_pk_fma_f32 v[32:33], v[50:51], v[96:97], v[32:33] op_sel_hi:[0,1,1]
	v_add_f32_e32 v30, v30, v31
	v_mul_f32_e32 v31, v65, v65
	v_mul_f32_e32 v36, v33, v33
	v_fmac_f32_e32 v31, v64, v64
	v_fmac_f32_e32 v36, v32, v32
	v_add_f32_e32 v31, v31, v36
	s_waitcnt lgkmcnt(0)
	v_add_f32_e32 v18, v18, v34
	s_waitcnt lgkmcnt(0)
	v_add_f32_e32 v19, v19, v35
	v_add_f32_e32 v30, v31, v30
	s_nop 1
	v_mov_b32_dpp v31, v18 row_mirror row_mask:0xf bank_mask:0xf
	s_nop 1
	v_mov_b32_dpp v34, v19 row_half_mirror row_mask:0xf bank_mask:0xf
	v_pk_mul_f32 v[6:7], v[56:57], v[60:61] op_sel_hi:[0,1]
	v_pk_mul_f32 v[8:9], v[174:175], v[8:9]
	v_pk_mul_f32 v[6:7], v[176:177], v[6:7]
	s_waitcnt lgkmcnt(0)
; __device__ __forceinline__ void st4_bf16(bf16* p, v4f o) { v2u w; w.x = cvt_pk_nv(o.x, o.y); w.y = cvt_pk_nv(o.z, o.w); *(v2u*)p = w; }
; __device__ __forceinline__ float wave_sum(float v) {
; #pragma unroll
;     for (int o = 1; o < 64; o <<= 1) v += __shfl_xor(v, o);
;     return v;
; }
; template <int R, bool BASE_F32, bool OUT_F32>
; __device__ __forceinline__ void rows_res(const Ctx& C, int m0, int stride, int mx, const float* gpost, float scale, int lane) {
;     ...
;         for (int r = 0; r < R; ++r) t[r] = wave_sum(t[r]) * (1.f / DM) + EPS;
; #pragma unroll
;         for (int r = 0; r < R; ++r) { const float rstd = rsqrtf(t[r]);
; #pragma unroll
;             for (int j = 0; j < 4; ++j) if (ok[r]) st4_bf16(XN + (size_t)mr[r] * DM + 4 * lane + 256 * j, d[r][j] * rstd);
;             if (lane == 0 && ok[r]) rs[mr[r]] = sqrtf(t[r]); }
	v_add_f32_e32 v18, v18, v31
	s_waitcnt lgkmcnt(0)
	v_add_f32_e32 v19, v19, v34
	ds_bpermute_b32 v31, v187, v18
	s_nop 1
	v_mov_b32_dpp v34, v19 row_mirror row_mask:0xf bank_mask:0xf
	v_pk_fma_f32 v[6:7], v[50:51], v[68:69], v[6:7] op_sel_hi:[0,1,1]
	v_pk_fma_f32 v[8:9], v[50:51], v[66:67], v[8:9] op_sel_hi:[0,1,1]
	v_mul_f32_e32 v35, v9, v9
	s_waitcnt lgkmcnt(0)
	v_add_f32_e32 v18, v18, v31
	s_waitcnt lgkmcnt(0)
	v_add_f32_e32 v19, v19, v34
	ds_bpermute_b32 v31, v188, v18
	ds_bpermute_b32 v34, v187, v19
	v_mul_f32_e32 v36, v7, v7
	v_fmac_f32_e32 v35, v8, v8
	v_fmac_f32_e32 v36, v6, v6
	v_add_f32_e32 v35, v35, v36
	v_add_f32_e32 v30, v35, v30
	s_waitcnt lgkmcnt(0)
	v_add_f32_e32 v36, v18, v31
	s_nop 1
	v_mov_b32_dpp v18, v28 quad_perm:[1,0,3,2] row_mask:0xf bank_mask:0xf
	s_waitcnt lgkmcnt(0)
	v_add_f32_e32 v34, v19, v34
	s_nop 1
	v_mov_b32_dpp v19, v29 quad_perm:[1,0,3,2] row_mask:0xf bank_mask:0xf
	s_nop 1
	v_mov_b32_dpp v31, v30 quad_perm:[1,0,3,2] row_mask:0xf bank_mask:0xf
	s_mov_b64 s[0:1], s[80:81]
	s_waitcnt lgkmcnt(0)
	v_add_f32_e32 v18, v28, v18
	s_nop 1
	v_mov_b32_dpp v28, v18 quad_perm:[2,3,0,1] row_mask:0xf bank_mask:0xf
	s_waitcnt lgkmcnt(0)
	v_add_f32_e32 v19, v29, v19
	s_waitcnt lgkmcnt(0)
	v_add_f32_e32 v30, v30, v31
	s_nop 1
	v_mov_b32_dpp v29, v19 quad_perm:[2,3,0,1] row_mask:0xf bank_mask:0xf
	s_nop 1
	v_mov_b32_dpp v31, v30 quad_perm:[2,3,0,1] row_mask:0xf bank_mask:0xf
	s_waitcnt lgkmcnt(0)
	v_add_f32_e32 v18, v18, v28
	s_nop 1
	v_mov_b32_dpp v28, v18 row_half_mirror row_mask:0xf bank_mask:0xf
	s_waitcnt lgkmcnt(0)
	v_add_f32_e32 v19, v19, v29
	s_waitcnt lgkmcnt(0)
	v_add_f32_e32 v30, v30, v31
	s_nop 1
	v_mov_b32_dpp v29, v19 row_half_mirror row_mask:0xf bank_mask:0xf
	s_nop 1
	v_mov_b32_dpp v31, v30 row_half_mirror row_mask:0xf bank_mask:0xf
	s_waitcnt lgkmcnt(0)
	v_add_f32_e32 v18, v18, v28
	s_nop 1
	v_mov_b32_dpp v28, v18 row_mirror row_mask:0xf bank_mask:0xf
	s_load_dwordx2 s[8:9], s[0:1], 0x110
	s_waitcnt lgkmcnt(0)
	v_add_f32_e32 v19, v19, v29
	v_add_f32_e32 v30, v30, v31
	s_nop 1
	v_mov_b32_dpp v29, v19 row_mirror row_mask:0xf bank_mask:0xf
	s_nop 1
	v_mov_b32_dpp v31, v30 row_mirror row_mask:0xf bank_mask:0xf
	v_add_f32_e32 v18, v18, v28
	ds_bpermute_b32 v28, v187, v18
	ds_bpermute_b32 v35, v188, v34
	s_waitcnt lgkmcnt(0)
	v_add_f32_e32 v19, v19, v29
	s_waitcnt lgkmcnt(0)
	v_add_f32_e32 v37, v30, v31
	ds_bpermute_b32 v29, v187, v19
	ds_bpermute_b32 v38, v187, v37
	s_waitcnt lgkmcnt(0)
	v_add_f32_e32 v30, v18, v28
	ds_bpermute_b32 v31, v188, v30
	v_fmac_f32_e32 v3, 0x3a800000, v36
	s_waitcnt lgkmcnt(0)
	v_add_f32_e32 v28, v19, v29
	s_waitcnt lgkmcnt(0)
	v_add_f32_e32 v18, v37, v38
	ds_bpermute_b32 v29, v188, v28
	ds_bpermute_b32 v19, v188, v18
	s_and_b64 vcc, exec, s[52:53]
	s_cbranch_vccnz .LBB0_387
	v_mul_f32_e32 v36, 0x4b800000, v3
	v_cmp_gt_f32_e32 vcc, s11, v3
	s_lshl_b64 s[0:1], s[12:13], 11
	s_nop 0
	v_cndmask_b32_e32 v36, v3, v36, vcc
	v_rsq_f32_e32 v38, v36
	v_lshl_add_u64 v[36:37], v[4:5], 0, s[0:1]
	v_mul_f32_e32 v39, 0x45800000, v38
	v_cndmask_b32_e32 v38, v38, v39, vcc
	v_pk_mul_f32 v[42:43], v[172:173], v[38:39] op_sel_hi:[1,0]
	v_pk_mul_f32 v[40:41], v[170:171], v[38:39] op_sel_hi:[1,0]
	v_cvt_pk_bf16_f32 v42, v42, v43
	s_nop 0
	v_cvt_pk_bf16_f32 v43, v40, v41
	global_store_dwordx2 v[36:37], v[42:43], off
	v_pk_mul_f32 v[42:43], v[120:121], v[38:39] op_sel_hi:[1,0]
	v_pk_mul_f32 v[40:41], v[118:119], v[38:39] op_sel_hi:[1,0]
	v_cvt_pk_bf16_f32 v42, v42, v43
	s_nop 0
	v_cvt_pk_bf16_f32 v43, v40, v41
	global_store_dwordx2 v[36:37], v[42:43], off offset:512
	v_pk_mul_f32 v[40:41], v[102:103], v[38:39] op_sel_hi:[1,0]
	v_pk_mul_f32 v[42:43], v[104:105], v[38:39] op_sel_hi:[1,0]
	s_nop 0
	v_cvt_pk_bf16_f32 v42, v42, v43
	v_cvt_pk_bf16_f32 v43, v40, v41
	v_pk_mul_f32 v[40:41], v[82:83], v[38:39] op_sel_hi:[1,0]
	v_pk_mul_f32 v[38:39], v[84:85], v[38:39] op_sel_hi:[1,0]
	global_store_dwordx2 v[36:37], v[42:43], off offset:1024
	v_cvt_pk_bf16_f32 v38, v38, v39
	v_cvt_pk_bf16_f32 v39, v40, v41
	global_store_dwordx2 v[36:37], v[38:39], off offset:1536

; __device__ __forceinline__ void st4_bf16(bf16* p, v4f o) { v2u w; w.x = cvt_pk_nv(o.x, o.y); w.y = cvt_pk_nv(o.z, o.w); *(v2u*)p = w; }
; template <int R, bool BASE_F32, bool OUT_F32>
; __device__ __forceinline__ void rows_res(const Ctx& C, int m0, int stride, int mx, const float* gpost, float scale, int lane) {
;     ...
;         for (int r = 0; r < R; ++r) t[r] = wave_sum(t[r]) * (1.f / DM) + EPS;
; #pragma unroll
;         for (int r = 0; r < R; ++r) { const float rstd = rsqrtf(t[r]);
; #pragma unroll
;             for (int j = 0; j < 4; ++j) if (ok[r]) st4_bf16(XN + (size_t)mr[r] * DM + 4 * lane + 256 * j, d[r][j] * rstd);
.LBB0_393:
	s_or_b64 exec, exec, s[38:39]
	s_waitcnt lgkmcnt(0)
	v_add_f32_e32 v24, v30, v31
	v_mov_b32_e32 v3, 0x358637bd
	s_andn2_b64 vcc, exec, s[36:37]
	v_fmac_f32_e32 v3, 0x3a800000, v24
	s_cbranch_vccnz .LBB0_395
	s_mov_b32 s0, 0x800000
	v_mul_f32_e32 v24, 0x4b800000, v3
	v_cmp_gt_f32_e32 vcc, s0, v3
	s_lshl_b64 s[0:1], s[26:27], 11
	v_lshl_add_u64 v[26:27], v[4:5], 0, s[0:1]
	v_cndmask_b32_e32 v24, v3, v24, vcc
	v_rsq_f32_e32 v24, v24
	s_nop 0
	v_mul_f32_e32 v25, 0x45800000, v24
	v_cndmask_b32_e32 v24, v24, v25, vcc
	v_pk_mul_f32 v[34:35], v[114:115], v[24:25] op_sel_hi:[1,0]
	v_pk_mul_f32 v[30:31], v[112:113], v[24:25] op_sel_hi:[1,0]
	v_cvt_pk_bf16_f32 v34, v34, v35
	v_pk_mul_f32 v[16:17], v[16:17], v[24:25] op_sel_hi:[1,0]
	v_cvt_pk_bf16_f32 v35, v30, v31
	global_store_dwordx2 v[26:27], v[34:35], off
	v_pk_mul_f32 v[34:35], v[90:91], v[24:25] op_sel_hi:[1,0]
	v_pk_mul_f32 v[30:31], v[94:95], v[24:25] op_sel_hi:[1,0]
	v_cvt_pk_bf16_f32 v34, v34, v35
	v_pk_mul_f32 v[14:15], v[14:15], v[24:25] op_sel_hi:[1,0]
	v_cvt_pk_bf16_f32 v35, v30, v31
	global_store_dwordx2 v[26:27], v[34:35], off offset:512
	v_pk_mul_f32 v[34:35], v[78:79], v[24:25] op_sel_hi:[1,0]
	v_pk_mul_f32 v[30:31], v[80:81], v[24:25] op_sel_hi:[1,0]
	v_cvt_pk_bf16_f32 v34, v34, v35
	v_cvt_pk_bf16_f32 v16, v16, v17
	v_cvt_pk_bf16_f32 v17, v14, v15
	global_store_dwordx2 v[26:27], v[16:17], off offset:1536
	v_cvt_pk_bf16_f32 v35, v30, v31
	global_store_dwordx2 v[26:27], v[34:35], off offset:1024

; __device__ __forceinline__ void st4_bf16(bf16* p, v4f o) { v2u w; w.x = cvt_pk_nv(o.x, o.y); w.y = cvt_pk_nv(o.z, o.w); *(v2u*)p = w; }
; template <int R, bool BASE_F32, bool OUT_F32>
; __device__ __forceinline__ void rows_res(const Ctx& C, int m0, int stride, int mx, const float* gpost, float scale, int lane) {
;     ...
;         for (int r = 0; r < R; ++r) t[r] = wave_sum(t[r]) * (1.f / DM) + EPS;
; #pragma unroll
;         for (int r = 0; r < R; ++r) { const float rstd = rsqrtf(t[r]);
; #pragma unroll
;             for (int j = 0; j < 4; ++j) if (ok[r]) st4_bf16(XN + (size_t)mr[r] * DM + 4 * lane + 256 * j, d[r][j] * rstd);
.LBB0_397:
	s_or_b64 exec, exec, s[30:31]
	s_waitcnt lgkmcnt(0)
	v_add_f32_e32 v14, v28, v29
	v_mov_b32_e32 v3, 0x358637bd
	s_andn2_b64 vcc, exec, s[28:29]
	v_fmac_f32_e32 v3, 0x3a800000, v14
	s_cbranch_vccnz .LBB0_399
	s_mov_b32 s0, 0x800000
	v_mul_f32_e32 v14, 0x4b800000, v3
	v_cmp_gt_f32_e32 vcc, s0, v3
	s_lshl_b64 s[0:1], s[22:23], 11
	v_lshl_add_u64 v[16:17], v[4:5], 0, s[0:1]
	v_cndmask_b32_e32 v14, v3, v14, vcc
	v_rsq_f32_e32 v14, v14
	s_nop 0
	v_mul_f32_e32 v15, 0x45800000, v14
	v_cndmask_b32_e32 v14, v14, v15, vcc
	v_pk_mul_f32 v[26:27], v[76:77], v[14:15] op_sel_hi:[1,0]
	v_pk_mul_f32 v[24:25], v[72:73], v[14:15] op_sel_hi:[1,0]
	v_cvt_pk_bf16_f32 v26, v26, v27
	v_pk_mul_f32 v[12:13], v[12:13], v[14:15] op_sel_hi:[1,0]
	v_cvt_pk_bf16_f32 v27, v24, v25
	global_store_dwordx2 v[16:17], v[26:27], off
	v_pk_mul_f32 v[26:27], v[88:89], v[14:15] op_sel_hi:[1,0]
	v_pk_mul_f32 v[24:25], v[86:87], v[14:15] op_sel_hi:[1,0]
	v_cvt_pk_bf16_f32 v26, v26, v27
	v_pk_mul_f32 v[10:11], v[10:11], v[14:15] op_sel_hi:[1,0]
	v_cvt_pk_bf16_f32 v27, v24, v25
	global_store_dwordx2 v[16:17], v[26:27], off offset:512
	v_pk_mul_f32 v[26:27], v[74:75], v[14:15] op_sel_hi:[1,0]
	v_pk_mul_f32 v[24:25], v[70:71], v[14:15] op_sel_hi:[1,0]
	v_cvt_pk_bf16_f32 v26, v26, v27
	v_cvt_pk_bf16_f32 v12, v12, v13
	v_cvt_pk_bf16_f32 v13, v10, v11
	global_store_dwordx2 v[16:17], v[12:13], off offset:1536
	v_cvt_pk_bf16_f32 v27, v24, v25
	global_store_dwordx2 v[16:17], v[26:27], off offset:1024

; __device__ __forceinline__ const float* xrow_ptr(const Ctx& C, int row) { return row < MPROMPT ? C.in(0) + (size_t)row * DM : C.in(1) + (size_t)(row - MPROMPT) * DM; }
; __device__ __forceinline__ v4f ld4_bf16(const bf16* p) { const v2u w = *(const v2u*)p; return (v4f){bf_lo(w.x), bf_hi(w.x), bf_lo(w.y), bf_hi(w.y)}; }
; template <int R, bool BASE_F32, bool OUT_F32>
; __device__ __forceinline__ void rows_res(const Ctx& C, int m0, int stride, int mx, const float* gpost, float scale, int lane) {
;     ...
;     for (int r = 0; r < R; ++r) { mr[r] = (r == 4) ? mx : m0 + r * stride; ok[r] = (r == 4) ? (mx < M) : (mr[r] < MPROMPT); const int mm = ok[r] ? mr[r] : 0;
; #pragma unroll
;         for (int j = 0; j < 4; ++j) d[r][j] = ld4_bf16(D + (size_t)mm * DM + 4 * lane + 256 * j);
;         if (BASE_F32) { const float* x = xrow_ptr(C, mm);
; #pragma unroll
;             for (int j = 0; j < 4; ++j) b[r][j] = ld4_f32(x + 4 * lane + 256 * j);
;         } else { const float inv = C.RS()[mm];
; #pragma unroll
;             for (int j = 0; j < 4; ++j) b[r][j] = ld4_bf16(XN + (size_t)mm * DM + 4 * lane + 256 * j) * inv;
;         } }
.LBB0_408:
	s_mov_b64 s[10:11], s[80:81]
	s_load_dwordx2 s[78:79], s[10:11], 0x110
	s_mov_b64 s[10:11], s[80:81]
	s_mov_b64 s[42:43], s[80:81]
	s_load_dwordx2 s[10:11], s[10:11], 0x110
	s_waitcnt lgkmcnt(0)
	v_lshl_add_u64 v[8:9], s[78:79], 0, v[0:1]
	v_lshl_add_u64 v[10:11], v[8:9], 0, s[52:53]
	v_lshl_add_u64 v[12:13], v[10:11], 0, s[14:15]
	s_mov_b64 s[42:43], s[80:81]
	global_load_dwordx2 v[102:103], v[12:13], off
	global_load_dwordx2 v[94:95], v[12:13], off offset:512
	global_load_dwordx2 v[100:101], v[12:13], off offset:1024
	global_load_dwordx2 v[22:23], v[12:13], off offset:1536
	s_load_dwordx2 s[42:43], s[42:43], 0x110
	v_lshl_add_u64 v[8:9], s[10:11], 0, v[0:1]
	v_lshl_add_u64 v[8:9], v[8:9], 0, s[54:55]
	v_lshl_add_u64 v[14:15], v[8:9], 0, s[14:15]
	global_load_dwordx2 v[24:25], v[14:15], off
	global_load_dwordx2 v[26:27], v[14:15], off offset:512
	global_load_dwordx2 v[28:29], v[14:15], off offset:1024
	s_waitcnt lgkmcnt(0)
	s_add_u32 s42, s42, s56
	s_addc_u32 s43, s43, s57
	global_load_dword v12, v39, s[42:43]
	global_load_dwordx2 v[30:31], v[14:15], off offset:1536
	v_lshl_add_u64 v[14:15], v[10:11], 0, s[18:19]
	s_mov_b64 s[42:43], s[80:81]
	global_load_dwordx2 v[110:111], v[14:15], off
	global_load_dwordx2 v[106:107], v[14:15], off offset:512
	global_load_dwordx2 v[108:109], v[14:15], off offset:1024
	global_load_dwordx2 v[32:33], v[14:15], off offset:1536
	v_lshl_add_u64 v[14:15], v[8:9], 0, s[18:19]
	global_load_dwordx2 v[34:35], v[14:15], off
	global_load_dwordx2 v[36:37], v[14:15], off offset:512
	s_load_dwordx2 s[42:43], s[42:43], 0x110
	s_mov_b64 s[70:71], s[80:81]
	v_lshl_add_u64 v[10:11], v[10:11], 0, s[22:23]
	v_lshl_add_u64 v[16:17], v[8:9], 0, s[22:23]
	global_load_dwordx2 v[40:41], v[14:15], off offset:1024
	global_load_dwordx2 v[42:43], v[14:15], off offset:1536
	s_waitcnt lgkmcnt(0)
	s_add_u32 s42, s42, s58
	s_addc_u32 s43, s43, s59
	global_load_dwordx2 v[122:123], v[10:11], off
	global_load_dwordx2 v[118:119], v[10:11], off offset:512
	global_load_dwordx2 v[120:121], v[10:11], off offset:1024
	global_load_dwordx2 v[44:45], v[10:11], off offset:1536
	global_load_dword v14, v39, s[42:43]
	global_load_dwordx2 v[46:47], v[16:17], off
	global_load_dwordx2 v[48:49], v[16:17], off offset:512
	global_load_dwordx2 v[66:67], v[16:17], off offset:1024
	v_lshl_add_u64 v[18:19], s[78:79], 0, v[4:5]
	v_lshl_add_u64 v[10:11], s[10:11], 0, v[4:5]
	global_load_dwordx2 v[74:75], v[16:17], off offset:1536
	global_load_dwordx2 v[140:141], v[18:19], off offset:-1536
	global_load_dwordx2 v[136:137], v[18:19], off offset:-1024
	global_load_dwordx2 v[138:139], v[18:19], off offset:-512
	global_load_dwordx2 v[78:79], v[18:19], off
	s_load_dwordx2 s[10:11], s[70:71], 0x110
	v_add_co_u32_e32 v82, vcc, s47, v10
	s_mov_b64 s[42:43], s[80:81]
	s_nop 0
	v_addc_co_u32_e32 v83, vcc, -1, v11, vcc
	s_waitcnt lgkmcnt(0)
	s_add_u32 s10, s10, s60
	s_addc_u32 s11, s11, s61
	global_load_dword v16, v39, s[10:11]
	global_load_dwordx2 v[84:85], v[82:83], off offset:-1536
	global_load_dwordx2 v[104:105], v[82:83], off offset:-1024
	global_load_dwordx2 v[112:113], v[82:83], off offset:-512
	s_load_dwordx2 s[10:11], s[42:43], 0x110
	s_waitcnt lgkmcnt(0)
	s_add_u32 s10, s10, s87
	s_addc_u32 s11, s11, s88
	global_load_dword v38, v1, s[10:11]
	global_load_dwordx2 v[134:135], v[82:83], off
	s_waitcnt vmcnt(35)
	v_and_b32_e32 v117, 0xffff0000, v103
	v_and_b32_e32 v115, 0xffff0000, v102
	v_lshlrev_b32_e32 v116, 16, v103
	s_waitcnt vmcnt(32)
	v_and_b32_e32 v19, 0xffff0000, v22
	v_mul_f32_e32 v18, v117, v117
	v_lshlrev_b32_e32 v114, 16, v102
	v_lshlrev_b32_e32 v21, 16, v22
	v_lshlrev_b32_e32 v103, 16, v95
	v_lshlrev_b32_e32 v102, 16, v94
	v_mov_b32_e32 v129, v21
	s_waitcnt vmcnt(30)
	v_lshlrev_b32_e32 v68, 16, v27
	v_and_b32_e32 v69, 0xffff0000, v27
	s_waitcnt vmcnt(29)
	v_lshlrev_b32_e32 v50, 16, v28
	v_and_b32_e32 v51, 0xffff0000, v28
	v_lshlrev_b32_e32 v52, 16, v29
	v_and_b32_e32 v53, 0xffff0000, v29
	v_lshlrev_b32_e32 v64, 16, v26
	s_waitcnt vmcnt(23)
	v_lshlrev_b32_e32 v27, 16, v32
	v_and_b32_e32 v13, 0xffff0000, v32
	v_lshlrev_b32_e32 v28, 16, v33
	v_and_b32_e32 v29, 0xffff0000, v33
	s_waitcnt vmcnt(21)
	v_lshlrev_b32_e32 v70, 16, v36
	v_and_b32_e32 v71, 0xffff0000, v36
	v_lshlrev_b32_e32 v72, 16, v37
	v_and_b32_e32 v73, 0xffff0000, v37
	s_waitcnt vmcnt(20)
	v_lshlrev_b32_e32 v54, 16, v40
	v_and_b32_e32 v55, 0xffff0000, v40
	v_lshlrev_b32_e32 v56, 16, v41
	v_and_b32_e32 v57, 0xffff0000, v41
	s_waitcnt vmcnt(19)
	v_lshlrev_b32_e32 v32, 16, v42
	v_and_b32_e32 v33, 0xffff0000, v42
	v_lshlrev_b32_e32 v40, 16, v43
	v_and_b32_e32 v41, 0xffff0000, v43
	s_waitcnt vmcnt(15)
	v_lshlrev_b32_e32 v36, 16, v45
	v_and_b32_e32 v37, 0xffff0000, v45
	s_waitcnt vmcnt(13)
	v_lshlrev_b32_e32 v86, 16, v46
	v_and_b32_e32 v87, 0xffff0000, v46
	v_lshlrev_b32_e32 v88, 16, v47
	v_and_b32_e32 v89, 0xffff0000, v47
	s_waitcnt vmcnt(12)
	v_lshlrev_b32_e32 v76, 16, v48
	v_and_b32_e32 v77, 0xffff0000, v48
	v_lshlrev_b32_e32 v80, 16, v49
	v_and_b32_e32 v81, 0xffff0000, v49
	s_waitcnt vmcnt(10)
	v_lshlrev_b32_e32 v42, 16, v74
	v_and_b32_e32 v43, 0xffff0000, v74
	v_lshlrev_b32_e32 v48, 16, v75
	v_and_b32_e32 v49, 0xffff0000, v75
	s_waitcnt vmcnt(6)
	v_lshlrev_b32_e32 v45, 16, v78
	v_and_b32_e32 v17, 0xffff0000, v78
	v_lshlrev_b32_e32 v46, 16, v79
	v_and_b32_e32 v47, 0xffff0000, v79
	s_waitcnt vmcnt(4)
	v_lshlrev_b32_e32 v96, 16, v84
	v_and_b32_e32 v97, 0xffff0000, v84
	v_lshlrev_b32_e32 v98, 16, v85
	v_and_b32_e32 v99, 0xffff0000, v85
	s_waitcnt vmcnt(3)
	v_lshlrev_b32_e32 v82, 16, v104
	v_and_b32_e32 v83, 0xffff0000, v104
	v_lshlrev_b32_e32 v84, 16, v105
	v_and_b32_e32 v85, 0xffff0000, v105
	s_waitcnt vmcnt(2)
; __device__ __forceinline__ v4f ld4_bf16(const bf16* p) { const v2u w = *(const v2u*)p; return (v4f){bf_lo(w.x), bf_hi(w.x), bf_lo(w.y), bf_hi(w.y)}; }
; __device__ __forceinline__ float ssq4(v4f v) { return (v.x * v.x + v.y * v.y) + (v.z * v.z + v.w * v.w); }
; __device__ __forceinline__ float wave_sum(float v) {
; #pragma unroll
;     for (int o = 1; o < 64; o <<= 1) v += __shfl_xor(v, o);
;     return v;
; }
; template <int R, bool BASE_F32, bool OUT_F32>
; __device__ __forceinline__ void rows_res(const Ctx& C, int m0, int stride, int mx, const float* gpost, float scale, int lane) {
;     ...
;             for (int j = 0; j < 4; ++j) b[r][j] = ld4_bf16(XN + (size_t)mm * DM + 4 * lane + 256 * j) * inv;
;         } }
; #pragma unroll
;     for (int r = 0; r < R; ++r) { float s = 0.f;
; #pragma unroll
;         for (int j = 0; j < 4; ++j) s += ssq4(d[r][j]);
;         r1[r] = s; }
; #pragma unroll
;     for (int r = 0; r < R; ++r) r1[r] = rsqrtf(wave_sum(r1[r]) * (1.f / DM) + EPS) * scale;
	v_lshlrev_b32_e32 v74, 16, v112
	v_and_b32_e32 v75, 0xffff0000, v112
	v_lshlrev_b32_e32 v78, 16, v113
	v_and_b32_e32 v79, 0xffff0000, v113
	v_pk_fma_f32 v[112:113], v[116:117], v[116:117], v[18:19] op_sel_hi:[1,1,0]
	v_and_b32_e32 v105, 0xffff0000, v95
	v_and_b32_e32 v104, 0xffff0000, v94
	v_mul_f32_e32 v18, v115, v115
	v_pk_mul_f32 v[94:95], v[104:105], v[104:105]
	v_pk_fma_f32 v[126:127], v[114:115], v[114:115], v[18:19] op_sel_hi:[1,1,0]
	v_pk_fma_f32 v[124:125], v[102:103], v[102:103], v[94:95]
	v_mov_b32_e32 v20, v126
	v_mov_b32_e32 v128, v112
	v_and_b32_e32 v65, 0xffff0000, v26
	v_and_b32_e32 v95, 0xffff0000, v100
	v_mul_f32_e32 v26, v19, v19
	v_pk_add_f32 v[112:113], v[126:127], v[112:113]
	v_pk_mul_f32 v[126:127], v[20:21], v[128:129]
	v_pk_add_f32 v[124:125], v[124:125], v[124:125] op_sel:[0,1] op_sel_hi:[1,0]
	v_lshlrev_b32_e32 v94, 16, v100
	v_lshlrev_b32_e32 v100, 16, v101
	v_and_b32_e32 v101, 0xffff0000, v101
	v_mov_b32_e32 v113, v127
	v_mov_b32_e32 v125, v26
	v_mul_f32_e32 v18, v95, v95
	v_lshlrev_b32_e32 v22, 16, v23
	v_and_b32_e32 v23, 0xffff0000, v23
	v_pk_add_f32 v[112:113], v[112:113], v[124:125]
	v_pk_fma_f32 v[124:125], v[94:95], v[94:95], v[18:19] op_sel_hi:[1,1,0]
	v_mul_f32_e32 v18, v101, v101
	v_lshlrev_b32_e32 v58, 16, v34
	v_and_b32_e32 v59, 0xffff0000, v34
	v_lshlrev_b32_e32 v60, 16, v35
	v_and_b32_e32 v61, 0xffff0000, v35
	v_lshlrev_b32_e32 v35, 16, v44
	v_and_b32_e32 v15, 0xffff0000, v44
	v_mul_f32_e32 v34, v22, v22
	v_mul_f32_e32 v44, v23, v23
	v_pk_fma_f32 v[126:127], v[100:101], v[100:101], v[18:19] op_sel_hi:[1,1,0]
	v_mov_b32_e32 v125, v34
	v_mov_b32_e32 v127, v44
	v_and_b32_e32 v129, 0xffff0000, v111
	v_pk_add_f32 v[124:125], v[124:125], v[126:127]
	v_and_b32_e32 v127, 0xffff0000, v110
	v_lshlrev_b32_e32 v128, 16, v111
	v_mul_f32_e32 v18, v129, v129
	v_pk_add_f32 v[148:149], v[112:113], v[124:125]
	v_lshlrev_b32_e32 v126, 16, v110
	v_pk_fma_f32 v[124:125], v[128:129], v[128:129], v[18:19] op_sel_hi:[1,1,0]
	v_and_b32_e32 v113, 0xffff0000, v107
	v_and_b32_e32 v112, 0xffff0000, v106
	v_mul_f32_e32 v18, v127, v127
	v_lshlrev_b32_e32 v111, 16, v107
	v_lshlrev_b32_e32 v110, 16, v106
	v_pk_mul_f32 v[106:107], v[112:113], v[112:113]
	v_pk_fma_f32 v[132:133], v[126:127], v[126:127], v[18:19] op_sel_hi:[1,1,0]
	v_pk_fma_f32 v[130:131], v[110:111], v[110:111], v[106:107]
	v_mov_b32_e32 v26, v132
	v_mov_b32_e32 v142, v124
	v_mov_b32_e32 v143, v27
	v_and_b32_e32 v107, 0xffff0000, v108
	v_mul_f32_e32 v20, v13, v13
	v_pk_add_f32 v[124:125], v[132:133], v[124:125]
	v_pk_mul_f32 v[132:133], v[26:27], v[142:143]
	v_pk_add_f32 v[130:131], v[130:131], v[130:131] op_sel:[0,1] op_sel_hi:[1,0]
	v_lshlrev_b32_e32 v106, 16, v108
	v_lshlrev_b32_e32 v108, 16, v109
	v_and_b32_e32 v109, 0xffff0000, v109
	v_mov_b32_e32 v125, v133
	v_mov_b32_e32 v131, v20
	v_mul_f32_e32 v18, v107, v107
	v_pk_add_f32 v[124:125], v[124:125], v[130:131]
	v_pk_fma_f32 v[130:131], v[106:107], v[106:107], v[18:19] op_sel_hi:[1,1,0]
	v_mul_f32_e32 v18, v109, v109
	v_mul_f32_e32 v34, v28, v28
	v_mul_f32_e32 v44, v29, v29
	v_pk_fma_f32 v[132:133], v[108:109], v[108:109], v[18:19] op_sel_hi:[1,1,0]
	v_mov_b32_e32 v131, v34
	v_mov_b32_e32 v133, v44
	v_pk_add_f32 v[130:131], v[130:131], v[132:133]
	v_and_b32_e32 v133, 0xffff0000, v123
	v_pk_add_f32 v[152:153], v[124:125], v[130:131]
	v_and_b32_e32 v131, 0xffff0000, v122
	v_lshlrev_b32_e32 v132, 16, v123
	v_mul_f32_e32 v18, v133, v133
	v_lshlrev_b32_e32 v130, 16, v122
	v_pk_fma_f32 v[142:143], v[132:133], v[132:133], v[18:19] op_sel_hi:[1,1,0]
	v_and_b32_e32 v125, 0xffff0000, v119
	v_and_b32_e32 v124, 0xffff0000, v118
	v_mul_f32_e32 v18, v131, v131
	v_lshlrev_b32_e32 v123, 16, v119
	v_lshlrev_b32_e32 v122, 16, v118
	v_pk_mul_f32 v[118:119], v[124:125], v[124:125]
	v_pk_fma_f32 v[146:147], v[130:131], v[130:131], v[18:19] op_sel_hi:[1,1,0]
	v_pk_fma_f32 v[144:145], v[122:123], v[122:123], v[118:119]
	v_mov_b32_e32 v34, v146
	v_mov_b32_e32 v154, v142
	v_mov_b32_e32 v155, v35
	v_mov_b32_e32 v162, v152
	v_mov_b32_e32 v163, v148
	v_mov_b32_e32 v148, v153
	v_and_b32_e32 v119, 0xffff0000, v120
	v_mul_f32_e32 v20, v15, v15
	v_pk_add_f32 v[142:143], v[146:147], v[142:143]
	v_pk_mul_f32 v[146:147], v[34:35], v[154:155]
	v_pk_add_f32 v[144:145], v[144:145], v[144:145] op_sel:[0,1] op_sel_hi:[1,0]
	v_pk_add_f32 v[148:149], v[162:163], v[148:149]
	v_lshlrev_b32_e32 v118, 16, v120
	v_lshlrev_b32_e32 v120, 16, v121
	v_and_b32_e32 v121, 0xffff0000, v121
	v_mov_b32_e32 v143, v147
	v_mov_b32_e32 v145, v20
	v_mul_f32_e32 v18, v119, v119
	s_nop 1
	v_mov_b32_dpp v153, v149 quad_perm:[1,0,3,2] row_mask:0xf bank_mask:0xf
	s_nop 1
	v_mov_b32_dpp v152, v148 quad_perm:[1,0,3,2] row_mask:0xf bank_mask:0xf
	v_pk_add_f32 v[142:143], v[142:143], v[144:145]
	v_pk_fma_f32 v[144:145], v[118:119], v[118:119], v[18:19] op_sel_hi:[1,1,0]
	v_mul_f32_e32 v18, v121, v121
	v_mul_f32_e32 v26, v36, v36
	v_mul_f32_e32 v44, v37, v37
	v_pk_fma_f32 v[146:147], v[120:121], v[120:121], v[18:19] op_sel_hi:[1,1,0]
	v_mov_b32_e32 v145, v26
	v_mov_b32_e32 v147, v44
	v_pk_add_f32 v[144:145], v[144:145], v[146:147]
	v_and_b32_e32 v147, 0xffff0000, v141
	v_pk_add_f32 v[156:157], v[142:143], v[144:145]
	v_and_b32_e32 v145, 0xffff0000, v140
	v_lshlrev_b32_e32 v146, 16, v141
	v_mul_f32_e32 v18, v147, v147
	s_waitcnt lgkmcnt(0)
; __device__ __forceinline__ float wave_sum(float v) {
; #pragma unroll
;     for (int o = 1; o < 64; o <<= 1) v += __shfl_xor(v, o);
;     return v;
; }
; template <int R, bool BASE_F32, bool OUT_F32>
; __device__ __forceinline__ void rows_res(const Ctx& C, int m0, int stride, int mx, const float* gpost, float scale, int lane) {
;     ...
;     for (int r = 0; r < R; ++r) r1[r] = rsqrtf(wave_sum(r1[r]) * (1.f / DM) + EPS) * scale;
; #pragma unroll
;     for (int j = 0; j < 4; ++j) { const v4f gp = ld4_f32(gpost + 4 * lane + 256 * j);
; #pragma unroll
;         for (int r = 0; r < R; ++r) d[r][j] = b[r][j] + d[r][j] * r1[r] * gp; }
	v_pk_add_f32 v[148:149], v[148:149], v[152:153]
	v_lshlrev_b32_e32 v144, 16, v140
	v_pk_fma_f32 v[154:155], v[146:147], v[146:147], v[18:19] op_sel_hi:[1,1,0]
	v_and_b32_e32 v143, 0xffff0000, v137
	v_and_b32_e32 v142, 0xffff0000, v136
	v_mul_f32_e32 v18, v145, v145
	s_nop 1
	v_mov_b32_dpp v153, v149 quad_perm:[2,3,0,1] row_mask:0xf bank_mask:0xf
	s_nop 1
	v_mov_b32_dpp v152, v148 quad_perm:[2,3,0,1] row_mask:0xf bank_mask:0xf
	v_lshlrev_b32_e32 v141, 16, v137
	v_lshlrev_b32_e32 v140, 16, v136
	v_pk_mul_f32 v[136:137], v[142:143], v[142:143]
	v_pk_fma_f32 v[160:161], v[144:145], v[144:145], v[18:19] op_sel_hi:[1,1,0]
	v_pk_fma_f32 v[158:159], v[140:141], v[140:141], v[136:137]
	v_mov_b32_e32 v44, v160
	v_mov_b32_e32 v162, v154
	v_mov_b32_e32 v163, v45
	v_mul_f32_e32 v20, v17, v17
	v_pk_add_f32 v[154:155], v[160:161], v[154:155]
	v_pk_mul_f32 v[160:161], v[44:45], v[162:163]
	v_pk_add_f32 v[158:159], v[158:159], v[158:159] op_sel:[0,1] op_sel_hi:[1,0]
	v_mov_b32_e32 v155, v161
	v_mov_b32_e32 v159, v20
	v_pk_add_f32 v[158:159], v[154:155], v[158:159]
	s_waitcnt lgkmcnt(0)
	v_pk_add_f32 v[148:149], v[148:149], v[152:153]
	global_load_dwordx4 v[152:155], v[2:3], off
	s_nop 1
	v_mov_b32_dpp v161, v149 row_half_mirror row_mask:0xf bank_mask:0xf
	s_nop 1
	v_mov_b32_dpp v160, v148 row_half_mirror row_mask:0xf bank_mask:0xf
	v_and_b32_e32 v137, 0xffff0000, v138
	v_lshlrev_b32_e32 v136, 16, v138
	v_lshlrev_b32_e32 v138, 16, v139
	v_and_b32_e32 v139, 0xffff0000, v139
	v_mul_f32_e32 v18, v137, v137
	s_waitcnt lgkmcnt(0)
	v_pk_add_f32 v[148:149], v[148:149], v[160:161]
	v_pk_fma_f32 v[162:163], v[136:137], v[136:137], v[18:19] op_sel_hi:[1,1,0]
	v_mul_f32_e32 v18, v139, v139
	s_nop 1
	v_mov_b32_dpp v161, v149 row_mirror row_mask:0xf bank_mask:0xf
	s_nop 1
	v_mov_b32_dpp v160, v148 row_mirror row_mask:0xf bank_mask:0xf
	v_mul_f32_e32 v26, v46, v46
	v_mul_f32_e32 v34, v47, v47
	v_pk_fma_f32 v[164:165], v[138:139], v[138:139], v[18:19] op_sel_hi:[1,1,0]
	v_mov_b32_e32 v163, v26
	v_mov_b32_e32 v165, v34
	v_pk_add_f32 v[162:163], v[162:163], v[164:165]
	s_waitcnt lgkmcnt(0)
	v_pk_add_f32 v[160:161], v[148:149], v[160:161]
	v_pk_add_f32 v[158:159], v[158:159], v[162:163]
	v_mov_b32_e32 v149, v156
	v_mov_b32_e32 v148, v158
	v_mov_b32_e32 v156, v159
	v_pk_add_f32 v[156:157], v[148:149], v[156:157]
	ds_bpermute_b32 v163, v187, v161
	ds_bpermute_b32 v162, v187, v160
	s_nop 1
	v_mov_b32_dpp v159, v157 quad_perm:[1,0,3,2] row_mask:0xf bank_mask:0xf
	s_nop 1
	v_mov_b32_dpp v158, v156 quad_perm:[1,0,3,2] row_mask:0xf bank_mask:0xf
	v_lshlrev_b32_e32 v90, 16, v24
	v_and_b32_e32 v91, 0xffff0000, v24
	s_waitcnt lgkmcnt(0)
	v_pk_add_f32 v[160:161], v[160:161], v[162:163]
	ds_bpermute_b32 v163, v188, v161
	s_waitcnt lgkmcnt(0)
	v_pk_add_f32 v[164:165], v[156:157], v[158:159]
	ds_bpermute_b32 v162, v188, v160
	s_nop 1
	v_mov_b32_dpp v167, v165 quad_perm:[2,3,0,1] row_mask:0xf bank_mask:0xf
	s_nop 1
	v_mov_b32_dpp v166, v164 quad_perm:[2,3,0,1] row_mask:0xf bank_mask:0xf
	global_load_dwordx4 v[156:159], v[2:3], off offset:1024
	v_lshlrev_b32_e32 v92, 16, v25
	s_waitcnt lgkmcnt(0)
	v_pk_add_f32 v[160:161], v[160:161], v[162:163]
	v_and_b32_e32 v93, 0xffff0000, v25
	s_waitcnt lgkmcnt(0)
	v_pk_add_f32 v[162:163], v[164:165], v[166:167]
	s_nop 1
	v_mov_b32_dpp v165, v163 row_half_mirror row_mask:0xf bank_mask:0xf
	s_nop 1
	v_mov_b32_dpp v164, v162 row_half_mirror row_mask:0xf bank_mask:0xf
	v_pk_fma_f32 v[160:161], v[160:161], s[0:1], v[6:7] op_sel_hi:[1,0,0]
	v_lshlrev_b32_e32 v24, 16, v30
	v_mul_f32_e32 v18, 0x4b800000, v161
	v_cmp_gt_f32_e32 vcc, s89, v161
	s_waitcnt lgkmcnt(0)
	v_pk_add_f32 v[162:163], v[162:163], v[164:165]
	s_nop 1
	v_mov_b32_dpp v165, v163 row_mirror row_mask:0xf bank_mask:0xf
	s_nop 1
	v_mov_b32_dpp v164, v162 row_mirror row_mask:0xf bank_mask:0xf
	v_cndmask_b32_e32 v18, v161, v18, vcc
	v_rsq_f32_e32 v18, v18
	v_and_b32_e32 v25, 0xffff0000, v30
	v_lshlrev_b32_e32 v30, 16, v31
	s_waitcnt lgkmcnt(0)
	v_pk_add_f32 v[162:163], v[162:163], v[164:165]
	ds_bpermute_b32 v165, v187, v163
	ds_bpermute_b32 v164, v187, v162
	v_mul_f32_e32 v20, 0x45800000, v18
	v_cndmask_b32_e32 v18, v18, v20, vcc
	v_mul_f32_e32 v20, 0.5, v18
	v_mul_f32_e32 v18, 0x4b800000, v160
	v_cmp_gt_f32_e32 vcc, s89, v160
	s_waitcnt lgkmcnt(0)
	v_pk_add_f32 v[164:165], v[162:163], v[164:165]
	ds_bpermute_b32 v167, v188, v165
	v_cndmask_b32_e32 v18, v160, v18, vcc
	ds_bpermute_b32 v166, v188, v164
	v_rsq_f32_e32 v18, v18
	global_load_dwordx4 v[160:163], v[2:3], off offset:2048
	v_pk_mul_f32 v[116:117], v[20:21], v[116:117] op_sel_hi:[0,1]
	v_pk_mul_f32 v[114:115], v[20:21], v[114:115] op_sel_hi:[0,1]
	v_mul_f32_e32 v26, 0x45800000, v18
	s_waitcnt lgkmcnt(0)
	v_pk_add_f32 v[164:165], v[164:165], v[166:167]
	v_cndmask_b32_e32 v18, v18, v26, vcc
	v_pk_fma_f32 v[164:165], v[164:165], s[0:1], v[6:7] op_sel_hi:[1,0,0]
	v_mul_f32_e32 v26, 0.5, v18
	v_mul_f32_e32 v18, 0x4b800000, v165
	v_cmp_gt_f32_e32 vcc, s89, v165
	v_mul_f32_e32 v34, 0x4b800000, v164
	v_cmp_gt_f32_e64 s[10:11], s89, v164
	v_cndmask_b32_e32 v18, v165, v18, vcc
	v_rsq_f32_e32 v18, v18
	v_cndmask_b32_e64 v34, v164, v34, s[10:11]
	s_waitcnt vmcnt(2)
; template <int R, bool BASE_F32, bool OUT_F32>
; __device__ __forceinline__ void rows_res(const Ctx& C, int m0, int stride, int mx, const float* gpost, float scale, int lane) {
;     ...
;     for (int r = 0; r < R; ++r) r1[r] = rsqrtf(wave_sum(r1[r]) * (1.f / DM) + EPS) * scale;
; #pragma unroll
;     for (int j = 0; j < 4; ++j) { const v4f gp = ld4_f32(gpost + 4 * lane + 256 * j);
; #pragma unroll
;         for (int r = 0; r < R; ++r) d[r][j] = b[r][j] + d[r][j] * r1[r] * gp; }
	v_pk_mul_f32 v[164:165], v[114:115], v[152:153]
	v_pk_mul_f32 v[114:115], v[116:117], v[154:155]
	v_pk_fma_f32 v[116:117], v[12:13], v[90:91], v[164:165] op_sel_hi:[0,1,1]
	v_pk_fma_f32 v[114:115], v[12:13], v[92:93], v[114:115] op_sel_hi:[0,1,1]
	v_pk_mul_f32 v[90:91], v[26:27], v[128:129] op_sel_hi:[0,1]
	v_pk_mul_f32 v[92:93], v[26:27], v[126:127] op_sel_hi:[0,1]
	global_load_dwordx4 v[126:129], v[2:3], off offset:3072
	v_rsq_f32_e32 v44, v34
	v_mul_f32_e32 v34, 0x45800000, v18
	v_cndmask_b32_e32 v18, v18, v34, vcc
	v_mul_f32_e32 v34, 0.5, v18
	v_mul_f32_e32 v18, 0x45800000, v44
	v_pk_mul_f32 v[90:91], v[154:155], v[90:91]
	v_cndmask_b32_e64 v18, v44, v18, s[10:11]
	v_pk_mul_f32 v[92:93], v[152:153], v[92:93]
	v_pk_fma_f32 v[90:91], v[14:15], v[60:61], v[90:91] op_sel_hi:[0,1,1]
	v_pk_mul_f32 v[60:61], v[34:35], v[130:131] op_sel_hi:[0,1]
	v_mul_f32_e32 v44, 0.5, v18
	v_pk_fma_f32 v[92:93], v[14:15], v[58:59], v[92:93] op_sel_hi:[0,1,1]
	v_pk_mul_f32 v[58:59], v[34:35], v[132:133] op_sel_hi:[0,1]
	v_pk_mul_f32 v[60:61], v[152:153], v[60:61]
	v_pk_mul_f32 v[58:59], v[154:155], v[58:59]
	v_pk_fma_f32 v[86:87], v[16:17], v[86:87], v[60:61] op_sel_hi:[0,1,1]
	v_pk_mul_f32 v[60:61], v[44:45], v[144:145] op_sel_hi:[0,1]
	v_pk_fma_f32 v[88:89], v[16:17], v[88:89], v[58:59] op_sel_hi:[0,1,1]
	v_pk_mul_f32 v[58:59], v[44:45], v[146:147] op_sel_hi:[0,1]
	v_pk_mul_f32 v[60:61], v[152:153], v[60:61]
	v_pk_mul_f32 v[58:59], v[154:155], v[58:59]
	v_pk_fma_f32 v[60:61], v[38:39], v[96:97], v[60:61] op_sel_hi:[0,1,1]
	v_mov_b32_e32 v96, v103
	v_mov_b32_e32 v103, v104
	v_pk_fma_f32 v[58:59], v[38:39], v[98:99], v[58:59] op_sel_hi:[0,1,1]
	v_pk_mul_f32 v[98:99], v[20:21], v[102:103] op_sel_hi:[0,1]
	v_mov_b32_e32 v97, v105
	s_waitcnt vmcnt(2)
	v_pk_mul_f32 v[98:99], v[98:99], v[156:157]
	v_pk_mul_f32 v[96:97], v[20:21], v[96:97] op_sel_hi:[0,1]
	v_pk_fma_f32 v[104:105], v[12:13], v[64:65], v[98:99] op_sel_hi:[0,1,1]
	v_mov_b32_e32 v64, v111
	v_mov_b32_e32 v65, v113
	v_pk_mul_f32 v[64:65], v[26:27], v[64:65] op_sel_hi:[0,1]
	v_pk_mul_f32 v[96:97], v[96:97], v[158:159]
	v_mov_b32_e32 v111, v112
	v_pk_mul_f32 v[64:65], v[64:65], v[158:159]
	v_pk_fma_f32 v[102:103], v[12:13], v[68:69], v[96:97] op_sel_hi:[0,1,1]
	v_pk_mul_f32 v[68:69], v[26:27], v[110:111] op_sel_hi:[0,1]
	v_pk_fma_f32 v[96:97], v[14:15], v[72:73], v[64:65] op_sel_hi:[0,1,1]
	v_mov_b32_e32 v64, v123
	v_mov_b32_e32 v65, v125
	v_pk_mul_f32 v[68:69], v[68:69], v[156:157]
	v_pk_mul_f32 v[64:65], v[34:35], v[64:65] op_sel_hi:[0,1]
	v_mov_b32_e32 v123, v124
	v_pk_fma_f32 v[98:99], v[14:15], v[70:71], v[68:69] op_sel_hi:[0,1,1]
	v_pk_mul_f32 v[68:69], v[34:35], v[122:123] op_sel_hi:[0,1]
	v_pk_mul_f32 v[64:65], v[158:159], v[64:65]
	v_pk_mul_f32 v[68:69], v[156:157], v[68:69]
	v_pk_fma_f32 v[70:71], v[16:17], v[80:81], v[64:65] op_sel_hi:[0,1,1]
	v_mov_b32_e32 v64, v141
	v_mov_b32_e32 v141, v142
	v_pk_fma_f32 v[72:73], v[16:17], v[76:77], v[68:69] op_sel_hi:[0,1,1]
	v_pk_mul_f32 v[68:69], v[44:45], v[140:141] op_sel_hi:[0,1]
	v_pk_mul_f32 v[76:77], v[20:21], v[100:101] op_sel_hi:[0,1]
	v_mov_b32_e32 v65, v143
	v_pk_mul_f32 v[68:69], v[156:157], v[68:69]
	v_pk_mul_f32 v[64:65], v[44:45], v[64:65] op_sel_hi:[0,1]
	v_pk_fma_f32 v[68:69], v[38:39], v[82:83], v[68:69] op_sel_hi:[0,1,1]
	s_waitcnt vmcnt(1)
	v_pk_mul_f32 v[76:77], v[76:77], v[162:163]
	v_pk_mul_f32 v[80:81], v[20:21], v[94:95] op_sel_hi:[0,1]
	v_pk_fma_f32 v[82:83], v[12:13], v[52:53], v[76:77] op_sel_hi:[0,1,1]
	v_pk_mul_f32 v[52:53], v[26:27], v[106:107] op_sel_hi:[0,1]
	v_pk_mul_f32 v[64:65], v[158:159], v[64:65]
	v_pk_mul_f32 v[80:81], v[80:81], v[160:161]
	v_pk_mul_f32 v[52:53], v[52:53], v[160:161]
	v_mov_b32_e32 v18, v21
	v_pk_fma_f32 v[64:65], v[38:39], v[84:85], v[64:65] op_sel_hi:[0,1,1]
	v_pk_fma_f32 v[84:85], v[12:13], v[50:51], v[80:81] op_sel_hi:[0,1,1]
	v_pk_mul_f32 v[50:51], v[26:27], v[108:109] op_sel_hi:[0,1]
	v_pk_fma_f32 v[80:81], v[14:15], v[54:55], v[52:53] op_sel_hi:[0,1,1]
	v_pk_mul_f32 v[52:53], v[34:35], v[118:119] op_sel_hi:[0,1]
	v_pk_mul_f32 v[22:23], v[20:21], v[22:23] op_sel_hi:[0,1]
	v_pk_mul_f32 v[18:19], v[20:21], v[18:19] op_sel_hi:[0,1]
	v_and_b32_e32 v31, 0xffff0000, v31
	v_lshlrev_b32_e32 v62, 16, v66
	v_and_b32_e32 v63, 0xffff0000, v66
	v_pk_mul_f32 v[50:51], v[50:51], v[162:163]
	v_pk_mul_f32 v[52:53], v[160:161], v[52:53]
	v_pk_fma_f32 v[76:77], v[14:15], v[56:57], v[50:51] op_sel_hi:[0,1,1]
	s_waitcnt vmcnt(0)
;     __device__ __forceinline__ float* out() const { return (float*)karg_in(33); }
; __device__ __forceinline__ float ssq4(v4f v) { return (v.x * v.x + v.y * v.y) + (v.z * v.z + v.w * v.w); }
; __device__ __forceinline__ float wave_sum(float v) {
; #pragma unroll
;     for (int o = 1; o < 64; o <<= 1) v += __shfl_xor(v, o);
;     return v;
; }
; template <int R, bool BASE_F32, bool OUT_F32>
; __device__ __forceinline__ void rows_res(const Ctx& C, int m0, int stride, int mx, const float* gpost, float scale, int lane) {
;     ...
;         for (int r = 0; r < R; ++r) d[r][j] = b[r][j] + d[r][j] * r1[r] * gp; }
;     if (OUT_F32) { float* Y = C.out();
; #pragma unroll
;         for (int r = 0; r < R; ++r)
; #pragma unroll
;             for (int j = 0; j < 4; ++j) if (ok[r]) *(v4f*)(Y + (size_t)mr[r] * DM + 4 * lane + 256 * j) = d[r][j];
;     } else { float* rs = C.RS(); float t[R];
; #pragma unroll
;         for (int r = 0; r < R; ++r) { float s = 0.f;
; #pragma unroll
;             for (int j = 0; j < 4; ++j) s += ssq4(d[r][j]);
;             t[r] = s; }
; #pragma unroll
;         for (int r = 0; r < R; ++r) t[r] = wave_sum(t[r]) * (1.f / DM) + EPS;
	v_pk_mul_f32 v[18:19], v[18:19], v[126:127]
	v_pk_mul_f32 v[20:21], v[22:23], v[128:129]
	v_pk_fma_f32 v[56:57], v[16:17], v[62:63], v[52:53] op_sel_hi:[0,1,1]
	v_pk_fma_f32 v[30:31], v[12:13], v[30:31], v[20:21] op_sel_hi:[0,1,1]
	v_pk_fma_f32 v[62:63], v[12:13], v[24:25], v[18:19] op_sel_hi:[0,1,1]
	v_mov_b32_e32 v12, v27
	v_pk_mul_f32 v[18:19], v[26:27], v[28:29] op_sel_hi:[0,1]
	v_pk_mul_f32 v[12:13], v[26:27], v[12:13] op_sel_hi:[0,1]
	v_pk_mul_f32 v[12:13], v[12:13], v[126:127]
	v_pk_mul_f32 v[18:19], v[18:19], v[128:129]
	v_pk_fma_f32 v[24:25], v[14:15], v[32:33], v[12:13] op_sel_hi:[0,1,1]
	v_pk_fma_f32 v[22:23], v[14:15], v[40:41], v[18:19] op_sel_hi:[0,1,1]
	v_mov_b32_e32 v14, v35
	v_pk_mul_f32 v[50:51], v[34:35], v[120:121] op_sel_hi:[0,1]
	v_pk_mul_f32 v[12:13], v[34:35], v[36:37] op_sel_hi:[0,1]
	v_pk_mul_f32 v[14:15], v[34:35], v[14:15] op_sel_hi:[0,1]
	v_lshlrev_b32_e32 v66, 16, v67
	v_and_b32_e32 v67, 0xffff0000, v67
	v_pk_mul_f32 v[50:51], v[162:163], v[50:51]
	v_pk_mul_f32 v[14:15], v[126:127], v[14:15]
	v_pk_mul_f32 v[12:13], v[128:129], v[12:13]
	v_pk_fma_f32 v[54:55], v[16:17], v[66:67], v[50:51] op_sel_hi:[0,1,1]
	v_pk_fma_f32 v[18:19], v[16:17], v[48:49], v[12:13] op_sel_hi:[0,1,1]
	v_pk_fma_f32 v[20:21], v[16:17], v[42:43], v[14:15] op_sel_hi:[0,1,1]
	v_mov_b32_e32 v16, v45
	v_pk_mul_f32 v[14:15], v[44:45], v[16:17] op_sel_hi:[0,1]
	v_mul_f32_e32 v16, v117, v117
	v_mul_f32_e32 v17, v115, v115
	v_fmac_f32_e32 v16, v116, v116
	v_fmac_f32_e32 v17, v114, v114
	v_add_f32_e32 v16, v16, v17
	v_mul_f32_e32 v17, v105, v105
	v_mul_f32_e32 v26, v103, v103
	v_fmac_f32_e32 v17, v104, v104
	v_fmac_f32_e32 v26, v102, v102
	v_add_f32_e32 v17, v17, v26
	v_add_f32_e32 v16, v16, v17
	v_mul_f32_e32 v17, v85, v85
	v_mul_f32_e32 v26, v83, v83
	v_fmac_f32_e32 v17, v84, v84
	v_fmac_f32_e32 v26, v82, v82
	v_add_f32_e32 v17, v17, v26
	v_add_f32_e32 v16, v16, v17
	v_mul_f32_e32 v17, v63, v63
	v_mul_f32_e32 v26, v31, v31
	v_fmac_f32_e32 v17, v62, v62
	v_fmac_f32_e32 v26, v30, v30
	v_add_f32_e32 v17, v17, v26
	v_add_f32_e32 v16, v16, v17
	v_mul_f32_e32 v17, v93, v93
	v_mul_f32_e32 v26, v91, v91
	v_fmac_f32_e32 v17, v92, v92
	v_fmac_f32_e32 v26, v90, v90
	v_add_f32_e32 v17, v17, v26
	v_mul_f32_e32 v26, v99, v99
	v_mul_f32_e32 v27, v97, v97
	v_fmac_f32_e32 v26, v98, v98
	v_fmac_f32_e32 v27, v96, v96
	v_add_f32_e32 v26, v26, v27
	v_add_f32_e32 v17, v17, v26
	v_mul_f32_e32 v26, v81, v81
	v_mul_f32_e32 v27, v77, v77
	s_nop 1
	v_mov_b32_dpp v29, v16 quad_perm:[1,0,3,2] row_mask:0xf bank_mask:0xf
	v_fmac_f32_e32 v26, v80, v80
	v_fmac_f32_e32 v27, v76, v76
	v_add_f32_e32 v26, v26, v27
	v_add_f32_e32 v17, v17, v26
	v_mul_f32_e32 v26, v25, v25
	v_mul_f32_e32 v27, v23, v23
	v_fmac_f32_e32 v26, v24, v24
	v_fmac_f32_e32 v27, v22, v22
	v_add_f32_e32 v26, v26, v27
	s_waitcnt lgkmcnt(0)
	v_add_f32_e32 v16, v16, v29
	v_add_f32_e32 v17, v17, v26
	v_mul_f32_e32 v26, v87, v87
	v_mul_f32_e32 v27, v89, v89
	s_nop 1
	v_mov_b32_dpp v29, v16 quad_perm:[2,3,0,1] row_mask:0xf bank_mask:0xf
	v_fmac_f32_e32 v26, v86, v86
	v_fmac_f32_e32 v27, v88, v88
	v_add_f32_e32 v26, v26, v27
	v_mul_f32_e32 v27, v73, v73
	v_mul_f32_e32 v28, v71, v71
	v_fmac_f32_e32 v27, v72, v72
	v_fmac_f32_e32 v28, v70, v70
	v_add_f32_e32 v27, v27, v28
	v_add_f32_e32 v26, v26, v27
	v_mul_f32_e32 v27, v57, v57
	v_mul_f32_e32 v28, v55, v55
	s_waitcnt lgkmcnt(0)
	v_add_f32_e32 v16, v16, v29
	v_fmac_f32_e32 v27, v56, v56
	v_fmac_f32_e32 v28, v54, v54
	s_nop 1
	v_mov_b32_dpp v29, v16 row_half_mirror row_mask:0xf bank_mask:0xf
	v_add_f32_e32 v27, v27, v28
	v_add_f32_e32 v26, v27, v26
	v_mul_f32_e32 v27, v21, v21
	v_mul_f32_e32 v28, v19, v19
	v_fmac_f32_e32 v27, v20, v20
	v_fmac_f32_e32 v28, v18, v18
	v_add_f32_e32 v27, v27, v28
	v_add_f32_e32 v26, v27, v26
	v_mul_f32_e32 v27, v61, v61
	v_mul_f32_e32 v28, v59, v59
	s_waitcnt lgkmcnt(0)
; __device__ __forceinline__ void st4_bf16(bf16* p, v4f o) { v2u w; w.x = cvt_pk_nv(o.x, o.y); w.y = cvt_pk_nv(o.z, o.w); *(v2u*)p = w; }
; __device__ __forceinline__ float ssq4(v4f v) { return (v.x * v.x + v.y * v.y) + (v.z * v.z + v.w * v.w); }
; __device__ __forceinline__ float wave_sum(float v) {
; #pragma unroll
;     for (int o = 1; o < 64; o <<= 1) v += __shfl_xor(v, o);
;     return v;
; }
; template <int R, bool BASE_F32, bool OUT_F32>
; __device__ __forceinline__ void rows_res(const Ctx& C, int m0, int stride, int mx, const float* gpost, float scale, int lane) {
;     ...
;     } else { float* rs = C.RS(); float t[R];
; #pragma unroll
;         for (int r = 0; r < R; ++r) { float s = 0.f;
; #pragma unroll
;             for (int j = 0; j < 4; ++j) s += ssq4(d[r][j]);
;             t[r] = s; }
; #pragma unroll
;         for (int r = 0; r < R; ++r) t[r] = wave_sum(t[r]) * (1.f / DM) + EPS;
; #pragma unroll
;         for (int r = 0; r < R; ++r) { const float rstd = rsqrtf(t[r]);
; #pragma unroll
;             for (int j = 0; j < 4; ++j) if (ok[r]) st4_bf16(XN + (size_t)mr[r] * DM + 4 * lane + 256 * j, d[r][j] * rstd);
;             if (lane == 0 && ok[r]) rs[mr[r]] = sqrtf(t[r]); }
	v_add_f32_e32 v16, v16, v29
	v_fmac_f32_e32 v27, v60, v60
	v_fmac_f32_e32 v28, v58, v58
	s_nop 1
	v_mov_b32_dpp v29, v16 row_mirror row_mask:0xf bank_mask:0xf
	v_pk_mul_f32 v[50:51], v[44:45], v[138:139] op_sel_hi:[0,1]
	v_pk_mul_f32 v[52:53], v[44:45], v[136:137] op_sel_hi:[0,1]
	v_add_f32_e32 v27, v27, v28
	v_mul_f32_e32 v28, v69, v69
	v_mul_f32_e32 v32, v65, v65
	v_pk_mul_f32 v[52:53], v[160:161], v[52:53]
	v_pk_mul_f32 v[50:51], v[162:163], v[50:51]
	v_fmac_f32_e32 v28, v68, v68
	v_fmac_f32_e32 v32, v64, v64
	v_pk_fma_f32 v[50:51], v[38:39], v[78:79], v[50:51] op_sel_hi:[0,1,1]
	v_pk_fma_f32 v[52:53], v[38:39], v[74:75], v[52:53] op_sel_hi:[0,1,1]
	v_add_f32_e32 v28, v28, v32
	v_pk_mul_f32 v[12:13], v[44:45], v[46:47] op_sel_hi:[0,1]
	v_add_f32_e32 v27, v27, v28
	v_mul_f32_e32 v28, v53, v53
	v_mul_f32_e32 v32, v51, v51
	v_lshlrev_b32_e32 v148, 16, v134
	v_and_b32_e32 v149, 0xffff0000, v134
	v_lshlrev_b32_e32 v134, 16, v135
	v_and_b32_e32 v135, 0xffff0000, v135
	v_pk_mul_f32 v[14:15], v[126:127], v[14:15]
	v_pk_mul_f32 v[12:13], v[128:129], v[12:13]
	v_fmac_f32_e32 v28, v52, v52
	v_fmac_f32_e32 v32, v50, v50
	s_waitcnt lgkmcnt(0)
	v_add_f32_e32 v16, v16, v29
	v_pk_fma_f32 v[12:13], v[38:39], v[134:135], v[12:13] op_sel_hi:[0,1,1]
	v_pk_fma_f32 v[14:15], v[38:39], v[148:149], v[14:15] op_sel_hi:[0,1,1]
	v_add_f32_e32 v28, v28, v32
	ds_bpermute_b32 v29, v187, v16
	v_add_f32_e32 v27, v28, v27
	v_mul_f32_e32 v28, v15, v15
	v_mul_f32_e32 v32, v13, v13
	v_fmac_f32_e32 v28, v14, v14
	v_fmac_f32_e32 v32, v12, v12
	v_add_f32_e32 v28, v28, v32
	v_add_f32_e32 v27, v28, v27
	s_nop 1
	v_mov_b32_dpp v28, v17 quad_perm:[1,0,3,2] row_mask:0xf bank_mask:0xf
	s_waitcnt lgkmcnt(0)
	v_add_f32_e32 v32, v16, v29
	s_nop 1
	v_mov_b32_dpp v16, v26 quad_perm:[1,0,3,2] row_mask:0xf bank_mask:0xf
	s_nop 1
	v_mov_b32_dpp v29, v27 quad_perm:[1,0,3,2] row_mask:0xf bank_mask:0xf
	ds_bpermute_b32 v33, v188, v32
	s_waitcnt lgkmcnt(0)
	v_add_f32_e32 v17, v17, v28
	s_nop 1
	v_mov_b32_dpp v28, v17 quad_perm:[2,3,0,1] row_mask:0xf bank_mask:0xf
	s_waitcnt lgkmcnt(0)
	v_add_f32_e32 v16, v26, v16
	s_waitcnt lgkmcnt(0)
	v_add_f32_e32 v27, v27, v29
	s_nop 1
	v_mov_b32_dpp v26, v16 quad_perm:[2,3,0,1] row_mask:0xf bank_mask:0xf
	s_nop 1
	v_mov_b32_dpp v29, v27 quad_perm:[2,3,0,1] row_mask:0xf bank_mask:0xf
	s_waitcnt lgkmcnt(0)
	v_add_f32_e32 v17, v17, v28
	s_nop 1
	v_mov_b32_dpp v28, v17 row_half_mirror row_mask:0xf bank_mask:0xf
	s_mov_b64 s[10:11], s[80:81]
	s_waitcnt lgkmcnt(0)
	v_add_f32_e32 v16, v16, v26
	s_waitcnt lgkmcnt(0)
	v_add_f32_e32 v27, v27, v29
	s_nop 1
	v_mov_b32_dpp v26, v16 row_half_mirror row_mask:0xf bank_mask:0xf
	s_nop 1
	v_mov_b32_dpp v29, v27 row_half_mirror row_mask:0xf bank_mask:0xf
	s_waitcnt lgkmcnt(0)
	v_add_f32_e32 v17, v17, v28
	s_nop 1
	v_mov_b32_dpp v28, v17 row_mirror row_mask:0xf bank_mask:0xf
	s_waitcnt lgkmcnt(0)
	v_add_f32_e32 v16, v16, v26
	s_waitcnt lgkmcnt(0)
	v_add_f32_e32 v27, v27, v29
	s_nop 1
	v_mov_b32_dpp v26, v16 row_mirror row_mask:0xf bank_mask:0xf
	s_nop 1
	v_mov_b32_dpp v29, v27 row_mirror row_mask:0xf bank_mask:0xf
	s_waitcnt lgkmcnt(0)
	v_add_f32_e32 v17, v17, v28
	ds_bpermute_b32 v28, v187, v17
	s_load_dwordx2 s[78:79], s[10:11], 0x110
	s_waitcnt lgkmcnt(0)
	v_add_f32_e32 v16, v16, v26
	v_add_f32_e32 v34, v27, v29
	ds_bpermute_b32 v26, v187, v16
	ds_bpermute_b32 v35, v187, v34
	v_add_f32_e32 v28, v17, v28
	ds_bpermute_b32 v29, v188, v28
	v_add_f32_e32 v32, v32, v33
	s_waitcnt lgkmcnt(0)
	v_add_f32_e32 v26, v16, v26
	s_waitcnt lgkmcnt(0)
	v_add_f32_e32 v16, v34, v35
	ds_bpermute_b32 v27, v188, v26
	ds_bpermute_b32 v17, v188, v16
	s_andn2_b64 vcc, exec, s[12:13]
	v_fmamk_f32 v32, v32, 0x3a800000, v150
	s_cbranch_vccnz .LBB0_410
	v_mul_f32_e32 v33, 0x4b800000, v32
	v_cmp_gt_f32_e32 vcc, s89, v32
	v_lshl_add_u64 v[34:35], v[8:9], 0, s[24:25]
	s_nop 0
	v_cndmask_b32_e32 v33, v32, v33, vcc
	v_rsq_f32_e32 v33, v33
	s_nop 0
	v_mul_f32_e32 v36, 0x45800000, v33
	v_cndmask_b32_e32 v36, v33, v36, vcc
	v_pk_mul_f32 v[42:43], v[116:117], v[36:37] op_sel_hi:[1,0]
	v_pk_mul_f32 v[40:41], v[114:115], v[36:37] op_sel_hi:[1,0]
	v_cvt_pk_bf16_f32 v42, v42, v43
	v_pk_mul_f32 v[30:31], v[30:31], v[36:37] op_sel_hi:[1,0]
	v_cvt_pk_bf16_f32 v43, v40, v41
	global_store_dwordx2 v[34:35], v[42:43], off
	v_pk_mul_f32 v[42:43], v[104:105], v[36:37] op_sel_hi:[1,0]
	v_pk_mul_f32 v[40:41], v[102:103], v[36:37] op_sel_hi:[1,0]
	v_cvt_pk_bf16_f32 v42, v42, v43
	s_nop 0
	v_cvt_pk_bf16_f32 v43, v40, v41
	global_store_dwordx2 v[34:35], v[42:43], off offset:512
	v_pk_mul_f32 v[40:41], v[82:83], v[36:37] op_sel_hi:[1,0]
	v_pk_mul_f32 v[42:43], v[84:85], v[36:37] op_sel_hi:[1,0]
	v_pk_mul_f32 v[36:37], v[62:63], v[36:37] op_sel_hi:[1,0]
	v_cvt_pk_bf16_f32 v42, v42, v43
	v_cvt_pk_bf16_f32 v43, v40, v41
	global_store_dwordx2 v[34:35], v[42:43], off offset:1024
	v_cvt_pk_bf16_f32 v36, v36, v37
	v_cvt_pk_bf16_f32 v37, v30, v31
	global_store_dwordx2 v[34:35], v[36:37], off offset:1536

; __device__ __forceinline__ void st4_bf16(bf16* p, v4f o) { v2u w; w.x = cvt_pk_nv(o.x, o.y); w.y = cvt_pk_nv(o.z, o.w); *(v2u*)p = w; }
; template <int R, bool BASE_F32, bool OUT_F32>
; __device__ __forceinline__ void rows_res(const Ctx& C, int m0, int stride, int mx, const float* gpost, float scale, int lane) {
;     ...
;         for (int r = 0; r < R; ++r) { const float rstd = rsqrtf(t[r]);
; #pragma unroll
;             for (int j = 0; j < 4; ++j) if (ok[r]) st4_bf16(XN + (size_t)mr[r] * DM + 4 * lane + 256 * j, d[r][j] * rstd);
;             if (lane == 0 && ok[r]) rs[mr[r]] = sqrtf(t[r]); }
.LBB0_412:
	s_or_b64 exec, exec, s[42:43]
	s_waitcnt lgkmcnt(0)
	v_add_f32_e32 v28, v28, v29
	s_andn2_b64 vcc, exec, s[16:17]
	v_fmamk_f32 v28, v28, 0x3a800000, v150
	s_cbranch_vccnz .LBB0_414
	v_mul_f32_e32 v29, 0x4b800000, v28
	v_cmp_gt_f32_e32 vcc, s89, v28
	v_lshl_add_u64 v[30:31], v[8:9], 0, s[28:29]
	s_nop 0
	v_cndmask_b32_e32 v29, v28, v29, vcc
	v_rsq_f32_e32 v29, v29
	s_nop 0
	v_mul_f32_e32 v32, 0x45800000, v29
	v_cndmask_b32_e32 v32, v29, v32, vcc
	v_pk_mul_f32 v[36:37], v[92:93], v[32:33] op_sel_hi:[1,0]
	v_pk_mul_f32 v[34:35], v[90:91], v[32:33] op_sel_hi:[1,0]
	v_cvt_pk_bf16_f32 v36, v36, v37
	v_pk_mul_f32 v[24:25], v[24:25], v[32:33] op_sel_hi:[1,0]
	v_cvt_pk_bf16_f32 v37, v34, v35
	global_store_dwordx2 v[30:31], v[36:37], off
	v_pk_mul_f32 v[36:37], v[98:99], v[32:33] op_sel_hi:[1,0]
	v_pk_mul_f32 v[34:35], v[96:97], v[32:33] op_sel_hi:[1,0]
	v_cvt_pk_bf16_f32 v36, v36, v37
	v_pk_mul_f32 v[22:23], v[22:23], v[32:33] op_sel_hi:[1,0]
	v_cvt_pk_bf16_f32 v37, v34, v35
	global_store_dwordx2 v[30:31], v[36:37], off offset:512
	v_pk_mul_f32 v[36:37], v[80:81], v[32:33] op_sel_hi:[1,0]
	v_pk_mul_f32 v[34:35], v[76:77], v[32:33] op_sel_hi:[1,0]
	v_cvt_pk_bf16_f32 v36, v36, v37
	v_cvt_pk_bf16_f32 v24, v24, v25
	v_cvt_pk_bf16_f32 v25, v22, v23
	global_store_dwordx2 v[30:31], v[24:25], off offset:1536
	v_cvt_pk_bf16_f32 v37, v34, v35
	global_store_dwordx2 v[30:31], v[36:37], off offset:1024

; __device__ __forceinline__ void st4_bf16(bf16* p, v4f o) { v2u w; w.x = cvt_pk_nv(o.x, o.y); w.y = cvt_pk_nv(o.z, o.w); *(v2u*)p = w; }
; template <int R, bool BASE_F32, bool OUT_F32>
; __device__ __forceinline__ void rows_res(const Ctx& C, int m0, int stride, int mx, const float* gpost, float scale, int lane) {
;     ...
;         for (int r = 0; r < R; ++r) { const float rstd = rsqrtf(t[r]);
; #pragma unroll
;             for (int j = 0; j < 4; ++j) if (ok[r]) st4_bf16(XN + (size_t)mr[r] * DM + 4 * lane + 256 * j, d[r][j] * rstd);
;             if (lane == 0 && ok[r]) rs[mr[r]] = sqrtf(t[r]); }
.LBB0_416:
	s_or_b64 exec, exec, s[42:43]
	s_waitcnt lgkmcnt(0)
	v_add_f32_e32 v22, v26, v27
	s_andn2_b64 vcc, exec, s[20:21]
	v_fmamk_f32 v22, v22, 0x3a800000, v150
	s_cbranch_vccnz .LBB0_418
	v_mul_f32_e32 v23, 0x4b800000, v22
	v_cmp_gt_f32_e32 vcc, s89, v22
	v_lshl_add_u64 v[8:9], v[8:9], 0, s[34:35]
	s_nop 0
	v_cndmask_b32_e32 v23, v22, v23, vcc
	v_rsq_f32_e32 v23, v23
	s_nop 0
	v_mul_f32_e32 v24, 0x45800000, v23
	v_cndmask_b32_e32 v24, v23, v24, vcc
	v_pk_mul_f32 v[28:29], v[86:87], v[24:25] op_sel_hi:[1,0]
	v_pk_mul_f32 v[26:27], v[88:89], v[24:25] op_sel_hi:[1,0]
	v_cvt_pk_bf16_f32 v28, v28, v29
	v_pk_mul_f32 v[20:21], v[20:21], v[24:25] op_sel_hi:[1,0]
	v_cvt_pk_bf16_f32 v29, v26, v27
	global_store_dwordx2 v[8:9], v[28:29], off
	v_pk_mul_f32 v[28:29], v[72:73], v[24:25] op_sel_hi:[1,0]
	v_pk_mul_f32 v[26:27], v[70:71], v[24:25] op_sel_hi:[1,0]
	v_cvt_pk_bf16_f32 v28, v28, v29
	v_pk_mul_f32 v[18:19], v[18:19], v[24:25] op_sel_hi:[1,0]
	v_cvt_pk_bf16_f32 v29, v26, v27
	global_store_dwordx2 v[8:9], v[28:29], off offset:512
	v_pk_mul_f32 v[28:29], v[56:57], v[24:25] op_sel_hi:[1,0]
	v_pk_mul_f32 v[26:27], v[54:55], v[24:25] op_sel_hi:[1,0]
	v_cvt_pk_bf16_f32 v28, v28, v29
	v_cvt_pk_bf16_f32 v20, v20, v21
	v_cvt_pk_bf16_f32 v21, v18, v19
	global_store_dwordx2 v[8:9], v[20:21], off offset:1536
	v_cvt_pk_bf16_f32 v29, v26, v27
	global_store_dwordx2 v[8:9], v[28:29], off offset:1024

; __device__ __forceinline__ unsigned xb_add(unsigned* p, unsigned v) { return __hip_atomic_fetch_add(p, v, __ATOMIC_RELAXED, __HIP_MEMORY_SCOPE_AGENT); }
; __device__ __forceinline__ void xcd_barrier(const XcdBarrier& b) {
;     asm volatile("s_waitcnt vmcnt(0)" ::: "memory");
;     __syncthreads();
;     if (threadIdx.x == 0) {
;         unsigned* bar = b.bar;
;         __builtin_amdgcn_s_waitcnt(0);
;         unsigned nloc = b.st[0], nx = b.st[1];
;         if (nloc == 0u) { xcd_barrier_complete(bar, b.x, nloc, nx); b.st[0] = nloc; b.st[1] = nx; }
;         const unsigned old = xb_add(&bar[XB_XSUB(b.x)], 1u);
;         const unsigned gen = old / nloc;
.LBB0_422:
	s_mov_b64 s[10:11], s[80:81]
	s_getreg_b32 s12, hwreg(HW_REG_XCC_ID, 0, 4)
	s_waitcnt vmcnt(0)
	s_barrier
	s_and_saveexec_b64 s[8:9], s[96:97]
	v_readlane_b32 s78, v232, 8
	v_readlane_b32 s70, v232, 6
	s_cbranch_execz .LBB0_474
	s_add_i32 s0, 0, 0x23fc0
	v_mov_b32_e32 v0, s0
	s_load_dwordx2 s[10:11], s[10:11], 0x110
	s_waitcnt vmcnt(0) expcnt(0) lgkmcnt(0)
	ds_read_b32 v2, v0
	s_add_i32 s0, 0, 0x23fc4
	v_mov_b32_e32 v0, s0
	ds_read_b32 v0, v0
	s_and_b32 s26, s12, 15
	s_waitcnt lgkmcnt(0)
	v_cmp_ne_u32_e32 vcc, 0, v2
	s_cbranch_vccnz .LBB0_438
	s_add_u32 s12, s10, 0x1000
	s_addc_u32 s13, s11, 0
	s_add_u32 s14, s10, 0x1100
	s_addc_u32 s15, s11, 0
	s_add_u32 s16, s10, 0x1200
	s_addc_u32 s17, s11, 0
	s_mul_i32 s27, s95, s93
	s_add_u32 s18, s10, 0x1300
	s_mul_i32 s27, s27, s94
	s_addc_u32 s19, s11, 0
	s_mov_b32 s28, 1
	v_mov_b32_e32 v16, 0
	s_branch .LBB0_426

; __device__ __forceinline__ float bf_lo(unsigned w) { return __uint_as_float(w << 16); }
; __device__ __forceinline__ float bf_hi(unsigned w) { return __uint_as_float(w & 0xffff0000u); }
; __device__ __forceinline__ unsigned cvt_pk_nv(float lo, float hi) { unsigned r; asm("v_cvt_pk_bf16_f32 %0, %1, %2" : "=v"(r) : "v"(lo), "v"(hi)); return r; }
; __device__ __forceinline__ float wave_sum(float v) {
; #pragma unroll
;     for (int o = 1; o < 64; o <<= 1) v += __shfl_xor(v, o);
;     return v;
; }
; template <int R>
; __device__ __forceinline__ void rows_norm512(bf16* base, int m0, int stride, int mx, const float* g, int lane) {
;     v4u w[R]; float ss[R]; int mr[R]; bool ok[R];
; #pragma unroll
;     for (int r = 0; r < R; ++r) { mr[r] = (r == 4) ? mx : m0 + r * stride; ok[r] = (r == 4) ? (mx < M) : (mr[r] < MPROMPT);
;         w[r] = *(const v4u*)(base + (size_t)(ok[r] ? mr[r] : 0) * DM + 8 * lane); }
;     const v4f g0 = *(const v4f*)(g + 8 * lane), g1 = *(const v4f*)(g + 8 * lane + 4);
; #pragma unroll
;     for (int r = 0; r < R; ++r) { const v4u x = w[r];
;         ss[r] = (bf_lo(x.x) * bf_lo(x.x) + bf_hi(x.x) * bf_hi(x.x)) + (bf_lo(x.y) * bf_lo(x.y) + bf_hi(x.y) * bf_hi(x.y)) + (bf_lo(x.z) * bf_lo(x.z) + bf_hi(x.z) * bf_hi(x.z)) + (bf_lo(x.w) * bf_lo(x.w) + bf_hi(x.w) * bf_hi(x.w)); }
; #pragma unroll
;     for (int r = 0; r < R; ++r) ss[r] = rsqrtf(wave_sum(ss[r]) * (1.f / 512.f) + EPS);
; #pragma unroll
;     for (int r = 0; r < R; ++r) { const v4u x = w[r]; const float q = ss[r];
;         v4u o; o.x = cvt_pk_nv(bf_lo(x.x) * q * g0.x, bf_hi(x.x) * q * g0.y); o.y = cvt_pk_nv(bf_lo(x.y) * q * g0.z, bf_hi(x.y) * q * g0.w);
;         o.z = cvt_pk_nv(bf_lo(x.z) * q * g1.x, bf_hi(x.z) * q * g1.y); o.w = cvt_pk_nv(bf_lo(x.w) * q * g1.z, bf_hi(x.w) * q * g1.w);
;         if (ok[r]) *(v4u*)(base + (size_t)mr[r] * DM + 8 * lane) = o; }
.LBB0_826:
	s_ashr_i32 s19, s18, 31
	s_lshl_b64 s[0:1], s[18:19], 10
	s_cmp_lt_i32 s18, 0x8000
	s_cselect_b32 s0, s0, 0
	s_cselect_b32 s1, s1, 0
	s_add_i32 s28, s46, s18
	s_ashr_i32 s29, s28, 31
	v_lshl_add_u64 v[0:1], s[0:1], 1, v[16:17]
	s_lshl_b64 s[0:1], s[28:29], 10
	s_cmp_lt_i32 s28, 0x8000
	s_cselect_b64 s[30:31], -1, 0
	s_and_b64 s[8:9], s[30:31], exec
	s_cselect_b32 s0, s0, 0
	s_cselect_b32 s1, s1, 0
	global_load_dwordx4 v[8:11], v[0:1], off
	v_lshl_add_u64 v[0:1], s[0:1], 1, v[16:17]
	global_load_dwordx4 v[22:25], v[0:1], off
	s_add_i32 s24, s77, s18
	s_ashr_i32 s25, s24, 31
	s_lshl_b64 s[0:1], s[24:25], 10
	s_cmp_lt_i32 s24, 0x8000
	s_cselect_b64 s[26:27], -1, 0
	s_and_b64 s[8:9], s[26:27], exec
	s_cselect_b32 s0, s0, 0
	s_cselect_b32 s1, s1, 0
	s_add_i32 s20, s78, s18
	s_ashr_i32 s21, s20, 31
	v_lshl_add_u64 v[0:1], s[0:1], 1, v[16:17]
	s_lshl_b64 s[0:1], s[20:21], 10
	s_cmp_lt_i32 s20, 0x8000
	s_cselect_b64 s[22:23], -1, 0
	s_and_b64 s[8:9], s[22:23], exec
	s_cselect_b32 s0, s0, 0
	s_cselect_b32 s1, s1, 0
	global_load_dwordx4 v[30:33], v[0:1], off
	v_lshl_add_u64 v[0:1], s[0:1], 1, v[16:17]
	global_load_dwordx4 v[46:49], v[0:1], off
	s_nop 0
	global_load_dwordx4 v[0:3], v[18:19], off offset:16
	global_load_dwordx4 v[4:7], v[18:19], off
	s_cmpk_gt_i32 s18, 0x7fff
	s_waitcnt vmcnt(5)
	v_lshlrev_b32_e32 v53, 16, v9
	v_lshlrev_b32_e32 v52, 16, v8
	v_and_b32_e32 v9, 0xffff0000, v9
	v_and_b32_e32 v8, 0xffff0000, v8
	s_waitcnt vmcnt(4)
	v_and_b32_e32 v43, 0xffff0000, v23
	v_and_b32_e32 v42, 0xffff0000, v22
	v_lshlrev_b32_e32 v55, 16, v11
	v_lshlrev_b32_e32 v54, 16, v10
	v_and_b32_e32 v11, 0xffff0000, v11
	v_and_b32_e32 v10, 0xffff0000, v10
	v_pk_mul_f32 v[26:27], v[8:9], v[8:9]
	v_lshlrev_b32_e32 v45, 16, v23
	v_lshlrev_b32_e32 v44, 16, v22
	v_and_b32_e32 v39, 0xffff0000, v25
	v_and_b32_e32 v38, 0xffff0000, v24
	v_pk_mul_f32 v[22:23], v[42:43], v[42:43]
	v_pk_mul_f32 v[28:29], v[10:11], v[10:11]
	v_pk_fma_f32 v[26:27], v[52:53], v[52:53], v[26:27]
	v_lshlrev_b32_e32 v41, 16, v25
	v_lshlrev_b32_e32 v40, 16, v24
	v_pk_mul_f32 v[24:25], v[38:39], v[38:39]
	v_pk_fma_f32 v[22:23], v[44:45], v[44:45], v[22:23]
	v_pk_fma_f32 v[34:35], v[54:55], v[54:55], v[28:29]
	v_mov_b32_e32 v29, v26
	v_pk_fma_f32 v[24:25], v[40:41], v[40:41], v[24:25]
	v_mov_b32_e32 v28, v22
	v_mov_b32_e32 v26, v23
	v_mov_b32_e32 v37, v34
	v_mov_b32_e32 v36, v24
	v_pk_add_f32 v[22:23], v[28:29], v[26:27]
	v_mov_b32_e32 v34, v25
	v_pk_add_f32 v[36:37], v[36:37], v[22:23]
	s_waitcnt vmcnt(3)
	v_and_b32_e32 v27, 0xffff0000, v31
	v_pk_add_f32 v[50:51], v[34:35], v[36:37]
	s_nop 1
	v_mov_b32_dpp v57, v51 quad_perm:[1,0,3,2] row_mask:0xf bank_mask:0xf
	s_nop 1
	v_mov_b32_dpp v56, v50 quad_perm:[1,0,3,2] row_mask:0xf bank_mask:0xf
	s_waitcnt vmcnt(2)
	v_lshlrev_b32_e32 v37, 16, v47
	v_lshlrev_b32_e32 v36, 16, v46
	v_and_b32_e32 v35, 0xffff0000, v47
	v_and_b32_e32 v34, 0xffff0000, v46
	s_waitcnt lgkmcnt(0)
	v_pk_add_f32 v[46:47], v[50:51], v[56:57]
	s_nop 1
	v_mov_b32_dpp v57, v47 quad_perm:[2,3,0,1] row_mask:0xf bank_mask:0xf
	s_nop 1
	v_mov_b32_dpp v56, v46 quad_perm:[2,3,0,1] row_mask:0xf bank_mask:0xf
	v_and_b32_e32 v26, 0xffff0000, v30
	v_lshlrev_b32_e32 v29, 16, v31
	v_lshlrev_b32_e32 v28, 16, v30
	v_and_b32_e32 v23, 0xffff0000, v33
	v_and_b32_e32 v22, 0xffff0000, v32
	v_pk_mul_f32 v[30:31], v[26:27], v[26:27]
	v_lshlrev_b32_e32 v25, 16, v33
	v_lshlrev_b32_e32 v24, 16, v32
	v_pk_mul_f32 v[32:33], v[22:23], v[22:23]
	v_pk_fma_f32 v[60:61], v[28:29], v[28:29], v[30:31]
	v_and_b32_e32 v31, 0xffff0000, v49
	v_and_b32_e32 v30, 0xffff0000, v48
	v_pk_fma_f32 v[62:63], v[24:25], v[24:25], v[32:33]
	v_lshlrev_b32_e32 v33, 16, v49
	v_lshlrev_b32_e32 v32, 16, v48
	v_pk_mul_f32 v[50:51], v[30:31], v[30:31]
	v_pk_mul_f32 v[48:49], v[34:35], v[34:35]
	v_pk_fma_f32 v[50:51], v[32:33], v[32:33], v[50:51]
	s_waitcnt lgkmcnt(0)
	v_pk_add_f32 v[46:47], v[46:47], v[56:57]
	v_mov_b32_e32 v67, v62
	v_pk_fma_f32 v[48:49], v[36:37], v[36:37], v[48:49]
	v_mov_b32_e32 v66, v50
	v_mov_b32_e32 v62, v51
	s_nop 1
	v_mov_b32_dpp v51, v47 row_half_mirror row_mask:0xf bank_mask:0xf
	s_nop 1
	v_mov_b32_dpp v50, v46 row_half_mirror row_mask:0xf bank_mask:0xf
	v_mov_b32_e32 v65, v60
	v_mov_b32_e32 v64, v48
	v_mov_b32_e32 v60, v49
	v_pk_add_f32 v[48:49], v[64:65], v[60:61]
	s_waitcnt lgkmcnt(0)
	v_pk_add_f32 v[46:47], v[46:47], v[50:51]
	v_pk_add_f32 v[48:49], v[66:67], v[48:49]
	s_nop 1
	v_mov_b32_dpp v51, v47 row_mirror row_mask:0xf bank_mask:0xf
	v_pk_add_f32 v[48:49], v[62:63], v[48:49]
	s_nop 1
	v_mov_b32_dpp v57, v49 quad_perm:[1,0,3,2] row_mask:0xf bank_mask:0xf
	s_nop 1
	v_mov_b32_dpp v56, v48 quad_perm:[1,0,3,2] row_mask:0xf bank_mask:0xf
	s_nop 1
	v_mov_b32_dpp v50, v46 row_mirror row_mask:0xf bank_mask:0xf
	s_waitcnt lgkmcnt(0)
	v_pk_add_f32 v[48:49], v[48:49], v[56:57]
	s_nop 1
	v_mov_b32_dpp v57, v49 quad_perm:[2,3,0,1] row_mask:0xf bank_mask:0xf
	s_nop 1
	v_mov_b32_dpp v56, v48 quad_perm:[2,3,0,1] row_mask:0xf bank_mask:0xf
	s_waitcnt lgkmcnt(0)
	v_pk_add_f32 v[46:47], v[46:47], v[50:51]
	ds_bpermute_b32 v51, v187, v47
	ds_bpermute_b32 v50, v187, v46
	s_waitcnt lgkmcnt(0)
	v_pk_add_f32 v[48:49], v[48:49], v[56:57]
	s_nop 1
	v_mov_b32_dpp v57, v49 row_half_mirror row_mask:0xf bank_mask:0xf
	s_nop 1
	v_mov_b32_dpp v56, v48 row_half_mirror row_mask:0xf bank_mask:0xf
	s_waitcnt lgkmcnt(0)
	v_pk_add_f32 v[46:47], v[46:47], v[50:51]
	ds_bpermute_b32 v51, v188, v47
	ds_bpermute_b32 v50, v188, v46
	s_waitcnt lgkmcnt(0)
	v_pk_add_f32 v[48:49], v[48:49], v[56:57]
	s_nop 1
	v_mov_b32_dpp v57, v49 row_mirror row_mask:0xf bank_mask:0xf
	s_nop 1
	v_mov_b32_dpp v56, v48 row_mirror row_mask:0xf bank_mask:0xf
	s_waitcnt lgkmcnt(0)
	v_pk_add_f32 v[46:47], v[46:47], v[50:51]
	s_nop 0
	v_pk_fma_f32 v[50:51], v[46:47], s[14:15], v[20:21] op_sel_hi:[1,0,0]
	s_waitcnt lgkmcnt(0)
	v_pk_add_f32 v[46:47], v[48:49], v[56:57]
	v_mul_f32_e32 v15, 0x4b800000, v51
	v_cmp_gt_f32_e64 s[8:9], s15, v51
	ds_bpermute_b32 v49, v187, v47
	ds_bpermute_b32 v48, v187, v46
	v_cndmask_b32_e64 v15, v51, v15, s[8:9]
	v_rsq_f32_e32 v15, v15
	v_cmp_gt_f32_e32 vcc, s15, v50
	s_waitcnt lgkmcnt(0)
	v_pk_add_f32 v[46:47], v[46:47], v[48:49]
	v_mul_f32_e32 v21, 0x45800000, v15
	v_cndmask_b32_e64 v15, v15, v21, s[8:9]
	v_mul_f32_e32 v21, v15, v52
	v_mul_f32_e32 v8, v15, v8
	s_waitcnt vmcnt(0)
	v_mul_f32_e32 v21, v4, v21
	v_mul_f32_e32 v8, v5, v8
	ds_bpermute_b32 v49, v188, v47
	ds_bpermute_b32 v48, v188, v46
	v_cvt_pk_bf16_f32 v8, v21, v8
	v_mul_f32_e32 v21, v15, v53
	v_mul_f32_e32 v9, v15, v9
	v_mul_f32_e32 v21, v6, v21
	v_mul_f32_e32 v9, v7, v9
	v_cvt_pk_bf16_f32 v9, v21, v9
	v_mul_f32_e32 v21, v15, v54
	v_mul_f32_e32 v10, v15, v10
	v_mul_f32_e32 v21, v0, v21
	v_mul_f32_e32 v10, v1, v10
	v_mul_f32_e32 v11, v15, v11
	v_cvt_pk_bf16_f32 v10, v21, v10
	v_mul_f32_e32 v21, v15, v55
	v_mul_f32_e32 v11, v3, v11
	v_mul_f32_e32 v21, v2, v21
	v_cvt_pk_bf16_f32 v11, v21, v11
	s_cbranch_scc1 .LBB0_828
	s_lshl_b64 s[0:1], s[18:19], 11
	v_lshl_add_u64 v[52:53], v[16:17], 0, s[0:1]
	global_store_dwordx4 v[52:53], v[8:11], off

; __device__ __forceinline__ float bf_lo(unsigned w) { return __uint_as_float(w << 16); }
; __device__ __forceinline__ float bf_hi(unsigned w) { return __uint_as_float(w & 0xffff0000u); }
; template <int R>
; __device__ __forceinline__ void rows_norm512(bf16* base, int m0, int stride, int mx, const float* g, int lane) {
;     ...
;     for (int r = 0; r < R; ++r) { mr[r] = (r == 4) ? mx : m0 + r * stride; ok[r] = (r == 4) ? (mx < M) : (mr[r] < MPROMPT);
;         w[r] = *(const v4u*)(base + (size_t)(ok[r] ? mr[r] : 0) * DM + 8 * lane); }
;     const v4f g0 = *(const v4f*)(g + 8 * lane), g1 = *(const v4f*)(g + 8 * lane + 4);
; #pragma unroll
;     for (int r = 0; r < R; ++r) { const v4u x = w[r];
;         ss[r] = (bf_lo(x.x) * bf_lo(x.x) + bf_hi(x.x) * bf_hi(x.x)) + (bf_lo(x.y) * bf_lo(x.y) + bf_hi(x.y) * bf_hi(x.y)) + (bf_lo(x.z) * bf_lo(x.z) + bf_hi(x.z) * bf_hi(x.z)) + (bf_lo(x.w) * bf_lo(x.w) + bf_hi(x.w) * bf_hi(x.w)); }
; #pragma unroll
;     for (int r = 0; r < R; ++r) ss[r] = rsqrtf(wave_sum(ss[r]) * (1.f / 512.f) + EPS);
.LBB0_834:
	s_add_i32 s8, s35, s86
	s_ashr_i32 s9, s8, 31
	s_add_i32 s14, s35, 0x8000
	s_lshl_b64 s[0:1], s[8:9], 10
	s_cmp_lt_i32 s8, 0x8000
	s_cselect_b32 s1, s1, 0
	s_cselect_b32 s0, s0, 0
	v_lshl_add_u64 v[16:17], s[16:17], 0, v[12:13]
	s_add_i32 s26, s8, s46
	v_lshl_add_u64 v[0:1], s[0:1], 1, v[16:17]
	s_cmp_lt_i32 s26, 0x8000
	global_load_dwordx4 v[8:11], v[0:1], off
	s_cselect_b64 s[28:29], -1, 0
	s_ashr_i32 s27, s26, 31
	s_lshl_b64 s[0:1], s[26:27], 10
	s_and_b64 s[16:17], s[28:29], exec
	s_cselect_b32 s1, s1, 0
	s_cselect_b32 s0, s0, 0
	s_add_i32 s22, s26, s46
	s_cmp_lt_i32 s22, 0x8000
	s_cselect_b64 s[24:25], -1, 0
	s_ashr_i32 s23, s22, 31
	v_lshl_add_u64 v[0:1], s[0:1], 1, v[16:17]
	s_lshl_b64 s[0:1], s[22:23], 10
	s_and_b64 s[16:17], s[24:25], exec
	s_cselect_b32 s1, s1, 0
	s_cselect_b32 s0, s0, 0
	global_load_dwordx4 v[18:21], v[0:1], off
	v_lshl_add_u64 v[0:1], s[0:1], 1, v[16:17]
	global_load_dwordx4 v[22:25], v[0:1], off
	s_add_i32 s18, s22, s46
	s_cmp_lt_i32 s18, 0x8000
	s_cselect_b64 s[20:21], -1, 0
	s_ashr_i32 s19, s18, 31
	s_lshl_b64 s[0:1], s[18:19], 10
	s_and_b64 s[16:17], s[20:21], exec
	s_cselect_b32 s1, s1, 0
	s_cselect_b32 s0, s0, 0
	v_lshl_add_u64 v[0:1], s[0:1], 1, v[16:17]
	global_load_dwordx4 v[50:53], v[0:1], off
	s_ashr_i32 s15, s14, 31
	s_lshl_b64 s[0:1], s[14:15], 10
	s_cmpk_lt_i32 s35, 0x80
	s_cselect_b64 s[16:17], -1, 0
	s_and_b64 s[30:31], s[16:17], exec
	s_cselect_b32 s0, s0, 0
	s_cselect_b32 s1, s1, 0
	v_lshl_add_u64 v[0:1], s[0:1], 1, v[16:17]
	global_load_dwordx4 v[54:57], v[0:1], off
	s_nop 0
	global_load_dwordx4 v[0:3], v14, s[12:13] offset:16
	global_load_dwordx4 v[4:7], v14, s[12:13]
	v_mov_b32_e32 v12, 0x358637bd
	s_mov_b32 s31, 0x800000
	s_cmpk_gt_i32 s8, 0x7fff
	s_mov_b32 s30, 0x3b000000
	s_waitcnt vmcnt(6)
	v_lshlrev_b32_e32 v61, 16, v9
	v_lshlrev_b32_e32 v60, 16, v8
	v_and_b32_e32 v9, 0xffff0000, v9
	v_and_b32_e32 v8, 0xffff0000, v8
	v_lshlrev_b32_e32 v63, 16, v11
	v_lshlrev_b32_e32 v62, 16, v10
	v_and_b32_e32 v11, 0xffff0000, v11
	v_and_b32_e32 v10, 0xffff0000, v10
	v_pk_mul_f32 v[26:27], v[8:9], v[8:9]
	v_pk_mul_f32 v[28:29], v[10:11], v[10:11]
	v_pk_fma_f32 v[26:27], v[60:61], v[60:61], v[26:27]
	v_pk_fma_f32 v[28:29], v[62:63], v[62:63], v[28:29]
	v_add_f32_e32 v15, v26, v27
	v_add_f32_e32 v15, v28, v15
	v_add_f32_e32 v15, v29, v15
	s_nop 1
	v_mov_b32_dpp v26, v15 quad_perm:[1,0,3,2] row_mask:0xf bank_mask:0xf
	s_waitcnt vmcnt(5)
	v_and_b32_e32 v47, 0xffff0000, v19
	v_and_b32_e32 v46, 0xffff0000, v18
	v_lshlrev_b32_e32 v49, 16, v19
	v_lshlrev_b32_e32 v48, 16, v18
	v_pk_mul_f32 v[18:19], v[46:47], v[46:47]
	s_waitcnt vmcnt(4)
	v_and_b32_e32 v39, 0xffff0000, v23
	v_and_b32_e32 v38, 0xffff0000, v22
	v_pk_fma_f32 v[64:65], v[48:49], v[48:49], v[18:19]
	v_lshlrev_b32_e32 v41, 16, v23
	v_lshlrev_b32_e32 v40, 16, v22
	v_pk_mul_f32 v[18:19], v[38:39], v[38:39]
	s_waitcnt lgkmcnt(0)
	v_add_f32_e32 v15, v15, v26
	v_pk_fma_f32 v[68:69], v[40:41], v[40:41], v[18:19]
	s_nop 1
	v_mov_b32_dpp v18, v15 quad_perm:[2,3,0,1] row_mask:0xf bank_mask:0xf
	s_waitcnt vmcnt(3)
	v_and_b32_e32 v31, 0xffff0000, v51
	v_and_b32_e32 v30, 0xffff0000, v50
	v_lshlrev_b32_e32 v33, 16, v51
	v_lshlrev_b32_e32 v32, 16, v50
	s_waitcnt lgkmcnt(0)
	v_add_f32_e32 v15, v15, v18
	s_nop 1
	v_mov_b32_dpp v22, v15 row_half_mirror row_mask:0xf bank_mask:0xf
	v_pk_mul_f32 v[18:19], v[30:31], v[30:31]
	v_lshlrev_b32_e32 v36, 16, v24
	v_pk_fma_f32 v[50:51], v[32:33], v[32:33], v[18:19]
	v_and_b32_e32 v34, 0xffff0000, v24
	s_waitcnt lgkmcnt(0)
	v_add_f32_e32 v15, v15, v22
	s_nop 1
	v_mov_b32_dpp v18, v15 row_mirror row_mask:0xf bank_mask:0xf
	s_waitcnt vmcnt(2)
	v_lshlrev_b32_e32 v24, 16, v54
	v_and_b32_e32 v22, 0xffff0000, v54
	v_and_b32_e32 v43, 0xffff0000, v21
	v_and_b32_e32 v42, 0xffff0000, v20
	s_waitcnt lgkmcnt(0)
	v_add_f32_e32 v15, v15, v18
	ds_bpermute_b32 v54, v187, v15
	v_lshlrev_b32_e32 v45, 16, v21
	v_lshlrev_b32_e32 v44, 16, v20
	v_pk_mul_f32 v[20:21], v[42:43], v[42:43]
	v_and_b32_e32 v35, 0xffff0000, v25
	v_pk_fma_f32 v[66:67], v[44:45], v[44:45], v[20:21]
	v_lshlrev_b32_e32 v37, 16, v25
	v_pk_mul_f32 v[20:21], v[34:35], v[34:35]
	v_and_b32_e32 v27, 0xffff0000, v53
	v_and_b32_e32 v26, 0xffff0000, v52
	v_and_b32_e32 v23, 0xffff0000, v55
	v_pk_fma_f32 v[70:71], v[36:37], v[36:37], v[20:21]
	v_lshlrev_b32_e32 v29, 16, v53
	v_lshlrev_b32_e32 v28, 16, v52
	v_pk_mul_f32 v[20:21], v[26:27], v[26:27]
	v_lshlrev_b32_e32 v25, 16, v55
	v_and_b32_e32 v19, 0xffff0000, v57
	v_and_b32_e32 v18, 0xffff0000, v56
	s_waitcnt lgkmcnt(0)
; __device__ __forceinline__ float bf_lo(unsigned w) { return __uint_as_float(w << 16); }
; __device__ __forceinline__ float bf_hi(unsigned w) { return __uint_as_float(w & 0xffff0000u); }
; __device__ __forceinline__ unsigned cvt_pk_nv(float lo, float hi) { unsigned r; asm("v_cvt_pk_bf16_f32 %0, %1, %2" : "=v"(r) : "v"(lo), "v"(hi)); return r; }
; __device__ __forceinline__ float wave_sum(float v) {
; #pragma unroll
;     for (int o = 1; o < 64; o <<= 1) v += __shfl_xor(v, o);
;     return v;
; }
; template <int R>
; __device__ __forceinline__ void rows_norm512(bf16* base, int m0, int stride, int mx, const float* g, int lane) {
;     ...
;         ss[r] = (bf_lo(x.x) * bf_lo(x.x) + bf_hi(x.x) * bf_hi(x.x)) + (bf_lo(x.y) * bf_lo(x.y) + bf_hi(x.y) * bf_hi(x.y)) + (bf_lo(x.z) * bf_lo(x.z) + bf_hi(x.z) * bf_hi(x.z)) + (bf_lo(x.w) * bf_lo(x.w) + bf_hi(x.w) * bf_hi(x.w)); }
; #pragma unroll
;     for (int r = 0; r < R; ++r) ss[r] = rsqrtf(wave_sum(ss[r]) * (1.f / 512.f) + EPS);
; #pragma unroll
;     for (int r = 0; r < R; ++r) { const v4u x = w[r]; const float q = ss[r];
;         v4u o; o.x = cvt_pk_nv(bf_lo(x.x) * q * g0.x, bf_hi(x.x) * q * g0.y); o.y = cvt_pk_nv(bf_lo(x.y) * q * g0.z, bf_hi(x.y) * q * g0.w);
;         o.z = cvt_pk_nv(bf_lo(x.z) * q * g1.x, bf_hi(x.z) * q * g1.y); o.w = cvt_pk_nv(bf_lo(x.w) * q * g1.z, bf_hi(x.w) * q * g1.w);
;         if (ok[r]) *(v4u*)(base + (size_t)mr[r] * DM + 8 * lane) = o; }
	v_add_f32_e32 v15, v15, v54
	v_pk_mul_f32 v[54:55], v[22:23], v[22:23]
	v_mov_b32_e32 v72, v68
	v_mov_b32_e32 v73, v64
	v_mov_b32_e32 v64, v69
	v_pk_fma_f32 v[52:53], v[28:29], v[28:29], v[20:21]
	v_lshlrev_b32_e32 v21, 16, v57
	v_lshlrev_b32_e32 v20, 16, v56
	v_pk_mul_f32 v[56:57], v[18:19], v[18:19]
	v_pk_fma_f32 v[54:55], v[24:25], v[24:25], v[54:55]
	v_pk_add_f32 v[64:65], v[72:73], v[64:65]
	v_mov_b32_e32 v68, v70
	v_mov_b32_e32 v69, v66
	v_pk_fma_f32 v[56:57], v[20:21], v[20:21], v[56:57]
	v_pk_add_f32 v[64:65], v[68:69], v[64:65]
	v_mov_b32_e32 v68, v54
	v_mov_b32_e32 v69, v50
	v_mov_b32_e32 v50, v55
	v_pk_add_f32 v[50:51], v[68:69], v[50:51]
	v_mov_b32_e32 v54, v56
	v_mov_b32_e32 v55, v52
	v_mov_b32_e32 v66, v71
	v_pk_add_f32 v[50:51], v[54:55], v[50:51]
	v_mov_b32_e32 v52, v57
	v_pk_add_f32 v[64:65], v[66:67], v[64:65]
	v_pk_add_f32 v[50:51], v[52:53], v[50:51]
	s_nop 1
	v_mov_b32_dpp v67, v65 quad_perm:[1,0,3,2] row_mask:0xf bank_mask:0xf
	s_nop 1
	v_mov_b32_dpp v66, v64 quad_perm:[1,0,3,2] row_mask:0xf bank_mask:0xf
	s_nop 1
	v_mov_b32_dpp v53, v51 quad_perm:[1,0,3,2] row_mask:0xf bank_mask:0xf
	s_nop 1
	v_mov_b32_dpp v52, v50 quad_perm:[1,0,3,2] row_mask:0xf bank_mask:0xf
	ds_bpermute_b32 v59, v188, v15
	s_waitcnt lgkmcnt(0)
	v_pk_add_f32 v[54:55], v[64:65], v[66:67]
	s_nop 1
	v_mov_b32_dpp v57, v55 quad_perm:[2,3,0,1] row_mask:0xf bank_mask:0xf
	s_waitcnt lgkmcnt(0)
	v_pk_add_f32 v[50:51], v[50:51], v[52:53]
	s_nop 1
	v_mov_b32_dpp v56, v54 quad_perm:[2,3,0,1] row_mask:0xf bank_mask:0xf
	s_nop 1
	v_mov_b32_dpp v53, v51 quad_perm:[2,3,0,1] row_mask:0xf bank_mask:0xf
	s_nop 1
	v_mov_b32_dpp v52, v50 quad_perm:[2,3,0,1] row_mask:0xf bank_mask:0xf
	s_waitcnt lgkmcnt(0)
	v_add_f32_e32 v15, v15, v59
	v_fmamk_f32 v15, v15, 0x3b000000, v12
	s_waitcnt lgkmcnt(0)
	v_pk_add_f32 v[54:55], v[54:55], v[56:57]
	s_nop 1
	v_mov_b32_dpp v57, v55 row_half_mirror row_mask:0xf bank_mask:0xf
	s_waitcnt lgkmcnt(0)
	v_pk_add_f32 v[50:51], v[50:51], v[52:53]
	s_nop 1
	v_mov_b32_dpp v56, v54 row_half_mirror row_mask:0xf bank_mask:0xf
	s_nop 1
	v_mov_b32_dpp v53, v51 row_half_mirror row_mask:0xf bank_mask:0xf
	s_nop 1
	v_mov_b32_dpp v52, v50 row_half_mirror row_mask:0xf bank_mask:0xf
	v_mul_f32_e32 v59, 0x4b800000, v15
	v_cmp_gt_f32_e32 vcc, s31, v15
	s_waitcnt lgkmcnt(0)
	v_pk_add_f32 v[54:55], v[54:55], v[56:57]
	s_nop 1
	v_mov_b32_dpp v57, v55 row_mirror row_mask:0xf bank_mask:0xf
	s_waitcnt lgkmcnt(0)
	v_pk_add_f32 v[50:51], v[50:51], v[52:53]
	s_nop 1
	v_mov_b32_dpp v56, v54 row_mirror row_mask:0xf bank_mask:0xf
	s_nop 1
	v_mov_b32_dpp v53, v51 row_mirror row_mask:0xf bank_mask:0xf
	s_nop 1
	v_mov_b32_dpp v52, v50 row_mirror row_mask:0xf bank_mask:0xf
	v_cndmask_b32_e32 v15, v15, v59, vcc
	v_rsq_f32_e32 v15, v15
	s_waitcnt lgkmcnt(0)
	v_pk_add_f32 v[54:55], v[54:55], v[56:57]
	ds_bpermute_b32 v57, v187, v55
	s_waitcnt lgkmcnt(0)
	v_pk_add_f32 v[50:51], v[50:51], v[52:53]
	ds_bpermute_b32 v56, v187, v54
	ds_bpermute_b32 v53, v187, v51
	ds_bpermute_b32 v52, v187, v50
	v_mul_f32_e32 v59, 0x45800000, v15
	v_cndmask_b32_e32 v15, v15, v59, vcc
	v_mul_f32_e32 v59, v15, v60
	v_mul_f32_e32 v8, v15, v8
	s_waitcnt lgkmcnt(0)
	v_pk_add_f32 v[54:55], v[54:55], v[56:57]
	s_waitcnt lgkmcnt(0)
	v_pk_add_f32 v[50:51], v[50:51], v[52:53]
	s_waitcnt vmcnt(0)
	v_mul_f32_e32 v59, v4, v59
	v_mul_f32_e32 v8, v5, v8
	ds_bpermute_b32 v57, v188, v55
	ds_bpermute_b32 v56, v188, v54
	ds_bpermute_b32 v53, v188, v51
	ds_bpermute_b32 v52, v188, v50
	v_cvt_pk_bf16_f32 v8, v59, v8
	v_mul_f32_e32 v59, v15, v61
	v_mul_f32_e32 v9, v15, v9
	v_mul_f32_e32 v59, v6, v59
	v_mul_f32_e32 v9, v7, v9
	v_cvt_pk_bf16_f32 v9, v59, v9
	v_mul_f32_e32 v59, v15, v62
	v_mul_f32_e32 v10, v15, v10
	v_mul_f32_e32 v59, v0, v59
	v_mul_f32_e32 v10, v1, v10
	v_mul_f32_e32 v11, v15, v11
	v_cvt_pk_bf16_f32 v10, v59, v10
	v_mul_f32_e32 v59, v15, v63
	v_mul_f32_e32 v11, v3, v11
	v_mul_f32_e32 v59, v2, v59
	v_cvt_pk_bf16_f32 v11, v59, v11
	s_cbranch_scc1 .LBB0_836
	s_lshl_b64 s[0:1], s[8:9], 11
	v_lshl_add_u64 v[60:61], v[16:17], 0, s[0:1]
	global_store_dwordx4 v[60:61], v[8:11], off
.LBB0_836:
	s_waitcnt lgkmcnt(0)
	s_nop 0
	v_pk_add_f32 v[8:9], v[54:55], v[56:57]
	s_nop 0
	v_pk_fma_f32 v[54:55], v[8:9], s[30:31], v[12:13] op_sel_hi:[1,0,0]
	s_nop 0
	v_mul_f32_e32 v8, 0x4b800000, v55
	v_cmp_gt_f32_e32 vcc, s31, v55
	v_cmp_gt_f32_e64 s[8:9], s31, v54
	s_nop 0
	v_cndmask_b32_e32 v8, v55, v8, vcc
	v_rsq_f32_e32 v8, v8
	s_nop 0
	v_mul_f32_e32 v9, 0x45800000, v8
	v_cndmask_b32_e32 v11, v8, v9, vcc
	v_mul_f32_e32 v8, v11, v48
	v_mul_f32_e32 v9, v11, v46
	v_mul_f32_e32 v8, v4, v8
	v_mul_f32_e32 v9, v5, v9
	v_cvt_pk_bf16_f32 v8, v8, v9
	v_mul_f32_e32 v9, v11, v49
	v_mul_f32_e32 v10, v11, v47
	v_mul_f32_e32 v9, v6, v9
	v_mul_f32_e32 v10, v7, v10
	v_cvt_pk_bf16_f32 v9, v9, v10
	v_mul_f32_e32 v10, v11, v44
	v_mul_f32_e32 v12, v11, v42
	v_mul_f32_e32 v10, v0, v10
	v_mul_f32_e32 v12, v1, v12
	v_cvt_pk_bf16_f32 v10, v10, v12
	v_mul_f32_e32 v12, v11, v45
	v_mul_f32_e32 v11, v11, v43
	v_mul_f32_e32 v11, v3, v11
	s_andn2_b64 vcc, exec, s[28:29]
	v_mul_f32_e32 v12, v2, v12
	v_cvt_pk_bf16_f32 v11, v12, v11
	s_cbranch_vccnz .LBB0_838
	s_lshl_b64 s[0:1], s[26:27], 11
	v_lshl_add_u64 v[42:43], v[16:17], 0, s[0:1]
	global_store_dwordx4 v[42:43], v[8:11], off

; __device__ __forceinline__ float bf_lo(unsigned w) { return __uint_as_float(w << 16); }
; __device__ __forceinline__ float bf_hi(unsigned w) { return __uint_as_float(w & 0xffff0000u); }
; __device__ __forceinline__ unsigned cvt_pk_nv(float lo, float hi) { unsigned r; asm("v_cvt_pk_bf16_f32 %0, %1, %2" : "=v"(r) : "v"(lo), "v"(hi)); return r; }
; template <int R>
; __device__ __forceinline__ void rows_norm512(bf16* base, int m0, int stride, int mx, const float* g, int lane) {
;     v4u w[R]; float ss[R]; int mr[R]; bool ok[R];
; #pragma unroll
;     for (int r = 0; r < R; ++r) { mr[r] = (r == 4) ? mx : m0 + r * stride; ok[r] = (r == 4) ? (mx < M) : (mr[r] < MPROMPT);
;         w[r] = *(const v4u*)(base + (size_t)(ok[r] ? mr[r] : 0) * DM + 8 * lane); }
;     const v4f g0 = *(const v4f*)(g + 8 * lane), g1 = *(const v4f*)(g + 8 * lane + 4);
; #pragma unroll
;     for (int r = 0; r < R; ++r) { const v4u x = w[r];
;         ss[r] = (bf_lo(x.x) * bf_lo(x.x) + bf_hi(x.x) * bf_hi(x.x)) + (bf_lo(x.y) * bf_lo(x.y) + bf_hi(x.y) * bf_hi(x.y)) + (bf_lo(x.z) * bf_lo(x.z) + bf_hi(x.z) * bf_hi(x.z)) + (bf_lo(x.w) * bf_lo(x.w) + bf_hi(x.w) * bf_hi(x.w)); }
; #pragma unroll
;     for (int r = 0; r < R; ++r) ss[r] = rsqrtf(wave_sum(ss[r]) * (1.f / 512.f) + EPS);
; #pragma unroll
;     for (int r = 0; r < R; ++r) { const v4u x = w[r]; const float q = ss[r];
;         v4u o; o.x = cvt_pk_nv(bf_lo(x.x) * q * g0.x, bf_hi(x.x) * q * g0.y); o.y = cvt_pk_nv(bf_lo(x.y) * q * g0.z, bf_hi(x.y) * q * g0.w);
;         o.z = cvt_pk_nv(bf_lo(x.z) * q * g1.x, bf_hi(x.z) * q * g1.y); o.w = cvt_pk_nv(bf_lo(x.w) * q * g1.z, bf_hi(x.w) * q * g1.w);
;         if (ok[r]) *(v4u*)(base + (size_t)mr[r] * DM + 8 * lane) = o; }
.LBB0_847:
	global_load_dwordx4 v[8:11], v[14:15], off
	global_load_dwordx4 v[30:33], v[18:19], off
	global_load_dwordx4 v[34:37], v[20:21], off
	global_load_dwordx4 v[54:57], v[26:27], off
	global_load_dwordx4 v[0:3], v[12:13], off offset:16
	global_load_dwordx4 v[4:7], v[12:13], off
	s_and_b64 vcc, exec, s[8:9]
	s_waitcnt vmcnt(5)
	v_lshlrev_b32_e32 v61, 16, v9
	v_lshlrev_b32_e32 v60, 16, v8
	v_and_b32_e32 v9, 0xffff0000, v9
	v_and_b32_e32 v8, 0xffff0000, v8
	s_waitcnt vmcnt(4)
	v_and_b32_e32 v49, 0xffff0000, v31
	v_and_b32_e32 v48, 0xffff0000, v30
	v_lshlrev_b32_e32 v63, 16, v11
	v_lshlrev_b32_e32 v62, 16, v10
	v_and_b32_e32 v11, 0xffff0000, v11
	v_and_b32_e32 v10, 0xffff0000, v10
	v_lshlrev_b32_e32 v53, 16, v31
	v_lshlrev_b32_e32 v52, 16, v30
	v_lshlrev_b32_e32 v47, 16, v33
	v_lshlrev_b32_e32 v46, 16, v32
	v_and_b32_e32 v51, 0xffff0000, v33
	v_and_b32_e32 v50, 0xffff0000, v32
	s_waitcnt vmcnt(3)
	v_lshlrev_b32_e32 v39, 16, v37
	v_lshlrev_b32_e32 v38, 16, v36
	v_and_b32_e32 v45, 0xffff0000, v37
	v_and_b32_e32 v44, 0xffff0000, v36
	s_waitcnt vmcnt(2)
	v_lshlrev_b32_e32 v37, 16, v55
	v_lshlrev_b32_e32 v36, 16, v54
	v_and_b32_e32 v33, 0xffff0000, v55
	v_and_b32_e32 v32, 0xffff0000, v54
	v_pk_mul_f32 v[54:55], v[8:9], v[8:9]
	v_pk_mul_f32 v[58:59], v[48:49], v[48:49]
	v_lshlrev_b32_e32 v41, 16, v35
	v_lshlrev_b32_e32 v40, 16, v34
	v_and_b32_e32 v43, 0xffff0000, v35
	v_and_b32_e32 v42, 0xffff0000, v34
	v_lshlrev_b32_e32 v31, 16, v57
	v_lshlrev_b32_e32 v30, 16, v56
	v_and_b32_e32 v35, 0xffff0000, v57
	v_and_b32_e32 v34, 0xffff0000, v56
	v_pk_mul_f32 v[56:57], v[10:11], v[10:11]
	v_pk_mul_f32 v[64:65], v[50:51], v[50:51]
	v_pk_fma_f32 v[54:55], v[60:61], v[60:61], v[54:55]
	v_pk_fma_f32 v[58:59], v[52:53], v[52:53], v[58:59]
	v_pk_fma_f32 v[56:57], v[62:63], v[62:63], v[56:57]
	v_pk_fma_f32 v[64:65], v[46:47], v[46:47], v[64:65]
	v_mov_b32_e32 v74, v58
	v_mov_b32_e32 v75, v54
	v_mov_b32_e32 v54, v59
	v_mov_b32_e32 v58, v64
	v_mov_b32_e32 v59, v56
	v_pk_add_f32 v[54:55], v[74:75], v[54:55]
	v_mov_b32_e32 v56, v65
	v_pk_add_f32 v[54:55], v[58:59], v[54:55]
	v_pk_mul_f32 v[66:67], v[42:43], v[42:43]
	v_pk_add_f32 v[54:55], v[56:57], v[54:55]
	s_nop 1
	v_mov_b32_dpp v57, v55 quad_perm:[1,0,3,2] row_mask:0xf bank_mask:0xf
	s_nop 1
	v_mov_b32_dpp v56, v54 quad_perm:[1,0,3,2] row_mask:0xf bank_mask:0xf
	v_pk_mul_f32 v[70:71], v[32:33], v[32:33]
	v_pk_mul_f32 v[68:69], v[44:45], v[44:45]
	v_pk_mul_f32 v[72:73], v[34:35], v[34:35]
	v_pk_fma_f32 v[66:67], v[40:41], v[40:41], v[66:67]
	v_pk_fma_f32 v[70:71], v[36:37], v[36:37], v[70:71]
	v_pk_fma_f32 v[68:69], v[38:39], v[38:39], v[68:69]
	v_pk_fma_f32 v[72:73], v[30:31], v[30:31], v[72:73]
	v_mov_b32_e32 v64, v70
	v_mov_b32_e32 v65, v66
	v_mov_b32_e32 v66, v71
	v_mov_b32_e32 v70, v72
	v_mov_b32_e32 v71, v68
	v_pk_add_f32 v[64:65], v[64:65], v[66:67]
	v_mov_b32_e32 v68, v73
	v_pk_add_f32 v[58:59], v[70:71], v[64:65]
	s_waitcnt lgkmcnt(0)
	v_pk_add_f32 v[54:55], v[54:55], v[56:57]
	v_pk_add_f32 v[58:59], v[68:69], v[58:59]
	s_nop 1
	v_mov_b32_dpp v57, v55 quad_perm:[2,3,0,1] row_mask:0xf bank_mask:0xf
	s_nop 1
	v_mov_b32_dpp v56, v54 quad_perm:[2,3,0,1] row_mask:0xf bank_mask:0xf
	s_nop 1
	v_mov_b32_dpp v65, v59 quad_perm:[1,0,3,2] row_mask:0xf bank_mask:0xf
	s_nop 1
	v_mov_b32_dpp v64, v58 quad_perm:[1,0,3,2] row_mask:0xf bank_mask:0xf
	s_waitcnt lgkmcnt(0)
	v_pk_add_f32 v[54:55], v[54:55], v[56:57]
	s_nop 1
	v_mov_b32_dpp v57, v55 row_half_mirror row_mask:0xf bank_mask:0xf
	s_waitcnt lgkmcnt(0)
	v_pk_add_f32 v[58:59], v[58:59], v[64:65]
	s_nop 1
	v_mov_b32_dpp v56, v54 row_half_mirror row_mask:0xf bank_mask:0xf
	s_nop 1
	v_mov_b32_dpp v65, v59 quad_perm:[2,3,0,1] row_mask:0xf bank_mask:0xf
	s_nop 1
	v_mov_b32_dpp v64, v58 quad_perm:[2,3,0,1] row_mask:0xf bank_mask:0xf
	s_waitcnt lgkmcnt(0)
	v_pk_add_f32 v[54:55], v[54:55], v[56:57]
	s_nop 1
	v_mov_b32_dpp v57, v55 row_mirror row_mask:0xf bank_mask:0xf
	s_waitcnt lgkmcnt(0)
	v_pk_add_f32 v[58:59], v[58:59], v[64:65]
	s_nop 1
	v_mov_b32_dpp v56, v54 row_mirror row_mask:0xf bank_mask:0xf
	s_nop 1
	v_mov_b32_dpp v65, v59 row_half_mirror row_mask:0xf bank_mask:0xf
	s_nop 1
	v_mov_b32_dpp v64, v58 row_half_mirror row_mask:0xf bank_mask:0xf
	s_waitcnt lgkmcnt(0)
	v_pk_add_f32 v[54:55], v[54:55], v[56:57]
	ds_bpermute_b32 v57, v187, v55
	s_waitcnt lgkmcnt(0)
	v_pk_add_f32 v[58:59], v[58:59], v[64:65]
	ds_bpermute_b32 v56, v187, v54
	s_nop 1
	v_mov_b32_dpp v65, v59 row_mirror row_mask:0xf bank_mask:0xf
	s_nop 1
	v_mov_b32_dpp v64, v58 row_mirror row_mask:0xf bank_mask:0xf
	s_waitcnt lgkmcnt(0)
	v_pk_add_f32 v[56:57], v[54:55], v[56:57]
	ds_bpermute_b32 v67, v188, v57
	s_waitcnt lgkmcnt(0)
	v_pk_add_f32 v[58:59], v[58:59], v[64:65]
	ds_bpermute_b32 v66, v188, v56
	ds_bpermute_b32 v65, v187, v59
	ds_bpermute_b32 v64, v187, v58
	s_waitcnt lgkmcnt(0)
	v_pk_add_f32 v[56:57], v[56:57], v[66:67]
	s_waitcnt lgkmcnt(0)
	v_pk_add_f32 v[54:55], v[58:59], v[64:65]
	v_pk_fma_f32 v[58:59], v[56:57], s[20:21], v[28:29] op_sel_hi:[1,0,0]
	ds_bpermute_b32 v57, v188, v55
	v_mul_f32_e32 v29, 0x4b800000, v59
	v_cmp_gt_f32_e64 s[12:13], s22, v59
	ds_bpermute_b32 v56, v188, v54
	v_cmp_gt_f32_e64 s[10:11], s22, v58
	v_cndmask_b32_e64 v29, v59, v29, s[12:13]
	v_rsq_f32_e32 v29, v29
	s_nop 0
	v_mul_f32_e32 v59, 0x45800000, v29
	v_cndmask_b32_e64 v29, v29, v59, s[12:13]
	v_mul_f32_e32 v8, v29, v8
	v_mul_f32_e32 v9, v29, v9
	v_mul_f32_e32 v10, v29, v10
	v_mul_f32_e32 v11, v29, v11
	v_mul_f32_e32 v59, v29, v60
	v_mul_f32_e32 v60, v29, v61
	v_mul_f32_e32 v61, v29, v62
	v_mul_f32_e32 v62, v29, v63
	s_waitcnt vmcnt(0)
	v_mul_f32_e32 v8, v5, v8
	v_mul_f32_e32 v9, v7, v9
	v_mul_f32_e32 v10, v1, v10
	v_mul_f32_e32 v11, v3, v11
	v_mul_f32_e32 v29, v4, v59
	v_mul_f32_e32 v59, v6, v60
	v_mul_f32_e32 v60, v0, v61
	v_mul_f32_e32 v61, v2, v62
	v_cvt_pk_bf16_f32 v8, v29, v8
	v_cvt_pk_bf16_f32 v9, v59, v9
	v_cvt_pk_bf16_f32 v10, v60, v10
	v_cvt_pk_bf16_f32 v11, v61, v11
	s_cbranch_vccnz .LBB0_849
	global_store_dwordx4 v[22:23], v[8:11], off

; __device__ __forceinline__ unsigned xb_add(unsigned* p, unsigned v) { return __hip_atomic_fetch_add(p, v, __ATOMIC_RELAXED, __HIP_MEMORY_SCOPE_AGENT); }
; __device__ __forceinline__ void xcd_barrier(const XcdBarrier& b) {
;     asm volatile("s_waitcnt vmcnt(0)" ::: "memory");
;     __syncthreads();
;     if (threadIdx.x == 0) {
;         unsigned* bar = b.bar;
;         __builtin_amdgcn_s_waitcnt(0);
;         unsigned nloc = b.st[0], nx = b.st[1];
;         if (nloc == 0u) { xcd_barrier_complete(bar, b.x, nloc, nx); b.st[0] = nloc; b.st[1] = nx; }
;         const unsigned old = xb_add(&bar[XB_XSUB(b.x)], 1u);
;         const unsigned gen = old / nloc;
.LBB0_853:
	s_mov_b64 s[10:11], s[80:81]
	s_getreg_b32 s12, hwreg(HW_REG_XCC_ID, 0, 4)
	s_waitcnt vmcnt(0)
	s_barrier
	s_and_saveexec_b64 s[8:9], s[96:97]
	s_cbranch_execz .LBB0_905
	s_add_i32 s0, 0, 0x23fc0
	v_mov_b32_e32 v0, s0
	s_load_dwordx2 s[10:11], s[10:11], 0x110
	s_waitcnt vmcnt(0) expcnt(0) lgkmcnt(0)
	ds_read_b32 v2, v0
	s_add_i32 s0, 0, 0x23fc4
	v_mov_b32_e32 v0, s0
	ds_read_b32 v0, v0
	s_and_b32 s26, s12, 15
	s_waitcnt lgkmcnt(0)
	v_cmp_ne_u32_e32 vcc, 0, v2
	s_cbranch_vccnz .LBB0_869
	s_add_u32 s12, s10, 0x1000
	s_addc_u32 s13, s11, 0
	s_add_u32 s14, s10, 0x1100
	s_addc_u32 s15, s11, 0
	s_add_u32 s16, s10, 0x1200
	s_addc_u32 s17, s11, 0
	s_mul_i32 s27, s95, s93
	s_add_u32 s18, s10, 0x1300
	s_mul_i32 s27, s27, s94
	s_addc_u32 s19, s11, 0
	s_mov_b32 s28, 1
	v_mov_b32_e32 v16, 0
	s_branch .LBB0_857

; __device__ __forceinline__ const float* xrow_ptr(const Ctx& C, int row) { return row < MPROMPT ? C.in(0) + (size_t)row * DM : C.in(1) + (size_t)(row - MPROMPT) * DM; }
; __device__ __forceinline__ v4f ld4_bf16(const bf16* p) { const v2u w = *(const v2u*)p; return (v4f){bf_lo(w.x), bf_hi(w.x), bf_lo(w.y), bf_hi(w.y)}; }
; template <int R, bool BASE_F32, bool OUT_F32>
; __device__ __forceinline__ void rows_res(const Ctx& C, int m0, int stride, int mx, const float* gpost, float scale, int lane) {
;     ...
;     for (int r = 0; r < R; ++r) { mr[r] = (r == 4) ? mx : m0 + r * stride; ok[r] = (r == 4) ? (mx < M) : (mr[r] < MPROMPT); const int mm = ok[r] ? mr[r] : 0;
; #pragma unroll
;         for (int j = 0; j < 4; ++j) d[r][j] = ld4_bf16(D + (size_t)mm * DM + 4 * lane + 256 * j);
;         if (BASE_F32) { const float* x = xrow_ptr(C, mm);
; #pragma unroll
;             for (int j = 0; j < 4; ++j) b[r][j] = ld4_f32(x + 4 * lane + 256 * j);
;         } else { const float inv = C.RS()[mm];
; #pragma unroll
;             for (int j = 0; j < 4; ++j) b[r][j] = ld4_bf16(XN + (size_t)mm * DM + 4 * lane + 256 * j) * inv;
;         } }
.LBB0_997:
	s_mov_b64 s[0:1], s[80:81]
	s_load_dwordx2 s[0:1], s[0:1], 0x110
	s_cmpk_gt_i32 s24, 0x7fff
	s_cselect_b64 s[52:53], -1, 0
	s_mov_b64 s[12:13], s[80:81]
	s_waitcnt lgkmcnt(0)
	v_lshl_add_u64 v[8:9], s[0:1], 0, v[0:1]
	s_and_b64 s[0:1], s[52:53], exec
	s_cselect_b32 s0, 0, s24
	s_ashr_i32 s1, s0, 31
	v_lshl_add_u64 v[14:15], v[8:9], 0, s[18:19]
	s_lshl_b64 s[14:15], s[0:1], 11
	v_lshl_add_u64 v[8:9], v[14:15], 0, s[14:15]
	s_mov_b64 s[26:27], s[80:81]
	s_load_dwordx2 s[12:13], s[12:13], 0x110
	global_load_dwordx2 v[100:101], v[8:9], off
	global_load_dwordx2 v[92:93], v[8:9], off offset:512
	global_load_dwordx2 v[98:99], v[8:9], off offset:1024
	global_load_dwordx2 v[20:21], v[8:9], off offset:1536
	s_load_dwordx2 s[26:27], s[26:27], 0x110
	s_lshl_b64 s[0:1], s[0:1], 2
	s_waitcnt lgkmcnt(0)
	v_lshl_add_u64 v[8:9], s[12:13], 0, v[0:1]
	v_lshl_add_u64 v[8:9], v[8:9], 0, s[20:21]
	v_lshl_add_u64 v[12:13], v[8:9], 0, s[14:15]
	s_add_u32 s0, s26, s0
	s_addc_u32 s1, s27, s1
	s_add_i32 s38, s46, s24
	s_cmp_lt_i32 s38, 0x8000
	s_cselect_b64 s[54:55], -1, 0
	s_cmpk_gt_i32 s38, 0x7fff
	s_cselect_b64 s[40:41], -1, 0
	global_load_dword v10, v3, s[0:1]
	s_and_b64 s[0:1], s[40:41], exec
	s_cselect_b32 s0, 0, s38
	s_ashr_i32 s1, s0, 31
	s_lshl_b64 s[12:13], s[0:1], 11
	global_load_dwordx2 v[22:23], v[12:13], off
	global_load_dwordx2 v[24:25], v[12:13], off offset:512
	global_load_dwordx2 v[26:27], v[12:13], off offset:1024
	global_load_dwordx2 v[28:29], v[12:13], off offset:1536
	v_lshl_add_u64 v[12:13], v[14:15], 0, s[12:13]
	s_mov_b64 s[14:15], s[80:81]
	global_load_dwordx2 v[108:109], v[12:13], off
	global_load_dwordx2 v[104:105], v[12:13], off offset:512
	global_load_dwordx2 v[106:107], v[12:13], off offset:1024
	global_load_dwordx2 v[30:31], v[12:13], off offset:1536
	s_load_dwordx2 s[14:15], s[14:15], 0x110
	s_lshl_b64 s[0:1], s[0:1], 2
	v_lshl_add_u64 v[16:17], v[8:9], 0, s[12:13]
	s_waitcnt lgkmcnt(0)
	s_add_u32 s0, s14, s0
	s_addc_u32 s1, s15, s1
	s_add_i32 s30, s77, s24
	s_cmp_lt_i32 s30, 0x8000
	s_cselect_b64 s[50:51], -1, 0
	s_cmpk_gt_i32 s30, 0x7fff
	s_cselect_b64 s[34:35], -1, 0
	global_load_dword v12, v3, s[0:1]
	s_and_b64 s[0:1], s[34:35], exec
	s_cselect_b32 s0, 0, s30
	s_ashr_i32 s1, s0, 31
	s_lshl_b64 s[12:13], s[0:1], 11
	global_load_dwordx2 v[34:35], v[16:17], off
	global_load_dwordx2 v[36:37], v[16:17], off offset:512
	global_load_dwordx2 v[38:39], v[16:17], off offset:1024
	global_load_dwordx2 v[42:43], v[16:17], off offset:1536
	v_lshl_add_u64 v[16:17], v[14:15], 0, s[12:13]
	s_mov_b64 s[14:15], s[80:81]
	global_load_dwordx2 v[120:121], v[16:17], off
	global_load_dwordx2 v[116:117], v[16:17], off offset:512
	global_load_dwordx2 v[118:119], v[16:17], off offset:1024
	global_load_dwordx2 v[44:45], v[16:17], off offset:1536
	s_load_dwordx2 s[14:15], s[14:15], 0x110
	s_lshl_b64 s[0:1], s[0:1], 2
	v_lshl_add_u64 v[16:17], v[8:9], 0, s[12:13]
	global_load_dwordx2 v[46:47], v[16:17], off
	global_load_dwordx2 v[48:49], v[16:17], off offset:512
	global_load_dwordx2 v[50:51], v[16:17], off offset:1024
	global_load_dwordx2 v[74:75], v[16:17], off offset:1536
	s_waitcnt lgkmcnt(0)
	s_add_u32 s0, s14, s0
	s_addc_u32 s1, s15, s1
	s_add_i32 s26, s78, s24
	s_cmp_lt_i32 s26, 0x8000
	s_cselect_b64 s[36:37], -1, 0
	s_cmpk_gt_i32 s26, 0x7fff
	s_cselect_b64 s[28:29], -1, 0
	s_and_b64 s[12:13], s[28:29], exec
	s_cselect_b32 s12, 0, s26
	s_ashr_i32 s13, s12, 31
	s_lshl_b64 s[14:15], s[12:13], 11
	v_lshl_add_u64 v[14:15], v[14:15], 0, s[14:15]
	global_load_dwordx2 v[78:79], v[14:15], off offset:1536
	global_load_dwordx2 v[138:139], v[14:15], off
	global_load_dwordx2 v[132:133], v[14:15], off offset:512
	global_load_dwordx2 v[136:137], v[14:15], off offset:1024
	s_nop 0
	global_load_dword v14, v3, s[0:1]
	s_mov_b64 s[0:1], s[80:81]
	v_lshl_add_u64 v[80:81], v[8:9], 0, s[14:15]
	global_load_dwordx2 v[82:83], v[80:81], off
	global_load_dwordx2 v[102:103], v[80:81], off offset:512
	global_load_dwordx2 v[110:111], v[80:81], off offset:1024
	s_load_dwordx2 s[0:1], s[0:1], 0x110
	s_lshl_b64 s[12:13], s[12:13], 2
	s_waitcnt lgkmcnt(0)
	s_add_u32 s0, s0, s12
	s_addc_u32 s1, s1, s13
	global_load_dword v40, v3, s[0:1]
	global_load_dwordx2 v[134:135], v[80:81], off offset:1536
	s_mov_b64 s[0:1], s[80:81]
	s_waitcnt vmcnt(35)
	v_and_b32_e32 v115, 0xffff0000, v101
	v_and_b32_e32 v113, 0xffff0000, v100
	v_lshlrev_b32_e32 v114, 16, v101
	s_waitcnt vmcnt(32)
	v_and_b32_e32 v17, 0xffff0000, v20
	v_mul_f32_e32 v16, v115, v115
	v_lshlrev_b32_e32 v112, 16, v100
	v_lshlrev_b32_e32 v19, 16, v20
	v_lshlrev_b32_e32 v101, 16, v93
	v_lshlrev_b32_e32 v100, 16, v92
	v_mov_b32_e32 v127, v19
	v_lshlrev_b32_e32 v20, 16, v21
	v_and_b32_e32 v21, 0xffff0000, v21
	s_waitcnt vmcnt(30)
	v_lshlrev_b32_e32 v88, 16, v22
	s_waitcnt vmcnt(29)
	v_lshlrev_b32_e32 v52, 16, v24
	v_and_b32_e32 v53, 0xffff0000, v24
	v_mul_f32_e32 v24, v17, v17
	v_lshlrev_b32_e32 v54, 16, v25
	v_and_b32_e32 v55, 0xffff0000, v25
	s_waitcnt vmcnt(23)
	v_lshlrev_b32_e32 v25, 16, v30
	v_and_b32_e32 v11, 0xffff0000, v30
	v_mov_b32_e32 v141, v25
	v_lshlrev_b32_e32 v56, 16, v26
	v_and_b32_e32 v57, 0xffff0000, v26
	v_lshlrev_b32_e32 v58, 16, v27
	v_and_b32_e32 v59, 0xffff0000, v27
	v_lshlrev_b32_e32 v26, 16, v31
	v_and_b32_e32 v27, 0xffff0000, v31
	v_and_b32_e32 v89, 0xffff0000, v22
	v_lshlrev_b32_e32 v90, 16, v23
	v_and_b32_e32 v91, 0xffff0000, v23
	v_lshlrev_b32_e32 v22, 16, v28
	v_and_b32_e32 v23, 0xffff0000, v28
	v_lshlrev_b32_e32 v32, 16, v29
	v_and_b32_e32 v33, 0xffff0000, v29
	s_waitcnt vmcnt(21)
	v_lshlrev_b32_e32 v30, 16, v35
	s_waitcnt vmcnt(20)
	v_lshlrev_b32_e32 v70, 16, v37
	v_and_b32_e32 v71, 0xffff0000, v37
	s_waitcnt vmcnt(19)
; __device__ __forceinline__ const float* xrow_ptr(const Ctx& C, int row) { return row < MPROMPT ? C.in(0) + (size_t)row * DM : C.in(1) + (size_t)(row - MPROMPT) * DM; }
; __device__ __forceinline__ v4f ld4_bf16(const bf16* p) { const v2u w = *(const v2u*)p; return (v4f){bf_lo(w.x), bf_hi(w.x), bf_lo(w.y), bf_hi(w.y)}; }
; __device__ __forceinline__ float ssq4(v4f v) { return (v.x * v.x + v.y * v.y) + (v.z * v.z + v.w * v.w); }
; template <int R, bool BASE_F32, bool OUT_F32>
; __device__ __forceinline__ void rows_res(const Ctx& C, int m0, int stride, int mx, const float* gpost, float scale, int lane) {
;     ...
;         for (int j = 0; j < 4; ++j) d[r][j] = ld4_bf16(D + (size_t)mm * DM + 4 * lane + 256 * j);
;         if (BASE_F32) { const float* x = xrow_ptr(C, mm);
; #pragma unroll
;             for (int j = 0; j < 4; ++j) b[r][j] = ld4_f32(x + 4 * lane + 256 * j);
;         } else { const float inv = C.RS()[mm];
; #pragma unroll
;             for (int j = 0; j < 4; ++j) b[r][j] = ld4_bf16(XN + (size_t)mm * DM + 4 * lane + 256 * j) * inv;
;         } }
; #pragma unroll
;     for (int r = 0; r < R; ++r) { float s = 0.f;
; #pragma unroll
;         for (int j = 0; j < 4; ++j) s += ssq4(d[r][j]);
;         r1[r] = s; }
	v_lshlrev_b32_e32 v60, 16, v38
	v_and_b32_e32 v61, 0xffff0000, v38
	v_lshlrev_b32_e32 v62, 16, v39
	v_and_b32_e32 v63, 0xffff0000, v39
	s_waitcnt vmcnt(14)
	v_lshlrev_b32_e32 v37, 16, v44
	v_and_b32_e32 v13, 0xffff0000, v44
	v_lshlrev_b32_e32 v38, 16, v45
	v_and_b32_e32 v39, 0xffff0000, v45
	s_waitcnt vmcnt(13)
	v_lshlrev_b32_e32 v86, 16, v47
	v_and_b32_e32 v87, 0xffff0000, v47
	s_waitcnt vmcnt(12)
	v_lshlrev_b32_e32 v72, 16, v48
	v_and_b32_e32 v73, 0xffff0000, v48
	v_lshlrev_b32_e32 v76, 16, v49
	v_and_b32_e32 v77, 0xffff0000, v49
	s_waitcnt vmcnt(11)
	v_lshlrev_b32_e32 v64, 16, v50
	v_and_b32_e32 v65, 0xffff0000, v50
	v_lshlrev_b32_e32 v66, 16, v51
	v_and_b32_e32 v67, 0xffff0000, v51
	s_waitcnt vmcnt(10)
	v_lshlrev_b32_e32 v44, 16, v74
	v_and_b32_e32 v45, 0xffff0000, v74
	v_lshlrev_b32_e32 v50, 16, v75
	v_and_b32_e32 v51, 0xffff0000, v75
	s_waitcnt vmcnt(9)
	v_lshlrev_b32_e32 v47, 16, v78
	v_and_b32_e32 v15, 0xffff0000, v78
	v_lshlrev_b32_e32 v48, 16, v79
	v_and_b32_e32 v49, 0xffff0000, v79
	s_waitcnt vmcnt(4)
	v_lshlrev_b32_e32 v94, 16, v82
	v_and_b32_e32 v95, 0xffff0000, v82
	v_lshlrev_b32_e32 v96, 16, v83
	v_and_b32_e32 v97, 0xffff0000, v83
	s_waitcnt vmcnt(3)
	v_lshlrev_b32_e32 v80, 16, v102
	v_and_b32_e32 v81, 0xffff0000, v102
	v_lshlrev_b32_e32 v82, 16, v103
	v_and_b32_e32 v83, 0xffff0000, v103
	s_waitcnt vmcnt(2)
	v_lshlrev_b32_e32 v74, 16, v110
	v_and_b32_e32 v75, 0xffff0000, v110
	v_lshlrev_b32_e32 v78, 16, v111
	v_and_b32_e32 v79, 0xffff0000, v111
	v_pk_fma_f32 v[110:111], v[114:115], v[114:115], v[16:17] op_sel_hi:[1,1,0]
	v_and_b32_e32 v103, 0xffff0000, v93
	v_and_b32_e32 v102, 0xffff0000, v92
	v_mul_f32_e32 v16, v113, v113
	v_pk_mul_f32 v[92:93], v[102:103], v[102:103]
	v_pk_fma_f32 v[124:125], v[112:113], v[112:113], v[16:17] op_sel_hi:[1,1,0]
	v_pk_fma_f32 v[122:123], v[100:101], v[100:101], v[92:93]
	v_mov_b32_e32 v18, v124
	v_mov_b32_e32 v126, v110
	v_and_b32_e32 v93, 0xffff0000, v98
	v_pk_add_f32 v[110:111], v[124:125], v[110:111]
	v_pk_mul_f32 v[124:125], v[18:19], v[126:127]
	v_pk_add_f32 v[122:123], v[122:123], v[122:123] op_sel:[0,1] op_sel_hi:[1,0]
	v_lshlrev_b32_e32 v92, 16, v98
	v_lshlrev_b32_e32 v98, 16, v99
	v_and_b32_e32 v99, 0xffff0000, v99
	v_mov_b32_e32 v111, v125
	v_mov_b32_e32 v123, v24
	v_mul_f32_e32 v16, v93, v93
	v_pk_add_f32 v[110:111], v[110:111], v[122:123]
	v_pk_fma_f32 v[122:123], v[92:93], v[92:93], v[16:17] op_sel_hi:[1,1,0]
	v_mul_f32_e32 v16, v99, v99
	v_lshlrev_b32_e32 v68, 16, v36
	v_and_b32_e32 v69, 0xffff0000, v36
	v_lshlrev_b32_e32 v84, 16, v46
	v_and_b32_e32 v85, 0xffff0000, v46
	v_mul_f32_e32 v36, v20, v20
	v_mul_f32_e32 v46, v21, v21
	v_pk_fma_f32 v[124:125], v[98:99], v[98:99], v[16:17] op_sel_hi:[1,1,0]
	v_mov_b32_e32 v123, v36
	v_mov_b32_e32 v125, v46
	v_and_b32_e32 v127, 0xffff0000, v109
	v_pk_add_f32 v[122:123], v[122:123], v[124:125]
	v_and_b32_e32 v125, 0xffff0000, v108
	v_lshlrev_b32_e32 v126, 16, v109
	v_mul_f32_e32 v16, v127, v127
	v_pk_add_f32 v[146:147], v[110:111], v[122:123]
	v_lshlrev_b32_e32 v124, 16, v108
	v_pk_fma_f32 v[122:123], v[126:127], v[126:127], v[16:17] op_sel_hi:[1,1,0]
	v_and_b32_e32 v111, 0xffff0000, v105
	v_and_b32_e32 v110, 0xffff0000, v104
	v_mul_f32_e32 v16, v125, v125
	v_lshlrev_b32_e32 v109, 16, v105
	v_lshlrev_b32_e32 v108, 16, v104
	v_pk_mul_f32 v[104:105], v[110:111], v[110:111]
	v_pk_fma_f32 v[130:131], v[124:125], v[124:125], v[16:17] op_sel_hi:[1,1,0]
	v_pk_fma_f32 v[128:129], v[108:109], v[108:109], v[104:105]
	v_mov_b32_e32 v24, v130
	v_mov_b32_e32 v140, v122
	v_and_b32_e32 v105, 0xffff0000, v106
	v_mul_f32_e32 v18, v11, v11
	v_pk_add_f32 v[122:123], v[130:131], v[122:123]
	v_pk_mul_f32 v[130:131], v[24:25], v[140:141]
	v_pk_add_f32 v[128:129], v[128:129], v[128:129] op_sel:[0,1] op_sel_hi:[1,0]
	v_lshlrev_b32_e32 v104, 16, v106
	v_lshlrev_b32_e32 v106, 16, v107
	v_and_b32_e32 v107, 0xffff0000, v107
	v_mov_b32_e32 v123, v131
	v_mov_b32_e32 v129, v18
	v_mul_f32_e32 v16, v105, v105
	v_pk_add_f32 v[122:123], v[122:123], v[128:129]
	v_pk_fma_f32 v[128:129], v[104:105], v[104:105], v[16:17] op_sel_hi:[1,1,0]
	v_mul_f32_e32 v16, v107, v107
	v_mul_f32_e32 v36, v26, v26
	v_mul_f32_e32 v46, v27, v27
	v_pk_fma_f32 v[130:131], v[106:107], v[106:107], v[16:17] op_sel_hi:[1,1,0]
	v_mov_b32_e32 v129, v36
	v_mov_b32_e32 v131, v46
	v_pk_add_f32 v[128:129], v[128:129], v[130:131]
	v_and_b32_e32 v131, 0xffff0000, v121
	v_pk_add_f32 v[150:151], v[122:123], v[128:129]
	v_and_b32_e32 v129, 0xffff0000, v120
	v_lshlrev_b32_e32 v130, 16, v121
	v_mul_f32_e32 v16, v131, v131
	v_lshlrev_b32_e32 v128, 16, v120
	v_pk_fma_f32 v[140:141], v[130:131], v[130:131], v[16:17] op_sel_hi:[1,1,0]
	v_and_b32_e32 v123, 0xffff0000, v117
	v_and_b32_e32 v122, 0xffff0000, v116
	v_mul_f32_e32 v16, v129, v129
	v_lshlrev_b32_e32 v121, 16, v117
	v_lshlrev_b32_e32 v120, 16, v116
	v_pk_mul_f32 v[116:117], v[122:123], v[122:123]
	v_pk_fma_f32 v[144:145], v[128:129], v[128:129], v[16:17] op_sel_hi:[1,1,0]
	v_pk_fma_f32 v[142:143], v[120:121], v[120:121], v[116:117]
	v_mov_b32_e32 v36, v144
	v_mov_b32_e32 v152, v140
	v_mov_b32_e32 v153, v37
	v_and_b32_e32 v117, 0xffff0000, v118
	v_mul_f32_e32 v18, v13, v13
	v_pk_add_f32 v[140:141], v[144:145], v[140:141]
	v_pk_mul_f32 v[144:145], v[36:37], v[152:153]
	v_pk_add_f32 v[142:143], v[142:143], v[142:143] op_sel:[0,1] op_sel_hi:[1,0]
	v_lshlrev_b32_e32 v116, 16, v118
	v_lshlrev_b32_e32 v118, 16, v119
	v_and_b32_e32 v119, 0xffff0000, v119
	v_mov_b32_e32 v141, v145
	v_mov_b32_e32 v143, v18
	v_mul_f32_e32 v16, v117, v117
	v_pk_add_f32 v[140:141], v[140:141], v[142:143]
	v_pk_fma_f32 v[142:143], v[116:117], v[116:117], v[16:17] op_sel_hi:[1,1,0]
; __device__ __forceinline__ float ssq4(v4f v) { return (v.x * v.x + v.y * v.y) + (v.z * v.z + v.w * v.w); }
; __device__ __forceinline__ float wave_sum(float v) {
; #pragma unroll
;     for (int o = 1; o < 64; o <<= 1) v += __shfl_xor(v, o);
;     return v;
; }
; template <int R, bool BASE_F32, bool OUT_F32>
; __device__ __forceinline__ void rows_res(const Ctx& C, int m0, int stride, int mx, const float* gpost, float scale, int lane) {
;     ...
;     for (int r = 0; r < R; ++r) { float s = 0.f;
; #pragma unroll
;         for (int j = 0; j < 4; ++j) s += ssq4(d[r][j]);
;         r1[r] = s; }
; #pragma unroll
;     for (int r = 0; r < R; ++r) r1[r] = rsqrtf(wave_sum(r1[r]) * (1.f / DM) + EPS) * scale;
; #pragma unroll
;     for (int j = 0; j < 4; ++j) { const v4f gp = ld4_f32(gpost + 4 * lane + 256 * j);
; #pragma unroll
;         for (int r = 0; r < R; ++r) d[r][j] = b[r][j] + d[r][j] * r1[r] * gp; }
	v_mul_f32_e32 v16, v119, v119
	v_mul_f32_e32 v24, v38, v38
	v_mul_f32_e32 v46, v39, v39
	v_pk_fma_f32 v[144:145], v[118:119], v[118:119], v[16:17] op_sel_hi:[1,1,0]
	v_mov_b32_e32 v143, v24
	v_mov_b32_e32 v145, v46
	v_pk_add_f32 v[142:143], v[142:143], v[144:145]
	v_and_b32_e32 v145, 0xffff0000, v139
	v_pk_add_f32 v[154:155], v[140:141], v[142:143]
	v_and_b32_e32 v143, 0xffff0000, v138
	v_lshlrev_b32_e32 v144, 16, v139
	v_mul_f32_e32 v16, v145, v145
	v_lshlrev_b32_e32 v142, 16, v138
	v_pk_fma_f32 v[152:153], v[144:145], v[144:145], v[16:17] op_sel_hi:[1,1,0]
	v_mul_f32_e32 v16, v143, v143
	v_pk_fma_f32 v[158:159], v[142:143], v[142:143], v[16:17] op_sel_hi:[1,1,0]
	v_mov_b32_e32 v160, v152
	v_mov_b32_e32 v46, v158
	v_mov_b32_e32 v161, v47
	v_pk_add_f32 v[152:153], v[158:159], v[152:153]
	v_pk_mul_f32 v[158:159], v[46:47], v[160:161]
	v_mov_b32_e32 v160, v150
	v_mov_b32_e32 v161, v146
	v_mov_b32_e32 v146, v151
	v_pk_add_f32 v[146:147], v[160:161], v[146:147]
	v_and_b32_e32 v141, 0xffff0000, v133
	v_and_b32_e32 v140, 0xffff0000, v132
	s_nop 1
	v_mov_b32_dpp v151, v147 quad_perm:[1,0,3,2] row_mask:0xf bank_mask:0xf
	s_nop 1
	v_mov_b32_dpp v150, v146 quad_perm:[1,0,3,2] row_mask:0xf bank_mask:0xf
	v_lshlrev_b32_e32 v139, 16, v133
	v_lshlrev_b32_e32 v138, 16, v132
	v_pk_mul_f32 v[132:133], v[140:141], v[140:141]
	v_mul_f32_e32 v18, v15, v15
	v_pk_fma_f32 v[156:157], v[138:139], v[138:139], v[132:133]
	v_mov_b32_e32 v153, v159
	v_pk_add_f32 v[156:157], v[156:157], v[156:157] op_sel:[0,1] op_sel_hi:[1,0]
	s_waitcnt lgkmcnt(0)
	v_pk_add_f32 v[146:147], v[146:147], v[150:151]
	v_mov_b32_e32 v157, v18
	v_pk_add_f32 v[156:157], v[152:153], v[156:157]
	global_load_dwordx4 v[150:153], v[4:5], off
	s_nop 1
	v_mov_b32_dpp v159, v147 quad_perm:[2,3,0,1] row_mask:0xf bank_mask:0xf
	s_nop 1
	v_mov_b32_dpp v158, v146 quad_perm:[2,3,0,1] row_mask:0xf bank_mask:0xf
	v_and_b32_e32 v133, 0xffff0000, v136
	v_lshlrev_b32_e32 v132, 16, v136
	v_lshlrev_b32_e32 v136, 16, v137
	v_and_b32_e32 v137, 0xffff0000, v137
	v_mul_f32_e32 v16, v133, v133
	s_waitcnt lgkmcnt(0)
	v_pk_add_f32 v[146:147], v[146:147], v[158:159]
	v_pk_fma_f32 v[160:161], v[132:133], v[132:133], v[16:17] op_sel_hi:[1,1,0]
	v_mul_f32_e32 v16, v137, v137
	s_nop 1
	v_mov_b32_dpp v159, v147 row_half_mirror row_mask:0xf bank_mask:0xf
	s_nop 1
	v_mov_b32_dpp v158, v146 row_half_mirror row_mask:0xf bank_mask:0xf
	v_mul_f32_e32 v24, v48, v48
	v_mul_f32_e32 v36, v49, v49
	v_pk_fma_f32 v[162:163], v[136:137], v[136:137], v[16:17] op_sel_hi:[1,1,0]
	v_mov_b32_e32 v161, v24
	v_mov_b32_e32 v163, v36
	v_pk_add_f32 v[160:161], v[160:161], v[162:163]
	s_waitcnt lgkmcnt(0)
	v_pk_add_f32 v[158:159], v[146:147], v[158:159]
	v_pk_add_f32 v[156:157], v[156:157], v[160:161]
	v_mov_b32_e32 v147, v154
	v_mov_b32_e32 v146, v156
	v_mov_b32_e32 v154, v157
	v_pk_add_f32 v[154:155], v[146:147], v[154:155]
	s_nop 1
	v_mov_b32_dpp v161, v159 row_mirror row_mask:0xf bank_mask:0xf
	s_nop 1
	v_mov_b32_dpp v160, v158 row_mirror row_mask:0xf bank_mask:0xf
	s_nop 1
	v_mov_b32_dpp v157, v155 quad_perm:[1,0,3,2] row_mask:0xf bank_mask:0xf
	s_nop 1
	v_mov_b32_dpp v156, v154 quad_perm:[1,0,3,2] row_mask:0xf bank_mask:0xf
	v_and_b32_e32 v31, 0xffff0000, v35
	v_lshlrev_b32_e32 v28, 16, v34
	s_waitcnt lgkmcnt(0)
	v_pk_add_f32 v[158:159], v[158:159], v[160:161]
	ds_bpermute_b32 v161, v187, v159
	s_waitcnt lgkmcnt(0)
	v_pk_add_f32 v[162:163], v[154:155], v[156:157]
	ds_bpermute_b32 v160, v187, v158
	s_nop 1
	v_mov_b32_dpp v165, v163 quad_perm:[2,3,0,1] row_mask:0xf bank_mask:0xf
	s_nop 1
	v_mov_b32_dpp v164, v162 quad_perm:[2,3,0,1] row_mask:0xf bank_mask:0xf
	global_load_dwordx4 v[154:157], v[4:5], off offset:1024
	v_and_b32_e32 v29, 0xffff0000, v34
	s_waitcnt lgkmcnt(0)
	v_pk_add_f32 v[158:159], v[158:159], v[160:161]
	ds_bpermute_b32 v161, v188, v159
	s_waitcnt lgkmcnt(0)
	v_pk_add_f32 v[162:163], v[162:163], v[164:165]
	ds_bpermute_b32 v160, v188, v158
	s_nop 1
	v_mov_b32_dpp v165, v163 row_half_mirror row_mask:0xf bank_mask:0xf
	s_nop 1
	v_mov_b32_dpp v164, v162 row_half_mirror row_mask:0xf bank_mask:0xf
	v_lshlrev_b32_e32 v34, 16, v42
	v_and_b32_e32 v35, 0xffff0000, v42
	s_waitcnt lgkmcnt(0)
	v_pk_add_f32 v[158:159], v[158:159], v[160:161]
	v_lshlrev_b32_e32 v42, 16, v43
	s_waitcnt lgkmcnt(0)
	v_pk_add_f32 v[160:161], v[162:163], v[164:165]
	s_nop 1
	v_mov_b32_dpp v163, v161 row_mirror row_mask:0xf bank_mask:0xf
	s_nop 1
	v_mov_b32_dpp v162, v160 row_mirror row_mask:0xf bank_mask:0xf
	v_pk_fma_f32 v[158:159], v[158:159], s[22:23], v[6:7] op_sel_hi:[1,0,0]
	v_and_b32_e32 v43, 0xffff0000, v43
	v_mul_f32_e32 v16, 0x4b800000, v159
	v_cmp_gt_f32_e32 vcc, s42, v159
	s_waitcnt lgkmcnt(0)
	v_pk_add_f32 v[160:161], v[160:161], v[162:163]
	ds_bpermute_b32 v163, v187, v161
	ds_bpermute_b32 v162, v187, v160
	v_cndmask_b32_e32 v16, v159, v16, vcc
	v_rsq_f32_e32 v16, v16
	v_mul_f32_e32 v18, 0x4b800000, v158
	v_cmp_gt_f32_e64 s[12:13], s42, v158
	s_waitcnt lgkmcnt(0)
	v_pk_add_f32 v[162:163], v[160:161], v[162:163]
	ds_bpermute_b32 v165, v188, v163
	ds_bpermute_b32 v164, v188, v162
	v_cndmask_b32_e64 v18, v158, v18, s[12:13]
	v_rsq_f32_e32 v24, v18
	v_mul_f32_e32 v18, 0x45800000, v16
	global_load_dwordx4 v[158:161], v[4:5], off offset:2048
	s_waitcnt lgkmcnt(0)
	v_pk_add_f32 v[162:163], v[162:163], v[164:165]
	v_cndmask_b32_e32 v18, v16, v18, vcc
	v_pk_fma_f32 v[162:163], v[162:163], s[22:23], v[6:7] op_sel_hi:[1,0,0]
	v_mul_f32_e32 v16, 0x45800000, v24
	v_mul_f32_e32 v36, 0x4b800000, v163
	v_cmp_gt_f32_e32 vcc, s42, v163
	v_mul_f32_e32 v46, 0x4b800000, v162
	v_cmp_gt_f32_e64 s[14:15], s42, v162
	v_pk_mul_f32 v[114:115], v[18:19], v[114:115] op_sel_hi:[0,1]
	v_pk_mul_f32 v[112:113], v[18:19], v[112:113] op_sel_hi:[0,1]
	v_cndmask_b32_e32 v36, v163, v36, vcc
	v_cndmask_b32_e64 v46, v162, v46, s[14:15]
	v_cndmask_b32_e64 v24, v24, v16, s[12:13]
	s_waitcnt vmcnt(2)
; template <int R, bool BASE_F32, bool OUT_F32>
; __device__ __forceinline__ void rows_res(const Ctx& C, int m0, int stride, int mx, const float* gpost, float scale, int lane) {
;     ...
;     for (int j = 0; j < 4; ++j) { const v4f gp = ld4_f32(gpost + 4 * lane + 256 * j);
; #pragma unroll
;         for (int r = 0; r < R; ++r) d[r][j] = b[r][j] + d[r][j] * r1[r] * gp; }
	v_pk_mul_f32 v[162:163], v[112:113], v[150:151]
	v_pk_mul_f32 v[112:113], v[114:115], v[152:153]
	v_pk_fma_f32 v[114:115], v[10:11], v[88:89], v[162:163] op_sel_hi:[0,1,1]
	v_pk_fma_f32 v[112:113], v[10:11], v[90:91], v[112:113] op_sel_hi:[0,1,1]
	v_pk_mul_f32 v[88:89], v[24:25], v[126:127] op_sel_hi:[0,1]
	v_pk_mul_f32 v[90:91], v[24:25], v[124:125] op_sel_hi:[0,1]
	global_load_dwordx4 v[124:127], v[4:5], off offset:3072
	v_rsq_f32_e32 v36, v36
	v_rsq_f32_e32 v46, v46
	v_pk_mul_f32 v[88:89], v[88:89], v[152:153]
	v_pk_mul_f32 v[90:91], v[90:91], v[150:151]
	v_mul_f32_e32 v16, 0x45800000, v36
	v_cndmask_b32_e32 v36, v36, v16, vcc
	v_mul_f32_e32 v16, 0x45800000, v46
	v_pk_fma_f32 v[88:89], v[12:13], v[30:31], v[88:89] op_sel_hi:[0,1,1]
	v_pk_mul_f32 v[30:31], v[36:37], v[128:129] op_sel_hi:[0,1]
	v_cndmask_b32_e64 v46, v46, v16, s[14:15]
	v_pk_fma_f32 v[90:91], v[12:13], v[28:29], v[90:91] op_sel_hi:[0,1,1]
	v_pk_mul_f32 v[28:29], v[36:37], v[130:131] op_sel_hi:[0,1]
	v_pk_mul_f32 v[30:31], v[150:151], v[30:31]
	v_pk_mul_f32 v[28:29], v[152:153], v[28:29]
	v_pk_fma_f32 v[84:85], v[14:15], v[84:85], v[30:31] op_sel_hi:[0,1,1]
	v_pk_mul_f32 v[30:31], v[46:47], v[142:143] op_sel_hi:[0,1]
	v_pk_fma_f32 v[86:87], v[14:15], v[86:87], v[28:29] op_sel_hi:[0,1,1]
	v_pk_mul_f32 v[28:29], v[46:47], v[144:145] op_sel_hi:[0,1]
	v_pk_mul_f32 v[30:31], v[150:151], v[30:31]
	v_pk_mul_f32 v[28:29], v[152:153], v[28:29]
	v_pk_fma_f32 v[30:31], v[40:41], v[94:95], v[30:31] op_sel_hi:[0,1,1]
	v_mov_b32_e32 v94, v101
	v_mov_b32_e32 v101, v102
	v_pk_fma_f32 v[28:29], v[40:41], v[96:97], v[28:29] op_sel_hi:[0,1,1]
	v_pk_mul_f32 v[96:97], v[18:19], v[100:101] op_sel_hi:[0,1]
	v_mov_b32_e32 v95, v103
	v_pk_mul_f32 v[94:95], v[18:19], v[94:95] op_sel_hi:[0,1]
	s_waitcnt vmcnt(2)
	v_pk_mul_f32 v[96:97], v[96:97], v[154:155]
	v_pk_mul_f32 v[94:95], v[94:95], v[156:157]
	v_pk_fma_f32 v[102:103], v[10:11], v[52:53], v[96:97] op_sel_hi:[0,1,1]
	v_mov_b32_e32 v52, v109
	v_mov_b32_e32 v53, v111
	v_pk_mul_f32 v[52:53], v[24:25], v[52:53] op_sel_hi:[0,1]
	v_mov_b32_e32 v109, v110
	v_pk_mul_f32 v[52:53], v[52:53], v[156:157]
	v_pk_fma_f32 v[100:101], v[10:11], v[54:55], v[94:95] op_sel_hi:[0,1,1]
	v_pk_mul_f32 v[54:55], v[24:25], v[108:109] op_sel_hi:[0,1]
	v_pk_fma_f32 v[94:95], v[12:13], v[70:71], v[52:53] op_sel_hi:[0,1,1]
	v_mov_b32_e32 v52, v121
	v_mov_b32_e32 v53, v123
	v_pk_mul_f32 v[54:55], v[54:55], v[154:155]
	v_pk_mul_f32 v[52:53], v[36:37], v[52:53] op_sel_hi:[0,1]
	v_mov_b32_e32 v121, v122
	v_pk_fma_f32 v[96:97], v[12:13], v[68:69], v[54:55] op_sel_hi:[0,1,1]
	v_pk_mul_f32 v[54:55], v[36:37], v[120:121] op_sel_hi:[0,1]
	v_pk_mul_f32 v[52:53], v[156:157], v[52:53]
	v_pk_mul_f32 v[54:55], v[154:155], v[54:55]
	v_pk_fma_f32 v[68:69], v[14:15], v[76:77], v[52:53] op_sel_hi:[0,1,1]
	v_mov_b32_e32 v52, v139
	v_mov_b32_e32 v139, v140
	v_pk_fma_f32 v[70:71], v[14:15], v[72:73], v[54:55] op_sel_hi:[0,1,1]
	v_pk_mul_f32 v[54:55], v[46:47], v[138:139] op_sel_hi:[0,1]
	v_pk_mul_f32 v[72:73], v[18:19], v[98:99] op_sel_hi:[0,1]
	v_mov_b32_e32 v53, v141
	v_pk_mul_f32 v[54:55], v[154:155], v[54:55]
	v_pk_mul_f32 v[52:53], v[46:47], v[52:53] op_sel_hi:[0,1]
	v_pk_fma_f32 v[54:55], v[40:41], v[80:81], v[54:55] op_sel_hi:[0,1,1]
	v_pk_mul_f32 v[76:77], v[18:19], v[92:93] op_sel_hi:[0,1]
	v_pk_mul_f32 v[52:53], v[156:157], v[52:53]
	s_waitcnt vmcnt(1)
	v_pk_mul_f32 v[72:73], v[72:73], v[160:161]
	v_pk_mul_f32 v[76:77], v[76:77], v[158:159]
	v_pk_fma_f32 v[80:81], v[10:11], v[58:59], v[72:73] op_sel_hi:[0,1,1]
	v_pk_mul_f32 v[58:59], v[24:25], v[104:105] op_sel_hi:[0,1]
	v_pk_mul_f32 v[58:59], v[58:59], v[158:159]
	v_mov_b32_e32 v16, v19
	v_pk_fma_f32 v[52:53], v[40:41], v[82:83], v[52:53] op_sel_hi:[0,1,1]
	v_pk_fma_f32 v[82:83], v[10:11], v[56:57], v[76:77] op_sel_hi:[0,1,1]
	v_pk_mul_f32 v[56:57], v[24:25], v[106:107] op_sel_hi:[0,1]
	v_pk_fma_f32 v[76:77], v[12:13], v[60:61], v[58:59] op_sel_hi:[0,1,1]
	v_pk_mul_f32 v[58:59], v[36:37], v[116:117] op_sel_hi:[0,1]
	v_pk_mul_f32 v[20:21], v[18:19], v[20:21] op_sel_hi:[0,1]
	v_pk_mul_f32 v[16:17], v[18:19], v[16:17] op_sel_hi:[0,1]
	v_pk_mul_f32 v[56:57], v[56:57], v[160:161]
	v_pk_mul_f32 v[58:59], v[158:159], v[58:59]
	v_pk_fma_f32 v[72:73], v[12:13], v[62:63], v[56:57] op_sel_hi:[0,1,1]
	v_pk_fma_f32 v[62:63], v[14:15], v[64:65], v[58:59] op_sel_hi:[0,1,1]
	v_pk_mul_f32 v[56:57], v[36:37], v[118:119] op_sel_hi:[0,1]
	v_pk_mul_f32 v[56:57], v[160:161], v[56:57]
	v_pk_mul_f32 v[58:59], v[46:47], v[132:133] op_sel_hi:[0,1]
	s_waitcnt vmcnt(0)
; __device__ __forceinline__ float ssq4(v4f v) { return (v.x * v.x + v.y * v.y) + (v.z * v.z + v.w * v.w); }
; __device__ __forceinline__ float wave_sum(float v) {
; #pragma unroll
;     for (int o = 1; o < 64; o <<= 1) v += __shfl_xor(v, o);
;     return v;
; }
; template <int R, bool BASE_F32, bool OUT_F32>
; __device__ __forceinline__ void rows_res(const Ctx& C, int m0, int stride, int mx, const float* gpost, float scale, int lane) {
;     ...
;     } else { float* rs = C.RS(); float t[R];
; #pragma unroll
;         for (int r = 0; r < R; ++r) { float s = 0.f;
; #pragma unroll
;             for (int j = 0; j < 4; ++j) s += ssq4(d[r][j]);
;             t[r] = s; }
; #pragma unroll
;         for (int r = 0; r < R; ++r) t[r] = wave_sum(t[r]) * (1.f / DM) + EPS;
	v_pk_mul_f32 v[16:17], v[16:17], v[124:125]
	v_pk_mul_f32 v[18:19], v[20:21], v[126:127]
	v_pk_fma_f32 v[64:65], v[10:11], v[22:23], v[16:17] op_sel_hi:[0,1,1]
	v_pk_fma_f32 v[32:33], v[10:11], v[32:33], v[18:19] op_sel_hi:[0,1,1]
	v_mov_b32_e32 v10, v25
	v_pk_mul_f32 v[16:17], v[24:25], v[26:27] op_sel_hi:[0,1]
	v_pk_mul_f32 v[10:11], v[24:25], v[10:11] op_sel_hi:[0,1]
	v_pk_mul_f32 v[10:11], v[10:11], v[124:125]
	v_pk_mul_f32 v[16:17], v[16:17], v[126:127]
	v_pk_fma_f32 v[22:23], v[12:13], v[34:35], v[10:11] op_sel_hi:[0,1,1]
	v_pk_fma_f32 v[20:21], v[12:13], v[42:43], v[16:17] op_sel_hi:[0,1,1]
	v_mov_b32_e32 v12, v37
	v_pk_mul_f32 v[10:11], v[36:37], v[38:39] op_sel_hi:[0,1]
	v_pk_mul_f32 v[12:13], v[36:37], v[12:13] op_sel_hi:[0,1]
	v_pk_mul_f32 v[12:13], v[124:125], v[12:13]
	v_pk_mul_f32 v[10:11], v[126:127], v[10:11]
	v_pk_fma_f32 v[60:61], v[14:15], v[66:67], v[56:57] op_sel_hi:[0,1,1]
	v_pk_fma_f32 v[16:17], v[14:15], v[50:51], v[10:11] op_sel_hi:[0,1,1]
	v_pk_fma_f32 v[18:19], v[14:15], v[44:45], v[12:13] op_sel_hi:[0,1,1]
	v_mov_b32_e32 v14, v47
	v_pk_mul_f32 v[12:13], v[46:47], v[14:15] op_sel_hi:[0,1]
	v_mul_f32_e32 v14, v115, v115
	v_mul_f32_e32 v15, v113, v113
	v_fmac_f32_e32 v14, v114, v114
	v_fmac_f32_e32 v15, v112, v112
	v_add_f32_e32 v14, v14, v15
	v_mul_f32_e32 v15, v103, v103
	v_mul_f32_e32 v24, v101, v101
	v_fmac_f32_e32 v15, v102, v102
	v_fmac_f32_e32 v24, v100, v100
	v_add_f32_e32 v15, v15, v24
	v_add_f32_e32 v14, v14, v15
	v_mul_f32_e32 v15, v83, v83
	v_mul_f32_e32 v24, v81, v81
	v_fmac_f32_e32 v15, v82, v82
	v_fmac_f32_e32 v24, v80, v80
	v_add_f32_e32 v15, v15, v24
	v_add_f32_e32 v14, v14, v15
	v_mul_f32_e32 v15, v65, v65
	v_mul_f32_e32 v24, v33, v33
	v_fmac_f32_e32 v15, v64, v64
	v_fmac_f32_e32 v24, v32, v32
	v_add_f32_e32 v15, v15, v24
	v_add_f32_e32 v14, v14, v15
	v_mul_f32_e32 v15, v91, v91
	v_mul_f32_e32 v24, v89, v89
	v_fmac_f32_e32 v15, v90, v90
	v_fmac_f32_e32 v24, v88, v88
	v_add_f32_e32 v15, v15, v24
	v_mul_f32_e32 v24, v97, v97
	v_mul_f32_e32 v25, v95, v95
	v_fmac_f32_e32 v24, v96, v96
	v_fmac_f32_e32 v25, v94, v94
	v_add_f32_e32 v24, v24, v25
	v_add_f32_e32 v15, v15, v24
	v_mul_f32_e32 v24, v77, v77
	v_mul_f32_e32 v25, v73, v73
	v_fmac_f32_e32 v24, v76, v76
	v_fmac_f32_e32 v25, v72, v72
	v_add_f32_e32 v24, v24, v25
	v_add_f32_e32 v15, v15, v24
	v_mul_f32_e32 v24, v23, v23
	v_mul_f32_e32 v25, v21, v21
	v_fmac_f32_e32 v24, v22, v22
	v_fmac_f32_e32 v25, v20, v20
	v_add_f32_e32 v24, v24, v25
	v_add_f32_e32 v15, v15, v24
	v_mul_f32_e32 v24, v85, v85
	v_mul_f32_e32 v25, v87, v87
	v_fmac_f32_e32 v24, v84, v84
	v_fmac_f32_e32 v25, v86, v86
	v_add_f32_e32 v24, v24, v25
	v_mul_f32_e32 v25, v71, v71
	v_mul_f32_e32 v26, v69, v69
	v_fmac_f32_e32 v25, v70, v70
	v_fmac_f32_e32 v26, v68, v68
	v_add_f32_e32 v25, v25, v26
	v_add_f32_e32 v24, v24, v25
	v_mul_f32_e32 v25, v63, v63
	v_mul_f32_e32 v26, v61, v61
	v_fmac_f32_e32 v25, v62, v62
	v_fmac_f32_e32 v26, v60, v60
	v_add_f32_e32 v25, v25, v26
	v_add_f32_e32 v24, v25, v24
	v_mul_f32_e32 v25, v19, v19
	v_mul_f32_e32 v26, v17, v17
	v_fmac_f32_e32 v25, v18, v18
	v_fmac_f32_e32 v26, v16, v16
	v_add_f32_e32 v25, v25, v26
	s_nop 1
	v_mov_b32_dpp v26, v14 quad_perm:[1,0,3,2] row_mask:0xf bank_mask:0xf
	v_add_f32_e32 v24, v25, v24
	v_mul_f32_e32 v25, v31, v31
	v_mul_f32_e32 v27, v29, v29
	v_fmac_f32_e32 v25, v30, v30
	s_waitcnt lgkmcnt(0)
	v_add_f32_e32 v14, v14, v26
	s_nop 1
	v_mov_b32_dpp v26, v14 quad_perm:[2,3,0,1] row_mask:0xf bank_mask:0xf
	v_fmac_f32_e32 v27, v28, v28
	v_pk_mul_f32 v[56:57], v[46:47], v[136:137] op_sel_hi:[0,1]
	v_add_f32_e32 v25, v25, v27
	v_mul_f32_e32 v27, v55, v55
	s_waitcnt lgkmcnt(0)
	v_add_f32_e32 v14, v14, v26
	s_nop 1
	v_mov_b32_dpp v26, v14 row_half_mirror row_mask:0xf bank_mask:0xf
	v_mul_f32_e32 v34, v53, v53
	v_pk_mul_f32 v[58:59], v[158:159], v[58:59]
	v_pk_mul_f32 v[56:57], v[160:161], v[56:57]
	v_fmac_f32_e32 v27, v54, v54
	s_waitcnt lgkmcnt(0)
	v_add_f32_e32 v14, v14, v26
	s_nop 1
	v_mov_b32_dpp v26, v14 row_mirror row_mask:0xf bank_mask:0xf
	v_fmac_f32_e32 v34, v52, v52
	v_pk_fma_f32 v[56:57], v[40:41], v[78:79], v[56:57] op_sel_hi:[0,1,1]
	v_pk_fma_f32 v[58:59], v[40:41], v[74:75], v[58:59] op_sel_hi:[0,1,1]
	v_add_f32_e32 v27, v27, v34
	s_waitcnt lgkmcnt(0)
; __device__ __forceinline__ void st4_bf16(bf16* p, v4f o) { v2u w; w.x = cvt_pk_nv(o.x, o.y); w.y = cvt_pk_nv(o.z, o.w); *(v2u*)p = w; }
; template <int R, bool BASE_F32, bool OUT_F32>
; __device__ __forceinline__ void rows_res(const Ctx& C, int m0, int stride, int mx, const float* gpost, float scale, int lane) {
;     ...
; #pragma unroll
;         for (int r = 0; r < R; ++r) t[r] = wave_sum(t[r]) * (1.f / DM) + EPS;
; #pragma unroll
;         for (int r = 0; r < R; ++r) { const float rstd = rsqrtf(t[r]);
; #pragma unroll
;             for (int j = 0; j < 4; ++j) if (ok[r]) st4_bf16(XN + (size_t)mr[r] * DM + 4 * lane + 256 * j, d[r][j] * rstd);
;             if (lane == 0 && ok[r]) rs[mr[r]] = sqrtf(t[r]); }
	v_add_f32_e32 v14, v14, v26
	ds_bpermute_b32 v26, v187, v14
	v_pk_mul_f32 v[10:11], v[46:47], v[48:49] op_sel_hi:[0,1]
	v_add_f32_e32 v25, v25, v27
	v_mul_f32_e32 v27, v59, v59
	v_mul_f32_e32 v34, v57, v57
	v_lshlrev_b32_e32 v146, 16, v134
	v_and_b32_e32 v147, 0xffff0000, v134
	v_lshlrev_b32_e32 v134, 16, v135
	v_and_b32_e32 v135, 0xffff0000, v135
	v_pk_mul_f32 v[12:13], v[124:125], v[12:13]
	v_pk_mul_f32 v[10:11], v[126:127], v[10:11]
	v_fmac_f32_e32 v27, v58, v58
	v_fmac_f32_e32 v34, v56, v56
	s_waitcnt lgkmcnt(0)
	v_add_f32_e32 v14, v14, v26
	v_pk_fma_f32 v[10:11], v[40:41], v[134:135], v[10:11] op_sel_hi:[0,1,1]
	v_pk_fma_f32 v[12:13], v[40:41], v[146:147], v[12:13] op_sel_hi:[0,1,1]
	v_add_f32_e32 v27, v27, v34
	ds_bpermute_b32 v26, v188, v14
	v_add_f32_e32 v25, v27, v25
	v_mul_f32_e32 v27, v13, v13
	v_mul_f32_e32 v34, v11, v11
	v_fmac_f32_e32 v27, v12, v12
	v_fmac_f32_e32 v34, v10, v10
	v_add_f32_e32 v27, v27, v34
	v_add_f32_e32 v25, v27, v25
	s_nop 1
	v_mov_b32_dpp v34, v15 quad_perm:[1,0,3,2] row_mask:0xf bank_mask:0xf
	s_nop 1
	v_mov_b32_dpp v27, v24 quad_perm:[1,0,3,2] row_mask:0xf bank_mask:0xf
	s_waitcnt lgkmcnt(0)
	v_add_f32_e32 v35, v14, v26
	s_nop 1
	v_mov_b32_dpp v14, v25 quad_perm:[1,0,3,2] row_mask:0xf bank_mask:0xf
	s_waitcnt lgkmcnt(0)
	v_add_f32_e32 v15, v15, v34
	s_waitcnt lgkmcnt(0)
	v_add_f32_e32 v24, v24, v27
	s_nop 1
	v_mov_b32_dpp v26, v15 quad_perm:[2,3,0,1] row_mask:0xf bank_mask:0xf
	s_waitcnt lgkmcnt(0)
	v_add_f32_e32 v14, v25, v14
	s_nop 1
	v_mov_b32_dpp v27, v24 quad_perm:[2,3,0,1] row_mask:0xf bank_mask:0xf
	s_nop 1
	v_mov_b32_dpp v25, v14 quad_perm:[2,3,0,1] row_mask:0xf bank_mask:0xf
	s_load_dwordx2 s[12:13], s[0:1], 0x110
	s_waitcnt lgkmcnt(0)
	v_add_f32_e32 v15, v15, v26
	s_nop 1
	v_mov_b32_dpp v26, v15 row_half_mirror row_mask:0xf bank_mask:0xf
	v_add_f32_e32 v24, v24, v27
	v_add_f32_e32 v14, v14, v25
	s_nop 1
	v_mov_b32_dpp v27, v24 row_half_mirror row_mask:0xf bank_mask:0xf
	s_nop 1
	v_mov_b32_dpp v25, v14 row_half_mirror row_mask:0xf bank_mask:0xf
	s_waitcnt lgkmcnt(0)
	v_add_f32_e32 v15, v15, v26
	s_nop 1
	v_mov_b32_dpp v26, v15 row_mirror row_mask:0xf bank_mask:0xf
	s_and_b64 vcc, s[52:53], exec
	s_waitcnt lgkmcnt(0)
	v_add_f32_e32 v24, v24, v27
	s_waitcnt lgkmcnt(0)
	v_add_f32_e32 v14, v14, v25
	s_nop 1
	v_mov_b32_dpp v27, v24 row_mirror row_mask:0xf bank_mask:0xf
	s_nop 1
	v_mov_b32_dpp v25, v14 row_mirror row_mask:0xf bank_mask:0xf
	s_waitcnt lgkmcnt(0)
	v_add_f32_e32 v15, v15, v26
	ds_bpermute_b32 v26, v187, v15
	s_waitcnt lgkmcnt(0)
	v_add_f32_e32 v24, v24, v27
	s_waitcnt lgkmcnt(0)
	v_add_f32_e32 v14, v14, v25
	ds_bpermute_b32 v34, v187, v24
	ds_bpermute_b32 v36, v187, v14
	s_waitcnt lgkmcnt(0)
	v_add_f32_e32 v26, v15, v26
	ds_bpermute_b32 v27, v188, v26
	s_waitcnt lgkmcnt(0)
	v_add_f32_e32 v24, v24, v34
	s_waitcnt lgkmcnt(0)
	v_add_f32_e32 v14, v14, v36
	ds_bpermute_b32 v25, v188, v24
	ds_bpermute_b32 v15, v188, v14
	v_fmamk_f32 v34, v35, 0x3a800000, v41
	s_cbranch_vccnz .LBB0_999
	v_mul_f32_e32 v35, 0x4b800000, v34
	v_cmp_gt_f32_e32 vcc, s42, v34
	s_ashr_i32 s25, s24, 31
	s_lshl_b64 s[0:1], s[24:25], 11
	v_cndmask_b32_e32 v35, v34, v35, vcc
	v_rsq_f32_e32 v35, v35
	v_lshl_add_u64 v[38:39], v[8:9], 0, s[0:1]
	v_mul_f32_e32 v36, 0x45800000, v35
	v_cndmask_b32_e32 v36, v35, v36, vcc
	v_pk_mul_f32 v[44:45], v[114:115], v[36:37] op_sel_hi:[1,0]
	v_pk_mul_f32 v[42:43], v[112:113], v[36:37] op_sel_hi:[1,0]
	v_cvt_pk_bf16_f32 v44, v44, v45
	v_pk_mul_f32 v[32:33], v[32:33], v[36:37] op_sel_hi:[1,0]
	v_cvt_pk_bf16_f32 v45, v42, v43
	global_store_dwordx2 v[38:39], v[44:45], off
	v_pk_mul_f32 v[44:45], v[102:103], v[36:37] op_sel_hi:[1,0]
	v_pk_mul_f32 v[42:43], v[100:101], v[36:37] op_sel_hi:[1,0]
	v_cvt_pk_bf16_f32 v44, v44, v45
	s_nop 0
	v_cvt_pk_bf16_f32 v45, v42, v43
	global_store_dwordx2 v[38:39], v[44:45], off offset:512
	v_pk_mul_f32 v[42:43], v[80:81], v[36:37] op_sel_hi:[1,0]
	v_pk_mul_f32 v[44:45], v[82:83], v[36:37] op_sel_hi:[1,0]
	v_pk_mul_f32 v[36:37], v[64:65], v[36:37] op_sel_hi:[1,0]
	v_cvt_pk_bf16_f32 v44, v44, v45
	v_cvt_pk_bf16_f32 v45, v42, v43
	global_store_dwordx2 v[38:39], v[44:45], off offset:1024
	v_cvt_pk_bf16_f32 v36, v36, v37
	v_cvt_pk_bf16_f32 v37, v32, v33
	global_store_dwordx2 v[38:39], v[36:37], off offset:1536

; __device__ __forceinline__ void st4_bf16(bf16* p, v4f o) { v2u w; w.x = cvt_pk_nv(o.x, o.y); w.y = cvt_pk_nv(o.z, o.w); *(v2u*)p = w; }
; template <int R, bool BASE_F32, bool OUT_F32>
; __device__ __forceinline__ void rows_res(const Ctx& C, int m0, int stride, int mx, const float* gpost, float scale, int lane) {
;     ...
;         for (int r = 0; r < R; ++r) { const float rstd = rsqrtf(t[r]);
; #pragma unroll
;             for (int j = 0; j < 4; ++j) if (ok[r]) st4_bf16(XN + (size_t)mr[r] * DM + 4 * lane + 256 * j, d[r][j] * rstd);
;             if (lane == 0 && ok[r]) rs[mr[r]] = sqrtf(t[r]); }
.LBB0_1001:
	s_or_b64 exec, exec, s[14:15]
	s_waitcnt lgkmcnt(0)
	v_add_f32_e32 v26, v26, v27
	s_andn2_b64 vcc, exec, s[54:55]
	v_fmamk_f32 v26, v26, 0x3a800000, v41
	s_cbranch_vccnz .LBB0_1003
	v_mul_f32_e32 v27, 0x4b800000, v26
	v_cmp_gt_f32_e32 vcc, s42, v26
	s_ashr_i32 s39, s38, 31
	s_lshl_b64 s[0:1], s[38:39], 11
	v_cndmask_b32_e32 v27, v26, v27, vcc
	v_rsq_f32_e32 v27, v27
	v_lshl_add_u64 v[34:35], v[8:9], 0, s[0:1]
	v_mul_f32_e32 v32, 0x45800000, v27
	v_cndmask_b32_e32 v32, v27, v32, vcc
	v_pk_mul_f32 v[38:39], v[90:91], v[32:33] op_sel_hi:[1,0]
	v_pk_mul_f32 v[36:37], v[88:89], v[32:33] op_sel_hi:[1,0]
	v_cvt_pk_bf16_f32 v38, v38, v39
	v_pk_mul_f32 v[22:23], v[22:23], v[32:33] op_sel_hi:[1,0]
	v_cvt_pk_bf16_f32 v39, v36, v37
	global_store_dwordx2 v[34:35], v[38:39], off
	v_pk_mul_f32 v[38:39], v[96:97], v[32:33] op_sel_hi:[1,0]
	v_pk_mul_f32 v[36:37], v[94:95], v[32:33] op_sel_hi:[1,0]
	v_cvt_pk_bf16_f32 v38, v38, v39
	v_pk_mul_f32 v[20:21], v[20:21], v[32:33] op_sel_hi:[1,0]
	v_cvt_pk_bf16_f32 v39, v36, v37
	global_store_dwordx2 v[34:35], v[38:39], off offset:512
	v_pk_mul_f32 v[38:39], v[76:77], v[32:33] op_sel_hi:[1,0]
	v_pk_mul_f32 v[36:37], v[72:73], v[32:33] op_sel_hi:[1,0]
	v_cvt_pk_bf16_f32 v38, v38, v39
	v_cvt_pk_bf16_f32 v22, v22, v23
	v_cvt_pk_bf16_f32 v23, v20, v21
	global_store_dwordx2 v[34:35], v[22:23], off offset:1536
	v_cvt_pk_bf16_f32 v39, v36, v37
	global_store_dwordx2 v[34:35], v[38:39], off offset:1024

; __device__ __forceinline__ void st4_bf16(bf16* p, v4f o) { v2u w; w.x = cvt_pk_nv(o.x, o.y); w.y = cvt_pk_nv(o.z, o.w); *(v2u*)p = w; }
; template <int R, bool BASE_F32, bool OUT_F32>
; __device__ __forceinline__ void rows_res(const Ctx& C, int m0, int stride, int mx, const float* gpost, float scale, int lane) {
;     ...
;         for (int r = 0; r < R; ++r) { const float rstd = rsqrtf(t[r]);
; #pragma unroll
;             for (int j = 0; j < 4; ++j) if (ok[r]) st4_bf16(XN + (size_t)mr[r] * DM + 4 * lane + 256 * j, d[r][j] * rstd);
;             if (lane == 0 && ok[r]) rs[mr[r]] = sqrtf(t[r]); }
.LBB0_1005:
	s_or_b64 exec, exec, s[14:15]
	s_waitcnt lgkmcnt(0)
	v_add_f32_e32 v20, v24, v25
	s_andn2_b64 vcc, exec, s[50:51]
	v_fmamk_f32 v20, v20, 0x3a800000, v41
	s_cbranch_vccnz .LBB0_1007
	v_mul_f32_e32 v21, 0x4b800000, v20
	v_cmp_gt_f32_e32 vcc, s42, v20
	s_ashr_i32 s31, s30, 31
	s_lshl_b64 s[0:1], s[30:31], 11
	v_cndmask_b32_e32 v21, v20, v21, vcc
	v_rsq_f32_e32 v21, v21
	v_lshl_add_u64 v[24:25], v[8:9], 0, s[0:1]
	v_mul_f32_e32 v22, 0x45800000, v21
	v_cndmask_b32_e32 v22, v21, v22, vcc
	v_pk_mul_f32 v[32:33], v[84:85], v[22:23] op_sel_hi:[1,0]
	v_pk_mul_f32 v[26:27], v[86:87], v[22:23] op_sel_hi:[1,0]
	v_cvt_pk_bf16_f32 v32, v32, v33
	v_pk_mul_f32 v[18:19], v[18:19], v[22:23] op_sel_hi:[1,0]
	v_cvt_pk_bf16_f32 v33, v26, v27
	global_store_dwordx2 v[24:25], v[32:33], off
	v_pk_mul_f32 v[32:33], v[70:71], v[22:23] op_sel_hi:[1,0]
	v_pk_mul_f32 v[26:27], v[68:69], v[22:23] op_sel_hi:[1,0]
	v_cvt_pk_bf16_f32 v32, v32, v33
	v_pk_mul_f32 v[16:17], v[16:17], v[22:23] op_sel_hi:[1,0]
	v_cvt_pk_bf16_f32 v33, v26, v27
	global_store_dwordx2 v[24:25], v[32:33], off offset:512
	v_pk_mul_f32 v[32:33], v[62:63], v[22:23] op_sel_hi:[1,0]
	v_pk_mul_f32 v[26:27], v[60:61], v[22:23] op_sel_hi:[1,0]
	v_cvt_pk_bf16_f32 v32, v32, v33
	v_cvt_pk_bf16_f32 v18, v18, v19
	v_cvt_pk_bf16_f32 v19, v16, v17
	global_store_dwordx2 v[24:25], v[18:19], off offset:1536
	v_cvt_pk_bf16_f32 v33, v26, v27
	global_store_dwordx2 v[24:25], v[32:33], off offset:1024

; __device__ __forceinline__ const float* xrow_ptr(const Ctx& C, int row) { return row < MPROMPT ? C.in(0) + (size_t)row * DM : C.in(1) + (size_t)(row - MPROMPT) * DM; }
; __device__ __forceinline__ v4f ld4_bf16(const bf16* p) { const v2u w = *(const v2u*)p; return (v4f){bf_lo(w.x), bf_hi(w.x), bf_lo(w.y), bf_hi(w.y)}; }
; template <int R, bool BASE_F32, bool OUT_F32>
; __device__ __forceinline__ void rows_res(const Ctx& C, int m0, int stride, int mx, const float* gpost, float scale, int lane) {
;     ...
;     for (int r = 0; r < R; ++r) { mr[r] = (r == 4) ? mx : m0 + r * stride; ok[r] = (r == 4) ? (mx < M) : (mr[r] < MPROMPT); const int mm = ok[r] ? mr[r] : 0;
; #pragma unroll
;         for (int j = 0; j < 4; ++j) d[r][j] = ld4_bf16(D + (size_t)mm * DM + 4 * lane + 256 * j);
;         if (BASE_F32) { const float* x = xrow_ptr(C, mm);
; #pragma unroll
;             for (int j = 0; j < 4; ++j) b[r][j] = ld4_f32(x + 4 * lane + 256 * j);
;         } else { const float inv = C.RS()[mm];
; #pragma unroll
;             for (int j = 0; j < 4; ++j) b[r][j] = ld4_bf16(XN + (size_t)mm * DM + 4 * lane + 256 * j) * inv;
;         } }
.LBB0_1013:
	s_mov_b64 s[0:1], s[80:81]
	s_load_dwordx2 s[0:1], s[0:1], 0x110
	s_mov_b64 s[10:11], s[80:81]
	s_add_i32 s14, s23, s86
	s_add_i32 s18, s23, 0x8000
	s_load_dwordx2 s[10:11], s[10:11], 0x110
	s_cmpk_lt_i32 s23, 0x80
	s_cselect_b64 s[20:21], -1, 0
	s_cmpk_gt_i32 s14, 0x7fff
	s_waitcnt lgkmcnt(0)
	v_lshl_add_u64 v[4:5], s[0:1], 0, v[0:1]
	s_mov_b64 s[0:1], 0x7100000
	s_cselect_b64 s[52:53], -1, 0
	s_ashr_i32 s15, s14, 31
	v_lshl_add_u64 v[18:19], v[4:5], 0, s[0:1]
	s_and_b64 s[0:1], s[52:53], exec
	s_cselect_b32 s1, 0, s15
	s_cselect_b32 s0, 0, s14
	v_lshl_add_u64 v[4:5], s[10:11], 0, v[0:1]
	s_lshl_b64 s[10:11], s[0:1], 11
	v_lshl_add_u64 v[6:7], v[18:19], 0, s[10:11]
	s_mov_b64 s[12:13], s[80:81]
	global_load_dwordx2 v[116:117], v[6:7], off
	global_load_dwordx2 v[106:107], v[6:7], off offset:512
	global_load_dwordx2 v[108:109], v[6:7], off offset:1024
	global_load_dwordx2 v[16:17], v[6:7], off offset:1536
	s_load_dwordx2 s[12:13], s[12:13], 0x110
	s_lshl_b64 s[0:1], s[0:1], 2
	v_mov_b32_e32 v3, 0x2a80000
	s_mov_b64 s[24:25], 0x3000000
	v_lshl_add_u64 v[4:5], v[4:5], 0, s[24:25]
	s_waitcnt lgkmcnt(0)
	s_add_u32 s0, s12, s0
	s_addc_u32 s1, s13, s1
	s_add_i32 s36, s14, s46
	s_cmpk_gt_i32 s36, 0x7fff
	s_cselect_b64 s[40:41], -1, 0
	s_cmp_lt_i32 s36, 0x8000
	s_cselect_b64 s[50:51], -1, 0
	s_ashr_i32 s37, s36, 31
	global_load_dword v6, v3, s[0:1]
	s_and_b64 s[0:1], s[40:41], exec
	s_cselect_b32 s1, 0, s37
	s_cselect_b32 s0, 0, s36
	v_lshl_add_u64 v[8:9], v[4:5], 0, s[10:11]
	s_lshl_b64 s[10:11], s[0:1], 11
	global_load_dwordx2 v[22:23], v[8:9], off
	global_load_dwordx2 v[24:25], v[8:9], off offset:512
	global_load_dwordx2 v[26:27], v[8:9], off offset:1024
	global_load_dwordx2 v[28:29], v[8:9], off offset:1536
	v_lshl_add_u64 v[8:9], v[18:19], 0, s[10:11]
	s_mov_b64 s[12:13], s[80:81]
	global_load_dwordx2 v[130:131], v[8:9], off
	global_load_dwordx2 v[124:125], v[8:9], off offset:512
	global_load_dwordx2 v[126:127], v[8:9], off offset:1024
	global_load_dwordx2 v[30:31], v[8:9], off offset:1536
	s_load_dwordx2 s[12:13], s[12:13], 0x110
	s_lshl_b64 s[0:1], s[0:1], 2
	v_lshl_add_u64 v[10:11], v[4:5], 0, s[10:11]
	s_mov_b32 s42, 0x3a800000
	s_mov_b32 s43, 0x800000
	s_waitcnt lgkmcnt(0)
	s_add_u32 s0, s12, s0
	s_addc_u32 s1, s13, s1
	s_add_i32 s28, s36, s46
	s_cmpk_gt_i32 s28, 0x7fff
	s_cselect_b64 s[34:35], -1, 0
	s_cmp_lt_i32 s28, 0x8000
	s_cselect_b64 s[38:39], -1, 0
	s_ashr_i32 s29, s28, 31
	global_load_dword v8, v3, s[0:1]
	s_and_b64 s[0:1], s[34:35], exec
	s_cselect_b32 s1, 0, s29
	s_cselect_b32 s0, 0, s28
	s_lshl_b64 s[10:11], s[0:1], 11
	global_load_dwordx2 v[34:35], v[10:11], off
	global_load_dwordx2 v[36:37], v[10:11], off offset:512
	global_load_dwordx2 v[38:39], v[10:11], off offset:1024
	global_load_dwordx2 v[40:41], v[10:11], off offset:1536
	v_lshl_add_u64 v[10:11], v[18:19], 0, s[10:11]
	s_mov_b64 s[12:13], s[80:81]
	global_load_dwordx2 v[142:143], v[10:11], off
	global_load_dwordx2 v[134:135], v[10:11], off offset:512
	global_load_dwordx2 v[138:139], v[10:11], off offset:1024
	global_load_dwordx2 v[44:45], v[10:11], off offset:1536
	s_load_dwordx2 s[12:13], s[12:13], 0x110
	s_lshl_b64 s[0:1], s[0:1], 2
	v_lshl_add_u64 v[12:13], v[4:5], 0, s[10:11]
	s_waitcnt lgkmcnt(0)
	s_add_u32 s0, s12, s0
	s_addc_u32 s1, s13, s1
	s_add_i32 s24, s28, s46
	s_cmpk_gt_i32 s24, 0x7fff
	s_cselect_b64 s[26:27], -1, 0
	s_cmp_lt_i32 s24, 0x8000
	s_cselect_b64 s[30:31], -1, 0
	s_ashr_i32 s25, s24, 31
	global_load_dword v10, v3, s[0:1]
	s_and_b64 s[0:1], s[26:27], exec
	s_cselect_b32 s1, 0, s25
	s_cselect_b32 s0, 0, s24
	s_lshl_b64 s[10:11], s[0:1], 11
	global_load_dwordx2 v[46:47], v[12:13], off
	global_load_dwordx2 v[50:51], v[12:13], off offset:512
	global_load_dwordx2 v[52:53], v[12:13], off offset:1024
	global_load_dwordx2 v[54:55], v[12:13], off offset:1536
	v_lshl_add_u64 v[12:13], v[18:19], 0, s[10:11]
	s_mov_b64 s[12:13], s[80:81]
	global_load_dwordx2 v[154:155], v[12:13], off
	global_load_dwordx2 v[146:147], v[12:13], off offset:512
	global_load_dwordx2 v[150:151], v[12:13], off offset:1024
	global_load_dwordx2 v[56:57], v[12:13], off offset:1536
	s_load_dwordx2 s[12:13], s[12:13], 0x110
	s_lshl_b64 s[0:1], s[0:1], 2
	v_lshl_add_u64 v[32:33], v[4:5], 0, s[10:11]
	global_load_dwordx2 v[58:59], v[32:33], off
	global_load_dwordx2 v[60:61], v[32:33], off offset:512
	s_waitcnt lgkmcnt(0)
	s_add_u32 s12, s12, s0
	s_addc_u32 s13, s13, s1
	s_ashr_i32 s19, s18, 31
	s_cmpk_gt_i32 s23, 0x7f
	s_cselect_b64 s[22:23], -1, 0
	s_and_b64 s[0:1], s[22:23], exec
	s_cselect_b32 s11, 0, s19
	s_cselect_b32 s10, 0, s18
	s_lshl_b64 s[0:1], s[10:11], 11
	v_lshl_add_u64 v[18:19], v[18:19], 0, s[0:1]
	global_load_dwordx2 v[62:63], v[32:33], off offset:1024
	global_load_dwordx2 v[66:67], v[32:33], off offset:1536
	global_load_dwordx2 v[166:167], v[18:19], off
	global_load_dwordx2 v[158:159], v[18:19], off offset:512
	global_load_dwordx2 v[162:163], v[18:19], off offset:1024
	global_load_dwordx2 v[68:69], v[18:19], off offset:1536
	v_lshl_add_u64 v[70:71], v[4:5], 0, s[0:1]
	global_load_dword v18, v3, s[12:13]
	s_mov_b64 s[12:13], s[80:81]
	global_load_dwordx2 v[92:93], v[70:71], off
	global_load_dwordx2 v[96:97], v[70:71], off offset:512
	global_load_dwordx2 v[118:119], v[70:71], off offset:1024
	global_load_dwordx2 v[132:133], v[70:71], off offset:1536
	s_load_dwordx2 s[0:1], s[12:13], 0x110
	s_waitcnt vmcnt(43)
	v_and_b32_e32 v141, 0xffff0000, v117
	s_waitcnt vmcnt(40)
	v_and_b32_e32 v13, 0xffff0000, v16
	v_and_b32_e32 v137, 0xffff0000, v116
	v_lshlrev_b32_e32 v140, 16, v117
	v_mul_f32_e32 v12, v141, v141
	s_lshl_b64 s[10:11], s[10:11], 2
	v_lshlrev_b32_e32 v136, 16, v116
	v_lshlrev_b32_e32 v15, 16, v16
	s_waitcnt lgkmcnt(0)
; __device__ __forceinline__ const float* xrow_ptr(const Ctx& C, int row) { return row < MPROMPT ? C.in(0) + (size_t)row * DM : C.in(1) + (size_t)(row - MPROMPT) * DM; }
; __device__ __forceinline__ v4f ld4_bf16(const bf16* p) { const v2u w = *(const v2u*)p; return (v4f){bf_lo(w.x), bf_hi(w.x), bf_lo(w.y), bf_hi(w.y)}; }
; __device__ __forceinline__ float ssq4(v4f v) { return (v.x * v.x + v.y * v.y) + (v.z * v.z + v.w * v.w); }
; template <int R, bool BASE_F32, bool OUT_F32>
; __device__ __forceinline__ void rows_res(const Ctx& C, int m0, int stride, int mx, const float* gpost, float scale, int lane) {
;     ...
;         for (int j = 0; j < 4; ++j) d[r][j] = ld4_bf16(D + (size_t)mm * DM + 4 * lane + 256 * j);
;         if (BASE_F32) { const float* x = xrow_ptr(C, mm);
; #pragma unroll
;             for (int j = 0; j < 4; ++j) b[r][j] = ld4_f32(x + 4 * lane + 256 * j);
;         } else { const float inv = C.RS()[mm];
; #pragma unroll
;             for (int j = 0; j < 4; ++j) b[r][j] = ld4_bf16(XN + (size_t)mm * DM + 4 * lane + 256 * j) * inv;
;         } }
; #pragma unroll
;     for (int r = 0; r < R; ++r) { float s = 0.f;
; #pragma unroll
;         for (int j = 0; j < 4; ++j) s += ssq4(d[r][j]);
;         r1[r] = s; }
	s_add_u32 s0, s0, s10
	v_lshlrev_b32_e32 v117, 16, v107
	v_lshlrev_b32_e32 v116, 16, v106
	s_addc_u32 s1, s1, s11
	v_mov_b32_e32 v153, v15
	v_lshlrev_b32_e32 v16, 16, v17
	v_and_b32_e32 v17, 0xffff0000, v17
	s_waitcnt vmcnt(37)
	v_lshlrev_b32_e32 v42, 16, v24
	v_and_b32_e32 v43, 0xffff0000, v24
	v_lshlrev_b32_e32 v48, 16, v25
	v_and_b32_e32 v49, 0xffff0000, v25
	s_waitcnt vmcnt(35)
	v_lshlrev_b32_e32 v24, 16, v28
	v_and_b32_e32 v25, 0xffff0000, v28
	v_mul_f32_e32 v28, v16, v16
	v_lshlrev_b32_e32 v32, 16, v26
	v_and_b32_e32 v33, 0xffff0000, v26
	s_waitcnt vmcnt(28)
	v_lshlrev_b32_e32 v86, 16, v36
	v_and_b32_e32 v87, 0xffff0000, v36
	v_mul_f32_e32 v36, v17, v17
	v_lshlrev_b32_e32 v64, 16, v27
	v_and_b32_e32 v65, 0xffff0000, v27
	v_lshlrev_b32_e32 v26, 16, v29
	v_and_b32_e32 v27, 0xffff0000, v29
	v_lshlrev_b32_e32 v29, 16, v30
	v_and_b32_e32 v7, 0xffff0000, v30
	v_mov_b32_e32 v165, v29
	v_lshlrev_b32_e32 v30, 16, v31
	v_and_b32_e32 v31, 0xffff0000, v31
	v_lshlrev_b32_e32 v88, 16, v37
	v_and_b32_e32 v89, 0xffff0000, v37
	s_waitcnt vmcnt(22)
	v_lshlrev_b32_e32 v37, 16, v44
	v_and_b32_e32 v9, 0xffff0000, v44
	v_mov_b32_e32 v175, v37
	v_lshlrev_b32_e32 v74, 16, v38
	v_and_b32_e32 v75, 0xffff0000, v38
	v_lshlrev_b32_e32 v76, 16, v39
	v_and_b32_e32 v77, 0xffff0000, v39
	v_lshlrev_b32_e32 v38, 16, v45
	s_waitcnt vmcnt(20)
	v_lshlrev_b32_e32 v110, 16, v47
	v_and_b32_e32 v111, 0xffff0000, v47
	s_waitcnt vmcnt(19)
	v_lshlrev_b32_e32 v90, 16, v50
	v_and_b32_e32 v91, 0xffff0000, v50
	v_lshlrev_b32_e32 v94, 16, v51
	v_and_b32_e32 v95, 0xffff0000, v51
	s_waitcnt vmcnt(13)
	v_lshlrev_b32_e32 v47, 16, v56
	v_and_b32_e32 v11, 0xffff0000, v56
	v_lshlrev_b32_e32 v50, 16, v57
	v_and_b32_e32 v51, 0xffff0000, v57
	v_lshlrev_b32_e32 v78, 16, v52
	s_waitcnt vmcnt(12)
	v_lshlrev_b32_e32 v122, 16, v59
	v_and_b32_e32 v123, 0xffff0000, v59
	s_waitcnt vmcnt(11)
	v_lshlrev_b32_e32 v98, 16, v60
	v_and_b32_e32 v99, 0xffff0000, v60
	v_lshlrev_b32_e32 v100, 16, v61
	v_and_b32_e32 v101, 0xffff0000, v61
	v_and_b32_e32 v79, 0xffff0000, v52
	global_load_dword v52, v3, s[0:1]
	v_mul_f32_e32 v3, v13, v13
	v_lshlrev_b32_e32 v112, 16, v46
	v_and_b32_e32 v113, 0xffff0000, v46
	s_waitcnt vmcnt(11)
	v_lshlrev_b32_e32 v82, 16, v62
	v_and_b32_e32 v83, 0xffff0000, v62
	v_lshlrev_b32_e32 v84, 16, v63
	v_and_b32_e32 v85, 0xffff0000, v63
	s_waitcnt vmcnt(10)
	v_lshlrev_b32_e32 v56, 16, v66
	v_and_b32_e32 v57, 0xffff0000, v66
	v_lshlrev_b32_e32 v62, 16, v67
	v_and_b32_e32 v63, 0xffff0000, v67
	s_waitcnt vmcnt(6)
	v_lshlrev_b32_e32 v59, 16, v68
	v_and_b32_e32 v19, 0xffff0000, v68
	v_lshlrev_b32_e32 v60, 16, v69
	v_and_b32_e32 v61, 0xffff0000, v69
	s_waitcnt vmcnt(4)
	v_lshlrev_b32_e32 v114, 16, v92
	v_and_b32_e32 v115, 0xffff0000, v92
	v_lshlrev_b32_e32 v128, 16, v93
	v_and_b32_e32 v129, 0xffff0000, v93
	s_waitcnt vmcnt(3)
	v_lshlrev_b32_e32 v102, 16, v96
	v_and_b32_e32 v103, 0xffff0000, v96
	v_lshlrev_b32_e32 v104, 16, v97
	v_and_b32_e32 v105, 0xffff0000, v97
	s_waitcnt vmcnt(2)
	v_lshlrev_b32_e32 v92, 16, v118
	v_and_b32_e32 v93, 0xffff0000, v118
	v_lshlrev_b32_e32 v96, 16, v119
	v_and_b32_e32 v97, 0xffff0000, v119
	s_waitcnt vmcnt(1)
	v_lshlrev_b32_e32 v66, 16, v132
	v_and_b32_e32 v67, 0xffff0000, v132
	v_lshlrev_b32_e32 v68, 16, v133
	v_and_b32_e32 v69, 0xffff0000, v133
	v_pk_fma_f32 v[132:133], v[140:141], v[140:141], v[12:13] op_sel_hi:[1,1,0]
	v_and_b32_e32 v119, 0xffff0000, v107
	v_and_b32_e32 v118, 0xffff0000, v106
	v_mul_f32_e32 v12, v137, v137
	v_pk_mul_f32 v[106:107], v[118:119], v[118:119]
	v_pk_fma_f32 v[148:149], v[136:137], v[136:137], v[12:13] op_sel_hi:[1,1,0]
	v_pk_fma_f32 v[144:145], v[116:117], v[116:117], v[106:107]
	v_mov_b32_e32 v14, v148
	v_mov_b32_e32 v152, v132
	v_and_b32_e32 v107, 0xffff0000, v108
	v_pk_add_f32 v[132:133], v[148:149], v[132:133]
	v_pk_mul_f32 v[148:149], v[14:15], v[152:153]
	v_pk_add_f32 v[144:145], v[144:145], v[144:145] op_sel:[0,1] op_sel_hi:[1,0]
	v_lshlrev_b32_e32 v106, 16, v108
	v_lshlrev_b32_e32 v108, 16, v109
	v_and_b32_e32 v109, 0xffff0000, v109
	v_mov_b32_e32 v133, v149
	v_mov_b32_e32 v145, v3
	v_mul_f32_e32 v12, v107, v107
	v_pk_add_f32 v[132:133], v[132:133], v[144:145]
	v_pk_fma_f32 v[144:145], v[106:107], v[106:107], v[12:13] op_sel_hi:[1,1,0]
	v_mul_f32_e32 v12, v109, v109
	v_pk_fma_f32 v[148:149], v[108:109], v[108:109], v[12:13] op_sel_hi:[1,1,0]
	v_mov_b32_e32 v145, v28
	v_mov_b32_e32 v149, v36
	v_pk_add_f32 v[144:145], v[144:145], v[148:149]
	v_and_b32_e32 v153, 0xffff0000, v131
	v_pk_add_f32 v[132:133], v[132:133], v[144:145]
	v_and_b32_e32 v149, 0xffff0000, v130
	v_lshlrev_b32_e32 v152, 16, v131
	v_mul_f32_e32 v12, v153, v153
	v_add_f32_e32 v3, v132, v133
	v_lshlrev_b32_e32 v148, 16, v130
	v_pk_fma_f32 v[144:145], v[152:153], v[152:153], v[12:13] op_sel_hi:[1,1,0]
	v_and_b32_e32 v133, 0xffff0000, v125
	v_and_b32_e32 v132, 0xffff0000, v124
	v_mul_f32_e32 v12, v149, v149
	v_lshlrev_b32_e32 v131, 16, v125
	v_lshlrev_b32_e32 v130, 16, v124
	v_pk_mul_f32 v[124:125], v[132:133], v[132:133]
	v_pk_fma_f32 v[160:161], v[148:149], v[148:149], v[12:13] op_sel_hi:[1,1,0]
	v_pk_fma_f32 v[156:157], v[130:131], v[130:131], v[124:125]
	v_mov_b32_e32 v28, v160
	v_mov_b32_e32 v164, v144
	v_and_b32_e32 v125, 0xffff0000, v126
	v_mul_f32_e32 v14, v7, v7
	v_pk_add_f32 v[144:145], v[160:161], v[144:145]
	v_pk_mul_f32 v[160:161], v[28:29], v[164:165]
	v_pk_add_f32 v[156:157], v[156:157], v[156:157] op_sel:[0,1] op_sel_hi:[1,0]
	v_lshlrev_b32_e32 v124, 16, v126
	v_lshlrev_b32_e32 v126, 16, v127
	v_and_b32_e32 v127, 0xffff0000, v127
	v_mov_b32_e32 v145, v161
	v_mov_b32_e32 v157, v14
	v_mul_f32_e32 v12, v125, v125
	v_pk_add_f32 v[144:145], v[144:145], v[156:157]
; __device__ __forceinline__ float ssq4(v4f v) { return (v.x * v.x + v.y * v.y) + (v.z * v.z + v.w * v.w); }
; __device__ __forceinline__ float wave_sum(float v) {
; #pragma unroll
;     for (int o = 1; o < 64; o <<= 1) v += __shfl_xor(v, o);
;     return v;
; }
; template <int R, bool BASE_F32, bool OUT_F32>
; __device__ __forceinline__ void rows_res(const Ctx& C, int m0, int stride, int mx, const float* gpost, float scale, int lane) {
;     ...
;     for (int r = 0; r < R; ++r) { float s = 0.f;
; #pragma unroll
;         for (int j = 0; j < 4; ++j) s += ssq4(d[r][j]);
;         r1[r] = s; }
; #pragma unroll
;     for (int r = 0; r < R; ++r) r1[r] = rsqrtf(wave_sum(r1[r]) * (1.f / DM) + EPS) * scale;
	v_pk_fma_f32 v[156:157], v[124:125], v[124:125], v[12:13] op_sel_hi:[1,1,0]
	v_mul_f32_e32 v12, v127, v127
	v_mul_f32_e32 v36, v30, v30
	v_mul_f32_e32 v46, v31, v31
	v_pk_fma_f32 v[160:161], v[126:127], v[126:127], v[12:13] op_sel_hi:[1,1,0]
	v_mov_b32_e32 v157, v36
	v_mov_b32_e32 v161, v46
	v_and_b32_e32 v165, 0xffff0000, v143
	v_pk_add_f32 v[156:157], v[156:157], v[160:161]
	v_and_b32_e32 v161, 0xffff0000, v142
	v_lshlrev_b32_e32 v164, 16, v143
	v_mul_f32_e32 v12, v165, v165
	v_pk_add_f32 v[170:171], v[144:145], v[156:157]
	v_lshlrev_b32_e32 v160, 16, v142
	v_pk_fma_f32 v[156:157], v[164:165], v[164:165], v[12:13] op_sel_hi:[1,1,0]
	v_and_b32_e32 v145, 0xffff0000, v135
	v_and_b32_e32 v144, 0xffff0000, v134
	v_mul_f32_e32 v12, v161, v161
	v_lshlrev_b32_e32 v143, 16, v135
	v_lshlrev_b32_e32 v142, 16, v134
	v_pk_mul_f32 v[134:135], v[144:145], v[144:145]
	v_pk_fma_f32 v[172:173], v[160:161], v[160:161], v[12:13] op_sel_hi:[1,1,0]
	v_pk_fma_f32 v[168:169], v[142:143], v[142:143], v[134:135]
	v_mov_b32_e32 v36, v172
	v_mov_b32_e32 v174, v156
	v_and_b32_e32 v135, 0xffff0000, v138
	v_mul_f32_e32 v14, v9, v9
	v_pk_add_f32 v[156:157], v[172:173], v[156:157]
	v_pk_mul_f32 v[172:173], v[36:37], v[174:175]
	v_pk_add_f32 v[168:169], v[168:169], v[168:169] op_sel:[0,1] op_sel_hi:[1,0]
	v_lshlrev_b32_e32 v134, 16, v138
	v_lshlrev_b32_e32 v138, 16, v139
	v_and_b32_e32 v139, 0xffff0000, v139
	v_mov_b32_e32 v157, v173
	v_mov_b32_e32 v169, v14
	v_mul_f32_e32 v12, v135, v135
	v_and_b32_e32 v39, 0xffff0000, v45
	v_pk_add_f32 v[156:157], v[156:157], v[168:169]
	v_pk_fma_f32 v[168:169], v[134:135], v[134:135], v[12:13] op_sel_hi:[1,1,0]
	v_mul_f32_e32 v12, v139, v139
	v_mul_f32_e32 v28, v38, v38
	v_mul_f32_e32 v46, v39, v39
	v_pk_fma_f32 v[172:173], v[138:139], v[138:139], v[12:13] op_sel_hi:[1,1,0]
	v_mov_b32_e32 v169, v28
	v_mov_b32_e32 v173, v46
	v_and_b32_e32 v177, 0xffff0000, v155
	v_pk_add_f32 v[168:169], v[168:169], v[172:173]
	v_and_b32_e32 v175, 0xffff0000, v154
	v_lshlrev_b32_e32 v176, 16, v155
	v_mul_f32_e32 v12, v177, v177
	v_pk_add_f32 v[172:173], v[156:157], v[168:169]
	v_lshlrev_b32_e32 v174, 16, v154
	v_pk_fma_f32 v[168:169], v[176:177], v[176:177], v[12:13] op_sel_hi:[1,1,0]
	v_and_b32_e32 v157, 0xffff0000, v147
	v_and_b32_e32 v156, 0xffff0000, v146
	v_mul_f32_e32 v12, v175, v175
	v_lshlrev_b32_e32 v155, 16, v147
	v_lshlrev_b32_e32 v154, 16, v146
	v_pk_mul_f32 v[146:147], v[156:157], v[156:157]
	v_pk_fma_f32 v[180:181], v[174:175], v[174:175], v[12:13] op_sel_hi:[1,1,0]
	v_pk_fma_f32 v[178:179], v[154:155], v[154:155], v[146:147]
	v_mov_b32_e32 v46, v180
	v_mov_b32_e32 v190, v168
	v_mov_b32_e32 v191, v47
	v_and_b32_e32 v147, 0xffff0000, v150
	v_mul_f32_e32 v14, v11, v11
	v_pk_add_f32 v[168:169], v[180:181], v[168:169]
	v_pk_mul_f32 v[180:181], v[46:47], v[190:191]
	v_pk_add_f32 v[178:179], v[178:179], v[178:179] op_sel:[0,1] op_sel_hi:[1,0]
	v_lshlrev_b32_e32 v146, 16, v150
	v_lshlrev_b32_e32 v150, 16, v151
	v_and_b32_e32 v151, 0xffff0000, v151
	v_mov_b32_e32 v169, v181
	v_mov_b32_e32 v179, v14
	v_mul_f32_e32 v12, v147, v147
	v_pk_add_f32 v[168:169], v[168:169], v[178:179]
	v_pk_fma_f32 v[178:179], v[146:147], v[146:147], v[12:13] op_sel_hi:[1,1,0]
	v_mul_f32_e32 v12, v151, v151
	s_nop 1
	v_mov_b32_dpp v46, v3 quad_perm:[1,0,3,2] row_mask:0xf bank_mask:0xf
	v_mul_f32_e32 v28, v50, v50
	v_mul_f32_e32 v36, v51, v51
	v_pk_fma_f32 v[180:181], v[150:151], v[150:151], v[12:13] op_sel_hi:[1,1,0]
	v_mov_b32_e32 v179, v28
	v_mov_b32_e32 v181, v36
	v_pk_add_f32 v[178:179], v[178:179], v[180:181]
	v_and_b32_e32 v181, 0xffff0000, v167
	v_pk_add_f32 v[194:195], v[168:169], v[178:179]
	v_and_b32_e32 v179, 0xffff0000, v166
	v_lshlrev_b32_e32 v180, 16, v167
	v_mul_f32_e32 v12, v181, v181
	v_lshlrev_b32_e32 v178, 16, v166
	v_pk_fma_f32 v[190:191], v[180:181], v[180:181], v[12:13] op_sel_hi:[1,1,0]
	v_mul_f32_e32 v12, v179, v179
	s_waitcnt lgkmcnt(0)
	v_add_f32_e32 v3, v3, v46
	v_pk_fma_f32 v[196:197], v[178:179], v[178:179], v[12:13] op_sel_hi:[1,1,0]
	s_nop 1
	v_mov_b32_dpp v12, v3 quad_perm:[2,3,0,1] row_mask:0xf bank_mask:0xf
	v_and_b32_e32 v169, 0xffff0000, v159
	v_and_b32_e32 v168, 0xffff0000, v158
	v_lshlrev_b32_e32 v167, 16, v159
	v_lshlrev_b32_e32 v166, 16, v158
	v_pk_mul_f32 v[158:159], v[168:169], v[168:169]
	v_lshlrev_b32_e32 v120, 16, v58
	v_and_b32_e32 v121, 0xffff0000, v58
	v_pk_fma_f32 v[192:193], v[166:167], v[166:167], v[158:159]
	v_mov_b32_e32 v58, v196
	v_mov_b32_e32 v198, v190
	v_mov_b32_e32 v199, v59
	v_and_b32_e32 v159, 0xffff0000, v162
	v_mul_f32_e32 v14, v19, v19
	v_pk_add_f32 v[190:191], v[196:197], v[190:191]
	v_pk_mul_f32 v[196:197], v[58:59], v[198:199]
	v_pk_add_f32 v[192:193], v[192:193], v[192:193] op_sel:[0,1] op_sel_hi:[1,0]
	v_lshlrev_b32_e32 v158, 16, v162
	v_lshlrev_b32_e32 v162, 16, v163
	v_and_b32_e32 v163, 0xffff0000, v163
	v_mov_b32_e32 v191, v197
	s_waitcnt lgkmcnt(0)
	v_add_f32_e32 v3, v3, v12
	v_mov_b32_e32 v193, v14
	v_mul_f32_e32 v12, v159, v159
	v_pk_add_f32 v[190:191], v[190:191], v[192:193]
	v_pk_fma_f32 v[192:193], v[158:159], v[158:159], v[12:13] op_sel_hi:[1,1,0]
	v_mul_f32_e32 v12, v163, v163
	v_mul_f32_e32 v28, v60, v60
	v_mul_f32_e32 v36, v61, v61
	v_pk_fma_f32 v[196:197], v[162:163], v[162:163], v[12:13] op_sel_hi:[1,1,0]
	v_mov_b32_e32 v193, v28
	v_mov_b32_e32 v197, v36
	v_pk_add_f32 v[192:193], v[192:193], v[196:197]
	v_mov_b32_e32 v198, v172
	v_pk_add_f32 v[196:197], v[190:191], v[192:193]
	global_load_dwordx4 v[190:193], v2, s[16:17]
	v_mov_b32_e32 v199, v170
	v_mov_b32_e32 v170, v173
	v_pk_add_f32 v[170:171], v[198:199], v[170:171]
	s_nop 1
	v_mov_b32_dpp v173, v171 quad_perm:[1,0,3,2] row_mask:0xf bank_mask:0xf
	s_nop 1
	v_mov_b32_dpp v172, v170 quad_perm:[1,0,3,2] row_mask:0xf bank_mask:0xf
	v_mov_b32_e32 v198, v196
	v_mov_b32_e32 v199, v194
	v_mov_b32_e32 v194, v197
	v_pk_add_f32 v[194:195], v[198:199], v[194:195]
	s_waitcnt lgkmcnt(0)
; template <int R, bool BASE_F32, bool OUT_F32>
; __device__ __forceinline__ void rows_res(const Ctx& C, int m0, int stride, int mx, const float* gpost, float scale, int lane) {
;     ...
;     for (int r = 0; r < R; ++r) r1[r] = rsqrtf(wave_sum(r1[r]) * (1.f / DM) + EPS) * scale;
; #pragma unroll
;     for (int j = 0; j < 4; ++j) { const v4f gp = ld4_f32(gpost + 4 * lane + 256 * j);
; #pragma unroll
;         for (int r = 0; r < R; ++r) d[r][j] = b[r][j] + d[r][j] * r1[r] * gp; }
	v_pk_add_f32 v[170:171], v[170:171], v[172:173]
	s_nop 1
	v_mov_b32_dpp v173, v171 quad_perm:[2,3,0,1] row_mask:0xf bank_mask:0xf
	s_nop 1
	v_mov_b32_dpp v172, v170 quad_perm:[2,3,0,1] row_mask:0xf bank_mask:0xf
	s_nop 1
	v_mov_b32_dpp v197, v195 quad_perm:[1,0,3,2] row_mask:0xf bank_mask:0xf
	s_nop 1
	v_mov_b32_dpp v196, v194 quad_perm:[1,0,3,2] row_mask:0xf bank_mask:0xf
	s_nop 1
	v_mov_b32_dpp v46, v3 row_half_mirror row_mask:0xf bank_mask:0xf
	s_mov_b32 s0, 0x358637bd
	s_waitcnt lgkmcnt(0)
	v_pk_add_f32 v[170:171], v[170:171], v[172:173]
	s_nop 1
	v_mov_b32_dpp v173, v171 row_half_mirror row_mask:0xf bank_mask:0xf
	s_nop 1
	v_mov_b32_dpp v172, v170 row_half_mirror row_mask:0xf bank_mask:0xf
	s_waitcnt lgkmcnt(0)
	v_pk_add_f32 v[194:195], v[194:195], v[196:197]
	s_nop 1
	v_mov_b32_dpp v197, v195 quad_perm:[2,3,0,1] row_mask:0xf bank_mask:0xf
	s_nop 1
	v_mov_b32_dpp v196, v194 quad_perm:[2,3,0,1] row_mask:0xf bank_mask:0xf
	s_waitcnt lgkmcnt(0)
	v_add_f32_e32 v3, v3, v46
	s_waitcnt lgkmcnt(0)
	v_pk_add_f32 v[170:171], v[170:171], v[172:173]
	s_nop 1
	v_mov_b32_dpp v173, v171 row_mirror row_mask:0xf bank_mask:0xf
	s_nop 1
	v_mov_b32_dpp v172, v170 row_mirror row_mask:0xf bank_mask:0xf
	s_nop 1
	v_mov_b32_dpp v14, v3 row_mirror row_mask:0xf bank_mask:0xf
	s_waitcnt lgkmcnt(0)
	v_pk_add_f32 v[198:199], v[194:195], v[196:197]
	s_nop 1
	v_mov_b32_dpp v201, v199 row_half_mirror row_mask:0xf bank_mask:0xf
	s_nop 1
	v_mov_b32_dpp v200, v198 row_half_mirror row_mask:0xf bank_mask:0xf
	s_waitcnt lgkmcnt(0)
	v_pk_add_f32 v[170:171], v[170:171], v[172:173]
	ds_bpermute_b32 v173, v187, v171
	ds_bpermute_b32 v172, v187, v170
	s_waitcnt lgkmcnt(0)
	v_add_f32_e32 v3, v3, v14
	ds_bpermute_b32 v12, v187, v3
	s_waitcnt lgkmcnt(0)
	v_pk_add_f32 v[198:199], v[198:199], v[200:201]
	s_nop 1
	v_mov_b32_dpp v201, v199 row_mirror row_mask:0xf bank_mask:0xf
	s_nop 1
	v_mov_b32_dpp v200, v198 row_mirror row_mask:0xf bank_mask:0xf
	s_waitcnt lgkmcnt(0)
	v_pk_add_f32 v[170:171], v[170:171], v[172:173]
	ds_bpermute_b32 v173, v188, v171
	ds_bpermute_b32 v172, v188, v170
	s_waitcnt lgkmcnt(0)
	v_add_f32_e32 v3, v3, v12
	ds_bpermute_b32 v12, v188, v3
	s_waitcnt lgkmcnt(0)
	v_pk_add_f32 v[198:199], v[198:199], v[200:201]
	ds_bpermute_b32 v201, v187, v199
	ds_bpermute_b32 v200, v187, v198
	s_waitcnt lgkmcnt(0)
	v_pk_add_f32 v[170:171], v[170:171], v[172:173]
	v_mov_b64_e32 v[172:173], s[0:1]
	global_load_dwordx4 v[194:197], v2, s[16:17] offset:1024
	v_pk_fma_f32 v[170:171], v[170:171], s[42:43], v[172:173] op_sel_hi:[1,0,0]
	s_waitcnt lgkmcnt(0)
	v_add_f32_e32 v12, v3, v12
	v_mov_b32_e32 v3, 0x358637bd
	v_mul_f32_e32 v28, 0x4b800000, v171
	v_cmp_gt_f32_e64 s[10:11], s43, v171
	v_mul_f32_e32 v36, 0x4b800000, v170
	v_cmp_gt_f32_e64 s[12:13], s43, v170
	v_fmamk_f32 v12, v12, 0x3a800000, v3
	v_cndmask_b32_e64 v28, v171, v28, s[10:11]
	v_cndmask_b32_e64 v36, v170, v36, s[12:13]
	s_waitcnt lgkmcnt(0)
	v_pk_add_f32 v[170:171], v[198:199], v[200:201]
	v_mul_f32_e32 v14, 0x4b800000, v12
	v_cmp_gt_f32_e32 vcc, s43, v12
	ds_bpermute_b32 v199, v188, v171
	ds_bpermute_b32 v198, v188, v170
	v_cndmask_b32_e32 v12, v12, v14, vcc
	v_rsq_f32_e32 v12, v12
	v_rsq_f32_e32 v28, v28
	v_lshlrev_b32_e32 v80, 16, v53
	s_waitcnt lgkmcnt(0)
	v_pk_add_f32 v[170:171], v[170:171], v[198:199]
	v_mul_f32_e32 v14, 0x45800000, v12
	v_pk_fma_f32 v[170:171], v[170:171], s[42:43], v[172:173] op_sel_hi:[1,0,0]
	v_and_b32_e32 v81, 0xffff0000, v53
	v_rsq_f32_e32 v53, v36
	v_cndmask_b32_e32 v46, v12, v14, vcc
	v_mul_f32_e32 v14, 0x4b800000, v171
	v_cmp_gt_f32_e32 vcc, s43, v171
	v_mul_f32_e32 v12, 0x45800000, v28
	v_cndmask_b32_e64 v36, v28, v12, s[10:11]
	v_cndmask_b32_e32 v14, v171, v14, vcc
	v_rsq_f32_e32 v28, v14
	global_load_dwordx4 v[198:201], v2, s[16:17] offset:2048
	v_pk_mul_f32 v[140:141], v[46:47], v[140:141] op_sel_hi:[0,1]
	v_pk_mul_f32 v[136:137], v[46:47], v[136:137] op_sel_hi:[0,1]
	v_lshlrev_b32_e32 v20, 16, v22
	v_and_b32_e32 v21, 0xffff0000, v22
	v_lshlrev_b32_e32 v22, 16, v23
	v_and_b32_e32 v23, 0xffff0000, v23
	v_mul_f32_e32 v14, 0x4b800000, v170
	v_cmp_gt_f32_e64 s[10:11], s43, v170
	s_waitcnt vmcnt(2)
	v_pk_mul_f32 v[136:137], v[136:137], v[190:191]
	v_pk_mul_f32 v[140:141], v[140:141], v[192:193]
	v_mul_f32_e32 v12, 0x45800000, v53
	v_cndmask_b32_e64 v14, v170, v14, s[10:11]
	v_pk_fma_f32 v[170:171], v[6:7], v[22:23], v[140:141] op_sel_hi:[0,1,1]
	v_pk_fma_f32 v[172:173], v[6:7], v[20:21], v[136:137] op_sel_hi:[0,1,1]
	v_pk_mul_f32 v[20:21], v[36:37], v[152:153] op_sel_hi:[0,1]
	v_pk_mul_f32 v[22:23], v[36:37], v[148:149] op_sel_hi:[0,1]
	v_lshlrev_b32_e32 v70, 16, v34
	v_and_b32_e32 v71, 0xffff0000, v34
	v_lshlrev_b32_e32 v72, 16, v35
	v_and_b32_e32 v73, 0xffff0000, v35
	v_rsq_f32_e32 v58, v14
	v_cndmask_b32_e64 v14, v53, v12, s[12:13]
	v_pk_mul_f32 v[22:23], v[22:23], v[190:191]
	v_pk_mul_f32 v[20:21], v[20:21], v[192:193]
	v_mul_f32_e32 v12, 0x45800000, v28
	v_pk_fma_f32 v[136:137], v[8:9], v[72:73], v[20:21] op_sel_hi:[0,1,1]
	v_pk_fma_f32 v[140:141], v[8:9], v[70:71], v[22:23] op_sel_hi:[0,1,1]
	v_pk_mul_f32 v[20:21], v[14:15], v[164:165] op_sel_hi:[0,1]
	v_pk_mul_f32 v[22:23], v[14:15], v[160:161] op_sel_hi:[0,1]
	v_cndmask_b32_e32 v28, v28, v12, vcc
	v_pk_mul_f32 v[22:23], v[22:23], v[190:191]
	v_pk_mul_f32 v[20:21], v[20:21], v[192:193]
	v_pk_fma_f32 v[112:113], v[10:11], v[112:113], v[22:23] op_sel_hi:[0,1,1]
	v_pk_fma_f32 v[110:111], v[10:11], v[110:111], v[20:21] op_sel_hi:[0,1,1]
	v_pk_mul_f32 v[20:21], v[28:29], v[176:177] op_sel_hi:[0,1]
	v_pk_mul_f32 v[22:23], v[28:29], v[174:175] op_sel_hi:[0,1]
	global_load_dwordx4 v[174:177], v2, s[16:17] offset:3072
	v_mul_f32_e32 v12, 0x45800000, v58
	v_cndmask_b32_e64 v58, v58, v12, s[10:11]
	v_pk_mul_f32 v[22:23], v[190:191], v[22:23]
	v_mov_b32_e32 v12, v15
	v_pk_fma_f32 v[72:73], v[18:19], v[120:121], v[22:23] op_sel_hi:[0,1,1]
	v_pk_mul_f32 v[22:23], v[58:59], v[178:179] op_sel_hi:[0,1]
	v_pk_mul_f32 v[22:23], v[190:191], v[22:23]
	v_pk_mul_f32 v[16:17], v[46:47], v[16:17] op_sel_hi:[0,1]
	v_pk_fma_f32 v[22:23], v[52:53], v[114:115], v[22:23] op_sel_hi:[0,1,1]
	v_mov_b32_e32 v114, v117
	v_mov_b32_e32 v117, v118
	v_pk_mul_f32 v[116:117], v[46:47], v[116:117] op_sel_hi:[0,1]
	s_waitcnt vmcnt(2)
;     __device__ __forceinline__ float* out() const { return (float*)karg_in(33); }
; __device__ __forceinline__ float ssq4(v4f v) { return (v.x * v.x + v.y * v.y) + (v.z * v.z + v.w * v.w); }
; template <int R, bool BASE_F32, bool OUT_F32>
; __device__ __forceinline__ void rows_res(const Ctx& C, int m0, int stride, int mx, const float* gpost, float scale, int lane) {
;     ...
;     for (int j = 0; j < 4; ++j) { const v4f gp = ld4_f32(gpost + 4 * lane + 256 * j);
; #pragma unroll
;         for (int r = 0; r < R; ++r) d[r][j] = b[r][j] + d[r][j] * r1[r] * gp; }
;     if (OUT_F32) { float* Y = C.out();
; #pragma unroll
;         for (int r = 0; r < R; ++r)
; #pragma unroll
;             for (int j = 0; j < 4; ++j) if (ok[r]) *(v4f*)(Y + (size_t)mr[r] * DM + 4 * lane + 256 * j) = d[r][j];
;     } else { float* rs = C.RS(); float t[R];
; #pragma unroll
;         for (int r = 0; r < R; ++r) { float s = 0.f;
; #pragma unroll
;             for (int j = 0; j < 4; ++j) s += ssq4(d[r][j]);
;             t[r] = s; }
	v_pk_mul_f32 v[116:117], v[116:117], v[194:195]
	v_mov_b32_e32 v115, v119
	v_pk_fma_f32 v[120:121], v[6:7], v[42:43], v[116:117] op_sel_hi:[0,1,1]
	v_mov_b32_e32 v42, v131
	v_mov_b32_e32 v43, v133
	v_pk_mul_f32 v[114:115], v[46:47], v[114:115] op_sel_hi:[0,1]
	v_pk_mul_f32 v[42:43], v[36:37], v[42:43] op_sel_hi:[0,1]
	v_pk_mul_f32 v[114:115], v[114:115], v[196:197]
	v_pk_mul_f32 v[42:43], v[42:43], v[196:197]
	v_pk_fma_f32 v[118:119], v[6:7], v[48:49], v[114:115] op_sel_hi:[0,1,1]
	v_mov_b32_e32 v131, v132
	v_pk_fma_f32 v[114:115], v[8:9], v[88:89], v[42:43] op_sel_hi:[0,1,1]
	v_mov_b32_e32 v42, v143
	v_mov_b32_e32 v43, v145
	v_pk_mul_f32 v[48:49], v[36:37], v[130:131] op_sel_hi:[0,1]
	v_pk_mul_f32 v[42:43], v[14:15], v[42:43] op_sel_hi:[0,1]
	v_pk_mul_f32 v[48:49], v[48:49], v[194:195]
	v_mov_b32_e32 v143, v144
	v_pk_mul_f32 v[42:43], v[42:43], v[196:197]
	v_pk_fma_f32 v[116:117], v[8:9], v[86:87], v[48:49] op_sel_hi:[0,1,1]
	v_pk_mul_f32 v[48:49], v[14:15], v[142:143] op_sel_hi:[0,1]
	v_pk_fma_f32 v[94:95], v[10:11], v[94:95], v[42:43] op_sel_hi:[0,1,1]
	v_mov_b32_e32 v42, v155
	v_mov_b32_e32 v43, v157
	v_pk_mul_f32 v[48:49], v[48:49], v[194:195]
	v_pk_mul_f32 v[42:43], v[28:29], v[42:43] op_sel_hi:[0,1]
	v_mov_b32_e32 v155, v156
	v_pk_fma_f32 v[90:91], v[10:11], v[90:91], v[48:49] op_sel_hi:[0,1,1]
	v_pk_mul_f32 v[48:49], v[28:29], v[154:155] op_sel_hi:[0,1]
	v_pk_mul_f32 v[42:43], v[196:197], v[42:43]
	v_pk_mul_f32 v[48:49], v[194:195], v[48:49]
	v_pk_fma_f32 v[86:87], v[18:19], v[100:101], v[42:43] op_sel_hi:[0,1,1]
	v_mov_b32_e32 v42, v167
	v_mov_b32_e32 v43, v169
	v_mov_b32_e32 v167, v168
	v_pk_fma_f32 v[88:89], v[18:19], v[98:99], v[48:49] op_sel_hi:[0,1,1]
	v_pk_mul_f32 v[42:43], v[58:59], v[42:43] op_sel_hi:[0,1]
	v_pk_mul_f32 v[48:49], v[58:59], v[166:167] op_sel_hi:[0,1]
	v_pk_mul_f32 v[98:99], v[46:47], v[108:109] op_sel_hi:[0,1]
	v_pk_mul_f32 v[100:101], v[46:47], v[106:107] op_sel_hi:[0,1]
	v_pk_mul_f32 v[48:49], v[194:195], v[48:49]
	v_pk_mul_f32 v[42:43], v[196:197], v[42:43]
	s_waitcnt vmcnt(1)
	v_pk_mul_f32 v[100:101], v[100:101], v[198:199]
	v_pk_mul_f32 v[98:99], v[98:99], v[200:201]
	v_pk_fma_f32 v[42:43], v[52:53], v[104:105], v[42:43] op_sel_hi:[0,1,1]
	v_pk_fma_f32 v[48:49], v[52:53], v[102:103], v[48:49] op_sel_hi:[0,1,1]
	v_pk_fma_f32 v[102:103], v[6:7], v[64:65], v[98:99] op_sel_hi:[0,1,1]
	v_pk_fma_f32 v[104:105], v[6:7], v[32:33], v[100:101] op_sel_hi:[0,1,1]
	v_pk_mul_f32 v[32:33], v[36:37], v[126:127] op_sel_hi:[0,1]
	v_pk_mul_f32 v[64:65], v[36:37], v[124:125] op_sel_hi:[0,1]
	v_pk_mul_f32 v[64:65], v[64:65], v[198:199]
	v_pk_mul_f32 v[32:33], v[32:33], v[200:201]
	v_pk_fma_f32 v[100:101], v[8:9], v[74:75], v[64:65] op_sel_hi:[0,1,1]
	v_pk_fma_f32 v[98:99], v[8:9], v[76:77], v[32:33] op_sel_hi:[0,1,1]
	v_pk_mul_f32 v[32:33], v[14:15], v[138:139] op_sel_hi:[0,1]
	v_pk_mul_f32 v[64:65], v[14:15], v[134:135] op_sel_hi:[0,1]
	v_pk_mul_f32 v[64:65], v[64:65], v[198:199]
	v_pk_mul_f32 v[32:33], v[32:33], v[200:201]
	v_pk_fma_f32 v[78:79], v[10:11], v[78:79], v[64:65] op_sel_hi:[0,1,1]
	v_pk_fma_f32 v[80:81], v[10:11], v[80:81], v[32:33] op_sel_hi:[0,1,1]
	v_pk_mul_f32 v[32:33], v[28:29], v[150:151] op_sel_hi:[0,1]
	v_pk_mul_f32 v[64:65], v[28:29], v[146:147] op_sel_hi:[0,1]
	v_pk_mul_f32 v[12:13], v[46:47], v[12:13] op_sel_hi:[0,1]
	v_pk_mul_f32 v[64:65], v[198:199], v[64:65]
	v_pk_mul_f32 v[32:33], v[200:201], v[32:33]
	v_pk_fma_f32 v[76:77], v[18:19], v[82:83], v[64:65] op_sel_hi:[0,1,1]
	v_pk_fma_f32 v[74:75], v[18:19], v[84:85], v[32:33] op_sel_hi:[0,1,1]
	s_waitcnt vmcnt(0)
	v_pk_mul_f32 v[12:13], v[12:13], v[174:175]
	v_pk_mul_f32 v[16:17], v[16:17], v[176:177]
	v_pk_fma_f32 v[84:85], v[6:7], v[24:25], v[12:13] op_sel_hi:[0,1,1]
	v_pk_fma_f32 v[82:83], v[6:7], v[26:27], v[16:17] op_sel_hi:[0,1,1]
	v_mov_b32_e32 v6, v29
	v_pk_mul_f32 v[12:13], v[36:37], v[30:31] op_sel_hi:[0,1]
	v_pk_mul_f32 v[6:7], v[36:37], v[6:7] op_sel_hi:[0,1]
	v_lshlrev_b32_e32 v34, 16, v40
	v_and_b32_e32 v35, 0xffff0000, v40
	v_lshlrev_b32_e32 v40, 16, v41
	v_and_b32_e32 v41, 0xffff0000, v41
	v_pk_mul_f32 v[6:7], v[6:7], v[174:175]
	v_pk_mul_f32 v[12:13], v[12:13], v[176:177]
	v_pk_fma_f32 v[26:27], v[8:9], v[34:35], v[6:7] op_sel_hi:[0,1,1]
	v_pk_fma_f32 v[24:25], v[8:9], v[40:41], v[12:13] op_sel_hi:[0,1,1]
	v_mov_b32_e32 v8, v37
	v_pk_mul_f32 v[6:7], v[14:15], v[38:39] op_sel_hi:[0,1]
	v_pk_mul_f32 v[8:9], v[14:15], v[8:9] op_sel_hi:[0,1]
	v_lshlrev_b32_e32 v44, 16, v54
	v_and_b32_e32 v45, 0xffff0000, v54
	v_lshlrev_b32_e32 v54, 16, v55
	v_and_b32_e32 v55, 0xffff0000, v55
	v_pk_mul_f32 v[8:9], v[8:9], v[174:175]
	v_pk_mul_f32 v[6:7], v[6:7], v[176:177]
	v_pk_fma_f32 v[16:17], v[10:11], v[44:45], v[8:9] op_sel_hi:[0,1,1]
	v_pk_fma_f32 v[14:15], v[10:11], v[54:55], v[6:7] op_sel_hi:[0,1,1]
	v_mov_b32_e32 v10, v47
	v_pk_mul_f32 v[6:7], v[28:29], v[50:51] op_sel_hi:[0,1]
	v_pk_mul_f32 v[8:9], v[28:29], v[10:11] op_sel_hi:[0,1]
	v_pk_mul_f32 v[20:21], v[192:193], v[20:21]
	v_pk_mul_f32 v[8:9], v[174:175], v[8:9]
	v_pk_mul_f32 v[6:7], v[176:177], v[6:7]
	v_pk_fma_f32 v[70:71], v[18:19], v[122:123], v[20:21] op_sel_hi:[0,1,1]
	v_pk_fma_f32 v[10:11], v[18:19], v[62:63], v[6:7] op_sel_hi:[0,1,1]
	v_pk_fma_f32 v[12:13], v[18:19], v[56:57], v[8:9] op_sel_hi:[0,1,1]
	v_mov_b32_e32 v18, v59
	v_pk_mul_f32 v[8:9], v[58:59], v[18:19] op_sel_hi:[0,1]
	v_mul_f32_e32 v18, v173, v173
	v_mul_f32_e32 v19, v171, v171
	v_fmac_f32_e32 v18, v172, v172
	v_fmac_f32_e32 v19, v170, v170
	v_add_f32_e32 v18, v18, v19
	v_mul_f32_e32 v19, v121, v121
	v_mul_f32_e32 v28, v119, v119
	v_fmac_f32_e32 v19, v120, v120
	v_fmac_f32_e32 v28, v118, v118
	v_add_f32_e32 v19, v19, v28
; __device__ __forceinline__ float ssq4(v4f v) { return (v.x * v.x + v.y * v.y) + (v.z * v.z + v.w * v.w); }
; template <int R, bool BASE_F32, bool OUT_F32>
; __device__ __forceinline__ void rows_res(const Ctx& C, int m0, int stride, int mx, const float* gpost, float scale, int lane) {
;     ...
;         for (int r = 0; r < R; ++r) { float s = 0.f;
; #pragma unroll
;             for (int j = 0; j < 4; ++j) s += ssq4(d[r][j]);
;             t[r] = s; }
; #pragma unroll
;         for (int r = 0; r < R; ++r) t[r] = wave_sum(t[r]) * (1.f / DM) + EPS;
	v_add_f32_e32 v18, v18, v19
	v_mul_f32_e32 v19, v105, v105
	v_mul_f32_e32 v28, v103, v103
	v_fmac_f32_e32 v19, v104, v104
	v_fmac_f32_e32 v28, v102, v102
	v_add_f32_e32 v19, v19, v28
	v_add_f32_e32 v18, v18, v19
	v_mul_f32_e32 v19, v85, v85
	v_mul_f32_e32 v28, v83, v83
	v_fmac_f32_e32 v19, v84, v84
	v_fmac_f32_e32 v28, v82, v82
	v_add_f32_e32 v19, v19, v28
	v_add_f32_e32 v18, v18, v19
	v_mul_f32_e32 v19, v141, v141
	v_mul_f32_e32 v28, v137, v137
	v_fmac_f32_e32 v19, v140, v140
	v_fmac_f32_e32 v28, v136, v136
	v_add_f32_e32 v19, v19, v28
	v_mul_f32_e32 v28, v117, v117
	v_mul_f32_e32 v29, v115, v115
	v_fmac_f32_e32 v28, v116, v116
	v_fmac_f32_e32 v29, v114, v114
	v_add_f32_e32 v28, v28, v29
	v_add_f32_e32 v19, v19, v28
	v_mul_f32_e32 v28, v101, v101
	v_mul_f32_e32 v29, v99, v99
	v_fmac_f32_e32 v28, v100, v100
	v_fmac_f32_e32 v29, v98, v98
	v_add_f32_e32 v28, v28, v29
	v_add_f32_e32 v19, v19, v28
	v_mul_f32_e32 v28, v27, v27
	v_mul_f32_e32 v29, v25, v25
	v_fmac_f32_e32 v28, v26, v26
	v_fmac_f32_e32 v29, v24, v24
	v_add_f32_e32 v28, v28, v29
	v_add_f32_e32 v19, v19, v28
	v_mul_f32_e32 v28, v113, v113
	v_mul_f32_e32 v29, v111, v111
	v_fmac_f32_e32 v28, v112, v112
	v_fmac_f32_e32 v29, v110, v110
	v_add_f32_e32 v28, v28, v29
	v_mul_f32_e32 v29, v91, v91
	v_mul_f32_e32 v30, v95, v95
	v_fmac_f32_e32 v29, v90, v90
	v_fmac_f32_e32 v30, v94, v94
	v_add_f32_e32 v29, v29, v30
	v_add_f32_e32 v28, v28, v29
	v_mul_f32_e32 v29, v79, v79
	v_mul_f32_e32 v30, v81, v81
	v_fmac_f32_e32 v29, v78, v78
	v_fmac_f32_e32 v30, v80, v80
	v_add_f32_e32 v29, v29, v30
	v_add_f32_e32 v28, v28, v29
	v_mul_f32_e32 v29, v17, v17
	v_mul_f32_e32 v30, v15, v15
	v_fmac_f32_e32 v29, v16, v16
	v_fmac_f32_e32 v30, v14, v14
	v_add_f32_e32 v29, v29, v30
	v_add_f32_e32 v28, v28, v29
	v_mul_f32_e32 v29, v73, v73
	v_mul_f32_e32 v30, v71, v71
	v_fmac_f32_e32 v29, v72, v72
	v_fmac_f32_e32 v30, v70, v70
	v_add_f32_e32 v29, v29, v30
	v_mul_f32_e32 v30, v89, v89
	v_mul_f32_e32 v31, v87, v87
	v_fmac_f32_e32 v30, v88, v88
	v_fmac_f32_e32 v31, v86, v86
	v_add_f32_e32 v30, v30, v31
	v_add_f32_e32 v29, v29, v30
	v_mul_f32_e32 v30, v77, v77
	v_mul_f32_e32 v31, v75, v75
	v_fmac_f32_e32 v30, v76, v76
	v_fmac_f32_e32 v31, v74, v74
	v_add_f32_e32 v30, v30, v31
	v_pk_mul_f32 v[20:21], v[58:59], v[180:181] op_sel_hi:[0,1]
	v_add_f32_e32 v29, v30, v29
	v_mul_f32_e32 v30, v13, v13
	v_mul_f32_e32 v31, v11, v11
	v_pk_mul_f32 v[20:21], v[192:193], v[20:21]
	v_fmac_f32_e32 v30, v12, v12
	v_fmac_f32_e32 v31, v10, v10
	s_nop 1
	v_mov_b32_dpp v35, v18 quad_perm:[1,0,3,2] row_mask:0xf bank_mask:0xf
	v_pk_fma_f32 v[20:21], v[52:53], v[128:129], v[20:21] op_sel_hi:[0,1,1]
	v_add_f32_e32 v30, v30, v31
	v_add_f32_e32 v29, v30, v29
	v_mul_f32_e32 v30, v23, v23
	v_mul_f32_e32 v31, v21, v21
	v_fmac_f32_e32 v30, v22, v22
	v_fmac_f32_e32 v31, v20, v20
	v_add_f32_e32 v30, v30, v31
	v_mul_f32_e32 v31, v49, v49
	v_mul_f32_e32 v34, v43, v43
	v_fmac_f32_e32 v31, v48, v48
	v_fmac_f32_e32 v34, v42, v42
	s_waitcnt lgkmcnt(0)
	v_add_f32_e32 v18, v18, v35
	v_add_f32_e32 v31, v31, v34
	s_nop 1
	v_mov_b32_dpp v34, v18 quad_perm:[2,3,0,1] row_mask:0xf bank_mask:0xf
	s_nop 1
	v_mov_b32_dpp v35, v19 quad_perm:[1,0,3,2] row_mask:0xf bank_mask:0xf
	v_pk_mul_f32 v[32:33], v[58:59], v[162:163] op_sel_hi:[0,1]
	v_pk_mul_f32 v[64:65], v[58:59], v[158:159] op_sel_hi:[0,1]
	v_pk_mul_f32 v[64:65], v[198:199], v[64:65]
	s_waitcnt lgkmcnt(0)
	v_add_f32_e32 v18, v18, v34
	s_waitcnt lgkmcnt(0)
	v_add_f32_e32 v19, v19, v35
	s_nop 1
	v_mov_b32_dpp v34, v18 row_half_mirror row_mask:0xf bank_mask:0xf
	s_nop 1
	v_mov_b32_dpp v35, v19 quad_perm:[2,3,0,1] row_mask:0xf bank_mask:0xf
	v_pk_mul_f32 v[32:33], v[200:201], v[32:33]
	v_pk_fma_f32 v[64:65], v[52:53], v[92:93], v[64:65] op_sel_hi:[0,1,1]
	v_pk_fma_f32 v[32:33], v[52:53], v[96:97], v[32:33] op_sel_hi:[0,1,1]
	v_add_f32_e32 v30, v30, v31
	v_mul_f32_e32 v31, v65, v65
	v_mul_f32_e32 v36, v33, v33
	v_fmac_f32_e32 v31, v64, v64
	v_fmac_f32_e32 v36, v32, v32
	v_add_f32_e32 v31, v31, v36
	s_waitcnt lgkmcnt(0)
	v_add_f32_e32 v18, v18, v34
	s_waitcnt lgkmcnt(0)
; __device__ __forceinline__ void st4_bf16(bf16* p, v4f o) { v2u w; w.x = cvt_pk_nv(o.x, o.y); w.y = cvt_pk_nv(o.z, o.w); *(v2u*)p = w; }
; __device__ __forceinline__ float wave_sum(float v) {
; #pragma unroll
;     for (int o = 1; o < 64; o <<= 1) v += __shfl_xor(v, o);
;     return v;
; }
; template <int R, bool BASE_F32, bool OUT_F32>
; __device__ __forceinline__ void rows_res(const Ctx& C, int m0, int stride, int mx, const float* gpost, float scale, int lane) {
;     ...
; #pragma unroll
;         for (int r = 0; r < R; ++r) t[r] = wave_sum(t[r]) * (1.f / DM) + EPS;
; #pragma unroll
;         for (int r = 0; r < R; ++r) { const float rstd = rsqrtf(t[r]);
; #pragma unroll
;             for (int j = 0; j < 4; ++j) if (ok[r]) st4_bf16(XN + (size_t)mr[r] * DM + 4 * lane + 256 * j, d[r][j] * rstd);
;             if (lane == 0 && ok[r]) rs[mr[r]] = sqrtf(t[r]); }
	v_add_f32_e32 v19, v19, v35
	v_add_f32_e32 v30, v31, v30
	s_nop 1
	v_mov_b32_dpp v31, v18 row_mirror row_mask:0xf bank_mask:0xf
	s_nop 1
	v_mov_b32_dpp v34, v19 row_half_mirror row_mask:0xf bank_mask:0xf
	v_pk_mul_f32 v[6:7], v[58:59], v[60:61] op_sel_hi:[0,1]
	v_pk_mul_f32 v[8:9], v[174:175], v[8:9]
	v_pk_mul_f32 v[6:7], v[176:177], v[6:7]
	s_waitcnt lgkmcnt(0)
	v_add_f32_e32 v18, v18, v31
	s_waitcnt lgkmcnt(0)
	v_add_f32_e32 v19, v19, v34
	ds_bpermute_b32 v31, v187, v18
	s_nop 1
	v_mov_b32_dpp v34, v19 row_mirror row_mask:0xf bank_mask:0xf
	v_pk_fma_f32 v[6:7], v[52:53], v[68:69], v[6:7] op_sel_hi:[0,1,1]
	v_pk_fma_f32 v[8:9], v[52:53], v[66:67], v[8:9] op_sel_hi:[0,1,1]
	v_mul_f32_e32 v35, v9, v9
	s_waitcnt lgkmcnt(0)
	v_add_f32_e32 v18, v18, v31
	s_waitcnt lgkmcnt(0)
	v_add_f32_e32 v19, v19, v34
	ds_bpermute_b32 v31, v188, v18
	ds_bpermute_b32 v34, v187, v19
	v_mul_f32_e32 v36, v7, v7
	v_fmac_f32_e32 v35, v8, v8
	v_fmac_f32_e32 v36, v6, v6
	v_add_f32_e32 v35, v35, v36
	v_add_f32_e32 v30, v35, v30
	s_waitcnt lgkmcnt(0)
	v_add_f32_e32 v36, v18, v31
	s_nop 1
	v_mov_b32_dpp v18, v28 quad_perm:[1,0,3,2] row_mask:0xf bank_mask:0xf
	s_waitcnt lgkmcnt(0)
	v_add_f32_e32 v34, v19, v34
	s_nop 1
	v_mov_b32_dpp v19, v29 quad_perm:[1,0,3,2] row_mask:0xf bank_mask:0xf
	s_nop 1
	v_mov_b32_dpp v31, v30 quad_perm:[1,0,3,2] row_mask:0xf bank_mask:0xf
	s_mov_b64 s[0:1], s[80:81]
	s_waitcnt lgkmcnt(0)
	v_add_f32_e32 v18, v28, v18
	s_nop 1
	v_mov_b32_dpp v28, v18 quad_perm:[2,3,0,1] row_mask:0xf bank_mask:0xf
	s_waitcnt lgkmcnt(0)
	v_add_f32_e32 v19, v29, v19
	s_waitcnt lgkmcnt(0)
	v_add_f32_e32 v30, v30, v31
	s_nop 1
	v_mov_b32_dpp v29, v19 quad_perm:[2,3,0,1] row_mask:0xf bank_mask:0xf
	s_nop 1
	v_mov_b32_dpp v31, v30 quad_perm:[2,3,0,1] row_mask:0xf bank_mask:0xf
	s_waitcnt lgkmcnt(0)
	v_add_f32_e32 v18, v18, v28
	s_nop 1
	v_mov_b32_dpp v28, v18 row_half_mirror row_mask:0xf bank_mask:0xf
	s_waitcnt lgkmcnt(0)
	v_add_f32_e32 v19, v19, v29
	s_waitcnt lgkmcnt(0)
	v_add_f32_e32 v30, v30, v31
	s_nop 1
	v_mov_b32_dpp v29, v19 row_half_mirror row_mask:0xf bank_mask:0xf
	s_nop 1
	v_mov_b32_dpp v31, v30 row_half_mirror row_mask:0xf bank_mask:0xf
	s_waitcnt lgkmcnt(0)
	v_add_f32_e32 v18, v18, v28
	s_nop 1
	v_mov_b32_dpp v28, v18 row_mirror row_mask:0xf bank_mask:0xf
	s_load_dwordx2 s[10:11], s[0:1], 0x110
	s_waitcnt lgkmcnt(0)
	v_add_f32_e32 v19, v19, v29
	v_add_f32_e32 v30, v30, v31
	s_nop 1
	v_mov_b32_dpp v29, v19 row_mirror row_mask:0xf bank_mask:0xf
	s_nop 1
	v_mov_b32_dpp v31, v30 row_mirror row_mask:0xf bank_mask:0xf
	v_add_f32_e32 v18, v18, v28
	ds_bpermute_b32 v28, v187, v18
	ds_bpermute_b32 v35, v188, v34
	s_waitcnt lgkmcnt(0)
	v_add_f32_e32 v19, v19, v29
	s_waitcnt lgkmcnt(0)
	v_add_f32_e32 v37, v30, v31
	ds_bpermute_b32 v29, v187, v19
	ds_bpermute_b32 v38, v187, v37
	s_waitcnt lgkmcnt(0)
	v_add_f32_e32 v30, v18, v28
	ds_bpermute_b32 v31, v188, v30
	v_fmac_f32_e32 v3, 0x3a800000, v36
	s_waitcnt lgkmcnt(0)
	v_add_f32_e32 v28, v19, v29
	s_waitcnt lgkmcnt(0)
	v_add_f32_e32 v18, v37, v38
	ds_bpermute_b32 v29, v188, v28
	ds_bpermute_b32 v19, v188, v18
	s_and_b64 vcc, exec, s[52:53]
	s_cbranch_vccnz .LBB0_1015
	v_mul_f32_e32 v36, 0x4b800000, v3
	v_cmp_gt_f32_e32 vcc, s43, v3
	s_lshl_b64 s[0:1], s[14:15], 11
	s_nop 0
	v_cndmask_b32_e32 v36, v3, v36, vcc
	v_rsq_f32_e32 v38, v36
	v_lshl_add_u64 v[36:37], v[4:5], 0, s[0:1]
	v_mul_f32_e32 v39, 0x45800000, v38
	v_cndmask_b32_e32 v38, v38, v39, vcc
	v_pk_mul_f32 v[44:45], v[172:173], v[38:39] op_sel_hi:[1,0]
	v_pk_mul_f32 v[40:41], v[170:171], v[38:39] op_sel_hi:[1,0]
	v_cvt_pk_bf16_f32 v44, v44, v45
	s_nop 0
	v_cvt_pk_bf16_f32 v45, v40, v41
	global_store_dwordx2 v[36:37], v[44:45], off
	v_pk_mul_f32 v[44:45], v[120:121], v[38:39] op_sel_hi:[1,0]
	v_pk_mul_f32 v[40:41], v[118:119], v[38:39] op_sel_hi:[1,0]
	v_cvt_pk_bf16_f32 v44, v44, v45
	s_nop 0
	v_cvt_pk_bf16_f32 v45, v40, v41
	global_store_dwordx2 v[36:37], v[44:45], off offset:512
	v_pk_mul_f32 v[40:41], v[102:103], v[38:39] op_sel_hi:[1,0]
	v_pk_mul_f32 v[44:45], v[104:105], v[38:39] op_sel_hi:[1,0]
	s_nop 0
	v_cvt_pk_bf16_f32 v44, v44, v45
	v_cvt_pk_bf16_f32 v45, v40, v41
	v_pk_mul_f32 v[40:41], v[82:83], v[38:39] op_sel_hi:[1,0]
	v_pk_mul_f32 v[38:39], v[84:85], v[38:39] op_sel_hi:[1,0]
	global_store_dwordx2 v[36:37], v[44:45], off offset:1024
	v_cvt_pk_bf16_f32 v38, v38, v39
	v_cvt_pk_bf16_f32 v39, v40, v41
	global_store_dwordx2 v[36:37], v[38:39], off offset:1536

; __device__ __forceinline__ void st4_bf16(bf16* p, v4f o) { v2u w; w.x = cvt_pk_nv(o.x, o.y); w.y = cvt_pk_nv(o.z, o.w); *(v2u*)p = w; }
; template <int R, bool BASE_F32, bool OUT_F32>
; __device__ __forceinline__ void rows_res(const Ctx& C, int m0, int stride, int mx, const float* gpost, float scale, int lane) {
;     ...
;         for (int r = 0; r < R; ++r) { const float rstd = rsqrtf(t[r]);
; #pragma unroll
;             for (int j = 0; j < 4; ++j) if (ok[r]) st4_bf16(XN + (size_t)mr[r] * DM + 4 * lane + 256 * j, d[r][j] * rstd);
;             if (lane == 0 && ok[r]) rs[mr[r]] = sqrtf(t[r]); }
.LBB0_1021:
	s_or_b64 exec, exec, s[40:41]
	s_waitcnt lgkmcnt(0)
	v_add_f32_e32 v24, v30, v31
	v_mov_b32_e32 v3, 0x358637bd
	s_andn2_b64 vcc, exec, s[38:39]
	v_fmac_f32_e32 v3, 0x3a800000, v24
	s_cbranch_vccnz .LBB0_1023
	s_mov_b32 s0, 0x800000
	v_mul_f32_e32 v24, 0x4b800000, v3
	v_cmp_gt_f32_e32 vcc, s0, v3
	s_lshl_b64 s[0:1], s[28:29], 11
	v_lshl_add_u64 v[26:27], v[4:5], 0, s[0:1]
	v_cndmask_b32_e32 v24, v3, v24, vcc
	v_rsq_f32_e32 v24, v24
	s_nop 0
	v_mul_f32_e32 v25, 0x45800000, v24
	v_cndmask_b32_e32 v24, v24, v25, vcc
	v_pk_mul_f32 v[34:35], v[112:113], v[24:25] op_sel_hi:[1,0]
	v_pk_mul_f32 v[30:31], v[110:111], v[24:25] op_sel_hi:[1,0]
	v_cvt_pk_bf16_f32 v34, v34, v35
	v_pk_mul_f32 v[16:17], v[16:17], v[24:25] op_sel_hi:[1,0]
	v_cvt_pk_bf16_f32 v35, v30, v31
	global_store_dwordx2 v[26:27], v[34:35], off
	v_pk_mul_f32 v[34:35], v[90:91], v[24:25] op_sel_hi:[1,0]
	v_pk_mul_f32 v[30:31], v[94:95], v[24:25] op_sel_hi:[1,0]
	v_cvt_pk_bf16_f32 v34, v34, v35
	v_pk_mul_f32 v[14:15], v[14:15], v[24:25] op_sel_hi:[1,0]
	v_cvt_pk_bf16_f32 v35, v30, v31
	global_store_dwordx2 v[26:27], v[34:35], off offset:512
	v_pk_mul_f32 v[34:35], v[78:79], v[24:25] op_sel_hi:[1,0]
	v_pk_mul_f32 v[30:31], v[80:81], v[24:25] op_sel_hi:[1,0]
	v_cvt_pk_bf16_f32 v34, v34, v35
	v_cvt_pk_bf16_f32 v16, v16, v17
	v_cvt_pk_bf16_f32 v17, v14, v15
	global_store_dwordx2 v[26:27], v[16:17], off offset:1536
	v_cvt_pk_bf16_f32 v35, v30, v31
	global_store_dwordx2 v[26:27], v[34:35], off offset:1024

; __device__ __forceinline__ void st4_bf16(bf16* p, v4f o) { v2u w; w.x = cvt_pk_nv(o.x, o.y); w.y = cvt_pk_nv(o.z, o.w); *(v2u*)p = w; }
; template <int R, bool BASE_F32, bool OUT_F32>
; __device__ __forceinline__ void rows_res(const Ctx& C, int m0, int stride, int mx, const float* gpost, float scale, int lane) {
;     ...
;         for (int r = 0; r < R; ++r) { const float rstd = rsqrtf(t[r]);
; #pragma unroll
;             for (int j = 0; j < 4; ++j) if (ok[r]) st4_bf16(XN + (size_t)mr[r] * DM + 4 * lane + 256 * j, d[r][j] * rstd);
;             if (lane == 0 && ok[r]) rs[mr[r]] = sqrtf(t[r]); }
.LBB0_1025:
	s_or_b64 exec, exec, s[34:35]
	s_waitcnt lgkmcnt(0)
	v_add_f32_e32 v14, v28, v29
	v_mov_b32_e32 v3, 0x358637bd
	s_andn2_b64 vcc, exec, s[30:31]
	v_fmac_f32_e32 v3, 0x3a800000, v14
	s_cbranch_vccnz .LBB0_1027
	s_mov_b32 s0, 0x800000
	v_mul_f32_e32 v14, 0x4b800000, v3
	v_cmp_gt_f32_e32 vcc, s0, v3
	s_lshl_b64 s[0:1], s[24:25], 11
	v_lshl_add_u64 v[16:17], v[4:5], 0, s[0:1]
	v_cndmask_b32_e32 v14, v3, v14, vcc
	v_rsq_f32_e32 v14, v14
	s_nop 0
	v_mul_f32_e32 v15, 0x45800000, v14
	v_cndmask_b32_e32 v14, v14, v15, vcc
	v_pk_mul_f32 v[26:27], v[72:73], v[14:15] op_sel_hi:[1,0]
	v_pk_mul_f32 v[24:25], v[70:71], v[14:15] op_sel_hi:[1,0]
	v_cvt_pk_bf16_f32 v26, v26, v27
	v_pk_mul_f32 v[12:13], v[12:13], v[14:15] op_sel_hi:[1,0]
	v_cvt_pk_bf16_f32 v27, v24, v25
	global_store_dwordx2 v[16:17], v[26:27], off
	v_pk_mul_f32 v[26:27], v[88:89], v[14:15] op_sel_hi:[1,0]
	v_pk_mul_f32 v[24:25], v[86:87], v[14:15] op_sel_hi:[1,0]
	v_cvt_pk_bf16_f32 v26, v26, v27
	v_pk_mul_f32 v[10:11], v[10:11], v[14:15] op_sel_hi:[1,0]
	v_cvt_pk_bf16_f32 v27, v24, v25
	global_store_dwordx2 v[16:17], v[26:27], off offset:512
	v_pk_mul_f32 v[26:27], v[76:77], v[14:15] op_sel_hi:[1,0]
	v_pk_mul_f32 v[24:25], v[74:75], v[14:15] op_sel_hi:[1,0]
	v_cvt_pk_bf16_f32 v26, v26, v27
	v_cvt_pk_bf16_f32 v12, v12, v13
	v_cvt_pk_bf16_f32 v13, v10, v11
	global_store_dwordx2 v[16:17], v[12:13], off offset:1536
	v_cvt_pk_bf16_f32 v27, v24, v25
	global_store_dwordx2 v[16:17], v[26:27], off offset:1024

; __device__ __forceinline__ const float* xrow_ptr(const Ctx& C, int row) { return row < MPROMPT ? C.in(0) + (size_t)row * DM : C.in(1) + (size_t)(row - MPROMPT) * DM; }
; __device__ __forceinline__ v4f ld4_bf16(const bf16* p) { const v2u w = *(const v2u*)p; return (v4f){bf_lo(w.x), bf_hi(w.x), bf_lo(w.y), bf_hi(w.y)}; }
; template <int R, bool BASE_F32, bool OUT_F32>
; __device__ __forceinline__ void rows_res(const Ctx& C, int m0, int stride, int mx, const float* gpost, float scale, int lane) {
;     v4f d[R][4], b[R][4]; int mr[R]; bool ok[R]; float r1[R];
;     const bf16* D = C.D(); bf16* XN = C.XN();
; #pragma unroll
;     for (int r = 0; r < R; ++r) { mr[r] = (r == 4) ? mx : m0 + r * stride; ok[r] = (r == 4) ? (mx < M) : (mr[r] < MPROMPT); const int mm = ok[r] ? mr[r] : 0;
; #pragma unroll
;         for (int j = 0; j < 4; ++j) d[r][j] = ld4_bf16(D + (size_t)mm * DM + 4 * lane + 256 * j);
;         if (BASE_F32) { const float* x = xrow_ptr(C, mm);
; #pragma unroll
;             for (int j = 0; j < 4; ++j) b[r][j] = ld4_f32(x + 4 * lane + 256 * j);
;         } else { const float inv = C.RS()[mm];
; #pragma unroll
;             for (int j = 0; j < 4; ++j) b[r][j] = ld4_bf16(XN + (size_t)mm * DM + 4 * lane + 256 * j) * inv;
;         } }
.LBB0_1036:
	s_mov_b64 s[12:13], s[80:81]
	s_load_dwordx2 s[14:15], s[12:13], 0x110
	s_mov_b64 s[12:13], s[80:81]
	s_mov_b64 s[42:43], s[80:81]
	s_load_dwordx2 s[12:13], s[12:13], 0x110
	s_waitcnt lgkmcnt(0)
	v_lshl_add_u64 v[8:9], s[14:15], 0, v[0:1]
	v_lshl_add_u64 v[10:11], v[8:9], 0, s[54:55]
	v_lshl_add_u64 v[12:13], v[10:11], 0, s[18:19]
	s_mov_b64 s[42:43], s[80:81]
	global_load_dwordx2 v[102:103], v[12:13], off
	global_load_dwordx2 v[94:95], v[12:13], off offset:512
	global_load_dwordx2 v[100:101], v[12:13], off offset:1024
	global_load_dwordx2 v[22:23], v[12:13], off offset:1536
	s_load_dwordx2 s[42:43], s[42:43], 0x110
	v_lshl_add_u64 v[8:9], s[12:13], 0, v[0:1]
	v_lshl_add_u64 v[8:9], v[8:9], 0, s[56:57]
	v_lshl_add_u64 v[14:15], v[8:9], 0, s[18:19]
	global_load_dwordx2 v[24:25], v[14:15], off
	global_load_dwordx2 v[26:27], v[14:15], off offset:512
	global_load_dwordx2 v[28:29], v[14:15], off offset:1024
	s_waitcnt lgkmcnt(0)
	s_add_u32 s42, s42, s58
	s_addc_u32 s43, s43, s59
	global_load_dword v12, v39, s[42:43]
	global_load_dwordx2 v[30:31], v[14:15], off offset:1536
	v_lshl_add_u64 v[14:15], v[10:11], 0, s[22:23]
	s_mov_b64 s[42:43], s[80:81]
	global_load_dwordx2 v[110:111], v[14:15], off
	global_load_dwordx2 v[106:107], v[14:15], off offset:512
	global_load_dwordx2 v[108:109], v[14:15], off offset:1024
	global_load_dwordx2 v[32:33], v[14:15], off offset:1536
	v_lshl_add_u64 v[14:15], v[8:9], 0, s[22:23]
	global_load_dwordx2 v[34:35], v[14:15], off
	global_load_dwordx2 v[36:37], v[14:15], off offset:512
	s_load_dwordx2 s[42:43], s[42:43], 0x110
	s_mov_b64 s[70:71], s[80:81]
	v_lshl_add_u64 v[10:11], v[10:11], 0, s[26:27]
	v_lshl_add_u64 v[16:17], v[8:9], 0, s[26:27]
	global_load_dwordx2 v[40:41], v[14:15], off offset:1024
	global_load_dwordx2 v[42:43], v[14:15], off offset:1536
	s_waitcnt lgkmcnt(0)
	s_add_u32 s42, s42, s60
	s_addc_u32 s43, s43, s61
	global_load_dwordx2 v[122:123], v[10:11], off
	global_load_dwordx2 v[118:119], v[10:11], off offset:512
	global_load_dwordx2 v[120:121], v[10:11], off offset:1024
	global_load_dwordx2 v[44:45], v[10:11], off offset:1536
	global_load_dword v14, v39, s[42:43]
	global_load_dwordx2 v[46:47], v[16:17], off
	global_load_dwordx2 v[48:49], v[16:17], off offset:512
	global_load_dwordx2 v[66:67], v[16:17], off offset:1024
	v_lshl_add_u64 v[18:19], s[14:15], 0, v[4:5]
	v_lshl_add_u64 v[10:11], s[12:13], 0, v[4:5]
	global_load_dwordx2 v[74:75], v[16:17], off offset:1536
	global_load_dwordx2 v[140:141], v[18:19], off offset:-1536
	global_load_dwordx2 v[134:135], v[18:19], off offset:-1024
	global_load_dwordx2 v[138:139], v[18:19], off offset:-512
	global_load_dwordx2 v[78:79], v[18:19], off
	s_load_dwordx2 s[12:13], s[70:71], 0x110
	v_add_co_u32_e32 v82, vcc, s47, v10
	s_mov_b64 s[42:43], s[80:81]
	s_nop 0
	v_addc_co_u32_e32 v83, vcc, -1, v11, vcc
	s_waitcnt lgkmcnt(0)
	s_add_u32 s12, s12, s62
	s_addc_u32 s13, s13, s63
	global_load_dword v16, v39, s[12:13]
	global_load_dwordx2 v[84:85], v[82:83], off offset:-1536
	global_load_dwordx2 v[104:105], v[82:83], off offset:-1024
	global_load_dwordx2 v[112:113], v[82:83], off offset:-512
	s_load_dwordx2 s[12:13], s[42:43], 0x110
	s_waitcnt lgkmcnt(0)
	s_add_u32 s12, s12, s87
	s_addc_u32 s13, s13, s88
	global_load_dword v38, v1, s[12:13]
	global_load_dwordx2 v[136:137], v[82:83], off
	s_waitcnt vmcnt(35)
	v_and_b32_e32 v117, 0xffff0000, v103
	v_and_b32_e32 v115, 0xffff0000, v102
	v_lshlrev_b32_e32 v116, 16, v103
	s_waitcnt vmcnt(32)
	v_and_b32_e32 v19, 0xffff0000, v22
	v_mul_f32_e32 v18, v117, v117
	v_lshlrev_b32_e32 v114, 16, v102
	v_lshlrev_b32_e32 v21, 16, v22
	v_lshlrev_b32_e32 v103, 16, v95
	v_lshlrev_b32_e32 v102, 16, v94
	v_mov_b32_e32 v129, v21
	s_waitcnt vmcnt(30)
	v_lshlrev_b32_e32 v68, 16, v27
	v_and_b32_e32 v69, 0xffff0000, v27
	s_waitcnt vmcnt(29)
	v_lshlrev_b32_e32 v50, 16, v28
	v_and_b32_e32 v51, 0xffff0000, v28
	v_lshlrev_b32_e32 v52, 16, v29
	v_and_b32_e32 v53, 0xffff0000, v29
	v_lshlrev_b32_e32 v64, 16, v26
	s_waitcnt vmcnt(23)
	v_lshlrev_b32_e32 v27, 16, v32
	v_and_b32_e32 v13, 0xffff0000, v32
	v_lshlrev_b32_e32 v28, 16, v33
	v_and_b32_e32 v29, 0xffff0000, v33
	s_waitcnt vmcnt(21)
	v_lshlrev_b32_e32 v70, 16, v36
	v_and_b32_e32 v71, 0xffff0000, v36
	v_lshlrev_b32_e32 v72, 16, v37
	v_and_b32_e32 v73, 0xffff0000, v37
	s_waitcnt vmcnt(20)
	v_lshlrev_b32_e32 v58, 16, v40
	v_and_b32_e32 v59, 0xffff0000, v40
	v_lshlrev_b32_e32 v60, 16, v41
	v_and_b32_e32 v61, 0xffff0000, v41
	s_waitcnt vmcnt(19)
	v_lshlrev_b32_e32 v32, 16, v42
	v_and_b32_e32 v33, 0xffff0000, v42
	v_lshlrev_b32_e32 v40, 16, v43
	v_and_b32_e32 v41, 0xffff0000, v43
	s_waitcnt vmcnt(15)
	v_lshlrev_b32_e32 v36, 16, v45
	v_and_b32_e32 v37, 0xffff0000, v45
	s_waitcnt vmcnt(13)
	v_lshlrev_b32_e32 v86, 16, v46
	v_and_b32_e32 v87, 0xffff0000, v46
	v_lshlrev_b32_e32 v88, 16, v47
	v_and_b32_e32 v89, 0xffff0000, v47
	s_waitcnt vmcnt(12)
	v_lshlrev_b32_e32 v76, 16, v48
	v_and_b32_e32 v77, 0xffff0000, v48
	v_lshlrev_b32_e32 v80, 16, v49
	v_and_b32_e32 v81, 0xffff0000, v49
	s_waitcnt vmcnt(10)
	v_lshlrev_b32_e32 v42, 16, v74
	v_and_b32_e32 v43, 0xffff0000, v74
	v_lshlrev_b32_e32 v48, 16, v75
	v_and_b32_e32 v49, 0xffff0000, v75
	s_waitcnt vmcnt(6)
	v_lshlrev_b32_e32 v45, 16, v78
	v_and_b32_e32 v17, 0xffff0000, v78
	v_lshlrev_b32_e32 v46, 16, v79
	v_and_b32_e32 v47, 0xffff0000, v79
	s_waitcnt vmcnt(4)
	v_lshlrev_b32_e32 v96, 16, v84
	v_and_b32_e32 v97, 0xffff0000, v84
	v_lshlrev_b32_e32 v98, 16, v85
	v_and_b32_e32 v99, 0xffff0000, v85
	s_waitcnt vmcnt(3)
	v_lshlrev_b32_e32 v82, 16, v104
	v_and_b32_e32 v83, 0xffff0000, v104
	v_lshlrev_b32_e32 v84, 16, v105
	v_and_b32_e32 v85, 0xffff0000, v105
	s_waitcnt vmcnt(2)
; __device__ __forceinline__ float ssq4(v4f v) { return (v.x * v.x + v.y * v.y) + (v.z * v.z + v.w * v.w); }
; template <int R, bool BASE_F32, bool OUT_F32>
; __device__ __forceinline__ void rows_res(const Ctx& C, int m0, int stride, int mx, const float* gpost, float scale, int lane) {
;     ...
;     for (int r = 0; r < R; ++r) { float s = 0.f;
; #pragma unroll
;         for (int j = 0; j < 4; ++j) s += ssq4(d[r][j]);
;         r1[r] = s; }
; #pragma unroll
;     for (int r = 0; r < R; ++r) r1[r] = rsqrtf(wave_sum(r1[r]) * (1.f / DM) + EPS) * scale;
	v_lshlrev_b32_e32 v74, 16, v112
	v_and_b32_e32 v75, 0xffff0000, v112
	v_lshlrev_b32_e32 v78, 16, v113
	v_and_b32_e32 v79, 0xffff0000, v113
	v_pk_fma_f32 v[112:113], v[116:117], v[116:117], v[18:19] op_sel_hi:[1,1,0]
	v_and_b32_e32 v105, 0xffff0000, v95
	v_and_b32_e32 v104, 0xffff0000, v94
	v_mul_f32_e32 v18, v115, v115
	v_pk_mul_f32 v[94:95], v[104:105], v[104:105]
	v_pk_fma_f32 v[126:127], v[114:115], v[114:115], v[18:19] op_sel_hi:[1,1,0]
	v_pk_fma_f32 v[124:125], v[102:103], v[102:103], v[94:95]
	v_mov_b32_e32 v20, v126
	v_mov_b32_e32 v128, v112
	v_and_b32_e32 v65, 0xffff0000, v26
	v_and_b32_e32 v95, 0xffff0000, v100
	v_mul_f32_e32 v26, v19, v19
	v_pk_add_f32 v[112:113], v[126:127], v[112:113]
	v_pk_mul_f32 v[126:127], v[20:21], v[128:129]
	v_pk_add_f32 v[124:125], v[124:125], v[124:125] op_sel:[0,1] op_sel_hi:[1,0]
	v_lshlrev_b32_e32 v94, 16, v100
	v_lshlrev_b32_e32 v100, 16, v101
	v_and_b32_e32 v101, 0xffff0000, v101
	v_mov_b32_e32 v113, v127
	v_mov_b32_e32 v125, v26
	v_mul_f32_e32 v18, v95, v95
	v_lshlrev_b32_e32 v22, 16, v23
	v_and_b32_e32 v23, 0xffff0000, v23
	v_pk_add_f32 v[112:113], v[112:113], v[124:125]
	v_pk_fma_f32 v[124:125], v[94:95], v[94:95], v[18:19] op_sel_hi:[1,1,0]
	v_mul_f32_e32 v18, v101, v101
	v_lshlrev_b32_e32 v54, 16, v34
	v_and_b32_e32 v55, 0xffff0000, v34
	v_lshlrev_b32_e32 v56, 16, v35
	v_and_b32_e32 v57, 0xffff0000, v35
	v_lshlrev_b32_e32 v35, 16, v44
	v_and_b32_e32 v15, 0xffff0000, v44
	v_mul_f32_e32 v34, v22, v22
	v_mul_f32_e32 v44, v23, v23
	v_pk_fma_f32 v[126:127], v[100:101], v[100:101], v[18:19] op_sel_hi:[1,1,0]
	v_mov_b32_e32 v125, v34
	v_mov_b32_e32 v127, v44
	v_and_b32_e32 v129, 0xffff0000, v111
	v_pk_add_f32 v[124:125], v[124:125], v[126:127]
	v_and_b32_e32 v127, 0xffff0000, v110
	v_lshlrev_b32_e32 v128, 16, v111
	v_mul_f32_e32 v18, v129, v129
	v_pk_add_f32 v[148:149], v[112:113], v[124:125]
	v_lshlrev_b32_e32 v126, 16, v110
	v_pk_fma_f32 v[124:125], v[128:129], v[128:129], v[18:19] op_sel_hi:[1,1,0]
	v_and_b32_e32 v113, 0xffff0000, v107
	v_and_b32_e32 v112, 0xffff0000, v106
	v_mul_f32_e32 v18, v127, v127
	v_lshlrev_b32_e32 v111, 16, v107
	v_lshlrev_b32_e32 v110, 16, v106
	v_pk_mul_f32 v[106:107], v[112:113], v[112:113]
	v_pk_fma_f32 v[132:133], v[126:127], v[126:127], v[18:19] op_sel_hi:[1,1,0]
	v_pk_fma_f32 v[130:131], v[110:111], v[110:111], v[106:107]
	v_mov_b32_e32 v26, v132
	v_mov_b32_e32 v142, v124
	v_mov_b32_e32 v143, v27
	v_and_b32_e32 v107, 0xffff0000, v108
	v_mul_f32_e32 v20, v13, v13
	v_pk_add_f32 v[124:125], v[132:133], v[124:125]
	v_pk_mul_f32 v[132:133], v[26:27], v[142:143]
	v_pk_add_f32 v[130:131], v[130:131], v[130:131] op_sel:[0,1] op_sel_hi:[1,0]
	v_lshlrev_b32_e32 v106, 16, v108
	v_lshlrev_b32_e32 v108, 16, v109
	v_and_b32_e32 v109, 0xffff0000, v109
	v_mov_b32_e32 v125, v133
	v_mov_b32_e32 v131, v20
	v_mul_f32_e32 v18, v107, v107
	v_pk_add_f32 v[124:125], v[124:125], v[130:131]
	v_pk_fma_f32 v[130:131], v[106:107], v[106:107], v[18:19] op_sel_hi:[1,1,0]
	v_mul_f32_e32 v18, v109, v109
	v_mul_f32_e32 v34, v28, v28
	v_mul_f32_e32 v44, v29, v29
	v_pk_fma_f32 v[132:133], v[108:109], v[108:109], v[18:19] op_sel_hi:[1,1,0]
	v_mov_b32_e32 v131, v34
	v_mov_b32_e32 v133, v44
	v_pk_add_f32 v[130:131], v[130:131], v[132:133]
	v_and_b32_e32 v133, 0xffff0000, v123
	v_pk_add_f32 v[152:153], v[124:125], v[130:131]
	v_and_b32_e32 v131, 0xffff0000, v122
	v_lshlrev_b32_e32 v132, 16, v123
	v_mul_f32_e32 v18, v133, v133
	v_lshlrev_b32_e32 v130, 16, v122
	v_pk_fma_f32 v[142:143], v[132:133], v[132:133], v[18:19] op_sel_hi:[1,1,0]
	v_and_b32_e32 v125, 0xffff0000, v119
	v_and_b32_e32 v124, 0xffff0000, v118
	v_mul_f32_e32 v18, v131, v131
	v_lshlrev_b32_e32 v123, 16, v119
	v_lshlrev_b32_e32 v122, 16, v118
	v_pk_mul_f32 v[118:119], v[124:125], v[124:125]
	v_pk_fma_f32 v[146:147], v[130:131], v[130:131], v[18:19] op_sel_hi:[1,1,0]
	v_pk_fma_f32 v[144:145], v[122:123], v[122:123], v[118:119]
	v_mov_b32_e32 v34, v146
	v_mov_b32_e32 v154, v142
	v_mov_b32_e32 v155, v35
	v_and_b32_e32 v119, 0xffff0000, v120
	v_mul_f32_e32 v20, v15, v15
	v_pk_add_f32 v[142:143], v[146:147], v[142:143]
	v_pk_mul_f32 v[146:147], v[34:35], v[154:155]
	v_pk_add_f32 v[144:145], v[144:145], v[144:145] op_sel:[0,1] op_sel_hi:[1,0]
	v_lshlrev_b32_e32 v118, 16, v120
	v_lshlrev_b32_e32 v120, 16, v121
	v_and_b32_e32 v121, 0xffff0000, v121
	v_mov_b32_e32 v143, v147
	v_mov_b32_e32 v145, v20
	v_mul_f32_e32 v18, v119, v119
	v_pk_add_f32 v[142:143], v[142:143], v[144:145]
	v_pk_fma_f32 v[144:145], v[118:119], v[118:119], v[18:19] op_sel_hi:[1,1,0]
	v_mul_f32_e32 v18, v121, v121
	v_mul_f32_e32 v26, v36, v36
	v_mul_f32_e32 v44, v37, v37
	v_pk_fma_f32 v[146:147], v[120:121], v[120:121], v[18:19] op_sel_hi:[1,1,0]
	v_mov_b32_e32 v145, v26
	v_mov_b32_e32 v147, v44
	v_pk_add_f32 v[144:145], v[144:145], v[146:147]
	v_and_b32_e32 v147, 0xffff0000, v141
	v_pk_add_f32 v[156:157], v[142:143], v[144:145]
	v_and_b32_e32 v145, 0xffff0000, v140
	v_lshlrev_b32_e32 v146, 16, v141
	v_mul_f32_e32 v18, v147, v147
	v_lshlrev_b32_e32 v144, 16, v140
	v_pk_fma_f32 v[154:155], v[146:147], v[146:147], v[18:19] op_sel_hi:[1,1,0]
	v_mul_f32_e32 v18, v145, v145
	v_pk_fma_f32 v[160:161], v[144:145], v[144:145], v[18:19] op_sel_hi:[1,1,0]
	v_mov_b32_e32 v162, v154
	v_mov_b32_e32 v44, v160
	v_mov_b32_e32 v163, v45
	v_pk_add_f32 v[154:155], v[160:161], v[154:155]
	v_pk_mul_f32 v[160:161], v[44:45], v[162:163]
	v_mov_b32_e32 v162, v152
	v_mov_b32_e32 v163, v148
	v_mov_b32_e32 v148, v153
	v_pk_add_f32 v[148:149], v[162:163], v[148:149]
	v_and_b32_e32 v143, 0xffff0000, v135
	v_and_b32_e32 v142, 0xffff0000, v134
	s_nop 1
	v_mov_b32_dpp v153, v149 quad_perm:[1,0,3,2] row_mask:0xf bank_mask:0xf
	s_nop 1
	v_mov_b32_dpp v152, v148 quad_perm:[1,0,3,2] row_mask:0xf bank_mask:0xf
	v_lshlrev_b32_e32 v141, 16, v135
	v_lshlrev_b32_e32 v140, 16, v134
	v_pk_mul_f32 v[134:135], v[142:143], v[142:143]
	v_mul_f32_e32 v20, v17, v17
	v_pk_fma_f32 v[158:159], v[140:141], v[140:141], v[134:135]
	v_mov_b32_e32 v155, v161
	v_pk_add_f32 v[158:159], v[158:159], v[158:159] op_sel:[0,1] op_sel_hi:[1,0]
	s_waitcnt lgkmcnt(0)
; template <int R, bool BASE_F32, bool OUT_F32>
; __device__ __forceinline__ void rows_res(const Ctx& C, int m0, int stride, int mx, const float* gpost, float scale, int lane) {
;     ...
;     for (int r = 0; r < R; ++r) r1[r] = rsqrtf(wave_sum(r1[r]) * (1.f / DM) + EPS) * scale;
; #pragma unroll
;     for (int j = 0; j < 4; ++j) { const v4f gp = ld4_f32(gpost + 4 * lane + 256 * j);
; #pragma unroll
;         for (int r = 0; r < R; ++r) d[r][j] = b[r][j] + d[r][j] * r1[r] * gp; }
	v_pk_add_f32 v[148:149], v[148:149], v[152:153]
	v_mov_b32_e32 v159, v20
	v_pk_add_f32 v[158:159], v[154:155], v[158:159]
	global_load_dwordx4 v[152:155], v[2:3], off
	s_nop 1
	v_mov_b32_dpp v161, v149 quad_perm:[2,3,0,1] row_mask:0xf bank_mask:0xf
	s_nop 1
	v_mov_b32_dpp v160, v148 quad_perm:[2,3,0,1] row_mask:0xf bank_mask:0xf
	v_and_b32_e32 v135, 0xffff0000, v138
	v_lshlrev_b32_e32 v134, 16, v138
	v_lshlrev_b32_e32 v138, 16, v139
	v_and_b32_e32 v139, 0xffff0000, v139
	v_mul_f32_e32 v18, v135, v135
	s_waitcnt lgkmcnt(0)
	v_pk_add_f32 v[148:149], v[148:149], v[160:161]
	v_pk_fma_f32 v[162:163], v[134:135], v[134:135], v[18:19] op_sel_hi:[1,1,0]
	v_mul_f32_e32 v18, v139, v139
	s_nop 1
	v_mov_b32_dpp v161, v149 row_half_mirror row_mask:0xf bank_mask:0xf
	s_nop 1
	v_mov_b32_dpp v160, v148 row_half_mirror row_mask:0xf bank_mask:0xf
	v_mul_f32_e32 v26, v46, v46
	v_mul_f32_e32 v34, v47, v47
	v_pk_fma_f32 v[164:165], v[138:139], v[138:139], v[18:19] op_sel_hi:[1,1,0]
	v_mov_b32_e32 v163, v26
	v_mov_b32_e32 v165, v34
	v_pk_add_f32 v[162:163], v[162:163], v[164:165]
	s_waitcnt lgkmcnt(0)
	v_pk_add_f32 v[160:161], v[148:149], v[160:161]
	v_pk_add_f32 v[158:159], v[158:159], v[162:163]
	v_mov_b32_e32 v149, v156
	v_mov_b32_e32 v148, v158
	v_mov_b32_e32 v156, v159
	v_pk_add_f32 v[156:157], v[148:149], v[156:157]
	s_nop 1
	v_mov_b32_dpp v163, v161 row_mirror row_mask:0xf bank_mask:0xf
	s_nop 1
	v_mov_b32_dpp v162, v160 row_mirror row_mask:0xf bank_mask:0xf
	s_nop 1
	v_mov_b32_dpp v159, v157 quad_perm:[1,0,3,2] row_mask:0xf bank_mask:0xf
	s_nop 1
	v_mov_b32_dpp v158, v156 quad_perm:[1,0,3,2] row_mask:0xf bank_mask:0xf
	v_lshlrev_b32_e32 v90, 16, v24
	v_and_b32_e32 v91, 0xffff0000, v24
	s_waitcnt lgkmcnt(0)
	v_pk_add_f32 v[160:161], v[160:161], v[162:163]
	ds_bpermute_b32 v163, v187, v161
	s_waitcnt lgkmcnt(0)
	v_pk_add_f32 v[164:165], v[156:157], v[158:159]
	ds_bpermute_b32 v162, v187, v160
	s_nop 1
	v_mov_b32_dpp v167, v165 quad_perm:[2,3,0,1] row_mask:0xf bank_mask:0xf
	s_nop 1
	v_mov_b32_dpp v166, v164 quad_perm:[2,3,0,1] row_mask:0xf bank_mask:0xf
	global_load_dwordx4 v[156:159], v[2:3], off offset:1024
	v_lshlrev_b32_e32 v92, 16, v25
	s_waitcnt lgkmcnt(0)
	v_pk_add_f32 v[160:161], v[160:161], v[162:163]
	ds_bpermute_b32 v163, v188, v161
	s_waitcnt lgkmcnt(0)
	v_pk_add_f32 v[164:165], v[164:165], v[166:167]
	ds_bpermute_b32 v162, v188, v160
	s_nop 1
	v_mov_b32_dpp v167, v165 row_half_mirror row_mask:0xf bank_mask:0xf
	s_nop 1
	v_mov_b32_dpp v166, v164 row_half_mirror row_mask:0xf bank_mask:0xf
	v_and_b32_e32 v93, 0xffff0000, v25
	v_lshlrev_b32_e32 v24, 16, v30
	s_waitcnt lgkmcnt(0)
	v_pk_add_f32 v[160:161], v[160:161], v[162:163]
	v_and_b32_e32 v25, 0xffff0000, v30
	s_waitcnt lgkmcnt(0)
	v_pk_add_f32 v[162:163], v[164:165], v[166:167]
	s_nop 1
	v_mov_b32_dpp v165, v163 row_mirror row_mask:0xf bank_mask:0xf
	s_nop 1
	v_mov_b32_dpp v164, v162 row_mirror row_mask:0xf bank_mask:0xf
	v_pk_fma_f32 v[160:161], v[160:161], s[72:73], v[6:7] op_sel_hi:[1,0,0]
	v_lshlrev_b32_e32 v30, 16, v31
	v_mul_f32_e32 v18, 0x4b800000, v161
	v_cmp_gt_f32_e32 vcc, s89, v161
	s_waitcnt lgkmcnt(0)
	v_pk_add_f32 v[162:163], v[162:163], v[164:165]
	ds_bpermute_b32 v165, v187, v163
	ds_bpermute_b32 v164, v187, v162
	v_cndmask_b32_e32 v18, v161, v18, vcc
	v_rsq_f32_e32 v18, v18
	v_mul_f32_e32 v20, 0x4b800000, v160
	v_cmp_gt_f32_e64 s[12:13], s89, v160
	s_waitcnt lgkmcnt(0)
	v_pk_add_f32 v[164:165], v[162:163], v[164:165]
	ds_bpermute_b32 v167, v188, v165
	ds_bpermute_b32 v166, v188, v164
	v_cndmask_b32_e64 v20, v160, v20, s[12:13]
	v_rsq_f32_e32 v26, v20
	v_mul_f32_e32 v20, 0x45800000, v18
	global_load_dwordx4 v[160:163], v[2:3], off offset:2048
	s_waitcnt lgkmcnt(0)
	v_pk_add_f32 v[164:165], v[164:165], v[166:167]
	v_cndmask_b32_e32 v20, v18, v20, vcc
	v_pk_fma_f32 v[164:165], v[164:165], s[72:73], v[6:7] op_sel_hi:[1,0,0]
	v_mul_f32_e32 v18, 0x45800000, v26
	v_mul_f32_e32 v34, 0x4b800000, v165
	v_cmp_gt_f32_e32 vcc, s89, v165
	v_mul_f32_e32 v44, 0x4b800000, v164
	v_cmp_gt_f32_e64 s[14:15], s89, v164
	v_pk_mul_f32 v[116:117], v[20:21], v[116:117] op_sel_hi:[0,1]
	v_pk_mul_f32 v[114:115], v[20:21], v[114:115] op_sel_hi:[0,1]
	v_cndmask_b32_e32 v34, v165, v34, vcc
	v_cndmask_b32_e64 v44, v164, v44, s[14:15]
	v_cndmask_b32_e64 v26, v26, v18, s[12:13]
	s_waitcnt vmcnt(2)
	v_pk_mul_f32 v[164:165], v[114:115], v[152:153]
	v_pk_mul_f32 v[114:115], v[116:117], v[154:155]
	v_pk_fma_f32 v[116:117], v[12:13], v[90:91], v[164:165] op_sel_hi:[0,1,1]
	v_pk_fma_f32 v[114:115], v[12:13], v[92:93], v[114:115] op_sel_hi:[0,1,1]
	v_pk_mul_f32 v[90:91], v[26:27], v[128:129] op_sel_hi:[0,1]
	v_pk_mul_f32 v[92:93], v[26:27], v[126:127] op_sel_hi:[0,1]
	global_load_dwordx4 v[126:129], v[2:3], off offset:3072
	v_rsq_f32_e32 v34, v34
	v_rsq_f32_e32 v44, v44
	v_pk_mul_f32 v[90:91], v[90:91], v[154:155]
	v_pk_mul_f32 v[92:93], v[92:93], v[152:153]
	v_mul_f32_e32 v18, 0x45800000, v34
	v_cndmask_b32_e32 v34, v34, v18, vcc
	v_mul_f32_e32 v18, 0x45800000, v44
	v_pk_fma_f32 v[90:91], v[14:15], v[56:57], v[90:91] op_sel_hi:[0,1,1]
	v_pk_mul_f32 v[56:57], v[34:35], v[130:131] op_sel_hi:[0,1]
	v_cndmask_b32_e64 v44, v44, v18, s[14:15]
	v_pk_fma_f32 v[92:93], v[14:15], v[54:55], v[92:93] op_sel_hi:[0,1,1]
	v_pk_mul_f32 v[54:55], v[34:35], v[132:133] op_sel_hi:[0,1]
	v_pk_mul_f32 v[56:57], v[152:153], v[56:57]
	v_pk_mul_f32 v[54:55], v[154:155], v[54:55]
	v_pk_fma_f32 v[86:87], v[16:17], v[86:87], v[56:57] op_sel_hi:[0,1,1]
	v_pk_mul_f32 v[56:57], v[44:45], v[144:145] op_sel_hi:[0,1]
	v_pk_fma_f32 v[88:89], v[16:17], v[88:89], v[54:55] op_sel_hi:[0,1,1]
	v_pk_mul_f32 v[54:55], v[44:45], v[146:147] op_sel_hi:[0,1]
	v_pk_mul_f32 v[56:57], v[152:153], v[56:57]
	v_pk_mul_f32 v[54:55], v[154:155], v[54:55]
	v_pk_fma_f32 v[56:57], v[38:39], v[96:97], v[56:57] op_sel_hi:[0,1,1]
	v_mov_b32_e32 v96, v103
	v_mov_b32_e32 v103, v104
	v_pk_fma_f32 v[54:55], v[38:39], v[98:99], v[54:55] op_sel_hi:[0,1,1]
	v_pk_mul_f32 v[98:99], v[20:21], v[102:103] op_sel_hi:[0,1]
	v_mov_b32_e32 v97, v105
	v_pk_mul_f32 v[96:97], v[20:21], v[96:97] op_sel_hi:[0,1]
	s_waitcnt vmcnt(2)
;     __device__ __forceinline__ float* out() const { return (float*)karg_in(33); }
; __device__ __forceinline__ float ssq4(v4f v) { return (v.x * v.x + v.y * v.y) + (v.z * v.z + v.w * v.w); }
; template <int R, bool BASE_F32, bool OUT_F32>
; __device__ __forceinline__ void rows_res(const Ctx& C, int m0, int stride, int mx, const float* gpost, float scale, int lane) {
;     ...
;     for (int j = 0; j < 4; ++j) { const v4f gp = ld4_f32(gpost + 4 * lane + 256 * j);
; #pragma unroll
;         for (int r = 0; r < R; ++r) d[r][j] = b[r][j] + d[r][j] * r1[r] * gp; }
;     if (OUT_F32) { float* Y = C.out();
; #pragma unroll
;         for (int r = 0; r < R; ++r)
; #pragma unroll
;             for (int j = 0; j < 4; ++j) if (ok[r]) *(v4f*)(Y + (size_t)mr[r] * DM + 4 * lane + 256 * j) = d[r][j];
;     } else { float* rs = C.RS(); float t[R];
; #pragma unroll
;         for (int r = 0; r < R; ++r) { float s = 0.f;
; #pragma unroll
;             for (int j = 0; j < 4; ++j) s += ssq4(d[r][j]);
;             t[r] = s; }
; #pragma unroll
;         for (int r = 0; r < R; ++r) t[r] = wave_sum(t[r]) * (1.f / DM) + EPS;
	v_pk_mul_f32 v[98:99], v[98:99], v[156:157]
	v_pk_mul_f32 v[96:97], v[96:97], v[158:159]
	v_pk_fma_f32 v[104:105], v[12:13], v[64:65], v[98:99] op_sel_hi:[0,1,1]
	v_mov_b32_e32 v64, v111
	v_mov_b32_e32 v65, v113
	v_pk_mul_f32 v[64:65], v[26:27], v[64:65] op_sel_hi:[0,1]
	v_mov_b32_e32 v111, v112
	v_pk_mul_f32 v[64:65], v[64:65], v[158:159]
	v_pk_fma_f32 v[102:103], v[12:13], v[68:69], v[96:97] op_sel_hi:[0,1,1]
	v_pk_mul_f32 v[68:69], v[26:27], v[110:111] op_sel_hi:[0,1]
	v_pk_fma_f32 v[96:97], v[14:15], v[72:73], v[64:65] op_sel_hi:[0,1,1]
	v_mov_b32_e32 v64, v123
	v_mov_b32_e32 v65, v125
	v_pk_mul_f32 v[68:69], v[68:69], v[156:157]
	v_pk_mul_f32 v[64:65], v[34:35], v[64:65] op_sel_hi:[0,1]
	v_mov_b32_e32 v123, v124
	v_pk_fma_f32 v[98:99], v[14:15], v[70:71], v[68:69] op_sel_hi:[0,1,1]
	v_pk_mul_f32 v[68:69], v[34:35], v[122:123] op_sel_hi:[0,1]
	v_pk_mul_f32 v[64:65], v[158:159], v[64:65]
	v_pk_mul_f32 v[68:69], v[156:157], v[68:69]
	v_pk_fma_f32 v[70:71], v[16:17], v[80:81], v[64:65] op_sel_hi:[0,1,1]
	v_mov_b32_e32 v64, v141
	v_mov_b32_e32 v141, v142
	v_pk_fma_f32 v[72:73], v[16:17], v[76:77], v[68:69] op_sel_hi:[0,1,1]
	v_pk_mul_f32 v[68:69], v[44:45], v[140:141] op_sel_hi:[0,1]
	v_pk_mul_f32 v[76:77], v[20:21], v[100:101] op_sel_hi:[0,1]
	v_mov_b32_e32 v65, v143
	v_pk_mul_f32 v[68:69], v[156:157], v[68:69]
	v_pk_mul_f32 v[64:65], v[44:45], v[64:65] op_sel_hi:[0,1]
	v_pk_fma_f32 v[68:69], v[38:39], v[82:83], v[68:69] op_sel_hi:[0,1,1]
	v_pk_mul_f32 v[80:81], v[20:21], v[94:95] op_sel_hi:[0,1]
	v_pk_mul_f32 v[64:65], v[158:159], v[64:65]
	s_waitcnt vmcnt(1)
	v_pk_mul_f32 v[76:77], v[76:77], v[162:163]
	v_pk_mul_f32 v[80:81], v[80:81], v[160:161]
	v_pk_fma_f32 v[82:83], v[12:13], v[52:53], v[76:77] op_sel_hi:[0,1,1]
	v_pk_mul_f32 v[52:53], v[26:27], v[106:107] op_sel_hi:[0,1]
	v_pk_mul_f32 v[52:53], v[52:53], v[160:161]
	v_mov_b32_e32 v18, v21
	v_pk_fma_f32 v[64:65], v[38:39], v[84:85], v[64:65] op_sel_hi:[0,1,1]
	v_pk_fma_f32 v[84:85], v[12:13], v[50:51], v[80:81] op_sel_hi:[0,1,1]
	v_pk_mul_f32 v[50:51], v[26:27], v[108:109] op_sel_hi:[0,1]
	v_pk_fma_f32 v[80:81], v[14:15], v[58:59], v[52:53] op_sel_hi:[0,1,1]
	v_pk_mul_f32 v[52:53], v[34:35], v[118:119] op_sel_hi:[0,1]
	v_pk_mul_f32 v[22:23], v[20:21], v[22:23] op_sel_hi:[0,1]
	v_pk_mul_f32 v[18:19], v[20:21], v[18:19] op_sel_hi:[0,1]
	v_and_b32_e32 v31, 0xffff0000, v31
	v_lshlrev_b32_e32 v62, 16, v66
	v_and_b32_e32 v63, 0xffff0000, v66
	v_pk_mul_f32 v[50:51], v[50:51], v[162:163]
	v_pk_mul_f32 v[52:53], v[160:161], v[52:53]
	v_pk_fma_f32 v[76:77], v[14:15], v[60:61], v[50:51] op_sel_hi:[0,1,1]
	v_pk_fma_f32 v[60:61], v[16:17], v[62:63], v[52:53] op_sel_hi:[0,1,1]
	s_waitcnt vmcnt(0)
	v_pk_mul_f32 v[18:19], v[18:19], v[126:127]
	v_pk_mul_f32 v[20:21], v[22:23], v[128:129]
	v_pk_fma_f32 v[62:63], v[12:13], v[24:25], v[18:19] op_sel_hi:[0,1,1]
	v_pk_fma_f32 v[30:31], v[12:13], v[30:31], v[20:21] op_sel_hi:[0,1,1]
	v_mov_b32_e32 v12, v27
	v_pk_mul_f32 v[18:19], v[26:27], v[28:29] op_sel_hi:[0,1]
	v_pk_mul_f32 v[12:13], v[26:27], v[12:13] op_sel_hi:[0,1]
	v_pk_mul_f32 v[12:13], v[12:13], v[126:127]
	v_pk_mul_f32 v[18:19], v[18:19], v[128:129]
	v_pk_fma_f32 v[24:25], v[14:15], v[32:33], v[12:13] op_sel_hi:[0,1,1]
	v_pk_fma_f32 v[22:23], v[14:15], v[40:41], v[18:19] op_sel_hi:[0,1,1]
	v_mov_b32_e32 v14, v35
	v_pk_mul_f32 v[50:51], v[34:35], v[120:121] op_sel_hi:[0,1]
	v_pk_mul_f32 v[12:13], v[34:35], v[36:37] op_sel_hi:[0,1]
	v_pk_mul_f32 v[14:15], v[34:35], v[14:15] op_sel_hi:[0,1]
	v_lshlrev_b32_e32 v66, 16, v67
	v_and_b32_e32 v67, 0xffff0000, v67
	v_pk_mul_f32 v[50:51], v[162:163], v[50:51]
	v_pk_mul_f32 v[14:15], v[126:127], v[14:15]
	v_pk_mul_f32 v[12:13], v[128:129], v[12:13]
	v_pk_fma_f32 v[58:59], v[16:17], v[66:67], v[50:51] op_sel_hi:[0,1,1]
	v_pk_fma_f32 v[18:19], v[16:17], v[48:49], v[12:13] op_sel_hi:[0,1,1]
	v_pk_fma_f32 v[20:21], v[16:17], v[42:43], v[14:15] op_sel_hi:[0,1,1]
	v_mov_b32_e32 v16, v45
	v_pk_mul_f32 v[14:15], v[44:45], v[16:17] op_sel_hi:[0,1]
	v_mul_f32_e32 v16, v117, v117
	v_mul_f32_e32 v17, v115, v115
	v_fmac_f32_e32 v16, v116, v116
	v_fmac_f32_e32 v17, v114, v114
	v_add_f32_e32 v16, v16, v17
	v_mul_f32_e32 v17, v105, v105
	v_mul_f32_e32 v26, v103, v103
	v_fmac_f32_e32 v17, v104, v104
	v_fmac_f32_e32 v26, v102, v102
	v_add_f32_e32 v17, v17, v26
	v_add_f32_e32 v16, v16, v17
	v_mul_f32_e32 v17, v85, v85
	v_mul_f32_e32 v26, v83, v83
	v_fmac_f32_e32 v17, v84, v84
	v_fmac_f32_e32 v26, v82, v82
	v_add_f32_e32 v17, v17, v26
	v_add_f32_e32 v16, v16, v17
	v_mul_f32_e32 v17, v63, v63
	v_mul_f32_e32 v26, v31, v31
	v_fmac_f32_e32 v17, v62, v62
	v_fmac_f32_e32 v26, v30, v30
	v_add_f32_e32 v17, v17, v26
	v_add_f32_e32 v16, v16, v17
	v_mul_f32_e32 v17, v93, v93
	v_mul_f32_e32 v26, v91, v91
	v_fmac_f32_e32 v17, v92, v92
	v_fmac_f32_e32 v26, v90, v90
	v_add_f32_e32 v17, v17, v26
	v_mul_f32_e32 v26, v99, v99
	v_mul_f32_e32 v27, v97, v97
	v_fmac_f32_e32 v26, v98, v98
	v_fmac_f32_e32 v27, v96, v96
	v_add_f32_e32 v26, v26, v27
	v_add_f32_e32 v17, v17, v26
	v_mul_f32_e32 v26, v81, v81
	v_mul_f32_e32 v27, v77, v77
	s_nop 1
	v_mov_b32_dpp v29, v16 quad_perm:[1,0,3,2] row_mask:0xf bank_mask:0xf
	v_fmac_f32_e32 v26, v80, v80
	v_fmac_f32_e32 v27, v76, v76
	v_add_f32_e32 v26, v26, v27
	v_add_f32_e32 v17, v17, v26
	v_mul_f32_e32 v26, v25, v25
	v_mul_f32_e32 v27, v23, v23
	v_fmac_f32_e32 v26, v24, v24
	v_fmac_f32_e32 v27, v22, v22
	v_add_f32_e32 v26, v26, v27
	s_waitcnt lgkmcnt(0)
; __device__ __forceinline__ void st4_bf16(bf16* p, v4f o) { v2u w; w.x = cvt_pk_nv(o.x, o.y); w.y = cvt_pk_nv(o.z, o.w); *(v2u*)p = w; }
; __device__ __forceinline__ float ssq4(v4f v) { return (v.x * v.x + v.y * v.y) + (v.z * v.z + v.w * v.w); }
; template <int R, bool BASE_F32, bool OUT_F32>
; __device__ __forceinline__ void rows_res(const Ctx& C, int m0, int stride, int mx, const float* gpost, float scale, int lane) {
;     ...
;         for (int r = 0; r < R; ++r) { float s = 0.f;
; #pragma unroll
;             for (int j = 0; j < 4; ++j) s += ssq4(d[r][j]);
;             t[r] = s; }
; #pragma unroll
;         for (int r = 0; r < R; ++r) t[r] = wave_sum(t[r]) * (1.f / DM) + EPS;
; #pragma unroll
;         for (int r = 0; r < R; ++r) { const float rstd = rsqrtf(t[r]);
; #pragma unroll
;             for (int j = 0; j < 4; ++j) if (ok[r]) st4_bf16(XN + (size_t)mr[r] * DM + 4 * lane + 256 * j, d[r][j] * rstd);
;             if (lane == 0 && ok[r]) rs[mr[r]] = sqrtf(t[r]); }
	v_add_f32_e32 v16, v16, v29
	v_add_f32_e32 v17, v17, v26
	v_mul_f32_e32 v26, v87, v87
	v_mul_f32_e32 v27, v89, v89
	s_nop 1
	v_mov_b32_dpp v29, v16 quad_perm:[2,3,0,1] row_mask:0xf bank_mask:0xf
	v_fmac_f32_e32 v26, v86, v86
	v_fmac_f32_e32 v27, v88, v88
	v_add_f32_e32 v26, v26, v27
	v_mul_f32_e32 v27, v73, v73
	v_mul_f32_e32 v28, v71, v71
	v_fmac_f32_e32 v27, v72, v72
	v_fmac_f32_e32 v28, v70, v70
	v_add_f32_e32 v27, v27, v28
	v_add_f32_e32 v26, v26, v27
	v_mul_f32_e32 v27, v61, v61
	v_mul_f32_e32 v28, v59, v59
	s_waitcnt lgkmcnt(0)
	v_add_f32_e32 v16, v16, v29
	v_fmac_f32_e32 v27, v60, v60
	v_fmac_f32_e32 v28, v58, v58
	s_nop 1
	v_mov_b32_dpp v29, v16 row_half_mirror row_mask:0xf bank_mask:0xf
	v_add_f32_e32 v27, v27, v28
	v_add_f32_e32 v26, v27, v26
	v_mul_f32_e32 v27, v21, v21
	v_mul_f32_e32 v28, v19, v19
	v_fmac_f32_e32 v27, v20, v20
	v_fmac_f32_e32 v28, v18, v18
	v_add_f32_e32 v27, v27, v28
	v_add_f32_e32 v26, v27, v26
	v_mul_f32_e32 v27, v57, v57
	v_mul_f32_e32 v28, v55, v55
	s_waitcnt lgkmcnt(0)
	v_add_f32_e32 v16, v16, v29
	v_fmac_f32_e32 v27, v56, v56
	v_fmac_f32_e32 v28, v54, v54
	s_nop 1
	v_mov_b32_dpp v29, v16 row_mirror row_mask:0xf bank_mask:0xf
	v_pk_mul_f32 v[50:51], v[44:45], v[138:139] op_sel_hi:[0,1]
	v_pk_mul_f32 v[52:53], v[44:45], v[134:135] op_sel_hi:[0,1]
	v_add_f32_e32 v27, v27, v28
	v_mul_f32_e32 v28, v69, v69
	v_mul_f32_e32 v32, v65, v65
	v_pk_mul_f32 v[52:53], v[160:161], v[52:53]
	v_pk_mul_f32 v[50:51], v[162:163], v[50:51]
	v_fmac_f32_e32 v28, v68, v68
	v_fmac_f32_e32 v32, v64, v64
	v_pk_fma_f32 v[50:51], v[38:39], v[78:79], v[50:51] op_sel_hi:[0,1,1]
	v_pk_fma_f32 v[52:53], v[38:39], v[74:75], v[52:53] op_sel_hi:[0,1,1]
	v_add_f32_e32 v28, v28, v32
	v_pk_mul_f32 v[12:13], v[44:45], v[46:47] op_sel_hi:[0,1]
	v_add_f32_e32 v27, v27, v28
	v_mul_f32_e32 v28, v53, v53
	v_mul_f32_e32 v32, v51, v51
	v_lshlrev_b32_e32 v148, 16, v136
	v_and_b32_e32 v149, 0xffff0000, v136
	v_lshlrev_b32_e32 v136, 16, v137
	v_and_b32_e32 v137, 0xffff0000, v137
	v_pk_mul_f32 v[14:15], v[126:127], v[14:15]
	v_pk_mul_f32 v[12:13], v[128:129], v[12:13]
	v_fmac_f32_e32 v28, v52, v52
	v_fmac_f32_e32 v32, v50, v50
	s_waitcnt lgkmcnt(0)
	v_add_f32_e32 v16, v16, v29
	v_pk_fma_f32 v[12:13], v[38:39], v[136:137], v[12:13] op_sel_hi:[0,1,1]
	v_pk_fma_f32 v[14:15], v[38:39], v[148:149], v[14:15] op_sel_hi:[0,1,1]
	v_add_f32_e32 v28, v28, v32
	ds_bpermute_b32 v29, v187, v16
	v_add_f32_e32 v27, v28, v27
	v_mul_f32_e32 v28, v15, v15
	v_mul_f32_e32 v32, v13, v13
	v_fmac_f32_e32 v28, v14, v14
	v_fmac_f32_e32 v32, v12, v12
	v_add_f32_e32 v28, v28, v32
	v_add_f32_e32 v27, v28, v27
	s_nop 1
	v_mov_b32_dpp v28, v17 quad_perm:[1,0,3,2] row_mask:0xf bank_mask:0xf
	s_waitcnt lgkmcnt(0)
	v_add_f32_e32 v32, v16, v29
	s_nop 1
	v_mov_b32_dpp v16, v26 quad_perm:[1,0,3,2] row_mask:0xf bank_mask:0xf
	s_nop 1
	v_mov_b32_dpp v29, v27 quad_perm:[1,0,3,2] row_mask:0xf bank_mask:0xf
	ds_bpermute_b32 v33, v188, v32
	s_waitcnt lgkmcnt(0)
	v_add_f32_e32 v17, v17, v28
	s_nop 1
	v_mov_b32_dpp v28, v17 quad_perm:[2,3,0,1] row_mask:0xf bank_mask:0xf
	s_waitcnt lgkmcnt(0)
	v_add_f32_e32 v16, v26, v16
	s_waitcnt lgkmcnt(0)
	v_add_f32_e32 v27, v27, v29
	s_nop 1
	v_mov_b32_dpp v26, v16 quad_perm:[2,3,0,1] row_mask:0xf bank_mask:0xf
	s_nop 1
	v_mov_b32_dpp v29, v27 quad_perm:[2,3,0,1] row_mask:0xf bank_mask:0xf
	s_waitcnt lgkmcnt(0)
	v_add_f32_e32 v17, v17, v28
	s_nop 1
	v_mov_b32_dpp v28, v17 row_half_mirror row_mask:0xf bank_mask:0xf
	s_mov_b64 s[12:13], s[80:81]
	s_waitcnt lgkmcnt(0)
	v_add_f32_e32 v16, v16, v26
	s_waitcnt lgkmcnt(0)
	v_add_f32_e32 v27, v27, v29
	s_nop 1
	v_mov_b32_dpp v26, v16 row_half_mirror row_mask:0xf bank_mask:0xf
	s_nop 1
	v_mov_b32_dpp v29, v27 row_half_mirror row_mask:0xf bank_mask:0xf
	s_waitcnt lgkmcnt(0)
	v_add_f32_e32 v17, v17, v28
	s_nop 1
	v_mov_b32_dpp v28, v17 row_mirror row_mask:0xf bank_mask:0xf
	s_waitcnt lgkmcnt(0)
	v_add_f32_e32 v16, v16, v26
	s_waitcnt lgkmcnt(0)
	v_add_f32_e32 v27, v27, v29
	s_nop 1
	v_mov_b32_dpp v26, v16 row_mirror row_mask:0xf bank_mask:0xf
	s_nop 1
	v_mov_b32_dpp v29, v27 row_mirror row_mask:0xf bank_mask:0xf
	s_waitcnt lgkmcnt(0)
	v_add_f32_e32 v17, v17, v28
	ds_bpermute_b32 v28, v187, v17
	s_load_dwordx2 s[14:15], s[12:13], 0x110
	s_waitcnt lgkmcnt(0)
	v_add_f32_e32 v16, v16, v26
	v_add_f32_e32 v34, v27, v29
	ds_bpermute_b32 v26, v187, v16
	ds_bpermute_b32 v35, v187, v34
	v_add_f32_e32 v28, v17, v28
	ds_bpermute_b32 v29, v188, v28
	v_add_f32_e32 v32, v32, v33
	s_waitcnt lgkmcnt(0)
	v_add_f32_e32 v26, v16, v26
	s_waitcnt lgkmcnt(0)
	v_add_f32_e32 v16, v34, v35
	ds_bpermute_b32 v27, v188, v26
	ds_bpermute_b32 v17, v188, v16
	s_andn2_b64 vcc, exec, s[16:17]
	v_fmamk_f32 v32, v32, 0x3a800000, v150
	s_cbranch_vccnz .LBB0_1038
	v_mul_f32_e32 v33, 0x4b800000, v32
	v_cmp_gt_f32_e32 vcc, s89, v32
	v_lshl_add_u64 v[34:35], v[8:9], 0, s[28:29]
	s_nop 0
	v_cndmask_b32_e32 v33, v32, v33, vcc
	v_rsq_f32_e32 v33, v33
	s_nop 0
	v_mul_f32_e32 v36, 0x45800000, v33
	v_cndmask_b32_e32 v36, v33, v36, vcc
	v_pk_mul_f32 v[42:43], v[116:117], v[36:37] op_sel_hi:[1,0]
	v_pk_mul_f32 v[40:41], v[114:115], v[36:37] op_sel_hi:[1,0]
	v_cvt_pk_bf16_f32 v42, v42, v43
	v_pk_mul_f32 v[30:31], v[30:31], v[36:37] op_sel_hi:[1,0]
	v_cvt_pk_bf16_f32 v43, v40, v41
	global_store_dwordx2 v[34:35], v[42:43], off
	v_pk_mul_f32 v[42:43], v[104:105], v[36:37] op_sel_hi:[1,0]
	v_pk_mul_f32 v[40:41], v[102:103], v[36:37] op_sel_hi:[1,0]
	v_cvt_pk_bf16_f32 v42, v42, v43
	s_nop 0
	v_cvt_pk_bf16_f32 v43, v40, v41
	global_store_dwordx2 v[34:35], v[42:43], off offset:512
	v_pk_mul_f32 v[40:41], v[82:83], v[36:37] op_sel_hi:[1,0]
	v_pk_mul_f32 v[42:43], v[84:85], v[36:37] op_sel_hi:[1,0]
	v_pk_mul_f32 v[36:37], v[62:63], v[36:37] op_sel_hi:[1,0]
	v_cvt_pk_bf16_f32 v42, v42, v43
	v_cvt_pk_bf16_f32 v43, v40, v41
	global_store_dwordx2 v[34:35], v[42:43], off offset:1024
	v_cvt_pk_bf16_f32 v36, v36, v37
	v_cvt_pk_bf16_f32 v37, v30, v31
	global_store_dwordx2 v[34:35], v[36:37], off offset:1536

; __device__ __forceinline__ void st4_bf16(bf16* p, v4f o) { v2u w; w.x = cvt_pk_nv(o.x, o.y); w.y = cvt_pk_nv(o.z, o.w); *(v2u*)p = w; }
; template <int R, bool BASE_F32, bool OUT_F32>
; __device__ __forceinline__ void rows_res(const Ctx& C, int m0, int stride, int mx, const float* gpost, float scale, int lane) {
;     ...
;         for (int r = 0; r < R; ++r) t[r] = wave_sum(t[r]) * (1.f / DM) + EPS;
; #pragma unroll
;         for (int r = 0; r < R; ++r) { const float rstd = rsqrtf(t[r]);
; #pragma unroll
;             for (int j = 0; j < 4; ++j) if (ok[r]) st4_bf16(XN + (size_t)mr[r] * DM + 4 * lane + 256 * j, d[r][j] * rstd);
;             if (lane == 0 && ok[r]) rs[mr[r]] = sqrtf(t[r]); }
.LBB0_1040:
	s_or_b64 exec, exec, s[42:43]
	s_waitcnt lgkmcnt(0)
	v_add_f32_e32 v28, v28, v29
	s_andn2_b64 vcc, exec, s[20:21]
	v_fmamk_f32 v28, v28, 0x3a800000, v150
	s_cbranch_vccnz .LBB0_1042
	v_mul_f32_e32 v29, 0x4b800000, v28
	v_cmp_gt_f32_e32 vcc, s89, v28
	v_lshl_add_u64 v[30:31], v[8:9], 0, s[34:35]
	s_nop 0
	v_cndmask_b32_e32 v29, v28, v29, vcc
	v_rsq_f32_e32 v29, v29
	s_nop 0
	v_mul_f32_e32 v32, 0x45800000, v29
	v_cndmask_b32_e32 v32, v29, v32, vcc
	v_pk_mul_f32 v[36:37], v[92:93], v[32:33] op_sel_hi:[1,0]
	v_pk_mul_f32 v[34:35], v[90:91], v[32:33] op_sel_hi:[1,0]
	v_cvt_pk_bf16_f32 v36, v36, v37
	v_pk_mul_f32 v[24:25], v[24:25], v[32:33] op_sel_hi:[1,0]
	v_cvt_pk_bf16_f32 v37, v34, v35
	global_store_dwordx2 v[30:31], v[36:37], off
	v_pk_mul_f32 v[36:37], v[98:99], v[32:33] op_sel_hi:[1,0]
	v_pk_mul_f32 v[34:35], v[96:97], v[32:33] op_sel_hi:[1,0]
	v_cvt_pk_bf16_f32 v36, v36, v37
	v_pk_mul_f32 v[22:23], v[22:23], v[32:33] op_sel_hi:[1,0]
	v_cvt_pk_bf16_f32 v37, v34, v35
	global_store_dwordx2 v[30:31], v[36:37], off offset:512
	v_pk_mul_f32 v[36:37], v[80:81], v[32:33] op_sel_hi:[1,0]
	v_pk_mul_f32 v[34:35], v[76:77], v[32:33] op_sel_hi:[1,0]
	v_cvt_pk_bf16_f32 v36, v36, v37
	v_cvt_pk_bf16_f32 v24, v24, v25
	v_cvt_pk_bf16_f32 v25, v22, v23
	global_store_dwordx2 v[30:31], v[24:25], off offset:1536
	v_cvt_pk_bf16_f32 v37, v34, v35
	global_store_dwordx2 v[30:31], v[36:37], off offset:1024

; __device__ __forceinline__ void st4_bf16(bf16* p, v4f o) { v2u w; w.x = cvt_pk_nv(o.x, o.y); w.y = cvt_pk_nv(o.z, o.w); *(v2u*)p = w; }
; template <int R, bool BASE_F32, bool OUT_F32>
; __device__ __forceinline__ void rows_res(const Ctx& C, int m0, int stride, int mx, const float* gpost, float scale, int lane) {
;     ...
;         for (int r = 0; r < R; ++r) t[r] = wave_sum(t[r]) * (1.f / DM) + EPS;
; #pragma unroll
;         for (int r = 0; r < R; ++r) { const float rstd = rsqrtf(t[r]);
; #pragma unroll
;             for (int j = 0; j < 4; ++j) if (ok[r]) st4_bf16(XN + (size_t)mr[r] * DM + 4 * lane + 256 * j, d[r][j] * rstd);
;             if (lane == 0 && ok[r]) rs[mr[r]] = sqrtf(t[r]); }
.LBB0_1044:
	s_or_b64 exec, exec, s[42:43]
	s_waitcnt lgkmcnt(0)
	v_add_f32_e32 v22, v26, v27
	s_andn2_b64 vcc, exec, s[24:25]
	v_fmamk_f32 v22, v22, 0x3a800000, v150
	s_cbranch_vccnz .LBB0_1046
	v_mul_f32_e32 v23, 0x4b800000, v22
	v_cmp_gt_f32_e32 vcc, s89, v22
	v_lshl_add_u64 v[8:9], v[8:9], 0, s[38:39]
	s_nop 0
	v_cndmask_b32_e32 v23, v22, v23, vcc
	v_rsq_f32_e32 v23, v23
	s_nop 0
	v_mul_f32_e32 v24, 0x45800000, v23
	v_cndmask_b32_e32 v24, v23, v24, vcc
	v_pk_mul_f32 v[28:29], v[86:87], v[24:25] op_sel_hi:[1,0]
	v_pk_mul_f32 v[26:27], v[88:89], v[24:25] op_sel_hi:[1,0]
	v_cvt_pk_bf16_f32 v28, v28, v29
	v_pk_mul_f32 v[20:21], v[20:21], v[24:25] op_sel_hi:[1,0]
	v_cvt_pk_bf16_f32 v29, v26, v27
	global_store_dwordx2 v[8:9], v[28:29], off
	v_pk_mul_f32 v[28:29], v[72:73], v[24:25] op_sel_hi:[1,0]
	v_pk_mul_f32 v[26:27], v[70:71], v[24:25] op_sel_hi:[1,0]
	v_cvt_pk_bf16_f32 v28, v28, v29
	v_pk_mul_f32 v[18:19], v[18:19], v[24:25] op_sel_hi:[1,0]
	v_cvt_pk_bf16_f32 v29, v26, v27
	global_store_dwordx2 v[8:9], v[28:29], off offset:512
	v_pk_mul_f32 v[28:29], v[60:61], v[24:25] op_sel_hi:[1,0]
	v_pk_mul_f32 v[26:27], v[58:59], v[24:25] op_sel_hi:[1,0]
	v_cvt_pk_bf16_f32 v28, v28, v29
	v_cvt_pk_bf16_f32 v20, v20, v21
	v_cvt_pk_bf16_f32 v21, v18, v19
	global_store_dwordx2 v[8:9], v[20:21], off offset:1536
	v_cvt_pk_bf16_f32 v29, v26, v27
	global_store_dwordx2 v[8:9], v[28:29], off offset:1024

; __device__ __forceinline__ unsigned xb_add(unsigned* p, unsigned v) { return __hip_atomic_fetch_add(p, v, __ATOMIC_RELAXED, __HIP_MEMORY_SCOPE_AGENT); }
; __device__ __forceinline__ void xcd_barrier(const XcdBarrier& b) {
;     asm volatile("s_waitcnt vmcnt(0)" ::: "memory");
;     __syncthreads();
;     if (threadIdx.x == 0) {
;         unsigned* bar = b.bar;
;         __builtin_amdgcn_s_waitcnt(0);
;         unsigned nloc = b.st[0], nx = b.st[1];
;         if (nloc == 0u) { xcd_barrier_complete(bar, b.x, nloc, nx); b.st[0] = nloc; b.st[1] = nx; }
;         const unsigned old = xb_add(&bar[XB_XSUB(b.x)], 1u);
;         const unsigned gen = old / nloc;
;         if (old + 1u == (gen + 1u) * nloc) {
.LBB0_1050:
	s_mov_b64 s[12:13], s[80:81]
	s_getreg_b32 s14, hwreg(HW_REG_XCC_ID, 0, 4)
	s_waitcnt vmcnt(0)
	s_barrier
	s_and_saveexec_b64 s[10:11], s[96:97]
	v_readlane_b32 s69, v232, 8
	v_readlane_b32 s70, v232, 7
	v_readlane_b32 s71, v232, 6
	s_cbranch_execz .LBB0_1102
	s_add_i32 s0, 0, 0x23fc0
	v_mov_b32_e32 v0, s0
	s_load_dwordx2 s[12:13], s[12:13], 0x110
	s_waitcnt vmcnt(0) expcnt(0) lgkmcnt(0)
	ds_read_b32 v2, v0
	s_add_i32 s0, 0, 0x23fc4
	v_mov_b32_e32 v0, s0
	ds_read_b32 v0, v0
	s_and_b32 s28, s14, 15
	s_waitcnt lgkmcnt(0)
	v_cmp_ne_u32_e32 vcc, 0, v2
	s_cbranch_vccnz .LBB0_1066
	s_add_u32 s14, s12, 0x1000
	s_addc_u32 s15, s13, 0
	s_add_u32 s16, s12, 0x1100
	s_addc_u32 s17, s13, 0
	s_add_u32 s18, s12, 0x1200
	s_addc_u32 s19, s13, 0
	s_mul_i32 s29, s95, s93
	s_add_u32 s20, s12, 0x1300
	s_mul_i32 s29, s29, s94
	s_addc_u32 s21, s13, 0
	s_mov_b32 s30, 1
	v_mov_b32_e32 v16, 0
	s_branch .LBB0_1054

; __device__ __forceinline__ const float* xrow_ptr(const Ctx& C, int row) { return row < MPROMPT ? C.in(0) + (size_t)row * DM : C.in(1) + (size_t)(row - MPROMPT) * DM; }
; __device__ __forceinline__ v4f ld4_bf16(const bf16* p) { const v2u w = *(const v2u*)p; return (v4f){bf_lo(w.x), bf_hi(w.x), bf_lo(w.y), bf_hi(w.y)}; }
; template <int R, bool BASE_F32, bool OUT_F32>
; __device__ __forceinline__ void rows_res(const Ctx& C, int m0, int stride, int mx, const float* gpost, float scale, int lane) {
;     v4f d[R][4], b[R][4]; int mr[R]; bool ok[R]; float r1[R];
;     const bf16* D = C.D(); bf16* XN = C.XN();
; #pragma unroll
;     for (int r = 0; r < R; ++r) { mr[r] = (r == 4) ? mx : m0 + r * stride; ok[r] = (r == 4) ? (mx < M) : (mr[r] < MPROMPT); const int mm = ok[r] ? mr[r] : 0;
; #pragma unroll
;         for (int j = 0; j < 4; ++j) d[r][j] = ld4_bf16(D + (size_t)mm * DM + 4 * lane + 256 * j);
;         if (BASE_F32) { const float* x = xrow_ptr(C, mm);
; #pragma unroll
;             for (int j = 0; j < 4; ++j) b[r][j] = ld4_f32(x + 4 * lane + 256 * j);
;         } else { const float inv = C.RS()[mm];
; #pragma unroll
;             for (int j = 0; j < 4; ++j) b[r][j] = ld4_bf16(XN + (size_t)mm * DM + 4 * lane + 256 * j) * inv;
;         } }
.LBB0_1275:
	s_mov_b64 s[0:1], s[80:81]
	s_load_dwordx2 s[0:1], s[0:1], 0x110
	s_cmp_lt_i32 s16, 0x8000
	s_mov_b64 s[2:3], s[80:81]
	s_mov_b64 s[6:7], s[80:81]
	s_waitcnt vmcnt(0) lgkmcnt(0)
	v_lshl_add_u64 v[0:1], s[0:1], 0, v[18:19]
	s_cselect_b32 s0, s16, 0
	s_ashr_i32 s1, s0, 31
	v_lshl_add_u64 v[0:1], v[0:1], 0, s[10:11]
	s_lshl_b64 s[4:5], s[0:1], 11
	v_lshl_add_u64 v[2:3], v[0:1], 0, s[4:5]
	s_load_dwordx2 s[2:3], s[2:3], 0x110
	global_load_dwordx2 v[4:5], v[2:3], off
	global_load_dwordx2 v[6:7], v[2:3], off offset:512
	global_load_dwordx2 v[8:9], v[2:3], off offset:1024
	global_load_dwordx2 v[10:11], v[2:3], off offset:1536
	s_load_dwordx2 s[6:7], s[6:7], 0x110
	s_lshl_b64 s[0:1], s[0:1], 2
	s_waitcnt lgkmcnt(0)
	v_lshl_add_u64 v[2:3], s[2:3], 0, v[18:19]
	v_lshl_add_u64 v[2:3], v[2:3], 0, s[12:13]
	v_lshl_add_u64 v[12:13], v[2:3], 0, s[4:5]
	s_add_u32 s0, s6, s0
	s_addc_u32 s1, s7, s1
	s_add_i32 s4, s46, s16
	s_cmp_lt_i32 s4, 0x8000
	s_cselect_b64 s[24:25], -1, 0
	global_load_dword v62, v23, s[0:1]
	s_and_b64 s[0:1], s[24:25], exec
	s_cselect_b32 s0, s4, 0
	s_ashr_i32 s1, s0, 31
	s_lshl_b64 s[2:3], s[0:1], 11
	global_load_dwordx2 v[70:71], v[12:13], off
	global_load_dwordx2 v[74:75], v[12:13], off offset:512
	global_load_dwordx2 v[80:81], v[12:13], off offset:1024
	global_load_dwordx2 v[94:95], v[12:13], off offset:1536
	v_lshl_add_u64 v[12:13], v[0:1], 0, s[2:3]
	s_mov_b64 s[6:7], s[80:81]
	global_load_dwordx2 v[14:15], v[12:13], off
	global_load_dwordx2 v[64:65], v[12:13], off offset:512
	global_load_dwordx2 v[66:67], v[12:13], off offset:1024
	global_load_dwordx2 v[28:29], v[12:13], off offset:1536
	s_load_dwordx2 s[6:7], s[6:7], 0x110
	s_lshl_b64 s[0:1], s[0:1], 2
	v_lshl_add_u64 v[12:13], v[2:3], 0, s[2:3]
	s_mov_b64 s[18:19], s[80:81]
	s_mov_b64 s[34:35], s[80:81]
	s_waitcnt lgkmcnt(0)
	s_add_u32 s0, s6, s0
	s_addc_u32 s1, s7, s1
	s_add_i32 s20, s70, s16
	s_cmp_lt_i32 s20, 0x8000
	s_cselect_b64 s[6:7], -1, 0
	global_load_dword v42, v23, s[0:1]
	s_and_b64 s[0:1], s[6:7], exec
	s_cselect_b32 s0, s20, 0
	s_ashr_i32 s1, s0, 31
	s_lshl_b64 s[2:3], s[0:1], 11
	global_load_dwordx2 v[60:61], v[12:13], off
	global_load_dwordx2 v[58:59], v[12:13], off offset:512
	global_load_dwordx2 v[56:57], v[12:13], off offset:1024
	global_load_dwordx2 v[54:55], v[12:13], off offset:1536
	v_lshl_add_u64 v[12:13], v[0:1], 0, s[2:3]
	global_load_dwordx2 v[72:73], v[12:13], off
	global_load_dwordx2 v[82:83], v[12:13], off offset:512
	global_load_dwordx2 v[88:89], v[12:13], off offset:1024
	global_load_dwordx2 v[30:31], v[12:13], off offset:1536
	s_load_dwordx2 s[18:19], s[18:19], 0x110
	s_lshl_b64 s[0:1], s[0:1], 2
	s_waitcnt lgkmcnt(0)
	s_add_u32 s0, s18, s0
	s_addc_u32 s1, s19, s1
	s_add_i32 s18, s69, s16
	s_cmp_lt_i32 s18, 0x8000
	s_cselect_b64 s[22:23], -1, 0
	s_and_b64 s[28:29], s[22:23], exec
	s_cselect_b32 s28, s18, 0
	s_ashr_i32 s29, s28, 31
	s_lshl_b64 s[30:31], s[28:29], 11
	v_lshl_add_u64 v[12:13], v[0:1], 0, s[30:31]
	global_load_dwordx2 v[84:85], v[12:13], off offset:1536
	global_load_dwordx2 v[0:1], v[12:13], off
	global_load_dwordx2 v[68:69], v[12:13], off offset:512
	global_load_dwordx2 v[98:99], v[12:13], off offset:1024
	v_lshl_add_u64 v[12:13], v[2:3], 0, s[2:3]
	v_lshl_add_u64 v[2:3], v[2:3], 0, s[30:31]
	global_load_dwordx2 v[48:49], v[12:13], off
	global_load_dwordx2 v[46:47], v[12:13], off offset:512
	global_load_dwordx2 v[44:45], v[12:13], off offset:1024
	global_load_dwordx2 v[40:41], v[12:13], off offset:1536
	global_load_dword v26, v23, s[0:1]
	s_load_dwordx2 s[2:3], s[34:35], 0x110
	global_load_dwordx2 v[38:39], v[2:3], off
	global_load_dwordx2 v[36:37], v[2:3], off offset:512
	global_load_dwordx2 v[34:35], v[2:3], off offset:1024
	global_load_dwordx2 v[32:33], v[2:3], off offset:1536
	s_lshl_b64 s[0:1], s[28:29], 2
	s_waitcnt lgkmcnt(0)
	s_add_u32 s0, s2, s0
	s_addc_u32 s1, s3, s1
	global_load_dword v24, v23, s[0:1]
	s_mov_b64 s[0:1], s[80:81]
	s_cmpk_gt_i32 s16, 0x7fff
	s_waitcnt vmcnt(35)
	v_and_b32_e32 v113, 0xffff0000, v4
	v_and_b32_e32 v117, 0xffff0000, v5
	v_lshlrev_b32_e32 v112, 16, v4
	v_lshlrev_b32_e32 v116, 16, v5
	v_mul_f32_e32 v2, v113, v113
	v_mul_f32_e32 v3, v117, v117
	s_waitcnt vmcnt(34)
	v_and_b32_e32 v119, 0xffff0000, v6
	v_and_b32_e32 v121, 0xffff0000, v7
	v_fmac_f32_e32 v2, v112, v112
	v_fmac_f32_e32 v3, v116, v116
	v_lshlrev_b32_e32 v118, 16, v6
	v_lshlrev_b32_e32 v120, 16, v7
	v_add_f32_e32 v2, v2, v3
	v_mul_f32_e32 v3, v119, v119
	v_mul_f32_e32 v4, v121, v121
	v_fmac_f32_e32 v3, v118, v118
	v_fmac_f32_e32 v4, v120, v120
	s_waitcnt vmcnt(33)
	v_and_b32_e32 v123, 0xffff0000, v8
	v_and_b32_e32 v125, 0xffff0000, v9
	v_add_f32_e32 v3, v3, v4
	v_lshlrev_b32_e32 v122, 16, v8
	v_lshlrev_b32_e32 v124, 16, v9
	v_add_f32_e32 v2, v2, v3
	v_mul_f32_e32 v3, v123, v123
	v_mul_f32_e32 v4, v125, v125
	v_fmac_f32_e32 v3, v122, v122
	v_fmac_f32_e32 v4, v124, v124
	s_waitcnt vmcnt(32)
	v_and_b32_e32 v127, 0xffff0000, v10
	v_and_b32_e32 v129, 0xffff0000, v11
	v_add_f32_e32 v3, v3, v4
	v_lshlrev_b32_e32 v126, 16, v10
	v_lshlrev_b32_e32 v128, 16, v11
	v_add_f32_e32 v2, v2, v3
	v_mul_f32_e32 v3, v127, v127
	v_mul_f32_e32 v4, v129, v129
	v_fmac_f32_e32 v3, v126, v126
	v_fmac_f32_e32 v4, v128, v128
	v_add_f32_e32 v3, v3, v4
	s_waitcnt vmcnt(26)
	v_and_b32_e32 v105, 0xffff0000, v14
	v_and_b32_e32 v111, 0xffff0000, v15
	v_add_f32_e32 v25, v2, v3
	v_lshlrev_b32_e32 v104, 16, v14
	v_lshlrev_b32_e32 v110, 16, v15
	v_mul_f32_e32 v2, v111, v111
	s_waitcnt vmcnt(25)
	v_and_b32_e32 v109, 0xffff0000, v65
	v_and_b32_e32 v108, 0xffff0000, v64
	v_mul_f32_e32 v6, v105, v105
	s_waitcnt vmcnt(23)
; __device__ __forceinline__ float ssq4(v4f v) { return (v.x * v.x + v.y * v.y) + (v.z * v.z + v.w * v.w); }
; template <int R, bool BASE_F32, bool OUT_F32>
; __device__ __forceinline__ void rows_res(const Ctx& C, int m0, int stride, int mx, const float* gpost, float scale, int lane) {
;     ...
;     for (int r = 0; r < R; ++r) { float s = 0.f;
; #pragma unroll
;         for (int j = 0; j < 4; ++j) s += ssq4(d[r][j]);
;         r1[r] = s; }
; #pragma unroll
;     for (int r = 0; r < R; ++r) r1[r] = rsqrtf(wave_sum(r1[r]) * (1.f / DM) + EPS) * scale;
	v_lshlrev_b32_e32 v77, 16, v28
	v_pk_fma_f32 v[2:3], v[110:111], v[110:111], v[2:3] op_sel_hi:[1,1,0]
	v_lshlrev_b32_e32 v103, 16, v65
	v_lshlrev_b32_e32 v102, 16, v64
	v_pk_mul_f32 v[4:5], v[108:109], v[108:109]
	v_pk_fma_f32 v[6:7], v[104:105], v[104:105], v[6:7] op_sel_hi:[1,1,0]
	v_and_b32_e32 v63, 0xffff0000, v28
	v_pk_fma_f32 v[4:5], v[102:103], v[102:103], v[4:5]
	v_mov_b32_e32 v76, v6
	v_mov_b32_e32 v8, v2
	v_mov_b32_e32 v9, v77
	v_mul_f32_e32 v10, v63, v63
	v_pk_add_f32 v[2:3], v[6:7], v[2:3]
	v_pk_mul_f32 v[6:7], v[76:77], v[8:9]
	v_pk_add_f32 v[4:5], v[4:5], v[4:5] op_sel:[0,1] op_sel_hi:[1,0]
	v_and_b32_e32 v101, 0xffff0000, v66
	v_and_b32_e32 v107, 0xffff0000, v67
	v_mov_b32_e32 v3, v7
	v_mov_b32_e32 v5, v10
	v_lshlrev_b32_e32 v78, 16, v29
	v_and_b32_e32 v79, 0xffff0000, v29
	v_lshlrev_b32_e32 v100, 16, v66
	v_lshlrev_b32_e32 v106, 16, v67
	v_pk_add_f32 v[2:3], v[2:3], v[4:5]
	v_mul_f32_e32 v4, v101, v101
	v_mul_f32_e32 v6, v107, v107
	v_mul_f32_e32 v11, v78, v78
	v_mul_f32_e32 v12, v79, v79
	v_pk_fma_f32 v[4:5], v[100:101], v[100:101], v[4:5] op_sel_hi:[1,1,0]
	v_pk_fma_f32 v[6:7], v[106:107], v[106:107], v[6:7] op_sel_hi:[1,1,0]
	v_mov_b32_e32 v5, v11
	v_mov_b32_e32 v7, v12
	v_pk_add_f32 v[4:5], v[4:5], v[6:7]
	s_waitcnt vmcnt(17)
	v_and_b32_e32 v87, 0xffff0000, v72
	v_pk_add_f32 v[2:3], v[2:3], v[4:5]
	v_and_b32_e32 v93, 0xffff0000, v73
	v_add_f32_e32 v76, v2, v3
	v_lshlrev_b32_e32 v86, 16, v72
	v_lshlrev_b32_e32 v92, 16, v73
	v_mul_f32_e32 v2, v93, v93
	s_waitcnt vmcnt(16)
	v_and_b32_e32 v91, 0xffff0000, v83
	v_and_b32_e32 v90, 0xffff0000, v82
	v_mul_f32_e32 v6, v87, v87
	s_waitcnt vmcnt(14)
	v_lshlrev_b32_e32 v51, 16, v30
	v_and_b32_e32 v43, 0xffff0000, v30
	v_lshlrev_b32_e32 v52, 16, v31
	v_and_b32_e32 v53, 0xffff0000, v31
	s_waitcnt vmcnt(13)
	v_lshlrev_b32_e32 v29, 16, v84
	v_and_b32_e32 v27, 0xffff0000, v84
	v_lshlrev_b32_e32 v30, 16, v85
	v_and_b32_e32 v31, 0xffff0000, v85
	v_pk_fma_f32 v[2:3], v[92:93], v[92:93], v[2:3] op_sel_hi:[1,1,0]
	v_lshlrev_b32_e32 v85, 16, v83
	v_lshlrev_b32_e32 v84, 16, v82
	v_pk_mul_f32 v[4:5], v[90:91], v[90:91]
	v_pk_fma_f32 v[6:7], v[86:87], v[86:87], v[6:7] op_sel_hi:[1,1,0]
	v_pk_fma_f32 v[4:5], v[84:85], v[84:85], v[4:5]
	v_mov_b32_e32 v50, v6
	v_mov_b32_e32 v8, v2
	v_mov_b32_e32 v9, v51
	v_mul_f32_e32 v10, v43, v43
	v_pk_add_f32 v[2:3], v[6:7], v[2:3]
	v_pk_mul_f32 v[6:7], v[50:51], v[8:9]
	v_pk_add_f32 v[4:5], v[4:5], v[4:5] op_sel:[0,1] op_sel_hi:[1,0]
	v_lshlrev_b32_e32 v82, 16, v88
	v_and_b32_e32 v83, 0xffff0000, v88
	v_lshlrev_b32_e32 v88, 16, v89
	v_and_b32_e32 v89, 0xffff0000, v89
	v_mov_b32_e32 v3, v7
	v_mov_b32_e32 v5, v10
	v_pk_add_f32 v[2:3], v[2:3], v[4:5]
	v_mul_f32_e32 v4, v83, v83
	v_mul_f32_e32 v6, v89, v89
	v_mul_f32_e32 v11, v52, v52
	v_mul_f32_e32 v12, v53, v53
	v_pk_fma_f32 v[4:5], v[82:83], v[82:83], v[4:5] op_sel_hi:[1,1,0]
	v_pk_fma_f32 v[6:7], v[88:89], v[88:89], v[6:7] op_sel_hi:[1,1,0]
	v_mov_b32_e32 v5, v11
	v_mov_b32_e32 v7, v12
	s_waitcnt vmcnt(12)
	v_and_b32_e32 v73, 0xffff0000, v1
	v_pk_add_f32 v[4:5], v[4:5], v[6:7]
	v_lshlrev_b32_e32 v66, 16, v0
	v_and_b32_e32 v67, 0xffff0000, v0
	v_lshlrev_b32_e32 v72, 16, v1
	v_mul_f32_e32 v0, v73, v73
	v_pk_add_f32 v[114:115], v[2:3], v[4:5]
	v_pk_fma_f32 v[130:131], v[72:73], v[72:73], v[0:1] op_sel_hi:[1,1,0]
	global_load_dwordx4 v[12:15], v[20:21], off
	global_load_dwordx4 v[8:11], v[20:21], off offset:1024
	global_load_dwordx4 v[4:7], v[20:21], off offset:2048
	global_load_dwordx4 v[0:3], v[20:21], off offset:3072
	s_waitcnt vmcnt(15)
	v_lshlrev_b32_e32 v65, 16, v69
	v_lshlrev_b32_e32 v64, 16, v68
	v_and_b32_e32 v69, 0xffff0000, v69
	v_and_b32_e32 v68, 0xffff0000, v68
	v_mul_f32_e32 v28, v67, v67
	v_pk_mul_f32 v[96:97], v[68:69], v[68:69]
	v_pk_fma_f32 v[134:135], v[66:67], v[66:67], v[28:29] op_sel_hi:[1,1,0]
	v_pk_fma_f32 v[132:133], v[64:65], v[64:65], v[96:97]
	v_mov_b32_e32 v28, v134
	v_mov_b32_e32 v136, v130
	v_mov_b32_e32 v137, v29
	s_waitcnt vmcnt(14)
	v_and_b32_e32 v97, 0xffff0000, v98
	v_mul_f32_e32 v50, v27, v27
	v_pk_add_f32 v[130:131], v[134:135], v[130:131]
	v_pk_mul_f32 v[134:135], v[28:29], v[136:137]
	v_pk_add_f32 v[132:133], v[132:133], v[132:133] op_sel:[0,1] op_sel_hi:[1,0]
	v_lshlrev_b32_e32 v96, 16, v98
	v_lshlrev_b32_e32 v98, 16, v99
	v_and_b32_e32 v99, 0xffff0000, v99
	v_mov_b32_e32 v131, v135
	v_mov_b32_e32 v133, v50
	v_mul_f32_e32 v28, v97, v97
	v_pk_add_f32 v[130:131], v[130:131], v[132:133]
	v_pk_fma_f32 v[132:133], v[96:97], v[96:97], v[28:29] op_sel_hi:[1,1,0]
	v_mul_f32_e32 v28, v99, v99
	v_mul_f32_e32 v138, v30, v30
	v_mul_f32_e32 v139, v31, v31
	v_pk_fma_f32 v[134:135], v[98:99], v[98:99], v[28:29] op_sel_hi:[1,1,0]
	v_mov_b32_e32 v133, v138
	v_mov_b32_e32 v135, v139
	v_pk_add_f32 v[132:133], v[132:133], v[134:135]
	s_nop 1
	v_mov_b32_dpp v28, v25 quad_perm:[1,0,3,2] row_mask:0xf bank_mask:0xf
	v_pk_add_f32 v[130:131], v[130:131], v[132:133]
	v_mov_b32_e32 v133, v114
	v_mov_b32_e32 v132, v130
	v_mov_b32_e32 v114, v131
	v_pk_add_f32 v[114:115], v[132:133], v[114:115]
	s_nop 1
	v_mov_b32_dpp v50, v76 quad_perm:[1,0,3,2] row_mask:0xf bank_mask:0xf
	s_nop 1
	v_mov_b32_dpp v131, v115 quad_perm:[1,0,3,2] row_mask:0xf bank_mask:0xf
	s_nop 1
	v_mov_b32_dpp v130, v114 quad_perm:[1,0,3,2] row_mask:0xf bank_mask:0xf
	s_waitcnt lgkmcnt(0)
	v_add_f32_e32 v25, v25, v28
	s_nop 1
	v_mov_b32_dpp v28, v25 quad_perm:[2,3,0,1] row_mask:0xf bank_mask:0xf
	s_waitcnt lgkmcnt(0)
	v_add_f32_e32 v50, v76, v50
	s_nop 1
	v_mov_b32_dpp v76, v50 quad_perm:[2,3,0,1] row_mask:0xf bank_mask:0xf
	s_waitcnt lgkmcnt(0)
;     __device__ __forceinline__ float* out() const { return (float*)karg_in(33); }
; template <int R, bool BASE_F32, bool OUT_F32>
; __device__ __forceinline__ void rows_res(const Ctx& C, int m0, int stride, int mx, const float* gpost, float scale, int lane) {
;     ...
;     for (int r = 0; r < R; ++r) r1[r] = rsqrtf(wave_sum(r1[r]) * (1.f / DM) + EPS) * scale;
; #pragma unroll
;     for (int j = 0; j < 4; ++j) { const v4f gp = ld4_f32(gpost + 4 * lane + 256 * j);
; #pragma unroll
;         for (int r = 0; r < R; ++r) d[r][j] = b[r][j] + d[r][j] * r1[r] * gp; }
;     if (OUT_F32) { float* Y = C.out();
; #pragma unroll
;         for (int r = 0; r < R; ++r)
; #pragma unroll
;             for (int j = 0; j < 4; ++j) if (ok[r]) *(v4f*)(Y + (size_t)mr[r] * DM + 4 * lane + 256 * j) = d[r][j];
	v_pk_add_f32 v[114:115], v[114:115], v[130:131]
	s_nop 1
	v_mov_b32_dpp v131, v115 quad_perm:[2,3,0,1] row_mask:0xf bank_mask:0xf
	s_nop 1
	v_mov_b32_dpp v130, v114 quad_perm:[2,3,0,1] row_mask:0xf bank_mask:0xf
	s_waitcnt lgkmcnt(0)
	v_add_f32_e32 v25, v25, v28
	s_waitcnt lgkmcnt(0)
	v_add_f32_e32 v50, v50, v76
	s_nop 1
	v_mov_b32_dpp v28, v25 row_half_mirror row_mask:0xf bank_mask:0xf
	s_nop 1
	v_mov_b32_dpp v76, v50 row_half_mirror row_mask:0xf bank_mask:0xf
	s_waitcnt lgkmcnt(0)
	v_pk_add_f32 v[114:115], v[114:115], v[130:131]
	s_nop 1
	v_mov_b32_dpp v131, v115 row_half_mirror row_mask:0xf bank_mask:0xf
	s_nop 1
	v_mov_b32_dpp v130, v114 row_half_mirror row_mask:0xf bank_mask:0xf
	s_waitcnt lgkmcnt(0)
	v_add_f32_e32 v25, v25, v28
	s_waitcnt lgkmcnt(0)
	v_add_f32_e32 v50, v50, v76
	s_nop 1
	v_mov_b32_dpp v28, v25 row_mirror row_mask:0xf bank_mask:0xf
	s_nop 1
	v_mov_b32_dpp v76, v50 row_mirror row_mask:0xf bank_mask:0xf
	s_waitcnt lgkmcnt(0)
	v_pk_add_f32 v[114:115], v[114:115], v[130:131]
	s_nop 1
	v_mov_b32_dpp v131, v115 row_mirror row_mask:0xf bank_mask:0xf
	s_nop 1
	v_mov_b32_dpp v130, v114 row_mirror row_mask:0xf bank_mask:0xf
	s_waitcnt lgkmcnt(0)
	v_add_f32_e32 v25, v25, v28
	s_waitcnt lgkmcnt(0)
	v_add_f32_e32 v132, v50, v76
	ds_bpermute_b32 v28, v187, v25
	ds_bpermute_b32 v133, v187, v132
	s_waitcnt lgkmcnt(0)
	v_pk_add_f32 v[114:115], v[114:115], v[130:131]
	ds_bpermute_b32 v131, v187, v115
	ds_bpermute_b32 v130, v187, v114
	s_waitcnt lgkmcnt(0)
	v_add_f32_e32 v50, v25, v28
	s_waitcnt lgkmcnt(0)
	v_add_f32_e32 v25, v132, v133
	s_load_dwordx2 s[0:1], s[0:1], 0x108
	s_waitcnt lgkmcnt(0)
	v_pk_add_f32 v[130:131], v[114:115], v[130:131]
	ds_bpermute_b32 v76, v188, v50
	ds_bpermute_b32 v28, v188, v25
	ds_bpermute_b32 v133, v188, v131
	ds_bpermute_b32 v132, v188, v130
	v_lshl_add_u64 v[114:115], s[0:1], 0, v[16:17]
	s_cbranch_scc1 .LBB0_1277
	s_waitcnt lgkmcnt(0)
	v_add_f32_e32 v50, v50, v76
	v_fmamk_f32 v50, v50, 0x3a800000, v22
	v_mul_f32_e32 v76, 0x4b800000, v50
	v_cmp_gt_f32_e32 vcc, s27, v50
	v_lshlrev_b32_e32 v134, 16, v94
	v_and_b32_e32 v135, 0xffff0000, v94
	v_cndmask_b32_e32 v50, v50, v76, vcc
	v_rsq_f32_e32 v50, v50
	v_lshlrev_b32_e32 v94, 16, v95
	v_and_b32_e32 v95, 0xffff0000, v95
	s_ashr_i32 s17, s16, 31
	v_mul_f32_e32 v76, 0x45800000, v50
	v_cndmask_b32_e32 v50, v50, v76, vcc
	v_mul_f32_e32 v50, 0.5, v50
	v_pk_mul_f32 v[128:129], v[50:51], v[128:129] op_sel_hi:[0,1]
	s_waitcnt vmcnt(0)
	v_pk_mul_f32 v[128:129], v[128:129], v[2:3]
	v_pk_mul_f32 v[122:123], v[50:51], v[122:123] op_sel_hi:[0,1]
	v_pk_fma_f32 v[128:129], v[62:63], v[94:95], v[128:129] op_sel_hi:[0,1,1]
	v_lshlrev_b32_e32 v94, 16, v80
	v_and_b32_e32 v95, 0xffff0000, v80
	v_pk_mul_f32 v[124:125], v[50:51], v[124:125] op_sel_hi:[0,1]
	v_pk_mul_f32 v[122:123], v[122:123], v[4:5]
	v_lshlrev_b32_e32 v80, 16, v81
	v_and_b32_e32 v81, 0xffff0000, v81
	v_pk_mul_f32 v[124:125], v[124:125], v[6:7]
	v_pk_fma_f32 v[122:123], v[62:63], v[94:95], v[122:123] op_sel_hi:[0,1,1]
	v_pk_mul_f32 v[94:95], v[50:51], v[120:121] op_sel_hi:[0,1]
	v_pk_mul_f32 v[118:119], v[50:51], v[118:119] op_sel_hi:[0,1]
	v_pk_fma_f32 v[124:125], v[62:63], v[80:81], v[124:125] op_sel_hi:[0,1,1]
	v_lshlrev_b32_e32 v80, 16, v74
	v_and_b32_e32 v81, 0xffff0000, v74
	v_lshlrev_b32_e32 v74, 16, v75
	v_and_b32_e32 v75, 0xffff0000, v75
	v_pk_mul_f32 v[118:119], v[118:119], v[8:9]
	v_pk_mul_f32 v[94:95], v[94:95], v[10:11]
	v_pk_mul_f32 v[126:127], v[50:51], v[126:127] op_sel_hi:[0,1]
	v_pk_fma_f32 v[120:121], v[62:63], v[74:75], v[94:95] op_sel_hi:[0,1,1]
	v_pk_fma_f32 v[118:119], v[62:63], v[80:81], v[118:119] op_sel_hi:[0,1,1]
	v_pk_mul_f32 v[80:81], v[50:51], v[116:117] op_sel_hi:[0,1]
	v_pk_mul_f32 v[94:95], v[50:51], v[112:113] op_sel_hi:[0,1]
	v_pk_mul_f32 v[126:127], v[126:127], v[0:1]
	v_lshlrev_b32_e32 v74, 16, v70
	v_and_b32_e32 v75, 0xffff0000, v70
	v_lshlrev_b32_e32 v70, 16, v71
	v_and_b32_e32 v71, 0xffff0000, v71
	v_pk_mul_f32 v[94:95], v[94:95], v[12:13]
	v_pk_mul_f32 v[80:81], v[80:81], v[14:15]
	s_lshl_b64 s[0:1], s[16:17], 12
	v_pk_fma_f32 v[126:127], v[62:63], v[134:135], v[126:127] op_sel_hi:[0,1,1]
	v_pk_fma_f32 v[136:137], v[62:63], v[70:71], v[80:81] op_sel_hi:[0,1,1]
	v_pk_fma_f32 v[134:135], v[62:63], v[74:75], v[94:95] op_sel_hi:[0,1,1]
	v_lshl_add_u64 v[70:71], v[114:115], 0, s[0:1]
	global_store_dwordx4 v[70:71], v[134:137], off
	global_store_dwordx4 v[70:71], v[118:121], off offset:1024
	global_store_dwordx4 v[70:71], v[122:125], off offset:2048
	global_store_dwordx4 v[70:71], v[126:129], off offset:3072
;     __device__ __forceinline__ float* out() const { return (float*)karg_in(33); }
; template <int R, bool BASE_F32, bool OUT_F32>
; __device__ __forceinline__ void rows_res(const Ctx& C, int m0, int stride, int mx, const float* gpost, float scale, int lane) {
;     ...
;     for (int r = 0; r < R; ++r) r1[r] = rsqrtf(wave_sum(r1[r]) * (1.f / DM) + EPS) * scale;
; #pragma unroll
;     for (int j = 0; j < 4; ++j) { const v4f gp = ld4_f32(gpost + 4 * lane + 256 * j);
; #pragma unroll
;         for (int r = 0; r < R; ++r) d[r][j] = b[r][j] + d[r][j] * r1[r] * gp; }
;     if (OUT_F32) { float* Y = C.out();
; #pragma unroll
;         for (int r = 0; r < R; ++r)
; #pragma unroll
;             for (int j = 0; j < 4; ++j) if (ok[r]) *(v4f*)(Y + (size_t)mr[r] * DM + 4 * lane + 256 * j) = d[r][j];
.LBB0_1277:
	s_andn2_b64 vcc, exec, s[24:25]
	s_cbranch_vccnz .LBB0_1279
	s_waitcnt lgkmcnt(0)
	v_add_f32_e32 v25, v25, v28
	v_fmamk_f32 v25, v25, 0x3a800000, v22
	v_mul_f32_e32 v28, 0x4b800000, v25
	v_cmp_gt_f32_e32 vcc, s27, v25
	v_lshlrev_b32_e32 v112, 16, v54
	v_and_b32_e32 v113, 0xffff0000, v54
	v_cndmask_b32_e32 v25, v25, v28, vcc
	v_rsq_f32_e32 v25, v25
	v_lshlrev_b32_e32 v116, 16, v55
	v_and_b32_e32 v117, 0xffff0000, v55
	v_lshlrev_b32_e32 v70, 16, v60
	v_mul_f32_e32 v28, 0x45800000, v25
	v_cndmask_b32_e32 v25, v25, v28, vcc
	v_mul_f32_e32 v28, 0.5, v25
	v_pk_mul_f32 v[54:55], v[28:29], v[110:111] op_sel_hi:[0,1]
	v_and_b32_e32 v71, 0xffff0000, v60
	v_lshlrev_b32_e32 v60, 16, v61
	v_and_b32_e32 v61, 0xffff0000, v61
	v_lshlrev_b32_e32 v80, 16, v56
	v_and_b32_e32 v81, 0xffff0000, v56
	v_lshlrev_b32_e32 v94, 16, v57
	v_and_b32_e32 v95, 0xffff0000, v57
	v_pk_mul_f32 v[56:57], v[28:29], v[104:105] op_sel_hi:[0,1]
	s_waitcnt vmcnt(3)
	v_pk_mul_f32 v[54:55], v[14:15], v[54:55]
	v_pk_mul_f32 v[104:105], v[12:13], v[56:57]
	v_pk_fma_f32 v[56:57], v[42:43], v[60:61], v[54:55] op_sel_hi:[0,1,1]
	v_mov_b32_e32 v60, v103
	v_mov_b32_e32 v61, v109
	v_mov_b32_e32 v103, v108
	v_pk_fma_f32 v[54:55], v[42:43], v[70:71], v[104:105] op_sel_hi:[0,1,1]
	v_pk_mul_f32 v[60:61], v[28:29], v[60:61] op_sel_hi:[0,1]
	v_pk_mul_f32 v[70:71], v[28:29], v[102:103] op_sel_hi:[0,1]
	v_lshlrev_b32_e32 v74, 16, v58
	v_and_b32_e32 v75, 0xffff0000, v58
	v_lshlrev_b32_e32 v58, 16, v59
	v_and_b32_e32 v59, 0xffff0000, v59
	s_waitcnt vmcnt(2)
	v_pk_mul_f32 v[70:71], v[70:71], v[8:9]
	v_pk_mul_f32 v[60:61], v[60:61], v[10:11]
	v_mov_b32_e32 v62, v77
	v_pk_fma_f32 v[60:61], v[42:43], v[58:59], v[60:61] op_sel_hi:[0,1,1]
	v_pk_fma_f32 v[58:59], v[42:43], v[74:75], v[70:71] op_sel_hi:[0,1,1]
	v_pk_mul_f32 v[70:71], v[28:29], v[106:107] op_sel_hi:[0,1]
	v_pk_mul_f32 v[74:75], v[28:29], v[100:101] op_sel_hi:[0,1]
	s_waitcnt vmcnt(1)
	v_pk_mul_f32 v[70:71], v[70:71], v[6:7]
	v_pk_mul_f32 v[62:63], v[28:29], v[62:63] op_sel_hi:[0,1]
	s_ashr_i32 s5, s4, 31
	v_pk_mul_f32 v[74:75], v[74:75], v[4:5]
	v_pk_fma_f32 v[102:103], v[42:43], v[94:95], v[70:71] op_sel_hi:[0,1,1]
	v_pk_mul_f32 v[70:71], v[28:29], v[78:79] op_sel_hi:[0,1]
	s_waitcnt vmcnt(0)
	v_pk_mul_f32 v[62:63], v[62:63], v[0:1]
	s_lshl_b64 s[0:1], s[4:5], 12
	v_pk_fma_f32 v[100:101], v[42:43], v[80:81], v[74:75] op_sel_hi:[0,1,1]
	v_pk_mul_f32 v[70:71], v[70:71], v[2:3]
	v_pk_fma_f32 v[74:75], v[42:43], v[112:113], v[62:63] op_sel_hi:[0,1,1]
	v_lshl_add_u64 v[62:63], v[114:115], 0, s[0:1]
	v_pk_fma_f32 v[76:77], v[42:43], v[116:117], v[70:71] op_sel_hi:[0,1,1]
	global_store_dwordx4 v[62:63], v[54:57], off
	global_store_dwordx4 v[62:63], v[58:61], off offset:1024
	global_store_dwordx4 v[62:63], v[100:103], off offset:2048
	global_store_dwordx4 v[62:63], v[74:77], off offset:3072

; __device__ __forceinline__ const float* xrow_ptr(const Ctx& C, int row) { return row < MPROMPT ? C.in(0) + (size_t)row * DM : C.in(1) + (size_t)(row - MPROMPT) * DM; }
; __device__ __forceinline__ v4f ld4_bf16(const bf16* p) { const v2u w = *(const v2u*)p; return (v4f){bf_lo(w.x), bf_hi(w.x), bf_lo(w.y), bf_hi(w.y)}; }
; template <int R, bool BASE_F32, bool OUT_F32>
; __device__ __forceinline__ void rows_res(const Ctx& C, int m0, int stride, int mx, const float* gpost, float scale, int lane) {
;     v4f d[R][4], b[R][4]; int mr[R]; bool ok[R]; float r1[R];
;     const bf16* D = C.D(); bf16* XN = C.XN();
; #pragma unroll
;     for (int r = 0; r < R; ++r) { mr[r] = (r == 4) ? mx : m0 + r * stride; ok[r] = (r == 4) ? (mx < M) : (mr[r] < MPROMPT); const int mm = ok[r] ? mr[r] : 0;
; #pragma unroll
;         for (int j = 0; j < 4; ++j) d[r][j] = ld4_bf16(D + (size_t)mm * DM + 4 * lane + 256 * j);
;         if (BASE_F32) { const float* x = xrow_ptr(C, mm);
; #pragma unroll
;             for (int j = 0; j < 4; ++j) b[r][j] = ld4_f32(x + 4 * lane + 256 * j);
;         } else { const float inv = C.RS()[mm];
; #pragma unroll
;             for (int j = 0; j < 4; ++j) b[r][j] = ld4_bf16(XN + (size_t)mm * DM + 4 * lane + 256 * j) * inv;
;         } }
.LBB0_1283:
	s_mov_b64 s[0:1], s[80:81]
	s_load_dwordx2 s[0:1], s[0:1], 0x110
	s_mov_b64 s[2:3], s[80:81]
	s_load_dwordx2 s[2:3], s[2:3], 0x110
	s_add_i32 s4, s15, s86
	s_add_i32 s10, s15, 0x8000
	v_mov_b32_e32 v19, v17
	s_ashr_i32 s5, s4, 31
	s_waitcnt vmcnt(0) lgkmcnt(0)
	v_lshl_add_u64 v[0:1], s[0:1], 0, v[18:19]
	s_mov_b64 s[0:1], 0x7100000
	s_cmp_lt_i32 s4, 0x8000
	v_lshl_add_u64 v[0:1], v[0:1], 0, s[0:1]
	s_cselect_b32 s1, s5, 0
	s_cselect_b32 s0, s4, 0
	v_lshl_add_u64 v[2:3], s[2:3], 0, v[18:19]
	s_lshl_b64 s[2:3], s[0:1], 11
	v_lshl_add_u64 v[4:5], v[0:1], 0, s[2:3]
	s_mov_b64 s[6:7], s[80:81]
	global_load_dwordx2 v[12:13], v[4:5], off
	global_load_dwordx2 v[14:15], v[4:5], off offset:512
	global_load_dwordx2 v[20:21], v[4:5], off offset:1024
	global_load_dwordx2 v[24:25], v[4:5], off offset:1536
	s_load_dwordx2 s[6:7], s[6:7], 0x110
	s_lshl_b64 s[0:1], s[0:1], 2
	v_mov_b32_e32 v19, 0x2a80000
	s_mov_b64 s[12:13], 0x3000000
	v_lshl_add_u64 v[28:29], v[2:3], 0, s[12:13]
	s_waitcnt lgkmcnt(0)
	s_add_u32 s0, s6, s0
	s_addc_u32 s1, s7, s1
	s_add_i32 s20, s4, s46
	s_cmp_lt_i32 s20, 0x8000
	s_cselect_b64 s[6:7], -1, 0
	s_ashr_i32 s21, s20, 31
	global_load_dword v84, v19, s[0:1]
	s_and_b64 s[0:1], s[6:7], exec
	s_cselect_b32 s1, s21, 0
	s_cselect_b32 s0, s20, 0
	v_lshl_add_u64 v[2:3], v[28:29], 0, s[2:3]
	s_lshl_b64 s[2:3], s[0:1], 11
	global_load_dwordx2 v[86:87], v[2:3], off
	global_load_dwordx2 v[100:101], v[2:3], off offset:512
	global_load_dwordx2 v[106:107], v[2:3], off offset:1024
	global_load_dwordx2 v[108:109], v[2:3], off offset:1536
	v_lshl_add_u64 v[2:3], v[0:1], 0, s[2:3]
	s_mov_b64 s[12:13], s[80:81]
	global_load_dwordx2 v[64:65], v[2:3], off
	global_load_dwordx2 v[66:67], v[2:3], off offset:512
	global_load_dwordx2 v[68:69], v[2:3], off offset:1024
	global_load_dwordx2 v[26:27], v[2:3], off offset:1536
	s_load_dwordx2 s[12:13], s[12:13], 0x110
	s_lshl_b64 s[0:1], s[0:1], 2
	v_lshl_add_u64 v[2:3], v[28:29], 0, s[2:3]
	s_mov_b64 s[24:25], s[80:81]
	s_waitcnt lgkmcnt(0)
	s_add_u32 s0, s12, s0
	s_addc_u32 s1, s13, s1
	s_add_i32 s16, s20, s46
	s_cmp_lt_i32 s16, 0x8000
	s_cselect_b64 s[22:23], -1, 0
	s_ashr_i32 s17, s16, 31
	global_load_dword v56, v19, s[0:1]
	s_and_b64 s[0:1], s[22:23], exec
	s_cselect_b32 s1, s17, 0
	s_cselect_b32 s0, s16, 0
	s_lshl_b64 s[2:3], s[0:1], 11
	global_load_dwordx2 v[82:83], v[2:3], off
	global_load_dwordx2 v[80:81], v[2:3], off offset:512
	global_load_dwordx2 v[78:79], v[2:3], off offset:1024
	global_load_dwordx2 v[74:75], v[2:3], off offset:1536
	v_lshl_add_u64 v[2:3], v[0:1], 0, s[2:3]
	s_mov_b64 s[12:13], s[80:81]
	global_load_dwordx2 v[70:71], v[2:3], off
	global_load_dwordx2 v[72:73], v[2:3], off offset:512
	global_load_dwordx2 v[76:77], v[2:3], off offset:1024
	global_load_dwordx2 v[30:31], v[2:3], off offset:1536
	s_load_dwordx2 s[12:13], s[12:13], 0x110
	s_lshl_b64 s[0:1], s[0:1], 2
	v_lshl_add_u64 v[2:3], v[28:29], 0, s[2:3]
	s_waitcnt lgkmcnt(0)
	s_add_u32 s0, s12, s0
	s_addc_u32 s1, s13, s1
	s_add_i32 s12, s16, s46
	s_cmp_lt_i32 s12, 0x8000
	s_cselect_b64 s[18:19], -1, 0
	s_ashr_i32 s13, s12, 31
	global_load_dword v36, v19, s[0:1]
	s_and_b64 s[0:1], s[18:19], exec
	s_cselect_b32 s1, s13, 0
	s_cselect_b32 s0, s12, 0
	s_lshl_b64 s[2:3], s[0:1], 11
	global_load_dwordx2 v[58:59], v[2:3], off
	global_load_dwordx2 v[54:55], v[2:3], off offset:512
	global_load_dwordx2 v[52:53], v[2:3], off offset:1024
	global_load_dwordx2 v[50:51], v[2:3], off offset:1536
	v_lshl_add_u64 v[2:3], v[0:1], 0, s[2:3]
	global_load_dwordx2 v[10:11], v[2:3], off
	global_load_dwordx2 v[8:9], v[2:3], off offset:512
	global_load_dwordx2 v[6:7], v[2:3], off offset:1024
	global_load_dwordx2 v[32:33], v[2:3], off offset:1536
	s_load_dwordx2 s[24:25], s[24:25], 0x110
	s_lshl_b64 s[0:1], s[0:1], 2
	s_waitcnt lgkmcnt(0)
	s_add_u32 s0, s24, s0
	s_addc_u32 s1, s25, s1
	s_ashr_i32 s11, s10, 31
	s_cmpk_lt_i32 s15, 0x80
	s_cselect_b64 s[14:15], -1, 0
	s_and_b64 s[24:25], s[14:15], exec
	s_cselect_b32 s25, s11, 0
	s_cselect_b32 s24, s10, 0
	s_lshl_b64 s[28:29], s[24:25], 11
	v_lshl_add_u64 v[34:35], v[0:1], 0, s[28:29]
	global_load_dwordx2 v[88:89], v[34:35], off offset:1536
	global_load_dwordx2 v[4:5], v[34:35], off
	global_load_dwordx2 v[2:3], v[34:35], off offset:512
	global_load_dwordx2 v[0:1], v[34:35], off offset:1024
	global_load_dword v22, v19, s[0:1]
	v_lshl_add_u64 v[34:35], v[28:29], 0, s[2:3]
	s_mov_b64 s[0:1], s[80:81]
	global_load_dwordx2 v[48:49], v[34:35], off
	global_load_dwordx2 v[46:47], v[34:35], off offset:512
	global_load_dwordx2 v[44:45], v[34:35], off offset:1024
	global_load_dwordx2 v[42:43], v[34:35], off offset:1536
	s_load_dwordx2 s[0:1], s[0:1], 0x110
	s_lshl_b64 s[2:3], s[24:25], 2
	s_waitcnt vmcnt(39)
	v_lshlrev_b32_e32 v136, 16, v12
	v_and_b32_e32 v137, 0xffff0000, v12
	v_lshlrev_b32_e32 v138, 16, v13
	s_waitcnt lgkmcnt(0)
	s_add_u32 s0, s0, s2
	s_addc_u32 s1, s1, s3
	v_and_b32_e32 v139, 0xffff0000, v13
	v_lshl_add_u64 v[12:13], v[28:29], 0, s[28:29]
	s_waitcnt vmcnt(37)
	v_lshlrev_b32_e32 v144, 16, v20
	v_and_b32_e32 v145, 0xffff0000, v20
	global_load_dword v20, v19, s[0:1]
	v_and_b32_e32 v141, 0xffff0000, v14
	v_and_b32_e32 v143, 0xffff0000, v15
	v_lshlrev_b32_e32 v140, 16, v14
	v_lshlrev_b32_e32 v142, 16, v15
	v_mul_f32_e32 v14, v143, v143
	v_fmac_f32_e32 v14, v142, v142
	v_and_b32_e32 v147, 0xffff0000, v21
	v_lshlrev_b32_e32 v146, 16, v21
	s_waitcnt vmcnt(37)
	v_and_b32_e32 v149, 0xffff0000, v24
	v_and_b32_e32 v151, 0xffff0000, v25
	v_lshlrev_b32_e32 v148, 16, v24
	v_lshlrev_b32_e32 v150, 16, v25
	s_waitcnt vmcnt(31)
; __device__ __forceinline__ const float* xrow_ptr(const Ctx& C, int row) { return row < MPROMPT ? C.in(0) + (size_t)row * DM : C.in(1) + (size_t)(row - MPROMPT) * DM; }
; __device__ __forceinline__ v4f ld4_bf16(const bf16* p) { const v2u w = *(const v2u*)p; return (v4f){bf_lo(w.x), bf_hi(w.x), bf_lo(w.y), bf_hi(w.y)}; }
; __device__ __forceinline__ float ssq4(v4f v) { return (v.x * v.x + v.y * v.y) + (v.z * v.z + v.w * v.w); }
; template <int R, bool BASE_F32, bool OUT_F32>
; __device__ __forceinline__ void rows_res(const Ctx& C, int m0, int stride, int mx, const float* gpost, float scale, int lane) {
;     ...
;     for (int r = 0; r < R; ++r) { mr[r] = (r == 4) ? mx : m0 + r * stride; ok[r] = (r == 4) ? (mx < M) : (mr[r] < MPROMPT); const int mm = ok[r] ? mr[r] : 0;
; #pragma unroll
;         for (int j = 0; j < 4; ++j) d[r][j] = ld4_bf16(D + (size_t)mm * DM + 4 * lane + 256 * j);
;         if (BASE_F32) { const float* x = xrow_ptr(C, mm);
; #pragma unroll
;             for (int j = 0; j < 4; ++j) b[r][j] = ld4_f32(x + 4 * lane + 256 * j);
;         } else { const float inv = C.RS()[mm];
; #pragma unroll
;             for (int j = 0; j < 4; ++j) b[r][j] = ld4_bf16(XN + (size_t)mm * DM + 4 * lane + 256 * j) * inv;
;         } }
; #pragma unroll
;     for (int r = 0; r < R; ++r) { float s = 0.f;
; #pragma unroll
;         for (int j = 0; j < 4; ++j) s += ssq4(d[r][j]);
;         r1[r] = s; }
	v_and_b32_e32 v129, 0xffff0000, v64
	v_and_b32_e32 v135, 0xffff0000, v65
	v_lshlrev_b32_e32 v128, 16, v64
	v_lshlrev_b32_e32 v134, 16, v65
	s_waitcnt vmcnt(30)
	v_and_b32_e32 v133, 0xffff0000, v67
	v_and_b32_e32 v132, 0xffff0000, v66
	v_mul_f32_e32 v24, v129, v129
	s_waitcnt vmcnt(28)
	v_lshlrev_b32_e32 v103, 16, v26
	v_lshlrev_b32_e32 v127, 16, v67
	v_lshlrev_b32_e32 v126, 16, v66
	v_and_b32_e32 v85, 0xffff0000, v26
	v_mov_b32_e32 v67, v103
	v_mul_f32_e32 v21, v85, v85
	v_and_b32_e32 v123, 0xffff0000, v68
	s_waitcnt vmcnt(19)
	v_lshlrev_b32_e32 v61, 16, v30
	v_and_b32_e32 v57, 0xffff0000, v30
	v_lshlrev_b32_e32 v62, 16, v31
	v_and_b32_e32 v63, 0xffff0000, v31
	v_and_b32_e32 v131, 0xffff0000, v69
	v_lshlrev_b32_e32 v104, 16, v27
	v_and_b32_e32 v105, 0xffff0000, v27
	v_lshlrev_b32_e32 v122, 16, v68
	v_lshlrev_b32_e32 v130, 16, v69
	v_mul_f32_e32 v38, v104, v104
	v_mul_f32_e32 v60, v105, v105
	v_and_b32_e32 v115, 0xffff0000, v70
	v_and_b32_e32 v121, 0xffff0000, v71
	v_lshlrev_b32_e32 v114, 16, v70
	v_lshlrev_b32_e32 v120, 16, v71
	v_and_b32_e32 v119, 0xffff0000, v73
	v_and_b32_e32 v118, 0xffff0000, v72
	v_lshlrev_b32_e32 v113, 16, v73
	v_lshlrev_b32_e32 v112, 16, v72
	v_and_b32_e32 v111, 0xffff0000, v76
	s_waitcnt vmcnt(10)
	v_lshlrev_b32_e32 v39, 16, v32
	v_and_b32_e32 v37, 0xffff0000, v32
	v_lshlrev_b32_e32 v40, 16, v33
	v_and_b32_e32 v41, 0xffff0000, v33
	global_load_dwordx2 v[34:35], v[12:13], off
	global_load_dwordx2 v[32:33], v[12:13], off offset:512
	global_load_dwordx2 v[30:31], v[12:13], off offset:1024
	global_load_dwordx2 v[28:29], v[12:13], off offset:1536
	v_mul_f32_e32 v12, v137, v137
	v_mul_f32_e32 v13, v139, v139
	v_fmac_f32_e32 v12, v136, v136
	v_fmac_f32_e32 v13, v138, v138
	v_add_f32_e32 v12, v12, v13
	v_mul_f32_e32 v13, v141, v141
	v_fmac_f32_e32 v13, v140, v140
	v_add_f32_e32 v13, v13, v14
	v_add_f32_e32 v12, v12, v13
	v_mul_f32_e32 v13, v145, v145
	v_mul_f32_e32 v14, v147, v147
	v_fmac_f32_e32 v13, v144, v144
	v_fmac_f32_e32 v14, v146, v146
	v_add_f32_e32 v13, v13, v14
	v_add_f32_e32 v12, v12, v13
	v_mul_f32_e32 v13, v149, v149
	v_mul_f32_e32 v14, v151, v151
	v_fmac_f32_e32 v13, v148, v148
	v_fmac_f32_e32 v14, v150, v150
	v_add_f32_e32 v13, v13, v14
	s_waitcnt vmcnt(13)
	v_lshlrev_b32_e32 v25, 16, v88
	v_add_f32_e32 v19, v12, v13
	v_mul_f32_e32 v12, v135, v135
	v_pk_fma_f32 v[12:13], v[134:135], v[134:135], v[12:13] op_sel_hi:[1,1,0]
	v_pk_mul_f32 v[14:15], v[132:133], v[132:133]
	v_pk_fma_f32 v[64:65], v[128:129], v[128:129], v[24:25] op_sel_hi:[1,1,0]
	v_pk_fma_f32 v[14:15], v[126:127], v[126:127], v[14:15]
	v_mov_b32_e32 v102, v64
	v_mov_b32_e32 v66, v12
	v_pk_add_f32 v[12:13], v[64:65], v[12:13]
	v_pk_mul_f32 v[64:65], v[102:103], v[66:67]
	v_pk_add_f32 v[14:15], v[14:15], v[14:15] op_sel:[0,1] op_sel_hi:[1,0]
	v_mov_b32_e32 v13, v65
	v_mov_b32_e32 v15, v21
	v_pk_add_f32 v[12:13], v[12:13], v[14:15]
	v_mul_f32_e32 v14, v123, v123
	v_mul_f32_e32 v24, v131, v131
	v_pk_fma_f32 v[14:15], v[122:123], v[122:123], v[14:15] op_sel_hi:[1,1,0]
	v_pk_fma_f32 v[64:65], v[130:131], v[130:131], v[24:25] op_sel_hi:[1,1,0]
	v_mov_b32_e32 v15, v38
	v_mov_b32_e32 v65, v60
	v_pk_add_f32 v[14:15], v[14:15], v[64:65]
	v_mul_f32_e32 v24, v115, v115
	v_pk_add_f32 v[124:125], v[12:13], v[14:15]
	v_mul_f32_e32 v12, v121, v121
	v_pk_fma_f32 v[12:13], v[120:121], v[120:121], v[12:13] op_sel_hi:[1,1,0]
	v_pk_mul_f32 v[14:15], v[118:119], v[118:119]
	v_pk_fma_f32 v[64:65], v[114:115], v[114:115], v[24:25] op_sel_hi:[1,1,0]
	v_pk_fma_f32 v[14:15], v[112:113], v[112:113], v[14:15]
	v_mov_b32_e32 v60, v64
	v_mov_b32_e32 v66, v12
	v_mov_b32_e32 v67, v61
	v_mul_f32_e32 v21, v57, v57
	v_pk_add_f32 v[12:13], v[64:65], v[12:13]
	v_pk_mul_f32 v[64:65], v[60:61], v[66:67]
	v_pk_add_f32 v[14:15], v[14:15], v[14:15] op_sel:[0,1] op_sel_hi:[1,0]
	v_and_b32_e32 v117, 0xffff0000, v77
	v_mov_b32_e32 v13, v65
	v_mov_b32_e32 v15, v21
	v_lshlrev_b32_e32 v110, 16, v76
	v_lshlrev_b32_e32 v116, 16, v77
	v_pk_add_f32 v[12:13], v[12:13], v[14:15]
	v_mul_f32_e32 v14, v111, v111
	v_mul_f32_e32 v24, v117, v117
	v_mul_f32_e32 v38, v62, v62
	v_mul_f32_e32 v68, v63, v63
	v_pk_fma_f32 v[14:15], v[110:111], v[110:111], v[14:15] op_sel_hi:[1,1,0]
	v_pk_fma_f32 v[64:65], v[116:117], v[116:117], v[24:25] op_sel_hi:[1,1,0]
	v_and_b32_e32 v93, 0xffff0000, v10
	v_and_b32_e32 v99, 0xffff0000, v11
	v_and_b32_e32 v23, 0xffff0000, v88
	v_lshlrev_b32_e32 v26, 16, v89
	v_and_b32_e32 v27, 0xffff0000, v89
	v_mov_b32_e32 v15, v38
	v_mov_b32_e32 v65, v68
	v_lshlrev_b32_e32 v92, 16, v10
	v_lshlrev_b32_e32 v98, 16, v11
	v_mul_f32_e32 v10, v99, v99
	v_and_b32_e32 v97, 0xffff0000, v9
	v_and_b32_e32 v96, 0xffff0000, v8
	v_lshlrev_b32_e32 v88, 16, v6
	v_and_b32_e32 v89, 0xffff0000, v6
	v_mul_f32_e32 v6, v93, v93
	v_pk_add_f32 v[14:15], v[14:15], v[64:65]
	v_pk_fma_f32 v[10:11], v[98:99], v[98:99], v[10:11] op_sel_hi:[1,1,0]
	v_lshlrev_b32_e32 v91, 16, v9
	v_lshlrev_b32_e32 v90, 16, v8
	v_pk_mul_f32 v[8:9], v[96:97], v[96:97]
	v_lshlrev_b32_e32 v94, 16, v7
	v_and_b32_e32 v95, 0xffff0000, v7
	v_pk_fma_f32 v[6:7], v[92:93], v[92:93], v[6:7] op_sel_hi:[1,1,0]
	v_pk_add_f32 v[152:153], v[12:13], v[14:15]
	v_pk_fma_f32 v[8:9], v[90:91], v[90:91], v[8:9]
	v_mov_b32_e32 v38, v6
	v_mov_b32_e32 v12, v10
	v_mov_b32_e32 v13, v39
	v_mul_f32_e32 v14, v37, v37
	v_pk_add_f32 v[6:7], v[6:7], v[10:11]
	v_pk_mul_f32 v[10:11], v[38:39], v[12:13]
	v_pk_add_f32 v[8:9], v[8:9], v[8:9] op_sel:[0,1] op_sel_hi:[1,0]
	v_mov_b32_e32 v7, v11
	v_mov_b32_e32 v9, v14
	v_pk_add_f32 v[6:7], v[6:7], v[8:9]
	v_mul_f32_e32 v8, v89, v89
	v_mul_f32_e32 v10, v95, v95
	v_mul_f32_e32 v15, v40, v40
	v_mul_f32_e32 v21, v41, v41
	v_pk_fma_f32 v[8:9], v[88:89], v[88:89], v[8:9] op_sel_hi:[1,1,0]
	v_pk_fma_f32 v[10:11], v[94:95], v[94:95], v[10:11] op_sel_hi:[1,1,0]
	v_mov_b32_e32 v9, v15
	v_mov_b32_e32 v11, v21
	s_waitcnt vmcnt(12)
; __device__ __forceinline__ float ssq4(v4f v) { return (v.x * v.x + v.y * v.y) + (v.z * v.z + v.w * v.w); }
; template <int R, bool BASE_F32, bool OUT_F32>
; __device__ __forceinline__ void rows_res(const Ctx& C, int m0, int stride, int mx, const float* gpost, float scale, int lane) {
;     ...
;     for (int r = 0; r < R; ++r) { float s = 0.f;
; #pragma unroll
;         for (int j = 0; j < 4; ++j) s += ssq4(d[r][j]);
;         r1[r] = s; }
; #pragma unroll
;     for (int r = 0; r < R; ++r) r1[r] = rsqrtf(wave_sum(r1[r]) * (1.f / DM) + EPS) * scale;
	v_and_b32_e32 v77, 0xffff0000, v5
	s_waitcnt vmcnt(11)
	v_and_b32_e32 v73, 0xffff0000, v3
	v_and_b32_e32 v72, 0xffff0000, v2
	v_pk_add_f32 v[8:9], v[8:9], v[10:11]
	v_lshlrev_b32_e32 v68, 16, v4
	v_and_b32_e32 v69, 0xffff0000, v4
	v_lshlrev_b32_e32 v76, 16, v5
	v_mul_f32_e32 v4, v77, v77
	v_lshlrev_b32_e32 v67, 16, v3
	v_lshlrev_b32_e32 v66, 16, v2
	v_pk_mul_f32 v[2:3], v[72:73], v[72:73]
	v_pk_add_f32 v[154:155], v[6:7], v[8:9]
	v_pk_fma_f32 v[156:157], v[76:77], v[76:77], v[4:5] op_sel_hi:[1,1,0]
	v_pk_fma_f32 v[158:159], v[66:67], v[66:67], v[2:3]
	s_waitcnt vmcnt(10)
	v_lshlrev_b32_e32 v64, 16, v0
	v_and_b32_e32 v65, 0xffff0000, v0
	v_lshlrev_b32_e32 v70, 16, v1
	v_and_b32_e32 v71, 0xffff0000, v1
	global_load_dwordx4 v[12:15], v16, s[8:9]
	global_load_dwordx4 v[8:11], v16, s[8:9] offset:1024
	global_load_dwordx4 v[4:7], v16, s[8:9] offset:2048
	global_load_dwordx4 v[0:3], v16, s[8:9] offset:3072
	v_mul_f32_e32 v24, v69, v69
	v_pk_fma_f32 v[160:161], v[68:69], v[68:69], v[24:25] op_sel_hi:[1,1,0]
	v_mov_b32_e32 v162, v156
	v_mov_b32_e32 v24, v160
	v_mov_b32_e32 v163, v25
	v_pk_add_f32 v[156:157], v[160:161], v[156:157]
	v_pk_mul_f32 v[160:161], v[24:25], v[162:163]
	s_nop 1
	v_mov_b32_dpp v24, v19 quad_perm:[1,0,3,2] row_mask:0xf bank_mask:0xf
	v_mul_f32_e32 v21, v23, v23
	v_pk_add_f32 v[158:159], v[158:159], v[158:159] op_sel:[0,1] op_sel_hi:[1,0]
	v_mov_b32_e32 v157, v161
	v_mov_b32_e32 v159, v21
	s_waitcnt lgkmcnt(0)
	v_add_f32_e32 v19, v19, v24
	v_mul_f32_e32 v24, v65, v65
	v_pk_add_f32 v[156:157], v[156:157], v[158:159]
	v_pk_fma_f32 v[158:159], v[64:65], v[64:65], v[24:25] op_sel_hi:[1,1,0]
	v_mul_f32_e32 v24, v71, v71
	v_mul_f32_e32 v38, v26, v26
	v_mul_f32_e32 v60, v27, v27
	v_pk_fma_f32 v[160:161], v[70:71], v[70:71], v[24:25] op_sel_hi:[1,1,0]
	v_mov_b32_e32 v159, v38
	v_mov_b32_e32 v161, v60
	v_pk_add_f32 v[158:159], v[158:159], v[160:161]
	s_nop 1
	v_mov_b32_dpp v21, v19 quad_perm:[2,3,0,1] row_mask:0xf bank_mask:0xf
	v_pk_add_f32 v[156:157], v[156:157], v[158:159]
	v_mov_b32_e32 v158, v152
	v_mov_b32_e32 v159, v124
	v_mov_b32_e32 v124, v153
	v_pk_add_f32 v[124:125], v[158:159], v[124:125]
	v_mov_b32_e32 v158, v156
	v_mov_b32_e32 v159, v154
	v_mov_b32_e32 v154, v157
	v_pk_add_f32 v[154:155], v[158:159], v[154:155]
	s_nop 1
	v_mov_b32_dpp v153, v125 quad_perm:[1,0,3,2] row_mask:0xf bank_mask:0xf
	s_nop 1
	v_mov_b32_dpp v152, v124 quad_perm:[1,0,3,2] row_mask:0xf bank_mask:0xf
	s_nop 1
	v_mov_b32_dpp v157, v155 quad_perm:[1,0,3,2] row_mask:0xf bank_mask:0xf
	s_nop 1
	v_mov_b32_dpp v156, v154 quad_perm:[1,0,3,2] row_mask:0xf bank_mask:0xf
	s_waitcnt lgkmcnt(0)
	v_add_f32_e32 v19, v19, v21
	s_nop 1
	v_mov_b32_dpp v21, v19 row_half_mirror row_mask:0xf bank_mask:0xf
	s_waitcnt lgkmcnt(0)
	v_pk_add_f32 v[124:125], v[124:125], v[152:153]
	s_nop 1
	v_mov_b32_dpp v153, v125 quad_perm:[2,3,0,1] row_mask:0xf bank_mask:0xf
	s_waitcnt lgkmcnt(0)
	v_pk_add_f32 v[154:155], v[154:155], v[156:157]
	s_nop 1
	v_mov_b32_dpp v152, v124 quad_perm:[2,3,0,1] row_mask:0xf bank_mask:0xf
	s_nop 1
	v_mov_b32_dpp v157, v155 quad_perm:[2,3,0,1] row_mask:0xf bank_mask:0xf
	s_nop 1
	v_mov_b32_dpp v156, v154 quad_perm:[2,3,0,1] row_mask:0xf bank_mask:0xf
	s_waitcnt lgkmcnt(0)
	v_add_f32_e32 v19, v19, v21
	s_nop 1
	v_mov_b32_dpp v21, v19 row_mirror row_mask:0xf bank_mask:0xf
	s_waitcnt lgkmcnt(0)
	v_pk_add_f32 v[124:125], v[124:125], v[152:153]
	s_nop 1
	v_mov_b32_dpp v153, v125 row_half_mirror row_mask:0xf bank_mask:0xf
	s_waitcnt lgkmcnt(0)
	v_pk_add_f32 v[154:155], v[154:155], v[156:157]
	s_nop 1
	v_mov_b32_dpp v152, v124 row_half_mirror row_mask:0xf bank_mask:0xf
	s_nop 1
	v_mov_b32_dpp v157, v155 row_half_mirror row_mask:0xf bank_mask:0xf
	s_nop 1
	v_mov_b32_dpp v156, v154 row_half_mirror row_mask:0xf bank_mask:0xf
	s_waitcnt lgkmcnt(0)
	v_add_f32_e32 v19, v19, v21
	ds_bpermute_b32 v21, v187, v19
	s_waitcnt lgkmcnt(0)
	v_pk_add_f32 v[124:125], v[124:125], v[152:153]
	s_nop 1
	v_mov_b32_dpp v153, v125 row_mirror row_mask:0xf bank_mask:0xf
	s_waitcnt lgkmcnt(0)
	v_pk_add_f32 v[154:155], v[154:155], v[156:157]
	s_nop 1
	v_mov_b32_dpp v152, v124 row_mirror row_mask:0xf bank_mask:0xf
	s_nop 1
	v_mov_b32_dpp v157, v155 row_mirror row_mask:0xf bank_mask:0xf
	s_nop 1
	v_mov_b32_dpp v156, v154 row_mirror row_mask:0xf bank_mask:0xf
	s_mov_b64 s[0:1], s[80:81]
	s_waitcnt lgkmcnt(0)
	v_pk_add_f32 v[124:125], v[124:125], v[152:153]
	ds_bpermute_b32 v153, v187, v125
	s_waitcnt lgkmcnt(0)
	v_pk_add_f32 v[154:155], v[154:155], v[156:157]
	ds_bpermute_b32 v152, v187, v124
	ds_bpermute_b32 v161, v187, v155
	ds_bpermute_b32 v160, v187, v154
	v_add_f32_e32 v19, v19, v21
	s_load_dwordx2 s[0:1], s[0:1], 0x108
	s_waitcnt lgkmcnt(0)
	v_pk_add_f32 v[156:157], v[124:125], v[152:153]
	ds_bpermute_b32 v21, v188, v19
	v_pk_add_f32 v[152:153], v[154:155], v[160:161]
	ds_bpermute_b32 v159, v188, v157
	ds_bpermute_b32 v158, v188, v156
	ds_bpermute_b32 v155, v188, v153
	ds_bpermute_b32 v154, v188, v152
	s_cmpk_gt_i32 s4, 0x7fff
	v_lshl_add_u64 v[124:125], s[0:1], 0, v[16:17]
	s_cbranch_scc1 .LBB0_1285
;     __device__ __forceinline__ float* out() const { return (float*)karg_in(33); }
; template <int R, bool BASE_F32, bool OUT_F32>
; __device__ __forceinline__ void rows_res(const Ctx& C, int m0, int stride, int mx, const float* gpost, float scale, int lane) {
;     ...
;     for (int r = 0; r < R; ++r) r1[r] = rsqrtf(wave_sum(r1[r]) * (1.f / DM) + EPS) * scale;
; #pragma unroll
;     for (int j = 0; j < 4; ++j) { const v4f gp = ld4_f32(gpost + 4 * lane + 256 * j);
; #pragma unroll
;         for (int r = 0; r < R; ++r) d[r][j] = b[r][j] + d[r][j] * r1[r] * gp; }
;     if (OUT_F32) { float* Y = C.out();
; #pragma unroll
;         for (int r = 0; r < R; ++r)
; #pragma unroll
;             for (int j = 0; j < 4; ++j) if (ok[r]) *(v4f*)(Y + (size_t)mr[r] * DM + 4 * lane + 256 * j) = d[r][j];
	s_waitcnt lgkmcnt(0)
	v_add_f32_e32 v19, v19, v21
	v_mov_b32_e32 v21, 0x358637bd
	v_fmac_f32_e32 v21, 0x3a800000, v19
	s_mov_b32 s0, 0x800000
	v_mul_f32_e32 v19, 0x4b800000, v21
	v_cmp_gt_f32_e32 vcc, s0, v21
	v_lshlrev_b32_e32 v160, 16, v108
	v_and_b32_e32 v161, 0xffff0000, v108
	v_cndmask_b32_e32 v19, v21, v19, vcc
	v_rsq_f32_e32 v19, v19
	v_lshlrev_b32_e32 v108, 16, v109
	v_and_b32_e32 v109, 0xffff0000, v109
	s_lshl_b64 s[0:1], s[4:5], 12
	v_mul_f32_e32 v21, 0x45800000, v19
	v_cndmask_b32_e32 v19, v19, v21, vcc
	v_mul_f32_e32 v24, 0.5, v19
	v_pk_mul_f32 v[150:151], v[24:25], v[150:151] op_sel_hi:[0,1]
	v_pk_mul_f32 v[148:149], v[24:25], v[148:149] op_sel_hi:[0,1]
	s_waitcnt vmcnt(0)
	v_pk_mul_f32 v[150:151], v[150:151], v[2:3]
	v_pk_mul_f32 v[148:149], v[148:149], v[0:1]
	v_pk_fma_f32 v[150:151], v[84:85], v[108:109], v[150:151] op_sel_hi:[0,1,1]
	v_pk_mul_f32 v[108:109], v[24:25], v[146:147] op_sel_hi:[0,1]
	v_pk_mul_f32 v[144:145], v[24:25], v[144:145] op_sel_hi:[0,1]
	v_pk_fma_f32 v[148:149], v[84:85], v[160:161], v[148:149] op_sel_hi:[0,1,1]
	v_lshlrev_b32_e32 v160, 16, v106
	v_and_b32_e32 v161, 0xffff0000, v106
	v_lshlrev_b32_e32 v106, 16, v107
	v_and_b32_e32 v107, 0xffff0000, v107
	v_pk_mul_f32 v[144:145], v[144:145], v[4:5]
	v_pk_mul_f32 v[108:109], v[108:109], v[6:7]
	v_pk_mul_f32 v[142:143], v[24:25], v[142:143] op_sel_hi:[0,1]
	v_pk_fma_f32 v[108:109], v[84:85], v[106:107], v[108:109] op_sel_hi:[0,1,1]
	v_pk_fma_f32 v[106:107], v[84:85], v[160:161], v[144:145] op_sel_hi:[0,1,1]
	v_lshlrev_b32_e32 v144, 16, v100
	v_and_b32_e32 v145, 0xffff0000, v100
	v_lshlrev_b32_e32 v100, 16, v101
	v_and_b32_e32 v101, 0xffff0000, v101
	v_pk_mul_f32 v[142:143], v[142:143], v[10:11]
	v_pk_mul_f32 v[138:139], v[24:25], v[138:139] op_sel_hi:[0,1]
	v_pk_mul_f32 v[136:137], v[24:25], v[136:137] op_sel_hi:[0,1]
	v_pk_mul_f32 v[140:141], v[24:25], v[140:141] op_sel_hi:[0,1]
	v_pk_fma_f32 v[142:143], v[84:85], v[100:101], v[142:143] op_sel_hi:[0,1,1]
	v_lshlrev_b32_e32 v100, 16, v86
	v_and_b32_e32 v101, 0xffff0000, v86
	v_lshlrev_b32_e32 v86, 16, v87
	v_and_b32_e32 v87, 0xffff0000, v87
	v_pk_mul_f32 v[136:137], v[136:137], v[12:13]
	v_pk_mul_f32 v[138:139], v[138:139], v[14:15]
	v_pk_mul_f32 v[140:141], v[140:141], v[8:9]
	v_pk_fma_f32 v[138:139], v[84:85], v[86:87], v[138:139] op_sel_hi:[0,1,1]
	v_pk_fma_f32 v[136:137], v[84:85], v[100:101], v[136:137] op_sel_hi:[0,1,1]
	v_lshl_add_u64 v[86:87], v[124:125], 0, s[0:1]
	v_pk_fma_f32 v[140:141], v[84:85], v[144:145], v[140:141] op_sel_hi:[0,1,1]
	global_store_dwordx4 v[86:87], v[136:139], off
	global_store_dwordx4 v[86:87], v[140:143], off offset:1024
	global_store_dwordx4 v[86:87], v[106:109], off offset:2048
	global_store_dwordx4 v[86:87], v[148:151], off offset:3072
.LBB0_1285:
	s_waitcnt lgkmcnt(0)
	v_pk_add_f32 v[86:87], v[156:157], v[158:159]
	s_mov_b32 s0, 0x3a800000
	v_mov_b32_e32 v24, 0x358637bd
	v_pk_fma_f32 v[86:87], v[86:87], s[0:1], v[24:25] op_sel_hi:[1,0,0]
	s_mov_b32 s0, 0x800000
	v_cmp_gt_f32_e64 s[4:5], s0, v87
	s_andn2_b64 vcc, exec, s[6:7]
	v_cmp_gt_f32_e64 s[6:7], s0, v86
	s_cbranch_vccnz .LBB0_1287
	v_mul_f32_e32 v19, 0x4b800000, v87
	v_cndmask_b32_e64 v19, v87, v19, s[4:5]
	v_rsq_f32_e32 v19, v19
	v_lshlrev_b32_e32 v136, 16, v78
	v_and_b32_e32 v137, 0xffff0000, v78
	v_lshlrev_b32_e32 v138, 16, v79
	v_mul_f32_e32 v21, 0x45800000, v19
	v_cndmask_b32_e64 v19, v19, v21, s[4:5]
	v_mul_f32_e32 v24, 0.5, v19
	v_and_b32_e32 v139, 0xffff0000, v79
	v_pk_mul_f32 v[78:79], v[24:25], v[134:135] op_sel_hi:[0,1]
	v_lshlrev_b32_e32 v100, 16, v82
	v_and_b32_e32 v101, 0xffff0000, v82
	v_lshlrev_b32_e32 v82, 16, v83
	v_and_b32_e32 v83, 0xffff0000, v83
	v_lshlrev_b32_e32 v106, 16, v80
	v_and_b32_e32 v107, 0xffff0000, v80
	v_lshlrev_b32_e32 v108, 16, v81
	v_and_b32_e32 v109, 0xffff0000, v81
	v_pk_mul_f32 v[80:81], v[24:25], v[128:129] op_sel_hi:[0,1]
	s_waitcnt vmcnt(3)
	v_pk_mul_f32 v[78:79], v[78:79], v[14:15]
	v_pk_mul_f32 v[128:129], v[80:81], v[12:13]
	v_pk_fma_f32 v[80:81], v[56:57], v[82:83], v[78:79] op_sel_hi:[0,1,1]
	v_mov_b32_e32 v82, v127
	v_mov_b32_e32 v83, v133
	v_pk_mul_f32 v[82:83], v[24:25], v[82:83] op_sel_hi:[0,1]
	v_mov_b32_e32 v127, v132
	s_waitcnt vmcnt(2)
	v_pk_mul_f32 v[82:83], v[82:83], v[10:11]
	v_pk_fma_f32 v[78:79], v[56:57], v[100:101], v[128:129] op_sel_hi:[0,1,1]
	v_pk_mul_f32 v[100:101], v[24:25], v[126:127] op_sel_hi:[0,1]
	v_pk_fma_f32 v[108:109], v[56:57], v[108:109], v[82:83] op_sel_hi:[0,1,1]
	v_pk_mul_f32 v[82:83], v[24:25], v[130:131] op_sel_hi:[0,1]
	v_pk_mul_f32 v[100:101], v[100:101], v[8:9]
	s_waitcnt vmcnt(1)
	v_pk_mul_f32 v[82:83], v[82:83], v[6:7]
	v_pk_fma_f32 v[106:107], v[56:57], v[106:107], v[100:101] op_sel_hi:[0,1,1]
	v_pk_mul_f32 v[100:101], v[24:25], v[122:123] op_sel_hi:[0,1]
	v_pk_fma_f32 v[128:129], v[56:57], v[138:139], v[82:83] op_sel_hi:[0,1,1]
	v_pk_mul_f32 v[82:83], v[24:25], v[104:105] op_sel_hi:[0,1]
	v_mov_b32_e32 v84, v103
	v_lshlrev_b32_e32 v140, 16, v74
	v_and_b32_e32 v141, 0xffff0000, v74
	v_lshlrev_b32_e32 v74, 16, v75
	v_and_b32_e32 v75, 0xffff0000, v75
	v_pk_mul_f32 v[100:101], v[100:101], v[4:5]
	v_pk_mul_f32 v[84:85], v[24:25], v[84:85] op_sel_hi:[0,1]
	s_waitcnt vmcnt(0)
	v_pk_mul_f32 v[82:83], v[82:83], v[2:3]
	s_lshl_b64 s[0:1], s[20:21], 12
	v_pk_fma_f32 v[126:127], v[56:57], v[136:137], v[100:101] op_sel_hi:[0,1,1]
	v_pk_mul_f32 v[100:101], v[84:85], v[0:1]
	v_pk_fma_f32 v[84:85], v[56:57], v[74:75], v[82:83] op_sel_hi:[0,1,1]
	v_lshl_add_u64 v[74:75], v[124:125], 0, s[0:1]
	v_pk_fma_f32 v[82:83], v[56:57], v[140:141], v[100:101] op_sel_hi:[0,1,1]
	global_store_dwordx4 v[74:75], v[78:81], off
	global_store_dwordx4 v[74:75], v[106:109], off offset:1024
	global_store_dwordx4 v[74:75], v[126:129], off offset:2048
	global_store_dwordx4 v[74:75], v[82:85], off offset:3072

; __device__ __forceinline__ const float* xrow_ptr(const Ctx& C, int row) { return row < MPROMPT ? C.in(0) + (size_t)row * DM : C.in(1) + (size_t)(row - MPROMPT) * DM; }
; __device__ __forceinline__ v4f ld4_bf16(const bf16* p) { const v2u w = *(const v2u*)p; return (v4f){bf_lo(w.x), bf_hi(w.x), bf_lo(w.y), bf_hi(w.y)}; }
; template <int R, bool BASE_F32, bool OUT_F32>
; __device__ __forceinline__ void rows_res(const Ctx& C, int m0, int stride, int mx, const float* gpost, float scale, int lane) {
;     v4f d[R][4], b[R][4]; int mr[R]; bool ok[R]; float r1[R];
;     const bf16* D = C.D(); bf16* XN = C.XN();
; #pragma unroll
;     for (int r = 0; r < R; ++r) { mr[r] = (r == 4) ? mx : m0 + r * stride; ok[r] = (r == 4) ? (mx < M) : (mr[r] < MPROMPT); const int mm = ok[r] ? mr[r] : 0;
; #pragma unroll
;         for (int j = 0; j < 4; ++j) d[r][j] = ld4_bf16(D + (size_t)mm * DM + 4 * lane + 256 * j);
;         if (BASE_F32) { const float* x = xrow_ptr(C, mm);
; #pragma unroll
;             for (int j = 0; j < 4; ++j) b[r][j] = ld4_f32(x + 4 * lane + 256 * j);
;         } else { const float inv = C.RS()[mm];
; #pragma unroll
;             for (int j = 0; j < 4; ++j) b[r][j] = ld4_bf16(XN + (size_t)mm * DM + 4 * lane + 256 * j) * inv;
;         } }
.LBB0_1296:
	s_mov_b64 s[0:1], s[80:81]
	s_load_dwordx2 s[4:5], s[0:1], 0x110
	s_mov_b64 s[0:1], s[80:81]
	s_mov_b64 s[44:45], s[80:81]
	s_load_dwordx2 s[2:3], s[0:1], 0x110
	s_waitcnt lgkmcnt(0)
	v_lshl_add_u64 v[0:1], s[4:5], 0, v[18:19]
	v_lshl_add_u64 v[0:1], v[0:1], 0, s[30:31]
	v_lshl_add_u64 v[2:3], v[0:1], 0, s[8:9]
	s_mov_b64 s[0:1], s[80:81]
	global_load_dwordx2 v[4:5], v[2:3], off
	global_load_dwordx2 v[6:7], v[2:3], off offset:512
	global_load_dwordx2 v[8:9], v[2:3], off offset:1024
	global_load_dwordx2 v[10:11], v[2:3], off offset:1536
	s_load_dwordx2 s[0:1], s[0:1], 0x110
	v_lshl_add_u64 v[2:3], s[2:3], 0, v[18:19]
	v_lshl_add_u64 v[2:3], v[2:3], 0, s[34:35]
	v_lshl_add_u64 v[12:13], v[2:3], 0, s[8:9]
	s_waitcnt lgkmcnt(0)
	s_add_u32 s0, s0, s36
	s_addc_u32 s1, s1, s37
	global_load_dword v74, v27, s[0:1]
	global_load_dwordx2 v[80:81], v[12:13], off
	global_load_dwordx2 v[90:91], v[12:13], off offset:512
	global_load_dwordx2 v[96:97], v[12:13], off offset:1024
	global_load_dwordx2 v[98:99], v[12:13], off offset:1536
	v_lshl_add_u64 v[12:13], v[0:1], 0, s[12:13]
	s_mov_b64 s[0:1], s[80:81]
	global_load_dwordx2 v[14:15], v[12:13], off
	global_load_dwordx2 v[60:61], v[12:13], off offset:512
	global_load_dwordx2 v[64:65], v[12:13], off offset:1024
	global_load_dwordx2 v[32:33], v[12:13], off offset:1536
	s_load_dwordx2 s[0:1], s[0:1], 0x110
	v_lshl_add_u64 v[12:13], v[2:3], 0, s[12:13]
	v_lshl_add_u64 v[0:1], v[0:1], 0, s[16:17]
	v_lshl_add_u64 v[2:3], v[2:3], 0, s[16:17]
	s_waitcnt lgkmcnt(0)
	s_add_u32 s0, s0, s38
	s_addc_u32 s1, s1, s39
	global_load_dword v44, v27, s[0:1]
	global_load_dwordx2 v[70:71], v[12:13], off
	global_load_dwordx2 v[66:67], v[12:13], off offset:512
	global_load_dwordx2 v[62:63], v[12:13], off offset:1024
	global_load_dwordx2 v[58:59], v[12:13], off offset:1536
	s_nop 0
	global_load_dwordx2 v[12:13], v[0:1], off
	global_load_dwordx2 v[72:73], v[0:1], off offset:512
	global_load_dwordx2 v[88:89], v[0:1], off offset:1024
	global_load_dwordx2 v[34:35], v[0:1], off offset:1536
	s_mov_b64 s[0:1], s[80:81]
	v_lshl_add_u64 v[0:1], s[4:5], 0, v[22:23]
	global_load_dwordx2 v[36:37], v[0:1], off
	global_load_dwordx2 v[100:101], v[0:1], off offset:-1536
	global_load_dwordx2 v[68:69], v[0:1], off offset:-1024
	global_load_dwordx2 v[102:103], v[0:1], off offset:-512
	s_load_dwordx2 s[0:1], s[0:1], 0x110
	s_mov_b64 s[4:5], s[80:81]
	global_load_dwordx2 v[56:57], v[2:3], off
	global_load_dwordx2 v[54:55], v[2:3], off offset:512
	global_load_dwordx2 v[52:53], v[2:3], off offset:1024
	global_load_dwordx2 v[50:51], v[2:3], off offset:1536
	v_lshl_add_u64 v[0:1], s[2:3], 0, v[22:23]
	v_add_co_u32_e32 v0, vcc, s47, v0
	s_waitcnt lgkmcnt(0)
	s_add_u32 s0, s0, s40
	s_addc_u32 s1, s1, s41
	global_load_dword v30, v27, s[0:1]
	s_load_dwordx2 s[0:1], s[4:5], 0x110
	v_addc_co_u32_e32 v1, vcc, -1, v1, vcc
	s_waitcnt lgkmcnt(0)
	s_add_u32 s0, s0, s43
	s_addc_u32 s1, s1, s48
	global_load_dword v28, v19, s[0:1]
	s_mov_b64 s[0:1], s[80:81]
	s_andn2_b64 vcc, exec, s[6:7]
	s_waitcnt vmcnt(31)
	v_and_b32_e32 v115, 0xffff0000, v4
	v_and_b32_e32 v119, 0xffff0000, v5
	v_lshlrev_b32_e32 v114, 16, v4
	v_lshlrev_b32_e32 v118, 16, v5
	s_waitcnt vmcnt(30)
	v_and_b32_e32 v121, 0xffff0000, v6
	v_and_b32_e32 v123, 0xffff0000, v7
	v_lshlrev_b32_e32 v120, 16, v6
	v_lshlrev_b32_e32 v122, 16, v7
	v_mul_f32_e32 v2, v123, v123
	v_fmac_f32_e32 v2, v122, v122
	s_waitcnt vmcnt(29)
	v_and_b32_e32 v125, 0xffff0000, v8
	v_and_b32_e32 v127, 0xffff0000, v9
	v_lshlrev_b32_e32 v124, 16, v8
	v_lshlrev_b32_e32 v126, 16, v9
	s_waitcnt vmcnt(28)
	v_and_b32_e32 v129, 0xffff0000, v10
	v_and_b32_e32 v131, 0xffff0000, v11
	s_waitcnt vmcnt(19)
	v_lshlrev_b32_e32 v78, 16, v33
	v_and_b32_e32 v79, 0xffff0000, v33
	v_lshlrev_b32_e32 v128, 16, v10
	v_lshlrev_b32_e32 v130, 16, v11
	v_and_b32_e32 v109, 0xffff0000, v14
	v_and_b32_e32 v117, 0xffff0000, v15
	v_lshlrev_b32_e32 v108, 16, v14
	v_lshlrev_b32_e32 v116, 16, v15
	v_and_b32_e32 v113, 0xffff0000, v61
	v_and_b32_e32 v112, 0xffff0000, v60
	v_mul_f32_e32 v4, v109, v109
	s_waitcnt vmcnt(10)
	v_lshlrev_b32_e32 v47, 16, v34
	v_and_b32_e32 v45, 0xffff0000, v34
	v_lshlrev_b32_e32 v48, 16, v35
	v_and_b32_e32 v49, 0xffff0000, v35
	s_waitcnt vmcnt(9)
; __device__ __forceinline__ const float* xrow_ptr(const Ctx& C, int row) { return row < MPROMPT ? C.in(0) + (size_t)row * DM : C.in(1) + (size_t)(row - MPROMPT) * DM; }
; __device__ __forceinline__ v4f ld4_bf16(const bf16* p) { const v2u w = *(const v2u*)p; return (v4f){bf_lo(w.x), bf_hi(w.x), bf_lo(w.y), bf_hi(w.y)}; }
; __device__ __forceinline__ float ssq4(v4f v) { return (v.x * v.x + v.y * v.y) + (v.z * v.z + v.w * v.w); }
; template <int R, bool BASE_F32, bool OUT_F32>
; __device__ __forceinline__ void rows_res(const Ctx& C, int m0, int stride, int mx, const float* gpost, float scale, int lane) {
;     ...
;     for (int r = 0; r < R; ++r) { mr[r] = (r == 4) ? mx : m0 + r * stride; ok[r] = (r == 4) ? (mx < M) : (mr[r] < MPROMPT); const int mm = ok[r] ? mr[r] : 0;
; #pragma unroll
;         for (int j = 0; j < 4; ++j) d[r][j] = ld4_bf16(D + (size_t)mm * DM + 4 * lane + 256 * j);
;         if (BASE_F32) { const float* x = xrow_ptr(C, mm);
; #pragma unroll
;             for (int j = 0; j < 4; ++j) b[r][j] = ld4_f32(x + 4 * lane + 256 * j);
;         } else { const float inv = C.RS()[mm];
; #pragma unroll
;             for (int j = 0; j < 4; ++j) b[r][j] = ld4_bf16(XN + (size_t)mm * DM + 4 * lane + 256 * j) * inv;
;         } }
; #pragma unroll
;     for (int r = 0; r < R; ++r) { float s = 0.f;
; #pragma unroll
;         for (int j = 0; j < 4; ++j) s += ssq4(d[r][j]);
;         r1[r] = s; }
	v_lshlrev_b32_e32 v33, 16, v36
	v_and_b32_e32 v31, 0xffff0000, v36
	v_lshlrev_b32_e32 v34, 16, v37
	v_and_b32_e32 v35, 0xffff0000, v37
	global_load_dwordx2 v[42:43], v[0:1], off offset:-1536
	global_load_dwordx2 v[40:41], v[0:1], off offset:-1024
	global_load_dwordx2 v[38:39], v[0:1], off offset:-512
	global_load_dwordx2 v[36:37], v[0:1], off
	v_mul_f32_e32 v0, v115, v115
	v_mul_f32_e32 v1, v119, v119
	v_fmac_f32_e32 v0, v114, v114
	v_fmac_f32_e32 v1, v118, v118
	v_add_f32_e32 v0, v0, v1
	v_mul_f32_e32 v1, v121, v121
	v_fmac_f32_e32 v1, v120, v120
	v_add_f32_e32 v1, v1, v2
	v_add_f32_e32 v0, v0, v1
	v_mul_f32_e32 v1, v125, v125
	v_mul_f32_e32 v2, v127, v127
	v_fmac_f32_e32 v1, v124, v124
	v_fmac_f32_e32 v2, v126, v126
	v_add_f32_e32 v1, v1, v2
	v_add_f32_e32 v0, v0, v1
	v_mul_f32_e32 v1, v129, v129
	v_mul_f32_e32 v2, v131, v131
	v_fmac_f32_e32 v1, v128, v128
	v_fmac_f32_e32 v2, v130, v130
	v_add_f32_e32 v1, v1, v2
	v_add_f32_e32 v29, v0, v1
	v_mul_f32_e32 v0, v117, v117
	v_lshlrev_b32_e32 v77, 16, v32
	v_pk_fma_f32 v[0:1], v[116:117], v[116:117], v[0:1] op_sel_hi:[1,1,0]
	v_lshlrev_b32_e32 v107, 16, v61
	v_lshlrev_b32_e32 v106, 16, v60
	v_pk_mul_f32 v[2:3], v[112:113], v[112:113]
	v_pk_fma_f32 v[4:5], v[108:109], v[108:109], v[4:5] op_sel_hi:[1,1,0]
	v_and_b32_e32 v75, 0xffff0000, v32
	v_pk_fma_f32 v[2:3], v[106:107], v[106:107], v[2:3]
	v_mov_b32_e32 v76, v4
	v_mov_b32_e32 v6, v0
	v_mov_b32_e32 v7, v77
	v_mul_f32_e32 v8, v75, v75
	v_pk_add_f32 v[0:1], v[4:5], v[0:1]
	v_pk_mul_f32 v[4:5], v[76:77], v[6:7]
	v_pk_add_f32 v[2:3], v[2:3], v[2:3] op_sel:[0,1] op_sel_hi:[1,0]
	v_and_b32_e32 v105, 0xffff0000, v64
	v_and_b32_e32 v111, 0xffff0000, v65
	v_mov_b32_e32 v1, v5
	v_mov_b32_e32 v3, v8
	v_lshlrev_b32_e32 v104, 16, v64
	v_lshlrev_b32_e32 v110, 16, v65
	v_pk_add_f32 v[0:1], v[0:1], v[2:3]
	v_mul_f32_e32 v2, v105, v105
	v_mul_f32_e32 v4, v111, v111
	v_mul_f32_e32 v9, v78, v78
	v_mul_f32_e32 v10, v79, v79
	v_pk_fma_f32 v[2:3], v[104:105], v[104:105], v[2:3] op_sel_hi:[1,1,0]
	v_pk_fma_f32 v[4:5], v[110:111], v[110:111], v[4:5] op_sel_hi:[1,1,0]
	v_mov_b32_e32 v3, v9
	v_mov_b32_e32 v5, v10
	v_pk_add_f32 v[2:3], v[2:3], v[4:5]
	v_and_b32_e32 v87, 0xffff0000, v12
	v_pk_add_f32 v[0:1], v[0:1], v[2:3]
	v_and_b32_e32 v95, 0xffff0000, v13
	v_add_f32_e32 v76, v0, v1
	v_lshlrev_b32_e32 v86, 16, v12
	v_lshlrev_b32_e32 v94, 16, v13
	v_mul_f32_e32 v0, v95, v95
	v_and_b32_e32 v93, 0xffff0000, v73
	v_and_b32_e32 v92, 0xffff0000, v72
	v_mul_f32_e32 v4, v87, v87
	v_pk_fma_f32 v[0:1], v[94:95], v[94:95], v[0:1] op_sel_hi:[1,1,0]
	v_lshlrev_b32_e32 v85, 16, v73
	v_lshlrev_b32_e32 v84, 16, v72
	v_pk_mul_f32 v[2:3], v[92:93], v[92:93]
	v_pk_fma_f32 v[4:5], v[86:87], v[86:87], v[4:5] op_sel_hi:[1,1,0]
	v_pk_fma_f32 v[2:3], v[84:85], v[84:85], v[2:3]
	v_mov_b32_e32 v46, v4
	v_mov_b32_e32 v6, v0
	v_mov_b32_e32 v7, v47
	v_mul_f32_e32 v8, v45, v45
	v_pk_add_f32 v[0:1], v[4:5], v[0:1]
	v_pk_mul_f32 v[4:5], v[46:47], v[6:7]
	v_pk_add_f32 v[2:3], v[2:3], v[2:3] op_sel:[0,1] op_sel_hi:[1,0]
	v_lshlrev_b32_e32 v82, 16, v88
	v_and_b32_e32 v83, 0xffff0000, v88
	v_lshlrev_b32_e32 v88, 16, v89
	v_and_b32_e32 v89, 0xffff0000, v89
	v_mov_b32_e32 v1, v5
	v_mov_b32_e32 v3, v8
	v_pk_add_f32 v[0:1], v[0:1], v[2:3]
	v_mul_f32_e32 v2, v83, v83
	v_mul_f32_e32 v4, v89, v89
	v_mul_f32_e32 v9, v48, v48
	v_mul_f32_e32 v10, v49, v49
	v_pk_fma_f32 v[2:3], v[82:83], v[82:83], v[2:3] op_sel_hi:[1,1,0]
	v_pk_fma_f32 v[4:5], v[88:89], v[88:89], v[4:5] op_sel_hi:[1,1,0]
	v_mov_b32_e32 v3, v9
	v_mov_b32_e32 v5, v10
	v_pk_add_f32 v[2:3], v[2:3], v[4:5]
	s_waitcnt vmcnt(12)
	v_and_b32_e32 v73, 0xffff0000, v101
	v_pk_add_f32 v[132:133], v[0:1], v[2:3]
	v_lshlrev_b32_e32 v72, 16, v101
	v_mul_f32_e32 v0, v73, v73
	v_pk_fma_f32 v[134:135], v[72:73], v[72:73], v[0:1] op_sel_hi:[1,1,0]
	global_load_dwordx4 v[12:15], v[20:21], off
	global_load_dwordx4 v[8:11], v[20:21], off offset:1024
	global_load_dwordx4 v[4:7], v[20:21], off offset:2048
	global_load_dwordx4 v[0:3], v[20:21], off offset:3072
	v_and_b32_e32 v65, 0xffff0000, v100
	v_lshlrev_b32_e32 v64, 16, v100
	s_waitcnt vmcnt(15)
; __device__ __forceinline__ float ssq4(v4f v) { return (v.x * v.x + v.y * v.y) + (v.z * v.z + v.w * v.w); }
; template <int R, bool BASE_F32, bool OUT_F32>
; __device__ __forceinline__ void rows_res(const Ctx& C, int m0, int stride, int mx, const float* gpost, float scale, int lane) {
;     ...
;     for (int r = 0; r < R; ++r) { float s = 0.f;
; #pragma unroll
;         for (int j = 0; j < 4; ++j) s += ssq4(d[r][j]);
;         r1[r] = s; }
; #pragma unroll
;     for (int r = 0; r < R; ++r) r1[r] = rsqrtf(wave_sum(r1[r]) * (1.f / DM) + EPS) * scale;
	v_lshlrev_b32_e32 v61, 16, v69
	v_lshlrev_b32_e32 v60, 16, v68
	v_and_b32_e32 v69, 0xffff0000, v69
	v_and_b32_e32 v68, 0xffff0000, v68
	v_mul_f32_e32 v32, v65, v65
	v_pk_mul_f32 v[100:101], v[68:69], v[68:69]
	v_pk_fma_f32 v[138:139], v[64:65], v[64:65], v[32:33] op_sel_hi:[1,1,0]
	v_pk_fma_f32 v[136:137], v[60:61], v[60:61], v[100:101]
	v_mov_b32_e32 v32, v138
	v_mov_b32_e32 v140, v134
	v_mov_b32_e32 v141, v33
	s_waitcnt vmcnt(14)
	v_and_b32_e32 v101, 0xffff0000, v102
	v_mul_f32_e32 v46, v31, v31
	v_pk_add_f32 v[134:135], v[138:139], v[134:135]
	v_pk_mul_f32 v[138:139], v[32:33], v[140:141]
	v_pk_add_f32 v[136:137], v[136:137], v[136:137] op_sel:[0,1] op_sel_hi:[1,0]
	v_lshlrev_b32_e32 v100, 16, v102
	v_lshlrev_b32_e32 v102, 16, v103
	v_and_b32_e32 v103, 0xffff0000, v103
	v_mov_b32_e32 v135, v139
	v_mov_b32_e32 v137, v46
	v_mul_f32_e32 v32, v101, v101
	v_pk_add_f32 v[134:135], v[134:135], v[136:137]
	v_pk_fma_f32 v[136:137], v[100:101], v[100:101], v[32:33] op_sel_hi:[1,1,0]
	v_mul_f32_e32 v32, v103, v103
	v_mul_f32_e32 v142, v34, v34
	v_mul_f32_e32 v143, v35, v35
	v_pk_fma_f32 v[138:139], v[102:103], v[102:103], v[32:33] op_sel_hi:[1,1,0]
	v_mov_b32_e32 v137, v142
	v_mov_b32_e32 v139, v143
	v_pk_add_f32 v[136:137], v[136:137], v[138:139]
	s_nop 1
	v_mov_b32_dpp v32, v29 quad_perm:[1,0,3,2] row_mask:0xf bank_mask:0xf
	v_pk_add_f32 v[134:135], v[134:135], v[136:137]
	v_mov_b32_e32 v137, v132
	v_mov_b32_e32 v136, v134
	v_mov_b32_e32 v132, v135
	v_pk_add_f32 v[132:133], v[136:137], v[132:133]
	s_nop 1
	v_mov_b32_dpp v46, v76 quad_perm:[1,0,3,2] row_mask:0xf bank_mask:0xf
	s_nop 1
	v_mov_b32_dpp v135, v133 quad_perm:[1,0,3,2] row_mask:0xf bank_mask:0xf
	s_nop 1
	v_mov_b32_dpp v134, v132 quad_perm:[1,0,3,2] row_mask:0xf bank_mask:0xf
	s_waitcnt lgkmcnt(0)
	v_add_f32_e32 v29, v29, v32
	s_nop 1
	v_mov_b32_dpp v32, v29 quad_perm:[2,3,0,1] row_mask:0xf bank_mask:0xf
	s_waitcnt lgkmcnt(0)
	v_add_f32_e32 v46, v76, v46
	s_nop 1
	v_mov_b32_dpp v76, v46 quad_perm:[2,3,0,1] row_mask:0xf bank_mask:0xf
	s_waitcnt lgkmcnt(0)
	v_pk_add_f32 v[132:133], v[132:133], v[134:135]
	s_nop 1
	v_mov_b32_dpp v135, v133 quad_perm:[2,3,0,1] row_mask:0xf bank_mask:0xf
	s_nop 1
	v_mov_b32_dpp v134, v132 quad_perm:[2,3,0,1] row_mask:0xf bank_mask:0xf
	s_waitcnt lgkmcnt(0)
	v_add_f32_e32 v29, v29, v32
	s_waitcnt lgkmcnt(0)
	v_add_f32_e32 v46, v46, v76
	s_nop 1
	v_mov_b32_dpp v32, v29 row_half_mirror row_mask:0xf bank_mask:0xf
	s_nop 1
	v_mov_b32_dpp v76, v46 row_half_mirror row_mask:0xf bank_mask:0xf
	s_waitcnt lgkmcnt(0)
	v_pk_add_f32 v[132:133], v[132:133], v[134:135]
	s_nop 1
	v_mov_b32_dpp v135, v133 row_half_mirror row_mask:0xf bank_mask:0xf
	s_nop 1
	v_mov_b32_dpp v134, v132 row_half_mirror row_mask:0xf bank_mask:0xf
	s_waitcnt lgkmcnt(0)
	v_add_f32_e32 v29, v29, v32
	s_waitcnt lgkmcnt(0)
	v_add_f32_e32 v46, v46, v76
	s_nop 1
	v_mov_b32_dpp v32, v29 row_mirror row_mask:0xf bank_mask:0xf
	s_nop 1
	v_mov_b32_dpp v76, v46 row_mirror row_mask:0xf bank_mask:0xf
	s_waitcnt lgkmcnt(0)
	v_pk_add_f32 v[132:133], v[132:133], v[134:135]
	s_nop 1
	v_mov_b32_dpp v135, v133 row_mirror row_mask:0xf bank_mask:0xf
	s_nop 1
	v_mov_b32_dpp v134, v132 row_mirror row_mask:0xf bank_mask:0xf
	s_waitcnt lgkmcnt(0)
	v_add_f32_e32 v29, v29, v32
	s_waitcnt lgkmcnt(0)
	v_add_f32_e32 v136, v46, v76
	ds_bpermute_b32 v32, v187, v29
	ds_bpermute_b32 v137, v187, v136
	s_waitcnt lgkmcnt(0)
	v_pk_add_f32 v[132:133], v[132:133], v[134:135]
	ds_bpermute_b32 v135, v187, v133
	ds_bpermute_b32 v134, v187, v132
	s_waitcnt lgkmcnt(0)
	v_add_f32_e32 v46, v29, v32
	s_waitcnt lgkmcnt(0)
	v_add_f32_e32 v29, v136, v137
	s_load_dwordx2 s[44:45], s[0:1], 0x108
	s_waitcnt lgkmcnt(0)
	v_pk_add_f32 v[134:135], v[132:133], v[134:135]
	ds_bpermute_b32 v76, v188, v46
	ds_bpermute_b32 v32, v188, v29
	ds_bpermute_b32 v137, v188, v135
	ds_bpermute_b32 v136, v188, v134
	v_lshl_add_u64 v[132:133], s[44:45], 0, v[16:17]
	s_cbranch_vccz .LBB0_1300
	s_andn2_b64 vcc, exec, s[10:11]
	s_cbranch_vccz .LBB0_1301

;     __device__ __forceinline__ float* out() const { return (float*)karg_in(33); }
; template <int R, bool BASE_F32, bool OUT_F32>
; __device__ __forceinline__ void rows_res(const Ctx& C, int m0, int stride, int mx, const float* gpost, float scale, int lane) {
;     ...
;     for (int r = 0; r < R; ++r) r1[r] = rsqrtf(wave_sum(r1[r]) * (1.f / DM) + EPS) * scale;
; #pragma unroll
;     for (int j = 0; j < 4; ++j) { const v4f gp = ld4_f32(gpost + 4 * lane + 256 * j);
; #pragma unroll
;         for (int r = 0; r < R; ++r) d[r][j] = b[r][j] + d[r][j] * r1[r] * gp; }
;     if (OUT_F32) { float* Y = C.out();
; #pragma unroll
;         for (int r = 0; r < R; ++r)
; #pragma unroll
;             for (int j = 0; j < 4; ++j) if (ok[r]) *(v4f*)(Y + (size_t)mr[r] * DM + 4 * lane + 256 * j) = d[r][j];
.LBB0_1300:
	s_waitcnt lgkmcnt(0)
	v_add_f32_e32 v46, v46, v76
	v_fmamk_f32 v46, v46, 0x3a800000, v26
	v_mul_f32_e32 v76, 0x4b800000, v46
	v_cmp_gt_f32_e32 vcc, s49, v46
	v_lshlrev_b32_e32 v140, 16, v98
	v_and_b32_e32 v141, 0xffff0000, v98
	v_cndmask_b32_e32 v46, v46, v76, vcc
	v_rsq_f32_e32 v46, v46
	v_lshlrev_b32_e32 v98, 16, v99
	v_and_b32_e32 v99, 0xffff0000, v99
	v_lshl_add_u64 v[138:139], v[132:133], 0, s[18:19]
	v_mul_f32_e32 v76, 0x45800000, v46
	v_cndmask_b32_e32 v46, v46, v76, vcc
	v_mul_f32_e32 v46, 0.5, v46
	v_pk_mul_f32 v[130:131], v[46:47], v[130:131] op_sel_hi:[0,1]
	v_pk_mul_f32 v[128:129], v[46:47], v[128:129] op_sel_hi:[0,1]
	s_waitcnt vmcnt(0)
	v_pk_mul_f32 v[130:131], v[130:131], v[2:3]
	v_pk_mul_f32 v[128:129], v[128:129], v[0:1]
	v_pk_fma_f32 v[130:131], v[74:75], v[98:99], v[130:131] op_sel_hi:[0,1,1]
	v_pk_mul_f32 v[98:99], v[46:47], v[126:127] op_sel_hi:[0,1]
	v_pk_mul_f32 v[124:125], v[46:47], v[124:125] op_sel_hi:[0,1]
	v_pk_fma_f32 v[128:129], v[74:75], v[140:141], v[128:129] op_sel_hi:[0,1,1]
	v_lshlrev_b32_e32 v140, 16, v96
	v_and_b32_e32 v141, 0xffff0000, v96
	v_lshlrev_b32_e32 v96, 16, v97
	v_and_b32_e32 v97, 0xffff0000, v97
	v_pk_mul_f32 v[124:125], v[124:125], v[4:5]
	v_pk_mul_f32 v[98:99], v[98:99], v[6:7]
	v_pk_mul_f32 v[122:123], v[46:47], v[122:123] op_sel_hi:[0,1]
	v_pk_fma_f32 v[98:99], v[74:75], v[96:97], v[98:99] op_sel_hi:[0,1,1]
	v_pk_fma_f32 v[96:97], v[74:75], v[140:141], v[124:125] op_sel_hi:[0,1,1]
	v_lshlrev_b32_e32 v124, 16, v90
	v_and_b32_e32 v125, 0xffff0000, v90
	v_lshlrev_b32_e32 v90, 16, v91
	v_and_b32_e32 v91, 0xffff0000, v91
	v_pk_mul_f32 v[120:121], v[46:47], v[120:121] op_sel_hi:[0,1]
	v_pk_mul_f32 v[122:123], v[122:123], v[10:11]
	v_pk_mul_f32 v[118:119], v[46:47], v[118:119] op_sel_hi:[0,1]
	v_pk_mul_f32 v[114:115], v[46:47], v[114:115] op_sel_hi:[0,1]
	v_pk_mul_f32 v[120:121], v[120:121], v[8:9]
	v_pk_fma_f32 v[122:123], v[74:75], v[90:91], v[122:123] op_sel_hi:[0,1,1]
	v_lshlrev_b32_e32 v90, 16, v80
	v_and_b32_e32 v91, 0xffff0000, v80
	v_lshlrev_b32_e32 v80, 16, v81
	v_and_b32_e32 v81, 0xffff0000, v81
	v_pk_mul_f32 v[114:115], v[114:115], v[12:13]
	v_pk_mul_f32 v[118:119], v[118:119], v[14:15]
	v_pk_fma_f32 v[120:121], v[74:75], v[124:125], v[120:121] op_sel_hi:[0,1,1]
	v_pk_fma_f32 v[126:127], v[74:75], v[80:81], v[118:119] op_sel_hi:[0,1,1]
	v_pk_fma_f32 v[124:125], v[74:75], v[90:91], v[114:115] op_sel_hi:[0,1,1]
	global_store_dwordx4 v[138:139], v[124:127], off
	global_store_dwordx4 v[138:139], v[120:123], off offset:1024
	global_store_dwordx4 v[138:139], v[96:99], off offset:2048
	global_store_dwordx4 v[138:139], v[128:131], off offset:3072
	s_andn2_b64 vcc, exec, s[10:11]
	s_cbranch_vccnz .LBB0_1298
.LBB0_1301:
	s_waitcnt lgkmcnt(0)
	v_add_f32_e32 v29, v29, v32
	v_fmamk_f32 v29, v29, 0x3a800000, v26
	v_mul_f32_e32 v32, 0x4b800000, v29
	v_cmp_gt_f32_e32 vcc, s49, v29
	v_lshlrev_b32_e32 v80, 16, v70
	v_and_b32_e32 v81, 0xffff0000, v70
	v_cndmask_b32_e32 v29, v29, v32, vcc
	v_rsq_f32_e32 v29, v29
	v_lshlrev_b32_e32 v70, 16, v71
	v_and_b32_e32 v71, 0xffff0000, v71
	v_lshlrev_b32_e32 v90, 16, v66
	v_mul_f32_e32 v32, 0x45800000, v29
	v_cndmask_b32_e32 v29, v29, v32, vcc
	v_mul_f32_e32 v32, 0.5, v29
	v_pk_mul_f32 v[96:97], v[32:33], v[116:117] op_sel_hi:[0,1]
	v_pk_mul_f32 v[98:99], v[32:33], v[108:109] op_sel_hi:[0,1]
	s_waitcnt vmcnt(3)
	v_pk_mul_f32 v[96:97], v[14:15], v[96:97]
	v_pk_mul_f32 v[108:109], v[12:13], v[98:99]
	v_pk_fma_f32 v[98:99], v[44:45], v[70:71], v[96:97] op_sel_hi:[0,1,1]
	v_mov_b32_e32 v70, v107
	v_mov_b32_e32 v71, v113
	v_pk_mul_f32 v[70:71], v[32:33], v[70:71] op_sel_hi:[0,1]
	v_and_b32_e32 v91, 0xffff0000, v66
	v_lshlrev_b32_e32 v66, 16, v67
	v_and_b32_e32 v67, 0xffff0000, v67
	s_waitcnt vmcnt(2)
	v_pk_mul_f32 v[70:71], v[70:71], v[10:11]
	v_pk_fma_f32 v[96:97], v[44:45], v[80:81], v[108:109] op_sel_hi:[0,1,1]
	v_pk_fma_f32 v[108:109], v[44:45], v[66:67], v[70:71] op_sel_hi:[0,1,1]
	v_pk_mul_f32 v[66:67], v[32:33], v[110:111] op_sel_hi:[0,1]
	v_lshlrev_b32_e32 v114, 16, v62
	v_and_b32_e32 v115, 0xffff0000, v62
	v_lshlrev_b32_e32 v62, 16, v63
	v_and_b32_e32 v63, 0xffff0000, v63
	s_waitcnt vmcnt(1)
	v_pk_mul_f32 v[66:67], v[66:67], v[6:7]
	v_mov_b32_e32 v107, v112
	v_pk_fma_f32 v[112:113], v[44:45], v[62:63], v[66:67] op_sel_hi:[0,1,1]
	v_pk_mul_f32 v[62:63], v[32:33], v[78:79] op_sel_hi:[0,1]
	v_mov_b32_e32 v74, v77
	v_lshlrev_b32_e32 v118, 16, v58
	v_and_b32_e32 v119, 0xffff0000, v58
	v_lshlrev_b32_e32 v58, 16, v59
	v_and_b32_e32 v59, 0xffff0000, v59
	v_pk_mul_f32 v[80:81], v[32:33], v[106:107] op_sel_hi:[0,1]
	v_pk_mul_f32 v[70:71], v[32:33], v[104:105] op_sel_hi:[0,1]
	v_pk_mul_f32 v[66:67], v[32:33], v[74:75] op_sel_hi:[0,1]
	s_waitcnt vmcnt(0)
	v_pk_mul_f32 v[62:63], v[62:63], v[2:3]
	v_pk_mul_f32 v[80:81], v[80:81], v[8:9]
	v_pk_mul_f32 v[70:71], v[70:71], v[4:5]
	v_pk_mul_f32 v[66:67], v[66:67], v[0:1]
	v_pk_fma_f32 v[76:77], v[44:45], v[58:59], v[62:63] op_sel_hi:[0,1,1]
	v_lshl_add_u64 v[58:59], v[132:133], 0, s[20:21]
	v_pk_fma_f32 v[106:107], v[44:45], v[90:91], v[80:81] op_sel_hi:[0,1,1]
	v_pk_fma_f32 v[110:111], v[44:45], v[114:115], v[70:71] op_sel_hi:[0,1,1]
	v_pk_fma_f32 v[74:75], v[44:45], v[118:119], v[66:67] op_sel_hi:[0,1,1]
	global_store_dwordx4 v[58:59], v[96:99], off
	global_store_dwordx4 v[58:59], v[106:109], off offset:1024
	global_store_dwordx4 v[58:59], v[110:113], off offset:2048
	global_store_dwordx4 v[58:59], v[74:77], off offset:3072
	s_branch .LBB0_1298
